# x-update row loops rewritten by hand: all 8 prompt rows of a wave loaded up front (32 loads in flight), gains loaded once
# speedup vs baseline: 1.0088x; 1.0088x over previous
.LBB0_446:
	s_waitcnt lgkmcnt(0)
	v_cndmask_b32_e64 v0, 0, 1, s[24:25]
	v_cmp_ne_u32_e64 s[0:1], 1, v0
	s_andn2_b64 vcc, exec, s[24:25]
	s_nop 0
	v_writelane_b32 v235, s0, 52
	s_barrier
	s_nop 0
	v_writelane_b32 v235, s1, 53
	v_mbcnt_lo_u32_b32 v0, -1, 0
	v_mbcnt_hi_u32_b32 v0, -1, v0
	s_cbranch_vccnz .LBB0_465
	v_lshlrev_b32_e32 v2, 3, v0
	v_ashrrev_i32_e32 v3, 31, v2
	v_readlane_b32 s4, v235, 4
	v_lshlrev_b64 v[4:5], 1, v[2:3]
	v_lshlrev_b64 v[2:3], 2, v[2:3]
	v_readlane_b32 s5, v235, 5
	v_readlane_b32 s6, v235, 6
	v_readlane_b32 s7, v235, 7
	v_readlane_b32 s8, v235, 8
	v_readlane_b32 s9, v235, 9
	v_readlane_b32 s10, v235, 10
	v_readlane_b32 s11, v235, 11
	v_readlane_b32 s12, v235, 12
	v_readlane_b32 s13, v235, 13
	v_readlane_b32 s14, v235, 14
	v_readlane_b32 s15, v235, 15
	v_readlane_b32 s16, v235, 16
	v_readlane_b32 s17, v235, 17
	v_readlane_b32 s18, v235, 18
	v_readlane_b32 s19, v235, 19
	v_lshl_add_u64 v[60:61], s[86:87], 0, v[4:5]
	v_lshl_add_u64 v[62:63], s[90:91], 0, v[2:3]
	v_lshl_add_u64 v[64:65], s[54:55], 0, v[4:5]
	v_lshl_add_u64 v[66:67], s[14:15], 0, v[2:3]
	s_mov_b32 s1, 0
	v_cmp_eq_u32_e64 s[4:5], 0, v0
	s_mov_b64 s[6:7], 0x200000
	s_mov_b64 s[8:9], 0x200800
	s_mov_b64 s[10:11], 0x400000
	s_mov_b64 s[12:13], 0x400800
	s_mov_b64 s[14:15], 0x600000
	s_mov_b64 s[16:17], 0x600800
	s_mov_b64 s[18:19], 0x800000
	s_mov_b32 s48, 0x800000
	s_mov_b64 s[20:21], 0x800800
	s_mov_b64 s[22:23], 0xa00000
	s_mov_b64 s[24:25], 0xa00800
	s_mov_b64 s[26:27], 0xc00000
	s_mov_b64 s[28:29], 0xc00800
	s_mov_b64 s[34:35], 0xe00000
	s_mov_b64 s[36:37], 0xe00800
	v_mov_b32_e32 v104, 0
	v_mov_b32_e32 v105, 0x358637bd
	s_mov_b32 s40, s80
	v_mbcnt_lo_u32_b32 v176, -1, 0
	v_mbcnt_hi_u32_b32 v176, -1, v176
	v_readlane_b32 s98, v235, 49
	v_readlane_b32 s99, v235, 20
	v_readlane_b32 s100, v235, 14
	v_readlane_b32 s101, v235, 15
	s_nop 3
	s_lshr_b32 vcc_lo, s98, 3
	s_and_b32 vcc_hi, vcc_lo, 7
	s_lshl_b32 vcc_hi, vcc_hi, 8
	s_lshr_b32 vcc_lo, vcc_lo, 3
	s_lshl_b32 vcc_lo, vcc_lo, 3
	s_add_i32 s98, vcc_hi, vcc_lo
	s_add_i32 s98, s98, s99
	v_lshlrev_b32_e32 v177, 4, v176
	s_lshl_b32 s99, s98, 11
	v_add_u32_e32 v177, s99, v177
	v_add_u32_e32 v178, 0x1800000, v177
	v_add_u32_e32 v179, 0x9e00000, v177
	v_lshlrev_b32_e32 v180, 5, v176
	global_load_dwordx4 v[128:131], v180, s[100:101]
	global_load_dwordx4 v[132:135], v180, s[100:101] offset:16
	global_load_dwordx4 v[136:139], v180, s[100:101] offset:2048
	global_load_dwordx4 v[140:143], v180, s[100:101] offset:2064
	v_mov_b32_e32 v182, 0x358637bd
	global_load_dwordx4 v[0:3], v178, s[78:79]
	global_load_dwordx4 v[4:7], v178, s[78:79] offset:1024
	global_load_dwordx4 v[8:11], v179, s[78:79]
	global_load_dwordx4 v[12:15], v179, s[78:79] offset:1024
	v_add_u32_e32 v178, 0x400000, v178
	v_add_u32_e32 v179, 0x400000, v179
	global_load_dwordx4 v[16:19], v178, s[78:79]
	global_load_dwordx4 v[20:23], v178, s[78:79] offset:1024
	global_load_dwordx4 v[24:27], v179, s[78:79]
	global_load_dwordx4 v[28:31], v179, s[78:79] offset:1024
	v_add_u32_e32 v178, 0x400000, v178
	v_add_u32_e32 v179, 0x400000, v179
	global_load_dwordx4 v[32:35], v178, s[78:79]
	global_load_dwordx4 v[36:39], v178, s[78:79] offset:1024
	global_load_dwordx4 v[40:43], v179, s[78:79]
	global_load_dwordx4 v[44:47], v179, s[78:79] offset:1024
	v_add_u32_e32 v178, 0x400000, v178
	v_add_u32_e32 v179, 0x400000, v179
	global_load_dwordx4 v[48:51], v178, s[78:79]
	global_load_dwordx4 v[52:55], v178, s[78:79] offset:1024
	global_load_dwordx4 v[56:59], v179, s[78:79]
	global_load_dwordx4 v[60:63], v179, s[78:79] offset:1024
	v_add_u32_e32 v178, 0x400000, v178
	v_add_u32_e32 v179, 0x400000, v179
	global_load_dwordx4 v[64:67], v178, s[78:79]
	global_load_dwordx4 v[68:71], v178, s[78:79] offset:1024
	global_load_dwordx4 v[72:75], v179, s[78:79]
	global_load_dwordx4 v[76:79], v179, s[78:79] offset:1024
	v_add_u32_e32 v178, 0x400000, v178
	v_add_u32_e32 v179, 0x400000, v179
	global_load_dwordx4 v[80:83], v178, s[78:79]
	global_load_dwordx4 v[84:87], v178, s[78:79] offset:1024
	global_load_dwordx4 v[88:91], v179, s[78:79]
	global_load_dwordx4 v[92:95], v179, s[78:79] offset:1024
	v_add_u32_e32 v178, 0x400000, v178
	v_add_u32_e32 v179, 0x400000, v179
	global_load_dwordx4 v[96:99], v178, s[78:79]
	global_load_dwordx4 v[100:103], v178, s[78:79] offset:1024
	global_load_dwordx4 v[104:107], v179, s[78:79]
	global_load_dwordx4 v[108:111], v179, s[78:79] offset:1024
	v_add_u32_e32 v178, 0x400000, v178
	v_add_u32_e32 v179, 0x400000, v179
	global_load_dwordx4 v[112:115], v178, s[78:79]
	global_load_dwordx4 v[116:119], v178, s[78:79] offset:1024
	global_load_dwordx4 v[120:123], v179, s[78:79]
	global_load_dwordx4 v[124:127], v179, s[78:79] offset:1024
	v_mov_b32_e32 v183, s98
	v_lshlrev_b32_e32 v237, 2, v183
	v_add_u32_e32 v237, 0x10000, v237
	v_mov_b32_e32 v179, v183
	s_waitcnt vmcnt(28)
	v_lshlrev_b32_e32 v144, 16, v0
	v_and_b32_e32 v145, 0xffff0000, v0
	v_lshlrev_b32_e32 v146, 16, v1
	v_and_b32_e32 v147, 0xffff0000, v1
	v_lshlrev_b32_e32 v148, 16, v2
	v_and_b32_e32 v149, 0xffff0000, v2
	v_lshlrev_b32_e32 v150, 16, v3
	v_and_b32_e32 v151, 0xffff0000, v3
	v_lshlrev_b32_e32 v152, 16, v4
	v_and_b32_e32 v153, 0xffff0000, v4
	v_lshlrev_b32_e32 v154, 16, v5
	v_and_b32_e32 v155, 0xffff0000, v5
	v_lshlrev_b32_e32 v156, 16, v6
	v_and_b32_e32 v157, 0xffff0000, v6
	v_lshlrev_b32_e32 v158, 16, v7
	v_and_b32_e32 v159, 0xffff0000, v7
	v_lshlrev_b32_e32 v160, 16, v8
	v_and_b32_e32 v161, 0xffff0000, v8
	v_lshlrev_b32_e32 v162, 16, v9
	v_and_b32_e32 v163, 0xffff0000, v9
	v_lshlrev_b32_e32 v164, 16, v10
	v_and_b32_e32 v165, 0xffff0000, v10
	v_lshlrev_b32_e32 v166, 16, v11
	v_and_b32_e32 v167, 0xffff0000, v11
	v_lshlrev_b32_e32 v168, 16, v12
	v_and_b32_e32 v169, 0xffff0000, v12
	v_lshlrev_b32_e32 v170, 16, v13
	v_and_b32_e32 v171, 0xffff0000, v13
	v_lshlrev_b32_e32 v172, 16, v14
	v_and_b32_e32 v173, 0xffff0000, v14
	v_lshlrev_b32_e32 v174, 16, v15
	v_and_b32_e32 v175, 0xffff0000, v15
	v_pk_mul_f32 v[252:253], v[160:161], v[160:161]
	v_pk_mul_f32 v[254:255], v[162:163], v[162:163]
	v_pk_fma_f32 v[252:253], v[164:165], v[164:165], v[252:253]
	v_pk_fma_f32 v[254:255], v[166:167], v[166:167], v[254:255]
	v_pk_fma_f32 v[252:253], v[168:169], v[168:169], v[252:253]
	v_pk_fma_f32 v[254:255], v[170:171], v[170:171], v[254:255]
	v_pk_fma_f32 v[252:253], v[172:173], v[172:173], v[252:253]
	v_pk_fma_f32 v[254:255], v[174:175], v[174:175], v[254:255]
	v_pk_add_f32 v[252:253], v[252:253], v[254:255]
	s_nop 0
	v_add_f32_e32 v183, v252, v253
	s_nop 1
	v_add_f32_dpp v183, v183, v183 quad_perm:[1,0,3,2] row_mask:0xf bank_mask:0xf bound_ctrl:1
	s_nop 1
	v_add_f32_dpp v183, v183, v183 quad_perm:[2,3,0,1] row_mask:0xf bank_mask:0xf bound_ctrl:1
	s_nop 1
	v_add_f32_dpp v183, v183, v183 row_half_mirror row_mask:0xf bank_mask:0xf bound_ctrl:1
	s_nop 1
	v_add_f32_dpp v183, v183, v183 row_mirror row_mask:0xf bank_mask:0xf bound_ctrl:1
	s_nop 1
	v_readlane_b32 s98, v183, 0
	v_readlane_b32 s99, v183, 16
	v_readlane_b32 s100, v183, 32
	v_readlane_b32 s101, v183, 48
	s_nop 1
	v_mov_b32_e32 v183, s98
	v_add_f32_e32 v183, s99, v183
	v_add_f32_e32 v183, s100, v183
	v_add_f32_e32 v183, s101, v183
	v_fmamk_f32 v183, v183, 0x3a800000, v182
	v_cmp_gt_f32_e32 vcc, 0x800000, v183
	v_mul_f32_e32 v181, 0x4b800000, v183
	s_nop 1
	v_cndmask_b32_e32 v183, v183, v181, vcc
	v_rsq_f32_e32 v183, v183
	s_nop 0
	v_mul_f32_e32 v181, 0x45800000, v183
	v_cndmask_b32_e32 v184, v183, v181, vcc
	v_mov_b32_e32 v185, v184
	v_pk_mul_f32 v[160:161], v[160:161], v[184:185]
	v_pk_mul_f32 v[162:163], v[162:163], v[184:185]
	v_pk_mul_f32 v[164:165], v[164:165], v[184:185]
	v_pk_mul_f32 v[166:167], v[166:167], v[184:185]
	v_pk_mul_f32 v[168:169], v[168:169], v[184:185]
	v_pk_mul_f32 v[170:171], v[170:171], v[184:185]
	v_pk_mul_f32 v[172:173], v[172:173], v[184:185]
	v_pk_mul_f32 v[174:175], v[174:175], v[184:185]
	v_pk_fma_f32 v[144:145], v[160:161], v[128:129], v[144:145]
	v_pk_fma_f32 v[146:147], v[162:163], v[130:131], v[146:147]
	v_pk_fma_f32 v[148:149], v[164:165], v[132:133], v[148:149]
	v_pk_fma_f32 v[150:151], v[166:167], v[134:135], v[150:151]
	v_pk_fma_f32 v[152:153], v[168:169], v[136:137], v[152:153]
	v_pk_fma_f32 v[154:155], v[170:171], v[138:139], v[154:155]
	v_pk_fma_f32 v[156:157], v[172:173], v[140:141], v[156:157]
	v_pk_fma_f32 v[158:159], v[174:175], v[142:143], v[158:159]
	v_pk_mul_f32 v[252:253], v[144:145], v[144:145]
	v_pk_mul_f32 v[254:255], v[146:147], v[146:147]
	v_pk_fma_f32 v[252:253], v[148:149], v[148:149], v[252:253]
	v_pk_fma_f32 v[254:255], v[150:151], v[150:151], v[254:255]
	v_pk_fma_f32 v[252:253], v[152:153], v[152:153], v[252:253]
	v_pk_fma_f32 v[254:255], v[154:155], v[154:155], v[254:255]
	v_pk_fma_f32 v[252:253], v[156:157], v[156:157], v[252:253]
	v_pk_fma_f32 v[254:255], v[158:159], v[158:159], v[254:255]
	v_pk_add_f32 v[252:253], v[252:253], v[254:255]
	s_nop 0
	v_add_f32_e32 v183, v252, v253
	s_nop 1
	v_add_f32_dpp v183, v183, v183 quad_perm:[1,0,3,2] row_mask:0xf bank_mask:0xf bound_ctrl:1
	s_nop 1
	v_add_f32_dpp v183, v183, v183 quad_perm:[2,3,0,1] row_mask:0xf bank_mask:0xf bound_ctrl:1
	s_nop 1
	v_add_f32_dpp v183, v183, v183 row_half_mirror row_mask:0xf bank_mask:0xf bound_ctrl:1
	s_nop 1
	v_add_f32_dpp v183, v183, v183 row_mirror row_mask:0xf bank_mask:0xf bound_ctrl:1
	s_nop 1
	v_readlane_b32 s98, v183, 0
	v_readlane_b32 s99, v183, 16
	v_readlane_b32 s100, v183, 32
	v_readlane_b32 s101, v183, 48
	s_nop 1
	v_mov_b32_e32 v183, s98
	v_add_f32_e32 v183, s99, v183
	v_add_f32_e32 v183, s100, v183
	v_add_f32_e32 v183, s101, v183
	v_fmamk_f32 v183, v183, 0x3a800000, v182
	v_cmp_gt_f32_e32 vcc, 0x800000, v183
	v_mul_f32_e32 v181, 0x4b800000, v183
	s_nop 1
	v_cndmask_b32_e32 v183, v183, v181, vcc
	v_rsq_f32_e32 v183, v183
	s_nop 0
	v_mul_f32_e32 v181, 0x45800000, v183
	v_cndmask_b32_e32 v184, v183, v181, vcc
	v_mov_b32_e32 v185, v184
	v_cvt_pk_bf16_f32 v0, v144, v145
	v_cvt_pk_bf16_f32 v1, v146, v147
	v_cvt_pk_bf16_f32 v2, v148, v149
	v_cvt_pk_bf16_f32 v3, v150, v151
	v_cvt_pk_bf16_f32 v4, v152, v153
	v_cvt_pk_bf16_f32 v5, v154, v155
	v_cvt_pk_bf16_f32 v6, v156, v157
	v_cvt_pk_bf16_f32 v7, v158, v159
	v_add_u32_e32 v181, 0x1800000, v177
	global_store_dwordx4 v181, v[0:3], s[78:79]
	global_store_dwordx4 v181, v[4:7], s[78:79] offset:1024
	v_add_u32_e32 v236, 0x0, v237
	s_mov_b64 exec, 1
	global_store_dword v236, v184, s[78:79]
	s_mov_b64 exec, -1
	s_waitcnt vmcnt(24)
	v_lshlrev_b32_e32 v144, 16, v16
	v_and_b32_e32 v145, 0xffff0000, v16
	v_lshlrev_b32_e32 v146, 16, v17
	v_and_b32_e32 v147, 0xffff0000, v17
	v_lshlrev_b32_e32 v148, 16, v18
	v_and_b32_e32 v149, 0xffff0000, v18
	v_lshlrev_b32_e32 v150, 16, v19
	v_and_b32_e32 v151, 0xffff0000, v19
	v_lshlrev_b32_e32 v152, 16, v20
	v_and_b32_e32 v153, 0xffff0000, v20
	v_lshlrev_b32_e32 v154, 16, v21
	v_and_b32_e32 v155, 0xffff0000, v21
	v_lshlrev_b32_e32 v156, 16, v22
	v_and_b32_e32 v157, 0xffff0000, v22
	v_lshlrev_b32_e32 v158, 16, v23
	v_and_b32_e32 v159, 0xffff0000, v23
	v_lshlrev_b32_e32 v160, 16, v24
	v_and_b32_e32 v161, 0xffff0000, v24
	v_lshlrev_b32_e32 v162, 16, v25
	v_and_b32_e32 v163, 0xffff0000, v25
	v_lshlrev_b32_e32 v164, 16, v26
	v_and_b32_e32 v165, 0xffff0000, v26
	v_lshlrev_b32_e32 v166, 16, v27
	v_and_b32_e32 v167, 0xffff0000, v27
	v_lshlrev_b32_e32 v168, 16, v28
	v_and_b32_e32 v169, 0xffff0000, v28
	v_lshlrev_b32_e32 v170, 16, v29
	v_and_b32_e32 v171, 0xffff0000, v29
	v_lshlrev_b32_e32 v172, 16, v30
	v_and_b32_e32 v173, 0xffff0000, v30
	v_lshlrev_b32_e32 v174, 16, v31
	v_and_b32_e32 v175, 0xffff0000, v31
	v_pk_mul_f32 v[252:253], v[160:161], v[160:161]
	v_pk_mul_f32 v[254:255], v[162:163], v[162:163]
	v_pk_fma_f32 v[252:253], v[164:165], v[164:165], v[252:253]
	v_pk_fma_f32 v[254:255], v[166:167], v[166:167], v[254:255]
	v_pk_fma_f32 v[252:253], v[168:169], v[168:169], v[252:253]
	v_pk_fma_f32 v[254:255], v[170:171], v[170:171], v[254:255]
	v_pk_fma_f32 v[252:253], v[172:173], v[172:173], v[252:253]
	v_pk_fma_f32 v[254:255], v[174:175], v[174:175], v[254:255]
	v_pk_add_f32 v[252:253], v[252:253], v[254:255]
	s_nop 0
	v_add_f32_e32 v183, v252, v253
	s_nop 1
	v_add_f32_dpp v183, v183, v183 quad_perm:[1,0,3,2] row_mask:0xf bank_mask:0xf bound_ctrl:1
	s_nop 1
	v_add_f32_dpp v183, v183, v183 quad_perm:[2,3,0,1] row_mask:0xf bank_mask:0xf bound_ctrl:1
	s_nop 1
	v_add_f32_dpp v183, v183, v183 row_half_mirror row_mask:0xf bank_mask:0xf bound_ctrl:1
	s_nop 1
	v_add_f32_dpp v183, v183, v183 row_mirror row_mask:0xf bank_mask:0xf bound_ctrl:1
	s_nop 1
	v_readlane_b32 s98, v183, 0
	v_readlane_b32 s99, v183, 16
	v_readlane_b32 s100, v183, 32
	v_readlane_b32 s101, v183, 48
	s_nop 1
	v_mov_b32_e32 v183, s98
	v_add_f32_e32 v183, s99, v183
	v_add_f32_e32 v183, s100, v183
	v_add_f32_e32 v183, s101, v183
	v_fmamk_f32 v183, v183, 0x3a800000, v182
	v_cmp_gt_f32_e32 vcc, 0x800000, v183
	v_mul_f32_e32 v181, 0x4b800000, v183
	s_nop 1
	v_cndmask_b32_e32 v183, v183, v181, vcc
	v_rsq_f32_e32 v183, v183
	s_nop 0
	v_mul_f32_e32 v181, 0x45800000, v183
	v_cndmask_b32_e32 v184, v183, v181, vcc
	v_mov_b32_e32 v185, v184
	v_pk_mul_f32 v[160:161], v[160:161], v[184:185]
	v_pk_mul_f32 v[162:163], v[162:163], v[184:185]
	v_pk_mul_f32 v[164:165], v[164:165], v[184:185]
	v_pk_mul_f32 v[166:167], v[166:167], v[184:185]
	v_pk_mul_f32 v[168:169], v[168:169], v[184:185]
	v_pk_mul_f32 v[170:171], v[170:171], v[184:185]
	v_pk_mul_f32 v[172:173], v[172:173], v[184:185]
	v_pk_mul_f32 v[174:175], v[174:175], v[184:185]
	v_pk_fma_f32 v[144:145], v[160:161], v[128:129], v[144:145]
	v_pk_fma_f32 v[146:147], v[162:163], v[130:131], v[146:147]
	v_pk_fma_f32 v[148:149], v[164:165], v[132:133], v[148:149]
	v_pk_fma_f32 v[150:151], v[166:167], v[134:135], v[150:151]
	v_pk_fma_f32 v[152:153], v[168:169], v[136:137], v[152:153]
	v_pk_fma_f32 v[154:155], v[170:171], v[138:139], v[154:155]
	v_pk_fma_f32 v[156:157], v[172:173], v[140:141], v[156:157]
	v_pk_fma_f32 v[158:159], v[174:175], v[142:143], v[158:159]
	v_pk_mul_f32 v[252:253], v[144:145], v[144:145]
	v_pk_mul_f32 v[254:255], v[146:147], v[146:147]
	v_pk_fma_f32 v[252:253], v[148:149], v[148:149], v[252:253]
	v_pk_fma_f32 v[254:255], v[150:151], v[150:151], v[254:255]
	v_pk_fma_f32 v[252:253], v[152:153], v[152:153], v[252:253]
	v_pk_fma_f32 v[254:255], v[154:155], v[154:155], v[254:255]
	v_pk_fma_f32 v[252:253], v[156:157], v[156:157], v[252:253]
	v_pk_fma_f32 v[254:255], v[158:159], v[158:159], v[254:255]
	v_pk_add_f32 v[252:253], v[252:253], v[254:255]
	s_nop 0
	v_add_f32_e32 v183, v252, v253
	s_nop 1
	v_add_f32_dpp v183, v183, v183 quad_perm:[1,0,3,2] row_mask:0xf bank_mask:0xf bound_ctrl:1
	s_nop 1
	v_add_f32_dpp v183, v183, v183 quad_perm:[2,3,0,1] row_mask:0xf bank_mask:0xf bound_ctrl:1
	s_nop 1
	v_add_f32_dpp v183, v183, v183 row_half_mirror row_mask:0xf bank_mask:0xf bound_ctrl:1
	s_nop 1
	v_add_f32_dpp v183, v183, v183 row_mirror row_mask:0xf bank_mask:0xf bound_ctrl:1
	s_nop 1
	v_readlane_b32 s98, v183, 0
	v_readlane_b32 s99, v183, 16
	v_readlane_b32 s100, v183, 32
	v_readlane_b32 s101, v183, 48
	s_nop 1
	v_mov_b32_e32 v183, s98
	v_add_f32_e32 v183, s99, v183
	v_add_f32_e32 v183, s100, v183
	v_add_f32_e32 v183, s101, v183
	v_fmamk_f32 v183, v183, 0x3a800000, v182
	v_cmp_gt_f32_e32 vcc, 0x800000, v183
	v_mul_f32_e32 v181, 0x4b800000, v183
	s_nop 1
	v_cndmask_b32_e32 v183, v183, v181, vcc
	v_rsq_f32_e32 v183, v183
	s_nop 0
	v_mul_f32_e32 v181, 0x45800000, v183
	v_cndmask_b32_e32 v184, v183, v181, vcc
	v_mov_b32_e32 v185, v184
	v_cvt_pk_bf16_f32 v16, v144, v145
	v_cvt_pk_bf16_f32 v17, v146, v147
	v_cvt_pk_bf16_f32 v18, v148, v149
	v_cvt_pk_bf16_f32 v19, v150, v151
	v_cvt_pk_bf16_f32 v20, v152, v153
	v_cvt_pk_bf16_f32 v21, v154, v155
	v_cvt_pk_bf16_f32 v22, v156, v157
	v_cvt_pk_bf16_f32 v23, v158, v159
	v_add_u32_e32 v181, 0x1c00000, v177
	global_store_dwordx4 v181, v[16:19], s[78:79]
	global_store_dwordx4 v181, v[20:23], s[78:79] offset:1024
	v_add_u32_e32 v236, 0x2000, v237
	s_mov_b64 exec, 1
	global_store_dword v236, v184, s[78:79]
	s_mov_b64 exec, -1
	s_waitcnt vmcnt(20)
	v_lshlrev_b32_e32 v144, 16, v32
	v_and_b32_e32 v145, 0xffff0000, v32
	v_lshlrev_b32_e32 v146, 16, v33
	v_and_b32_e32 v147, 0xffff0000, v33
	v_lshlrev_b32_e32 v148, 16, v34
	v_and_b32_e32 v149, 0xffff0000, v34
	v_lshlrev_b32_e32 v150, 16, v35
	v_and_b32_e32 v151, 0xffff0000, v35
	v_lshlrev_b32_e32 v152, 16, v36
	v_and_b32_e32 v153, 0xffff0000, v36
	v_lshlrev_b32_e32 v154, 16, v37
	v_and_b32_e32 v155, 0xffff0000, v37
	v_lshlrev_b32_e32 v156, 16, v38
	v_and_b32_e32 v157, 0xffff0000, v38
	v_lshlrev_b32_e32 v158, 16, v39
	v_and_b32_e32 v159, 0xffff0000, v39
	v_lshlrev_b32_e32 v160, 16, v40
	v_and_b32_e32 v161, 0xffff0000, v40
	v_lshlrev_b32_e32 v162, 16, v41
	v_and_b32_e32 v163, 0xffff0000, v41
	v_lshlrev_b32_e32 v164, 16, v42
	v_and_b32_e32 v165, 0xffff0000, v42
	v_lshlrev_b32_e32 v166, 16, v43
	v_and_b32_e32 v167, 0xffff0000, v43
	v_lshlrev_b32_e32 v168, 16, v44
	v_and_b32_e32 v169, 0xffff0000, v44
	v_lshlrev_b32_e32 v170, 16, v45
	v_and_b32_e32 v171, 0xffff0000, v45
	v_lshlrev_b32_e32 v172, 16, v46
	v_and_b32_e32 v173, 0xffff0000, v46
	v_lshlrev_b32_e32 v174, 16, v47
	v_and_b32_e32 v175, 0xffff0000, v47
	v_pk_mul_f32 v[252:253], v[160:161], v[160:161]
	v_pk_mul_f32 v[254:255], v[162:163], v[162:163]
	v_pk_fma_f32 v[252:253], v[164:165], v[164:165], v[252:253]
	v_pk_fma_f32 v[254:255], v[166:167], v[166:167], v[254:255]
	v_pk_fma_f32 v[252:253], v[168:169], v[168:169], v[252:253]
	v_pk_fma_f32 v[254:255], v[170:171], v[170:171], v[254:255]
	v_pk_fma_f32 v[252:253], v[172:173], v[172:173], v[252:253]
	v_pk_fma_f32 v[254:255], v[174:175], v[174:175], v[254:255]
	v_pk_add_f32 v[252:253], v[252:253], v[254:255]
	s_nop 0
	v_add_f32_e32 v183, v252, v253
	s_nop 1
	v_add_f32_dpp v183, v183, v183 quad_perm:[1,0,3,2] row_mask:0xf bank_mask:0xf bound_ctrl:1
	s_nop 1
	v_add_f32_dpp v183, v183, v183 quad_perm:[2,3,0,1] row_mask:0xf bank_mask:0xf bound_ctrl:1
	s_nop 1
	v_add_f32_dpp v183, v183, v183 row_half_mirror row_mask:0xf bank_mask:0xf bound_ctrl:1
	s_nop 1
	v_add_f32_dpp v183, v183, v183 row_mirror row_mask:0xf bank_mask:0xf bound_ctrl:1
	s_nop 1
	v_readlane_b32 s98, v183, 0
	v_readlane_b32 s99, v183, 16
	v_readlane_b32 s100, v183, 32
	v_readlane_b32 s101, v183, 48
	s_nop 1
	v_mov_b32_e32 v183, s98
	v_add_f32_e32 v183, s99, v183
	v_add_f32_e32 v183, s100, v183
	v_add_f32_e32 v183, s101, v183
	v_fmamk_f32 v183, v183, 0x3a800000, v182
	v_cmp_gt_f32_e32 vcc, 0x800000, v183
	v_mul_f32_e32 v181, 0x4b800000, v183
	s_nop 1
	v_cndmask_b32_e32 v183, v183, v181, vcc
	v_rsq_f32_e32 v183, v183
	s_nop 0
	v_mul_f32_e32 v181, 0x45800000, v183
	v_cndmask_b32_e32 v184, v183, v181, vcc
	v_mov_b32_e32 v185, v184
	v_pk_mul_f32 v[160:161], v[160:161], v[184:185]
	v_pk_mul_f32 v[162:163], v[162:163], v[184:185]
	v_pk_mul_f32 v[164:165], v[164:165], v[184:185]
	v_pk_mul_f32 v[166:167], v[166:167], v[184:185]
	v_pk_mul_f32 v[168:169], v[168:169], v[184:185]
	v_pk_mul_f32 v[170:171], v[170:171], v[184:185]
	v_pk_mul_f32 v[172:173], v[172:173], v[184:185]
	v_pk_mul_f32 v[174:175], v[174:175], v[184:185]
	v_pk_fma_f32 v[144:145], v[160:161], v[128:129], v[144:145]
	v_pk_fma_f32 v[146:147], v[162:163], v[130:131], v[146:147]
	v_pk_fma_f32 v[148:149], v[164:165], v[132:133], v[148:149]
	v_pk_fma_f32 v[150:151], v[166:167], v[134:135], v[150:151]
	v_pk_fma_f32 v[152:153], v[168:169], v[136:137], v[152:153]
	v_pk_fma_f32 v[154:155], v[170:171], v[138:139], v[154:155]
	v_pk_fma_f32 v[156:157], v[172:173], v[140:141], v[156:157]
	v_pk_fma_f32 v[158:159], v[174:175], v[142:143], v[158:159]
	v_pk_mul_f32 v[252:253], v[144:145], v[144:145]
	v_pk_mul_f32 v[254:255], v[146:147], v[146:147]
	v_pk_fma_f32 v[252:253], v[148:149], v[148:149], v[252:253]
	v_pk_fma_f32 v[254:255], v[150:151], v[150:151], v[254:255]
	v_pk_fma_f32 v[252:253], v[152:153], v[152:153], v[252:253]
	v_pk_fma_f32 v[254:255], v[154:155], v[154:155], v[254:255]
	v_pk_fma_f32 v[252:253], v[156:157], v[156:157], v[252:253]
	v_pk_fma_f32 v[254:255], v[158:159], v[158:159], v[254:255]
	v_pk_add_f32 v[252:253], v[252:253], v[254:255]
	s_nop 0
	v_add_f32_e32 v183, v252, v253
	s_nop 1
	v_add_f32_dpp v183, v183, v183 quad_perm:[1,0,3,2] row_mask:0xf bank_mask:0xf bound_ctrl:1
	s_nop 1
	v_add_f32_dpp v183, v183, v183 quad_perm:[2,3,0,1] row_mask:0xf bank_mask:0xf bound_ctrl:1
	s_nop 1
	v_add_f32_dpp v183, v183, v183 row_half_mirror row_mask:0xf bank_mask:0xf bound_ctrl:1
	s_nop 1
	v_add_f32_dpp v183, v183, v183 row_mirror row_mask:0xf bank_mask:0xf bound_ctrl:1
	s_nop 1
	v_readlane_b32 s98, v183, 0
	v_readlane_b32 s99, v183, 16
	v_readlane_b32 s100, v183, 32
	v_readlane_b32 s101, v183, 48
	s_nop 1
	v_mov_b32_e32 v183, s98
	v_add_f32_e32 v183, s99, v183
	v_add_f32_e32 v183, s100, v183
	v_add_f32_e32 v183, s101, v183
	v_fmamk_f32 v183, v183, 0x3a800000, v182
	v_cmp_gt_f32_e32 vcc, 0x800000, v183
	v_mul_f32_e32 v181, 0x4b800000, v183
	s_nop 1
	v_cndmask_b32_e32 v183, v183, v181, vcc
	v_rsq_f32_e32 v183, v183
	s_nop 0
	v_mul_f32_e32 v181, 0x45800000, v183
	v_cndmask_b32_e32 v184, v183, v181, vcc
	v_mov_b32_e32 v185, v184
	v_cvt_pk_bf16_f32 v32, v144, v145
	v_cvt_pk_bf16_f32 v33, v146, v147
	v_cvt_pk_bf16_f32 v34, v148, v149
	v_cvt_pk_bf16_f32 v35, v150, v151
	v_cvt_pk_bf16_f32 v36, v152, v153
	v_cvt_pk_bf16_f32 v37, v154, v155
	v_cvt_pk_bf16_f32 v38, v156, v157
	v_cvt_pk_bf16_f32 v39, v158, v159
	v_add_u32_e32 v181, 0x2000000, v177
	global_store_dwordx4 v181, v[32:35], s[78:79]
	global_store_dwordx4 v181, v[36:39], s[78:79] offset:1024
	v_add_u32_e32 v236, 0x4000, v237
	s_mov_b64 exec, 1
	global_store_dword v236, v184, s[78:79]
	s_mov_b64 exec, -1
	s_waitcnt vmcnt(16)
	v_lshlrev_b32_e32 v144, 16, v48
	v_and_b32_e32 v145, 0xffff0000, v48
	v_lshlrev_b32_e32 v146, 16, v49
	v_and_b32_e32 v147, 0xffff0000, v49
	v_lshlrev_b32_e32 v148, 16, v50
	v_and_b32_e32 v149, 0xffff0000, v50
	v_lshlrev_b32_e32 v150, 16, v51
	v_and_b32_e32 v151, 0xffff0000, v51
	v_lshlrev_b32_e32 v152, 16, v52
	v_and_b32_e32 v153, 0xffff0000, v52
	v_lshlrev_b32_e32 v154, 16, v53
	v_and_b32_e32 v155, 0xffff0000, v53
	v_lshlrev_b32_e32 v156, 16, v54
	v_and_b32_e32 v157, 0xffff0000, v54
	v_lshlrev_b32_e32 v158, 16, v55
	v_and_b32_e32 v159, 0xffff0000, v55
	v_lshlrev_b32_e32 v160, 16, v56
	v_and_b32_e32 v161, 0xffff0000, v56
	v_lshlrev_b32_e32 v162, 16, v57
	v_and_b32_e32 v163, 0xffff0000, v57
	v_lshlrev_b32_e32 v164, 16, v58
	v_and_b32_e32 v165, 0xffff0000, v58
	v_lshlrev_b32_e32 v166, 16, v59
	v_and_b32_e32 v167, 0xffff0000, v59
	v_lshlrev_b32_e32 v168, 16, v60
	v_and_b32_e32 v169, 0xffff0000, v60
	v_lshlrev_b32_e32 v170, 16, v61
	v_and_b32_e32 v171, 0xffff0000, v61
	v_lshlrev_b32_e32 v172, 16, v62
	v_and_b32_e32 v173, 0xffff0000, v62
	v_lshlrev_b32_e32 v174, 16, v63
	v_and_b32_e32 v175, 0xffff0000, v63
	v_pk_mul_f32 v[252:253], v[160:161], v[160:161]
	v_pk_mul_f32 v[254:255], v[162:163], v[162:163]
	v_pk_fma_f32 v[252:253], v[164:165], v[164:165], v[252:253]
	v_pk_fma_f32 v[254:255], v[166:167], v[166:167], v[254:255]
	v_pk_fma_f32 v[252:253], v[168:169], v[168:169], v[252:253]
	v_pk_fma_f32 v[254:255], v[170:171], v[170:171], v[254:255]
	v_pk_fma_f32 v[252:253], v[172:173], v[172:173], v[252:253]
	v_pk_fma_f32 v[254:255], v[174:175], v[174:175], v[254:255]
	v_pk_add_f32 v[252:253], v[252:253], v[254:255]
	s_nop 0
	v_add_f32_e32 v183, v252, v253
	s_nop 1
	v_add_f32_dpp v183, v183, v183 quad_perm:[1,0,3,2] row_mask:0xf bank_mask:0xf bound_ctrl:1
	s_nop 1
	v_add_f32_dpp v183, v183, v183 quad_perm:[2,3,0,1] row_mask:0xf bank_mask:0xf bound_ctrl:1
	s_nop 1
	v_add_f32_dpp v183, v183, v183 row_half_mirror row_mask:0xf bank_mask:0xf bound_ctrl:1
	s_nop 1
	v_add_f32_dpp v183, v183, v183 row_mirror row_mask:0xf bank_mask:0xf bound_ctrl:1
	s_nop 1
	v_readlane_b32 s98, v183, 0
	v_readlane_b32 s99, v183, 16
	v_readlane_b32 s100, v183, 32
	v_readlane_b32 s101, v183, 48
	s_nop 1
	v_mov_b32_e32 v183, s98
	v_add_f32_e32 v183, s99, v183
	v_add_f32_e32 v183, s100, v183
	v_add_f32_e32 v183, s101, v183
	v_fmamk_f32 v183, v183, 0x3a800000, v182
	v_cmp_gt_f32_e32 vcc, 0x800000, v183
	v_mul_f32_e32 v181, 0x4b800000, v183
	s_nop 1
	v_cndmask_b32_e32 v183, v183, v181, vcc
	v_rsq_f32_e32 v183, v183
	s_nop 0
	v_mul_f32_e32 v181, 0x45800000, v183
	v_cndmask_b32_e32 v184, v183, v181, vcc
	v_mov_b32_e32 v185, v184
	v_pk_mul_f32 v[160:161], v[160:161], v[184:185]
	v_pk_mul_f32 v[162:163], v[162:163], v[184:185]
	v_pk_mul_f32 v[164:165], v[164:165], v[184:185]
	v_pk_mul_f32 v[166:167], v[166:167], v[184:185]
	v_pk_mul_f32 v[168:169], v[168:169], v[184:185]
	v_pk_mul_f32 v[170:171], v[170:171], v[184:185]
	v_pk_mul_f32 v[172:173], v[172:173], v[184:185]
	v_pk_mul_f32 v[174:175], v[174:175], v[184:185]
	v_pk_fma_f32 v[144:145], v[160:161], v[128:129], v[144:145]
	v_pk_fma_f32 v[146:147], v[162:163], v[130:131], v[146:147]
	v_pk_fma_f32 v[148:149], v[164:165], v[132:133], v[148:149]
	v_pk_fma_f32 v[150:151], v[166:167], v[134:135], v[150:151]
	v_pk_fma_f32 v[152:153], v[168:169], v[136:137], v[152:153]
	v_pk_fma_f32 v[154:155], v[170:171], v[138:139], v[154:155]
	v_pk_fma_f32 v[156:157], v[172:173], v[140:141], v[156:157]
	v_pk_fma_f32 v[158:159], v[174:175], v[142:143], v[158:159]
	v_pk_mul_f32 v[252:253], v[144:145], v[144:145]
	v_pk_mul_f32 v[254:255], v[146:147], v[146:147]
	v_pk_fma_f32 v[252:253], v[148:149], v[148:149], v[252:253]
	v_pk_fma_f32 v[254:255], v[150:151], v[150:151], v[254:255]
	v_pk_fma_f32 v[252:253], v[152:153], v[152:153], v[252:253]
	v_pk_fma_f32 v[254:255], v[154:155], v[154:155], v[254:255]
	v_pk_fma_f32 v[252:253], v[156:157], v[156:157], v[252:253]
	v_pk_fma_f32 v[254:255], v[158:159], v[158:159], v[254:255]
	v_pk_add_f32 v[252:253], v[252:253], v[254:255]
	s_nop 0
	v_add_f32_e32 v183, v252, v253
	s_nop 1
	v_add_f32_dpp v183, v183, v183 quad_perm:[1,0,3,2] row_mask:0xf bank_mask:0xf bound_ctrl:1
	s_nop 1
	v_add_f32_dpp v183, v183, v183 quad_perm:[2,3,0,1] row_mask:0xf bank_mask:0xf bound_ctrl:1
	s_nop 1
	v_add_f32_dpp v183, v183, v183 row_half_mirror row_mask:0xf bank_mask:0xf bound_ctrl:1
	s_nop 1
	v_add_f32_dpp v183, v183, v183 row_mirror row_mask:0xf bank_mask:0xf bound_ctrl:1
	s_nop 1
	v_readlane_b32 s98, v183, 0
	v_readlane_b32 s99, v183, 16
	v_readlane_b32 s100, v183, 32
	v_readlane_b32 s101, v183, 48
	s_nop 1
	v_mov_b32_e32 v183, s98
	v_add_f32_e32 v183, s99, v183
	v_add_f32_e32 v183, s100, v183
	v_add_f32_e32 v183, s101, v183
	v_fmamk_f32 v183, v183, 0x3a800000, v182
	v_cmp_gt_f32_e32 vcc, 0x800000, v183
	v_mul_f32_e32 v181, 0x4b800000, v183
	s_nop 1
	v_cndmask_b32_e32 v183, v183, v181, vcc
	v_rsq_f32_e32 v183, v183
	s_nop 0
	v_mul_f32_e32 v181, 0x45800000, v183
	v_cndmask_b32_e32 v184, v183, v181, vcc
	v_mov_b32_e32 v185, v184
	v_cvt_pk_bf16_f32 v48, v144, v145
	v_cvt_pk_bf16_f32 v49, v146, v147
	v_cvt_pk_bf16_f32 v50, v148, v149
	v_cvt_pk_bf16_f32 v51, v150, v151
	v_cvt_pk_bf16_f32 v52, v152, v153
	v_cvt_pk_bf16_f32 v53, v154, v155
	v_cvt_pk_bf16_f32 v54, v156, v157
	v_cvt_pk_bf16_f32 v55, v158, v159
	v_add_u32_e32 v181, 0x2400000, v177
	global_store_dwordx4 v181, v[48:51], s[78:79]
	global_store_dwordx4 v181, v[52:55], s[78:79] offset:1024
	v_add_u32_e32 v236, 0x6000, v237
	s_mov_b64 exec, 1
	global_store_dword v236, v184, s[78:79]
	s_mov_b64 exec, -1
	s_waitcnt vmcnt(12)
	v_lshlrev_b32_e32 v144, 16, v64
	v_and_b32_e32 v145, 0xffff0000, v64
	v_lshlrev_b32_e32 v146, 16, v65
	v_and_b32_e32 v147, 0xffff0000, v65
	v_lshlrev_b32_e32 v148, 16, v66
	v_and_b32_e32 v149, 0xffff0000, v66
	v_lshlrev_b32_e32 v150, 16, v67
	v_and_b32_e32 v151, 0xffff0000, v67
	v_lshlrev_b32_e32 v152, 16, v68
	v_and_b32_e32 v153, 0xffff0000, v68
	v_lshlrev_b32_e32 v154, 16, v69
	v_and_b32_e32 v155, 0xffff0000, v69
	v_lshlrev_b32_e32 v156, 16, v70
	v_and_b32_e32 v157, 0xffff0000, v70
	v_lshlrev_b32_e32 v158, 16, v71
	v_and_b32_e32 v159, 0xffff0000, v71
	v_lshlrev_b32_e32 v160, 16, v72
	v_and_b32_e32 v161, 0xffff0000, v72
	v_lshlrev_b32_e32 v162, 16, v73
	v_and_b32_e32 v163, 0xffff0000, v73
	v_lshlrev_b32_e32 v164, 16, v74
	v_and_b32_e32 v165, 0xffff0000, v74
	v_lshlrev_b32_e32 v166, 16, v75
	v_and_b32_e32 v167, 0xffff0000, v75
	v_lshlrev_b32_e32 v168, 16, v76
	v_and_b32_e32 v169, 0xffff0000, v76
	v_lshlrev_b32_e32 v170, 16, v77
	v_and_b32_e32 v171, 0xffff0000, v77
	v_lshlrev_b32_e32 v172, 16, v78
	v_and_b32_e32 v173, 0xffff0000, v78
	v_lshlrev_b32_e32 v174, 16, v79
	v_and_b32_e32 v175, 0xffff0000, v79
	v_pk_mul_f32 v[252:253], v[160:161], v[160:161]
	v_pk_mul_f32 v[254:255], v[162:163], v[162:163]
	v_pk_fma_f32 v[252:253], v[164:165], v[164:165], v[252:253]
	v_pk_fma_f32 v[254:255], v[166:167], v[166:167], v[254:255]
	v_pk_fma_f32 v[252:253], v[168:169], v[168:169], v[252:253]
	v_pk_fma_f32 v[254:255], v[170:171], v[170:171], v[254:255]
	v_pk_fma_f32 v[252:253], v[172:173], v[172:173], v[252:253]
	v_pk_fma_f32 v[254:255], v[174:175], v[174:175], v[254:255]
	v_pk_add_f32 v[252:253], v[252:253], v[254:255]
	s_nop 0
	v_add_f32_e32 v183, v252, v253
	s_nop 1
	v_add_f32_dpp v183, v183, v183 quad_perm:[1,0,3,2] row_mask:0xf bank_mask:0xf bound_ctrl:1
	s_nop 1
	v_add_f32_dpp v183, v183, v183 quad_perm:[2,3,0,1] row_mask:0xf bank_mask:0xf bound_ctrl:1
	s_nop 1
	v_add_f32_dpp v183, v183, v183 row_half_mirror row_mask:0xf bank_mask:0xf bound_ctrl:1
	s_nop 1
	v_add_f32_dpp v183, v183, v183 row_mirror row_mask:0xf bank_mask:0xf bound_ctrl:1
	s_nop 1
	v_readlane_b32 s98, v183, 0
	v_readlane_b32 s99, v183, 16
	v_readlane_b32 s100, v183, 32
	v_readlane_b32 s101, v183, 48
	s_nop 1
	v_mov_b32_e32 v183, s98
	v_add_f32_e32 v183, s99, v183
	v_add_f32_e32 v183, s100, v183
	v_add_f32_e32 v183, s101, v183
	v_fmamk_f32 v183, v183, 0x3a800000, v182
	v_cmp_gt_f32_e32 vcc, 0x800000, v183
	v_mul_f32_e32 v181, 0x4b800000, v183
	s_nop 1
	v_cndmask_b32_e32 v183, v183, v181, vcc
	v_rsq_f32_e32 v183, v183
	s_nop 0
	v_mul_f32_e32 v181, 0x45800000, v183
	v_cndmask_b32_e32 v184, v183, v181, vcc
	v_mov_b32_e32 v185, v184
	v_pk_mul_f32 v[160:161], v[160:161], v[184:185]
	v_pk_mul_f32 v[162:163], v[162:163], v[184:185]
	v_pk_mul_f32 v[164:165], v[164:165], v[184:185]
	v_pk_mul_f32 v[166:167], v[166:167], v[184:185]
	v_pk_mul_f32 v[168:169], v[168:169], v[184:185]
	v_pk_mul_f32 v[170:171], v[170:171], v[184:185]
	v_pk_mul_f32 v[172:173], v[172:173], v[184:185]
	v_pk_mul_f32 v[174:175], v[174:175], v[184:185]
	v_pk_fma_f32 v[144:145], v[160:161], v[128:129], v[144:145]
	v_pk_fma_f32 v[146:147], v[162:163], v[130:131], v[146:147]
	v_pk_fma_f32 v[148:149], v[164:165], v[132:133], v[148:149]
	v_pk_fma_f32 v[150:151], v[166:167], v[134:135], v[150:151]
	v_pk_fma_f32 v[152:153], v[168:169], v[136:137], v[152:153]
	v_pk_fma_f32 v[154:155], v[170:171], v[138:139], v[154:155]
	v_pk_fma_f32 v[156:157], v[172:173], v[140:141], v[156:157]
	v_pk_fma_f32 v[158:159], v[174:175], v[142:143], v[158:159]
	v_pk_mul_f32 v[252:253], v[144:145], v[144:145]
	v_pk_mul_f32 v[254:255], v[146:147], v[146:147]
	v_pk_fma_f32 v[252:253], v[148:149], v[148:149], v[252:253]
	v_pk_fma_f32 v[254:255], v[150:151], v[150:151], v[254:255]
	v_pk_fma_f32 v[252:253], v[152:153], v[152:153], v[252:253]
	v_pk_fma_f32 v[254:255], v[154:155], v[154:155], v[254:255]
	v_pk_fma_f32 v[252:253], v[156:157], v[156:157], v[252:253]
	v_pk_fma_f32 v[254:255], v[158:159], v[158:159], v[254:255]
	v_pk_add_f32 v[252:253], v[252:253], v[254:255]
	s_nop 0
	v_add_f32_e32 v183, v252, v253
	s_nop 1
	v_add_f32_dpp v183, v183, v183 quad_perm:[1,0,3,2] row_mask:0xf bank_mask:0xf bound_ctrl:1
	s_nop 1
	v_add_f32_dpp v183, v183, v183 quad_perm:[2,3,0,1] row_mask:0xf bank_mask:0xf bound_ctrl:1
	s_nop 1
	v_add_f32_dpp v183, v183, v183 row_half_mirror row_mask:0xf bank_mask:0xf bound_ctrl:1
	s_nop 1
	v_add_f32_dpp v183, v183, v183 row_mirror row_mask:0xf bank_mask:0xf bound_ctrl:1
	s_nop 1
	v_readlane_b32 s98, v183, 0
	v_readlane_b32 s99, v183, 16
	v_readlane_b32 s100, v183, 32
	v_readlane_b32 s101, v183, 48
	s_nop 1
	v_mov_b32_e32 v183, s98
	v_add_f32_e32 v183, s99, v183
	v_add_f32_e32 v183, s100, v183
	v_add_f32_e32 v183, s101, v183
	v_fmamk_f32 v183, v183, 0x3a800000, v182
	v_cmp_gt_f32_e32 vcc, 0x800000, v183
	v_mul_f32_e32 v181, 0x4b800000, v183
	s_nop 1
	v_cndmask_b32_e32 v183, v183, v181, vcc
	v_rsq_f32_e32 v183, v183
	s_nop 0
	v_mul_f32_e32 v181, 0x45800000, v183
	v_cndmask_b32_e32 v184, v183, v181, vcc
	v_mov_b32_e32 v185, v184
	v_cvt_pk_bf16_f32 v64, v144, v145
	v_cvt_pk_bf16_f32 v65, v146, v147
	v_cvt_pk_bf16_f32 v66, v148, v149
	v_cvt_pk_bf16_f32 v67, v150, v151
	v_cvt_pk_bf16_f32 v68, v152, v153
	v_cvt_pk_bf16_f32 v69, v154, v155
	v_cvt_pk_bf16_f32 v70, v156, v157
	v_cvt_pk_bf16_f32 v71, v158, v159
	v_add_u32_e32 v181, 0x2800000, v177
	global_store_dwordx4 v181, v[64:67], s[78:79]
	global_store_dwordx4 v181, v[68:71], s[78:79] offset:1024
	v_add_u32_e32 v236, 0x8000, v237
	s_mov_b64 exec, 1
	global_store_dword v236, v184, s[78:79]
	s_mov_b64 exec, -1
	s_waitcnt vmcnt(8)
	v_lshlrev_b32_e32 v144, 16, v80
	v_and_b32_e32 v145, 0xffff0000, v80
	v_lshlrev_b32_e32 v146, 16, v81
	v_and_b32_e32 v147, 0xffff0000, v81
	v_lshlrev_b32_e32 v148, 16, v82
	v_and_b32_e32 v149, 0xffff0000, v82
	v_lshlrev_b32_e32 v150, 16, v83
	v_and_b32_e32 v151, 0xffff0000, v83
	v_lshlrev_b32_e32 v152, 16, v84
	v_and_b32_e32 v153, 0xffff0000, v84
	v_lshlrev_b32_e32 v154, 16, v85
	v_and_b32_e32 v155, 0xffff0000, v85
	v_lshlrev_b32_e32 v156, 16, v86
	v_and_b32_e32 v157, 0xffff0000, v86
	v_lshlrev_b32_e32 v158, 16, v87
	v_and_b32_e32 v159, 0xffff0000, v87
	v_lshlrev_b32_e32 v160, 16, v88
	v_and_b32_e32 v161, 0xffff0000, v88
	v_lshlrev_b32_e32 v162, 16, v89
	v_and_b32_e32 v163, 0xffff0000, v89
	v_lshlrev_b32_e32 v164, 16, v90
	v_and_b32_e32 v165, 0xffff0000, v90
	v_lshlrev_b32_e32 v166, 16, v91
	v_and_b32_e32 v167, 0xffff0000, v91
	v_lshlrev_b32_e32 v168, 16, v92
	v_and_b32_e32 v169, 0xffff0000, v92
	v_lshlrev_b32_e32 v170, 16, v93
	v_and_b32_e32 v171, 0xffff0000, v93
	v_lshlrev_b32_e32 v172, 16, v94
	v_and_b32_e32 v173, 0xffff0000, v94
	v_lshlrev_b32_e32 v174, 16, v95
	v_and_b32_e32 v175, 0xffff0000, v95
	v_pk_mul_f32 v[252:253], v[160:161], v[160:161]
	v_pk_mul_f32 v[254:255], v[162:163], v[162:163]
	v_pk_fma_f32 v[252:253], v[164:165], v[164:165], v[252:253]
	v_pk_fma_f32 v[254:255], v[166:167], v[166:167], v[254:255]
	v_pk_fma_f32 v[252:253], v[168:169], v[168:169], v[252:253]
	v_pk_fma_f32 v[254:255], v[170:171], v[170:171], v[254:255]
	v_pk_fma_f32 v[252:253], v[172:173], v[172:173], v[252:253]
	v_pk_fma_f32 v[254:255], v[174:175], v[174:175], v[254:255]
	v_pk_add_f32 v[252:253], v[252:253], v[254:255]
	s_nop 0
	v_add_f32_e32 v183, v252, v253
	s_nop 1
	v_add_f32_dpp v183, v183, v183 quad_perm:[1,0,3,2] row_mask:0xf bank_mask:0xf bound_ctrl:1
	s_nop 1
	v_add_f32_dpp v183, v183, v183 quad_perm:[2,3,0,1] row_mask:0xf bank_mask:0xf bound_ctrl:1
	s_nop 1
	v_add_f32_dpp v183, v183, v183 row_half_mirror row_mask:0xf bank_mask:0xf bound_ctrl:1
	s_nop 1
	v_add_f32_dpp v183, v183, v183 row_mirror row_mask:0xf bank_mask:0xf bound_ctrl:1
	s_nop 1
	v_readlane_b32 s98, v183, 0
	v_readlane_b32 s99, v183, 16
	v_readlane_b32 s100, v183, 32
	v_readlane_b32 s101, v183, 48
	s_nop 1
	v_mov_b32_e32 v183, s98
	v_add_f32_e32 v183, s99, v183
	v_add_f32_e32 v183, s100, v183
	v_add_f32_e32 v183, s101, v183
	v_fmamk_f32 v183, v183, 0x3a800000, v182
	v_cmp_gt_f32_e32 vcc, 0x800000, v183
	v_mul_f32_e32 v181, 0x4b800000, v183
	s_nop 1
	v_cndmask_b32_e32 v183, v183, v181, vcc
	v_rsq_f32_e32 v183, v183
	s_nop 0
	v_mul_f32_e32 v181, 0x45800000, v183
	v_cndmask_b32_e32 v184, v183, v181, vcc
	v_mov_b32_e32 v185, v184
	v_pk_mul_f32 v[160:161], v[160:161], v[184:185]
	v_pk_mul_f32 v[162:163], v[162:163], v[184:185]
	v_pk_mul_f32 v[164:165], v[164:165], v[184:185]
	v_pk_mul_f32 v[166:167], v[166:167], v[184:185]
	v_pk_mul_f32 v[168:169], v[168:169], v[184:185]
	v_pk_mul_f32 v[170:171], v[170:171], v[184:185]
	v_pk_mul_f32 v[172:173], v[172:173], v[184:185]
	v_pk_mul_f32 v[174:175], v[174:175], v[184:185]
	v_pk_fma_f32 v[144:145], v[160:161], v[128:129], v[144:145]
	v_pk_fma_f32 v[146:147], v[162:163], v[130:131], v[146:147]
	v_pk_fma_f32 v[148:149], v[164:165], v[132:133], v[148:149]
	v_pk_fma_f32 v[150:151], v[166:167], v[134:135], v[150:151]
	v_pk_fma_f32 v[152:153], v[168:169], v[136:137], v[152:153]
	v_pk_fma_f32 v[154:155], v[170:171], v[138:139], v[154:155]
	v_pk_fma_f32 v[156:157], v[172:173], v[140:141], v[156:157]
	v_pk_fma_f32 v[158:159], v[174:175], v[142:143], v[158:159]
	v_pk_mul_f32 v[252:253], v[144:145], v[144:145]
	v_pk_mul_f32 v[254:255], v[146:147], v[146:147]
	v_pk_fma_f32 v[252:253], v[148:149], v[148:149], v[252:253]
	v_pk_fma_f32 v[254:255], v[150:151], v[150:151], v[254:255]
	v_pk_fma_f32 v[252:253], v[152:153], v[152:153], v[252:253]
	v_pk_fma_f32 v[254:255], v[154:155], v[154:155], v[254:255]
	v_pk_fma_f32 v[252:253], v[156:157], v[156:157], v[252:253]
	v_pk_fma_f32 v[254:255], v[158:159], v[158:159], v[254:255]
	v_pk_add_f32 v[252:253], v[252:253], v[254:255]
	s_nop 0
	v_add_f32_e32 v183, v252, v253
	s_nop 1
	v_add_f32_dpp v183, v183, v183 quad_perm:[1,0,3,2] row_mask:0xf bank_mask:0xf bound_ctrl:1
	s_nop 1
	v_add_f32_dpp v183, v183, v183 quad_perm:[2,3,0,1] row_mask:0xf bank_mask:0xf bound_ctrl:1
	s_nop 1
	v_add_f32_dpp v183, v183, v183 row_half_mirror row_mask:0xf bank_mask:0xf bound_ctrl:1
	s_nop 1
	v_add_f32_dpp v183, v183, v183 row_mirror row_mask:0xf bank_mask:0xf bound_ctrl:1
	s_nop 1
	v_readlane_b32 s98, v183, 0
	v_readlane_b32 s99, v183, 16
	v_readlane_b32 s100, v183, 32
	v_readlane_b32 s101, v183, 48
	s_nop 1
	v_mov_b32_e32 v183, s98
	v_add_f32_e32 v183, s99, v183
	v_add_f32_e32 v183, s100, v183
	v_add_f32_e32 v183, s101, v183
	v_fmamk_f32 v183, v183, 0x3a800000, v182
	v_cmp_gt_f32_e32 vcc, 0x800000, v183
	v_mul_f32_e32 v181, 0x4b800000, v183
	s_nop 1
	v_cndmask_b32_e32 v183, v183, v181, vcc
	v_rsq_f32_e32 v183, v183
	s_nop 0
	v_mul_f32_e32 v181, 0x45800000, v183
	v_cndmask_b32_e32 v184, v183, v181, vcc
	v_mov_b32_e32 v185, v184
	v_cvt_pk_bf16_f32 v80, v144, v145
	v_cvt_pk_bf16_f32 v81, v146, v147
	v_cvt_pk_bf16_f32 v82, v148, v149
	v_cvt_pk_bf16_f32 v83, v150, v151
	v_cvt_pk_bf16_f32 v84, v152, v153
	v_cvt_pk_bf16_f32 v85, v154, v155
	v_cvt_pk_bf16_f32 v86, v156, v157
	v_cvt_pk_bf16_f32 v87, v158, v159
	v_add_u32_e32 v181, 0x2c00000, v177
	global_store_dwordx4 v181, v[80:83], s[78:79]
	global_store_dwordx4 v181, v[84:87], s[78:79] offset:1024
	v_add_u32_e32 v236, 0xa000, v237
	s_mov_b64 exec, 1
	global_store_dword v236, v184, s[78:79]
	s_mov_b64 exec, -1
	s_waitcnt vmcnt(4)
	v_lshlrev_b32_e32 v144, 16, v96
	v_and_b32_e32 v145, 0xffff0000, v96
	v_lshlrev_b32_e32 v146, 16, v97
	v_and_b32_e32 v147, 0xffff0000, v97
	v_lshlrev_b32_e32 v148, 16, v98
	v_and_b32_e32 v149, 0xffff0000, v98
	v_lshlrev_b32_e32 v150, 16, v99
	v_and_b32_e32 v151, 0xffff0000, v99
	v_lshlrev_b32_e32 v152, 16, v100
	v_and_b32_e32 v153, 0xffff0000, v100
	v_lshlrev_b32_e32 v154, 16, v101
	v_and_b32_e32 v155, 0xffff0000, v101
	v_lshlrev_b32_e32 v156, 16, v102
	v_and_b32_e32 v157, 0xffff0000, v102
	v_lshlrev_b32_e32 v158, 16, v103
	v_and_b32_e32 v159, 0xffff0000, v103
	v_lshlrev_b32_e32 v160, 16, v104
	v_and_b32_e32 v161, 0xffff0000, v104
	v_lshlrev_b32_e32 v162, 16, v105
	v_and_b32_e32 v163, 0xffff0000, v105
	v_lshlrev_b32_e32 v164, 16, v106
	v_and_b32_e32 v165, 0xffff0000, v106
	v_lshlrev_b32_e32 v166, 16, v107
	v_and_b32_e32 v167, 0xffff0000, v107
	v_lshlrev_b32_e32 v168, 16, v108
	v_and_b32_e32 v169, 0xffff0000, v108
	v_lshlrev_b32_e32 v170, 16, v109
	v_and_b32_e32 v171, 0xffff0000, v109
	v_lshlrev_b32_e32 v172, 16, v110
	v_and_b32_e32 v173, 0xffff0000, v110
	v_lshlrev_b32_e32 v174, 16, v111
	v_and_b32_e32 v175, 0xffff0000, v111
	v_pk_mul_f32 v[252:253], v[160:161], v[160:161]
	v_pk_mul_f32 v[254:255], v[162:163], v[162:163]
	v_pk_fma_f32 v[252:253], v[164:165], v[164:165], v[252:253]
	v_pk_fma_f32 v[254:255], v[166:167], v[166:167], v[254:255]
	v_pk_fma_f32 v[252:253], v[168:169], v[168:169], v[252:253]
	v_pk_fma_f32 v[254:255], v[170:171], v[170:171], v[254:255]
	v_pk_fma_f32 v[252:253], v[172:173], v[172:173], v[252:253]
	v_pk_fma_f32 v[254:255], v[174:175], v[174:175], v[254:255]
	v_pk_add_f32 v[252:253], v[252:253], v[254:255]
	s_nop 0
	v_add_f32_e32 v183, v252, v253
	s_nop 1
	v_add_f32_dpp v183, v183, v183 quad_perm:[1,0,3,2] row_mask:0xf bank_mask:0xf bound_ctrl:1
	s_nop 1
	v_add_f32_dpp v183, v183, v183 quad_perm:[2,3,0,1] row_mask:0xf bank_mask:0xf bound_ctrl:1
	s_nop 1
	v_add_f32_dpp v183, v183, v183 row_half_mirror row_mask:0xf bank_mask:0xf bound_ctrl:1
	s_nop 1
	v_add_f32_dpp v183, v183, v183 row_mirror row_mask:0xf bank_mask:0xf bound_ctrl:1
	s_nop 1
	v_readlane_b32 s98, v183, 0
	v_readlane_b32 s99, v183, 16
	v_readlane_b32 s100, v183, 32
	v_readlane_b32 s101, v183, 48
	s_nop 1
	v_mov_b32_e32 v183, s98
	v_add_f32_e32 v183, s99, v183
	v_add_f32_e32 v183, s100, v183
	v_add_f32_e32 v183, s101, v183
	v_fmamk_f32 v183, v183, 0x3a800000, v182
	v_cmp_gt_f32_e32 vcc, 0x800000, v183
	v_mul_f32_e32 v181, 0x4b800000, v183
	s_nop 1
	v_cndmask_b32_e32 v183, v183, v181, vcc
	v_rsq_f32_e32 v183, v183
	s_nop 0
	v_mul_f32_e32 v181, 0x45800000, v183
	v_cndmask_b32_e32 v184, v183, v181, vcc
	v_mov_b32_e32 v185, v184
	v_pk_mul_f32 v[160:161], v[160:161], v[184:185]
	v_pk_mul_f32 v[162:163], v[162:163], v[184:185]
	v_pk_mul_f32 v[164:165], v[164:165], v[184:185]
	v_pk_mul_f32 v[166:167], v[166:167], v[184:185]
	v_pk_mul_f32 v[168:169], v[168:169], v[184:185]
	v_pk_mul_f32 v[170:171], v[170:171], v[184:185]
	v_pk_mul_f32 v[172:173], v[172:173], v[184:185]
	v_pk_mul_f32 v[174:175], v[174:175], v[184:185]
	v_pk_fma_f32 v[144:145], v[160:161], v[128:129], v[144:145]
	v_pk_fma_f32 v[146:147], v[162:163], v[130:131], v[146:147]
	v_pk_fma_f32 v[148:149], v[164:165], v[132:133], v[148:149]
	v_pk_fma_f32 v[150:151], v[166:167], v[134:135], v[150:151]
	v_pk_fma_f32 v[152:153], v[168:169], v[136:137], v[152:153]
	v_pk_fma_f32 v[154:155], v[170:171], v[138:139], v[154:155]
	v_pk_fma_f32 v[156:157], v[172:173], v[140:141], v[156:157]
	v_pk_fma_f32 v[158:159], v[174:175], v[142:143], v[158:159]
	v_pk_mul_f32 v[252:253], v[144:145], v[144:145]
	v_pk_mul_f32 v[254:255], v[146:147], v[146:147]
	v_pk_fma_f32 v[252:253], v[148:149], v[148:149], v[252:253]
	v_pk_fma_f32 v[254:255], v[150:151], v[150:151], v[254:255]
	v_pk_fma_f32 v[252:253], v[152:153], v[152:153], v[252:253]
	v_pk_fma_f32 v[254:255], v[154:155], v[154:155], v[254:255]
	v_pk_fma_f32 v[252:253], v[156:157], v[156:157], v[252:253]
	v_pk_fma_f32 v[254:255], v[158:159], v[158:159], v[254:255]
	v_pk_add_f32 v[252:253], v[252:253], v[254:255]
	s_nop 0
	v_add_f32_e32 v183, v252, v253
	s_nop 1
	v_add_f32_dpp v183, v183, v183 quad_perm:[1,0,3,2] row_mask:0xf bank_mask:0xf bound_ctrl:1
	s_nop 1
	v_add_f32_dpp v183, v183, v183 quad_perm:[2,3,0,1] row_mask:0xf bank_mask:0xf bound_ctrl:1
	s_nop 1
	v_add_f32_dpp v183, v183, v183 row_half_mirror row_mask:0xf bank_mask:0xf bound_ctrl:1
	s_nop 1
	v_add_f32_dpp v183, v183, v183 row_mirror row_mask:0xf bank_mask:0xf bound_ctrl:1
	s_nop 1
	v_readlane_b32 s98, v183, 0
	v_readlane_b32 s99, v183, 16
	v_readlane_b32 s100, v183, 32
	v_readlane_b32 s101, v183, 48
	s_nop 1
	v_mov_b32_e32 v183, s98
	v_add_f32_e32 v183, s99, v183
	v_add_f32_e32 v183, s100, v183
	v_add_f32_e32 v183, s101, v183
	v_fmamk_f32 v183, v183, 0x3a800000, v182
	v_cmp_gt_f32_e32 vcc, 0x800000, v183
	v_mul_f32_e32 v181, 0x4b800000, v183
	s_nop 1
	v_cndmask_b32_e32 v183, v183, v181, vcc
	v_rsq_f32_e32 v183, v183
	s_nop 0
	v_mul_f32_e32 v181, 0x45800000, v183
	v_cndmask_b32_e32 v184, v183, v181, vcc
	v_mov_b32_e32 v185, v184
	v_cvt_pk_bf16_f32 v96, v144, v145
	v_cvt_pk_bf16_f32 v97, v146, v147
	v_cvt_pk_bf16_f32 v98, v148, v149
	v_cvt_pk_bf16_f32 v99, v150, v151
	v_cvt_pk_bf16_f32 v100, v152, v153
	v_cvt_pk_bf16_f32 v101, v154, v155
	v_cvt_pk_bf16_f32 v102, v156, v157
	v_cvt_pk_bf16_f32 v103, v158, v159
	v_add_u32_e32 v181, 0x3000000, v177
	global_store_dwordx4 v181, v[96:99], s[78:79]
	global_store_dwordx4 v181, v[100:103], s[78:79] offset:1024
	v_add_u32_e32 v236, 0xc000, v237
	s_mov_b64 exec, 1
	global_store_dword v236, v184, s[78:79]
	s_mov_b64 exec, -1
	s_waitcnt vmcnt(0)
	v_lshlrev_b32_e32 v144, 16, v112
	v_and_b32_e32 v145, 0xffff0000, v112
	v_lshlrev_b32_e32 v146, 16, v113
	v_and_b32_e32 v147, 0xffff0000, v113
	v_lshlrev_b32_e32 v148, 16, v114
	v_and_b32_e32 v149, 0xffff0000, v114
	v_lshlrev_b32_e32 v150, 16, v115
	v_and_b32_e32 v151, 0xffff0000, v115
	v_lshlrev_b32_e32 v152, 16, v116
	v_and_b32_e32 v153, 0xffff0000, v116
	v_lshlrev_b32_e32 v154, 16, v117
	v_and_b32_e32 v155, 0xffff0000, v117
	v_lshlrev_b32_e32 v156, 16, v118
	v_and_b32_e32 v157, 0xffff0000, v118
	v_lshlrev_b32_e32 v158, 16, v119
	v_and_b32_e32 v159, 0xffff0000, v119
	v_lshlrev_b32_e32 v160, 16, v120
	v_and_b32_e32 v161, 0xffff0000, v120
	v_lshlrev_b32_e32 v162, 16, v121
	v_and_b32_e32 v163, 0xffff0000, v121
	v_lshlrev_b32_e32 v164, 16, v122
	v_and_b32_e32 v165, 0xffff0000, v122
	v_lshlrev_b32_e32 v166, 16, v123
	v_and_b32_e32 v167, 0xffff0000, v123
	v_lshlrev_b32_e32 v168, 16, v124
	v_and_b32_e32 v169, 0xffff0000, v124
	v_lshlrev_b32_e32 v170, 16, v125
	v_and_b32_e32 v171, 0xffff0000, v125
	v_lshlrev_b32_e32 v172, 16, v126
	v_and_b32_e32 v173, 0xffff0000, v126
	v_lshlrev_b32_e32 v174, 16, v127
	v_and_b32_e32 v175, 0xffff0000, v127
	v_pk_mul_f32 v[252:253], v[160:161], v[160:161]
	v_pk_mul_f32 v[254:255], v[162:163], v[162:163]
	v_pk_fma_f32 v[252:253], v[164:165], v[164:165], v[252:253]
	v_pk_fma_f32 v[254:255], v[166:167], v[166:167], v[254:255]
	v_pk_fma_f32 v[252:253], v[168:169], v[168:169], v[252:253]
	v_pk_fma_f32 v[254:255], v[170:171], v[170:171], v[254:255]
	v_pk_fma_f32 v[252:253], v[172:173], v[172:173], v[252:253]
	v_pk_fma_f32 v[254:255], v[174:175], v[174:175], v[254:255]
	v_pk_add_f32 v[252:253], v[252:253], v[254:255]
	s_nop 0
	v_add_f32_e32 v183, v252, v253
	s_nop 1
	v_add_f32_dpp v183, v183, v183 quad_perm:[1,0,3,2] row_mask:0xf bank_mask:0xf bound_ctrl:1
	s_nop 1
	v_add_f32_dpp v183, v183, v183 quad_perm:[2,3,0,1] row_mask:0xf bank_mask:0xf bound_ctrl:1
	s_nop 1
	v_add_f32_dpp v183, v183, v183 row_half_mirror row_mask:0xf bank_mask:0xf bound_ctrl:1
	s_nop 1
	v_add_f32_dpp v183, v183, v183 row_mirror row_mask:0xf bank_mask:0xf bound_ctrl:1
	s_nop 1
	v_readlane_b32 s98, v183, 0
	v_readlane_b32 s99, v183, 16
	v_readlane_b32 s100, v183, 32
	v_readlane_b32 s101, v183, 48
	s_nop 1
	v_mov_b32_e32 v183, s98
	v_add_f32_e32 v183, s99, v183
	v_add_f32_e32 v183, s100, v183
	v_add_f32_e32 v183, s101, v183
	v_fmamk_f32 v183, v183, 0x3a800000, v182
	v_cmp_gt_f32_e32 vcc, 0x800000, v183
	v_mul_f32_e32 v181, 0x4b800000, v183
	s_nop 1
	v_cndmask_b32_e32 v183, v183, v181, vcc
	v_rsq_f32_e32 v183, v183
	s_nop 0
	v_mul_f32_e32 v181, 0x45800000, v183
	v_cndmask_b32_e32 v184, v183, v181, vcc
	v_mov_b32_e32 v185, v184
	v_pk_mul_f32 v[160:161], v[160:161], v[184:185]
	v_pk_mul_f32 v[162:163], v[162:163], v[184:185]
	v_pk_mul_f32 v[164:165], v[164:165], v[184:185]
	v_pk_mul_f32 v[166:167], v[166:167], v[184:185]
	v_pk_mul_f32 v[168:169], v[168:169], v[184:185]
	v_pk_mul_f32 v[170:171], v[170:171], v[184:185]
	v_pk_mul_f32 v[172:173], v[172:173], v[184:185]
	v_pk_mul_f32 v[174:175], v[174:175], v[184:185]
	v_pk_fma_f32 v[144:145], v[160:161], v[128:129], v[144:145]
	v_pk_fma_f32 v[146:147], v[162:163], v[130:131], v[146:147]
	v_pk_fma_f32 v[148:149], v[164:165], v[132:133], v[148:149]
	v_pk_fma_f32 v[150:151], v[166:167], v[134:135], v[150:151]
	v_pk_fma_f32 v[152:153], v[168:169], v[136:137], v[152:153]
	v_pk_fma_f32 v[154:155], v[170:171], v[138:139], v[154:155]
	v_pk_fma_f32 v[156:157], v[172:173], v[140:141], v[156:157]
	v_pk_fma_f32 v[158:159], v[174:175], v[142:143], v[158:159]
	v_pk_mul_f32 v[252:253], v[144:145], v[144:145]
	v_pk_mul_f32 v[254:255], v[146:147], v[146:147]
	v_pk_fma_f32 v[252:253], v[148:149], v[148:149], v[252:253]
	v_pk_fma_f32 v[254:255], v[150:151], v[150:151], v[254:255]
	v_pk_fma_f32 v[252:253], v[152:153], v[152:153], v[252:253]
	v_pk_fma_f32 v[254:255], v[154:155], v[154:155], v[254:255]
	v_pk_fma_f32 v[252:253], v[156:157], v[156:157], v[252:253]
	v_pk_fma_f32 v[254:255], v[158:159], v[158:159], v[254:255]
	v_pk_add_f32 v[252:253], v[252:253], v[254:255]
	s_nop 0
	v_add_f32_e32 v183, v252, v253
	s_nop 1
	v_add_f32_dpp v183, v183, v183 quad_perm:[1,0,3,2] row_mask:0xf bank_mask:0xf bound_ctrl:1
	s_nop 1
	v_add_f32_dpp v183, v183, v183 quad_perm:[2,3,0,1] row_mask:0xf bank_mask:0xf bound_ctrl:1
	s_nop 1
	v_add_f32_dpp v183, v183, v183 row_half_mirror row_mask:0xf bank_mask:0xf bound_ctrl:1
	s_nop 1
	v_add_f32_dpp v183, v183, v183 row_mirror row_mask:0xf bank_mask:0xf bound_ctrl:1
	s_nop 1
	v_readlane_b32 s98, v183, 0
	v_readlane_b32 s99, v183, 16
	v_readlane_b32 s100, v183, 32
	v_readlane_b32 s101, v183, 48
	s_nop 1
	v_mov_b32_e32 v183, s98
	v_add_f32_e32 v183, s99, v183
	v_add_f32_e32 v183, s100, v183
	v_add_f32_e32 v183, s101, v183
	v_fmamk_f32 v183, v183, 0x3a800000, v182
	v_cmp_gt_f32_e32 vcc, 0x800000, v183
	v_mul_f32_e32 v181, 0x4b800000, v183
	s_nop 1
	v_cndmask_b32_e32 v183, v183, v181, vcc
	v_rsq_f32_e32 v183, v183
	s_nop 0
	v_mul_f32_e32 v181, 0x45800000, v183
	v_cndmask_b32_e32 v184, v183, v181, vcc
	v_mov_b32_e32 v185, v184
	v_cvt_pk_bf16_f32 v112, v144, v145
	v_cvt_pk_bf16_f32 v113, v146, v147
	v_cvt_pk_bf16_f32 v114, v148, v149
	v_cvt_pk_bf16_f32 v115, v150, v151
	v_cvt_pk_bf16_f32 v116, v152, v153
	v_cvt_pk_bf16_f32 v117, v154, v155
	v_cvt_pk_bf16_f32 v118, v156, v157
	v_cvt_pk_bf16_f32 v119, v158, v159
	v_add_u32_e32 v181, 0x3400000, v177
	global_store_dwordx4 v181, v[112:115], s[78:79]
	global_store_dwordx4 v181, v[116:119], s[78:79] offset:1024
	v_add_u32_e32 v236, 0xe000, v237
	s_mov_b64 exec, 1
	global_store_dword v236, v184, s[78:79]
	s_mov_b64 exec, -1
	v_readfirstlane_b32 s98, v179
	s_nop 3
	s_cmp_ge_u32 s98, 512
	s_cbranch_scc1 .Lmyxupd_done_0
	v_add_u32_e32 v181, 0x3800000, v177
	global_load_dwordx4 v[0:3], v181, s[78:79]
	global_load_dwordx4 v[4:7], v181, s[78:79] offset:1024
	v_lshl_add_u32 v183, v179, 12, v180
	v_add_u32_e32 v183, 0xbf00000, v183
	v_add_u32_e32 v181, 0x0, v183
	global_load_dwordx4 v[8:11], v181, s[78:79]
	global_load_dwordx4 v[12:15], v181, s[78:79] offset:16
	global_load_dwordx4 v[16:19], v181, s[78:79] offset:2048
	global_load_dwordx4 v[20:23], v181, s[78:79] offset:2064
	v_add_u32_e32 v181, 0x200000, v183
	global_load_dwordx4 v[24:27], v181, s[78:79]
	global_load_dwordx4 v[28:31], v181, s[78:79] offset:16
	global_load_dwordx4 v[32:35], v181, s[78:79] offset:2048
	global_load_dwordx4 v[36:39], v181, s[78:79] offset:2064
	v_add_u32_e32 v181, 0x400000, v183
	global_load_dwordx4 v[40:43], v181, s[78:79]
	global_load_dwordx4 v[44:47], v181, s[78:79] offset:16
	global_load_dwordx4 v[48:51], v181, s[78:79] offset:2048
	global_load_dwordx4 v[52:55], v181, s[78:79] offset:2064
	v_add_u32_e32 v181, 0x600000, v183
	global_load_dwordx4 v[56:59], v181, s[78:79]
	global_load_dwordx4 v[60:63], v181, s[78:79] offset:16
	global_load_dwordx4 v[64:67], v181, s[78:79] offset:2048
	global_load_dwordx4 v[68:71], v181, s[78:79] offset:2064
	v_add_u32_e32 v181, 0x800000, v183
	global_load_dwordx4 v[72:75], v181, s[78:79]
	global_load_dwordx4 v[76:79], v181, s[78:79] offset:16
	global_load_dwordx4 v[80:83], v181, s[78:79] offset:2048
	global_load_dwordx4 v[84:87], v181, s[78:79] offset:2064
	v_add_u32_e32 v181, 0xa00000, v183
	global_load_dwordx4 v[88:91], v181, s[78:79]
	global_load_dwordx4 v[92:95], v181, s[78:79] offset:16
	global_load_dwordx4 v[96:99], v181, s[78:79] offset:2048
	global_load_dwordx4 v[100:103], v181, s[78:79] offset:2064
	s_waitcnt vmcnt(20)
	v_pk_add_f32 v[160:161], v[8:9], 0 op_sel_hi:[1,0]
	v_pk_add_f32 v[162:163], v[10:11], 0 op_sel_hi:[1,0]
	v_pk_add_f32 v[164:165], v[12:13], 0 op_sel_hi:[1,0]
	v_pk_add_f32 v[166:167], v[14:15], 0 op_sel_hi:[1,0]
	v_pk_add_f32 v[168:169], v[16:17], 0 op_sel_hi:[1,0]
	v_pk_add_f32 v[170:171], v[18:19], 0 op_sel_hi:[1,0]
	v_pk_add_f32 v[172:173], v[20:21], 0 op_sel_hi:[1,0]
	v_pk_add_f32 v[174:175], v[22:23], 0 op_sel_hi:[1,0]
	s_waitcnt vmcnt(16)
	v_pk_add_f32 v[160:161], v[160:161], v[24:25]
	v_pk_add_f32 v[162:163], v[162:163], v[26:27]
	v_pk_add_f32 v[164:165], v[164:165], v[28:29]
	v_pk_add_f32 v[166:167], v[166:167], v[30:31]
	v_pk_add_f32 v[168:169], v[168:169], v[32:33]
	v_pk_add_f32 v[170:171], v[170:171], v[34:35]
	v_pk_add_f32 v[172:173], v[172:173], v[36:37]
	v_pk_add_f32 v[174:175], v[174:175], v[38:39]
	s_waitcnt vmcnt(12)
	v_pk_add_f32 v[160:161], v[160:161], v[40:41]
	v_pk_add_f32 v[162:163], v[162:163], v[42:43]
	v_pk_add_f32 v[164:165], v[164:165], v[44:45]
	v_pk_add_f32 v[166:167], v[166:167], v[46:47]
	v_pk_add_f32 v[168:169], v[168:169], v[48:49]
	v_pk_add_f32 v[170:171], v[170:171], v[50:51]
	v_pk_add_f32 v[172:173], v[172:173], v[52:53]
	v_pk_add_f32 v[174:175], v[174:175], v[54:55]
	s_waitcnt vmcnt(8)
	v_pk_add_f32 v[160:161], v[160:161], v[56:57]
	v_pk_add_f32 v[162:163], v[162:163], v[58:59]
	v_pk_add_f32 v[164:165], v[164:165], v[60:61]
	v_pk_add_f32 v[166:167], v[166:167], v[62:63]
	v_pk_add_f32 v[168:169], v[168:169], v[64:65]
	v_pk_add_f32 v[170:171], v[170:171], v[66:67]
	v_pk_add_f32 v[172:173], v[172:173], v[68:69]
	v_pk_add_f32 v[174:175], v[174:175], v[70:71]
	s_waitcnt vmcnt(4)
	v_pk_add_f32 v[160:161], v[160:161], v[72:73]
	v_pk_add_f32 v[162:163], v[162:163], v[74:75]
	v_pk_add_f32 v[164:165], v[164:165], v[76:77]
	v_pk_add_f32 v[166:167], v[166:167], v[78:79]
	v_pk_add_f32 v[168:169], v[168:169], v[80:81]
	v_pk_add_f32 v[170:171], v[170:171], v[82:83]
	v_pk_add_f32 v[172:173], v[172:173], v[84:85]
	v_pk_add_f32 v[174:175], v[174:175], v[86:87]
	s_waitcnt vmcnt(0)
	v_pk_add_f32 v[160:161], v[160:161], v[88:89]
	v_pk_add_f32 v[162:163], v[162:163], v[90:91]
	v_pk_add_f32 v[164:165], v[164:165], v[92:93]
	v_pk_add_f32 v[166:167], v[166:167], v[94:95]
	v_pk_add_f32 v[168:169], v[168:169], v[96:97]
	v_pk_add_f32 v[170:171], v[170:171], v[98:99]
	v_pk_add_f32 v[172:173], v[172:173], v[100:101]
	v_pk_add_f32 v[174:175], v[174:175], v[102:103]
	v_lshlrev_b32_e32 v144, 16, v0
	v_and_b32_e32 v145, 0xffff0000, v0
	v_lshlrev_b32_e32 v146, 16, v1
	v_and_b32_e32 v147, 0xffff0000, v1
	v_lshlrev_b32_e32 v148, 16, v2
	v_and_b32_e32 v149, 0xffff0000, v2
	v_lshlrev_b32_e32 v150, 16, v3
	v_and_b32_e32 v151, 0xffff0000, v3
	v_lshlrev_b32_e32 v152, 16, v4
	v_and_b32_e32 v153, 0xffff0000, v4
	v_lshlrev_b32_e32 v154, 16, v5
	v_and_b32_e32 v155, 0xffff0000, v5
	v_lshlrev_b32_e32 v156, 16, v6
	v_and_b32_e32 v157, 0xffff0000, v6
	v_lshlrev_b32_e32 v158, 16, v7
	v_and_b32_e32 v159, 0xffff0000, v7
	v_add_u32_e32 v181, 0xc00000, v183
	global_load_dwordx4 v[8:11], v181, s[78:79]
	global_load_dwordx4 v[12:15], v181, s[78:79] offset:16
	global_load_dwordx4 v[16:19], v181, s[78:79] offset:2048
	global_load_dwordx4 v[20:23], v181, s[78:79] offset:2064
	v_add_u32_e32 v181, 0xe00000, v183
	global_load_dwordx4 v[24:27], v181, s[78:79]
	global_load_dwordx4 v[28:31], v181, s[78:79] offset:16
	global_load_dwordx4 v[32:35], v181, s[78:79] offset:2048
	global_load_dwordx4 v[36:39], v181, s[78:79] offset:2064
	s_waitcnt vmcnt(4)
	v_pk_add_f32 v[160:161], v[160:161], v[8:9]
	v_pk_add_f32 v[162:163], v[162:163], v[10:11]
	v_pk_add_f32 v[164:165], v[164:165], v[12:13]
	v_pk_add_f32 v[166:167], v[166:167], v[14:15]
	v_pk_add_f32 v[168:169], v[168:169], v[16:17]
	v_pk_add_f32 v[170:171], v[170:171], v[18:19]
	v_pk_add_f32 v[172:173], v[172:173], v[20:21]
	v_pk_add_f32 v[174:175], v[174:175], v[22:23]
	s_waitcnt vmcnt(0)
	v_pk_add_f32 v[160:161], v[160:161], v[24:25]
	v_pk_add_f32 v[162:163], v[162:163], v[26:27]
	v_pk_add_f32 v[164:165], v[164:165], v[28:29]
	v_pk_add_f32 v[166:167], v[166:167], v[30:31]
	v_pk_add_f32 v[168:169], v[168:169], v[32:33]
	v_pk_add_f32 v[170:171], v[170:171], v[34:35]
	v_pk_add_f32 v[172:173], v[172:173], v[36:37]
	v_pk_add_f32 v[174:175], v[174:175], v[38:39]
	v_pk_mul_f32 v[252:253], v[160:161], v[160:161]
	v_pk_mul_f32 v[254:255], v[162:163], v[162:163]
	v_pk_fma_f32 v[252:253], v[164:165], v[164:165], v[252:253]
	v_pk_fma_f32 v[254:255], v[166:167], v[166:167], v[254:255]
	v_pk_fma_f32 v[252:253], v[168:169], v[168:169], v[252:253]
	v_pk_fma_f32 v[254:255], v[170:171], v[170:171], v[254:255]
	v_pk_fma_f32 v[252:253], v[172:173], v[172:173], v[252:253]
	v_pk_fma_f32 v[254:255], v[174:175], v[174:175], v[254:255]
	v_pk_add_f32 v[252:253], v[252:253], v[254:255]
	s_nop 0
	v_add_f32_e32 v183, v252, v253
	s_nop 1
	v_add_f32_dpp v183, v183, v183 quad_perm:[1,0,3,2] row_mask:0xf bank_mask:0xf bound_ctrl:1
	s_nop 1
	v_add_f32_dpp v183, v183, v183 quad_perm:[2,3,0,1] row_mask:0xf bank_mask:0xf bound_ctrl:1
	s_nop 1
	v_add_f32_dpp v183, v183, v183 row_half_mirror row_mask:0xf bank_mask:0xf bound_ctrl:1
	s_nop 1
	v_add_f32_dpp v183, v183, v183 row_mirror row_mask:0xf bank_mask:0xf bound_ctrl:1
	s_nop 1
	v_readlane_b32 s98, v183, 0
	v_readlane_b32 s99, v183, 16
	v_readlane_b32 s100, v183, 32
	v_readlane_b32 s101, v183, 48
	s_nop 1
	v_mov_b32_e32 v183, s98
	v_add_f32_e32 v183, s99, v183
	v_add_f32_e32 v183, s100, v183
	v_add_f32_e32 v183, s101, v183
	v_fmamk_f32 v183, v183, 0x3a800000, v182
	v_cmp_gt_f32_e32 vcc, 0x800000, v183
	v_mul_f32_e32 v181, 0x4b800000, v183
	s_nop 1
	v_cndmask_b32_e32 v183, v183, v181, vcc
	v_rsq_f32_e32 v183, v183
	s_nop 0
	v_mul_f32_e32 v181, 0x45800000, v183
	v_cndmask_b32_e32 v184, v183, v181, vcc
	v_mov_b32_e32 v185, v184
	v_pk_mul_f32 v[160:161], v[160:161], v[184:185]
	v_pk_mul_f32 v[162:163], v[162:163], v[184:185]
	v_pk_mul_f32 v[164:165], v[164:165], v[184:185]
	v_pk_mul_f32 v[166:167], v[166:167], v[184:185]
	v_pk_mul_f32 v[168:169], v[168:169], v[184:185]
	v_pk_mul_f32 v[170:171], v[170:171], v[184:185]
	v_pk_mul_f32 v[172:173], v[172:173], v[184:185]
	v_pk_mul_f32 v[174:175], v[174:175], v[184:185]
	v_pk_fma_f32 v[144:145], v[160:161], v[128:129], v[144:145]
	v_pk_fma_f32 v[146:147], v[162:163], v[130:131], v[146:147]
	v_pk_fma_f32 v[148:149], v[164:165], v[132:133], v[148:149]
	v_pk_fma_f32 v[150:151], v[166:167], v[134:135], v[150:151]
	v_pk_fma_f32 v[152:153], v[168:169], v[136:137], v[152:153]
	v_pk_fma_f32 v[154:155], v[170:171], v[138:139], v[154:155]
	v_pk_fma_f32 v[156:157], v[172:173], v[140:141], v[156:157]
	v_pk_fma_f32 v[158:159], v[174:175], v[142:143], v[158:159]
	v_pk_mul_f32 v[252:253], v[144:145], v[144:145]
	v_pk_mul_f32 v[254:255], v[146:147], v[146:147]
	v_pk_fma_f32 v[252:253], v[148:149], v[148:149], v[252:253]
	v_pk_fma_f32 v[254:255], v[150:151], v[150:151], v[254:255]
	v_pk_fma_f32 v[252:253], v[152:153], v[152:153], v[252:253]
	v_pk_fma_f32 v[254:255], v[154:155], v[154:155], v[254:255]
	v_pk_fma_f32 v[252:253], v[156:157], v[156:157], v[252:253]
	v_pk_fma_f32 v[254:255], v[158:159], v[158:159], v[254:255]
	v_pk_add_f32 v[252:253], v[252:253], v[254:255]
	s_nop 0
	v_add_f32_e32 v183, v252, v253
	s_nop 1
	v_add_f32_dpp v183, v183, v183 quad_perm:[1,0,3,2] row_mask:0xf bank_mask:0xf bound_ctrl:1
	s_nop 1
	v_add_f32_dpp v183, v183, v183 quad_perm:[2,3,0,1] row_mask:0xf bank_mask:0xf bound_ctrl:1
	s_nop 1
	v_add_f32_dpp v183, v183, v183 row_half_mirror row_mask:0xf bank_mask:0xf bound_ctrl:1
	s_nop 1
	v_add_f32_dpp v183, v183, v183 row_mirror row_mask:0xf bank_mask:0xf bound_ctrl:1
	s_nop 1
	v_readlane_b32 s98, v183, 0
	v_readlane_b32 s99, v183, 16
	v_readlane_b32 s100, v183, 32
	v_readlane_b32 s101, v183, 48
	s_nop 1
	v_mov_b32_e32 v183, s98
	v_add_f32_e32 v183, s99, v183
	v_add_f32_e32 v183, s100, v183
	v_add_f32_e32 v183, s101, v183
	v_fmamk_f32 v183, v183, 0x3a800000, v182
	v_cmp_gt_f32_e32 vcc, 0x800000, v183
	v_mul_f32_e32 v181, 0x4b800000, v183
	s_nop 1
	v_cndmask_b32_e32 v183, v183, v181, vcc
	v_rsq_f32_e32 v183, v183
	s_nop 0
	v_mul_f32_e32 v181, 0x45800000, v183
	v_cndmask_b32_e32 v184, v183, v181, vcc
	v_mov_b32_e32 v185, v184
	v_cvt_pk_bf16_f32 v0, v144, v145
	v_cvt_pk_bf16_f32 v1, v146, v147
	v_cvt_pk_bf16_f32 v2, v148, v149
	v_cvt_pk_bf16_f32 v3, v150, v151
	v_cvt_pk_bf16_f32 v4, v152, v153
	v_cvt_pk_bf16_f32 v5, v154, v155
	v_cvt_pk_bf16_f32 v6, v156, v157
	v_cvt_pk_bf16_f32 v7, v158, v159
	v_add_u32_e32 v181, 0x3800000, v177
	global_store_dwordx4 v181, v[0:3], s[78:79]
	global_store_dwordx4 v181, v[4:7], s[78:79] offset:1024
	v_add_u32_e32 v236, 0x10000, v237
	s_mov_b64 exec, 1
	global_store_dword v236, v184, s[78:79]
	s_mov_b64 exec, -1
.Lmyxupd_done_0:
.LBB0_465:
	s_waitcnt vmcnt(0)
	v_readlane_b32 s0, v235, 41
	v_readlane_b32 s1, v235, 42
	s_and_b64 vcc, exec, s[0:1]
	s_barrier
	s_cbranch_vccnz .LBB0_519
	v_mbcnt_lo_u32_b32 v0, -1, 0
	v_mbcnt_hi_u32_b32 v0, -1, v0
	s_nop 0
	v_cmp_eq_u32_e32 vcc, 0, v0
	s_and_saveexec_b64 s[0:1], vcc
	s_cbranch_execz .LBB0_518
	s_add_i32 s4, 0, 0x20000
	v_mov_b32_e32 v0, s4
	s_waitcnt vmcnt(0) expcnt(0) lgkmcnt(0)
	ds_read_b32 v2, v0
	s_add_i32 s4, 0, 0x20004
	v_mov_b32_e32 v0, s4
	ds_read_b32 v0, v0
	s_waitcnt lgkmcnt(1)
	v_cmp_ne_u32_e32 vcc, 0, v2
	s_cbranch_vccnz .LBB0_482
	v_readlane_b32 s4, v235, 0
	v_readlane_b32 s5, v235, 1
	v_readlane_b32 s6, v235, 2
	s_mul_i32 s18, s5, s6
	s_mul_i32 s18, s18, s4
	s_add_u32 s4, s78, 0x1000
	s_addc_u32 s5, s79, 0
	s_add_u32 s6, s78, 0x1100
	s_addc_u32 s7, s79, 0
	s_add_u32 s8, s78, 0x1200
	s_addc_u32 s9, s79, 0
	s_add_u32 s10, s78, 0x1300
	s_addc_u32 s11, s79, 0
	s_mov_b32 s19, 1
	v_mov_b32_e32 v16, 0
	s_branch .LBB0_470

.LBB0_721:
	v_readlane_b32 s0, v235, 52
	v_readlane_b32 s1, v235, 53
	s_and_b64 vcc, exec, s[0:1]
	s_waitcnt lgkmcnt(0)
	s_barrier
	v_mbcnt_lo_u32_b32 v0, -1, 0
	v_mbcnt_hi_u32_b32 v0, -1, v0
	v_writelane_b32 v234, s93, 4
	s_cbranch_vccnz .LBB0_741
	v_readlane_b32 s4, v235, 4
	v_readlane_b32 s8, v235, 8
	v_readlane_b32 s9, v235, 9
	v_readlane_b32 s6, v235, 6
	v_readlane_b32 s7, v235, 7
	v_readlane_b32 s12, v235, 12
	v_readlane_b32 s13, v235, 13
	v_readlane_b32 s8, v235, 61
	v_readlane_b32 s10, v235, 10
	v_readlane_b32 s6, v235, 0
	v_readlane_b32 s9, v235, 62
	s_mov_b32 s12, s8
	s_ashr_i32 s13, s8, 31
	v_lshlrev_b32_e32 v2, 3, v0
	v_readlane_b32 s11, v235, 11
	s_lshl_b32 s6, s6, 4
	s_add_i32 s0, s8, 0xffffc000
	s_lshl_b64 s[8:9], s[12:13], 2
	s_mov_b32 s10, s12
	v_ashrrev_i32_e32 v3, 31, v2
	v_readlane_b32 s5, v235, 5
	v_readlane_b32 s14, v235, 14
	v_readlane_b32 s15, v235, 15
	v_readlane_b32 s16, v235, 16
	v_readlane_b32 s17, v235, 17
	v_readlane_b32 s18, v235, 18
	v_readlane_b32 s19, v235, 19
	v_readlane_b32 s7, v235, 1
	s_add_u32 s80, s8, 0x10000
	v_writelane_b32 v235, s10, 61
	v_lshlrev_b64 v[4:5], 1, v[2:3]
	v_lshlrev_b64 v[2:3], 2, v[2:3]
	s_addc_u32 s14, s9, 0
	s_ashr_i32 s7, s6, 31
	v_writelane_b32 v235, s11, 62
	s_lshl_b64 s[10:11], s[12:13], 11
	v_lshl_add_u64 v[152:153], s[86:87], 0, v[4:5]
	v_lshl_add_u64 v[154:155], s[90:91], 0, v[2:3]
	v_lshl_add_u64 v[156:157], s[54:55], 0, v[4:5]
	v_lshl_add_u64 v[158:159], s[18:19], 0, v[2:3]
	s_mov_b32 s1, 0
	v_cmp_eq_u32_e64 s[4:5], 0, v0
	s_lshl_b64 s[8:9], s[6:7], 2
	v_lshl_add_u64 v[160:161], s[10:11], 0, v[4:5]
	s_lshl_b64 s[10:11], s[6:7], 11
	s_mov_b64 s[24:25], 0x600000
	s_mov_b64 s[26:27], 0x600800
	s_mov_b64 s[28:29], 0x800000
	s_mov_b32 s7, 0x800000
	s_mov_b64 s[36:37], 0x800800
	s_mov_b64 s[38:39], 0xa00000
	s_mov_b64 s[40:41], 0xa00800
	s_mov_b64 s[42:43], 0xc00000
	s_mov_b64 s[44:45], 0xc00800
	s_mov_b64 s[46:47], 0xe00000
	s_mov_b64 s[48:49], 0xe00800
	s_mov_b64 s[50:51], 0x1000000
	s_mov_b32 s15, 0x1000000
	s_mov_b64 s[12:13], 0x1000800
	s_mov_b64 s[82:83], 0x1200000
	s_mov_b32 s16, 0x1200000
	s_mov_b64 s[90:91], 0x1200800
	s_mov_b64 s[20:21], 0x1400000
	s_mov_b32 s17, 0x1400000
	s_mov_b64 s[22:23], 0x1400800
	v_mov_b32_e32 v215, 0
	v_mov_b32_e32 v216, 0x358637bd
	v_mbcnt_lo_u32_b32 v176, -1, 0
	v_mbcnt_hi_u32_b32 v176, -1, v176
	v_readlane_b32 s98, v235, 49
	v_readlane_b32 s99, v235, 20
	v_readlane_b32 s100, v235, 18
	v_readlane_b32 s101, v235, 19
	s_nop 3
	s_lshr_b32 vcc_lo, s98, 3
	s_and_b32 vcc_hi, vcc_lo, 7
	s_lshl_b32 vcc_hi, vcc_hi, 8
	s_lshr_b32 vcc_lo, vcc_lo, 3
	s_lshl_b32 vcc_lo, vcc_lo, 3
	s_add_i32 s98, vcc_hi, vcc_lo
	s_add_i32 s98, s98, s99
	v_lshlrev_b32_e32 v177, 4, v176
	s_lshl_b32 s99, s98, 11
	v_add_u32_e32 v177, s99, v177
	v_add_u32_e32 v178, 0x1800000, v177
	v_add_u32_e32 v179, 0x9e00000, v177
	v_lshlrev_b32_e32 v180, 5, v176
	global_load_dwordx4 v[128:131], v180, s[100:101]
	global_load_dwordx4 v[132:135], v180, s[100:101] offset:16
	global_load_dwordx4 v[136:139], v180, s[100:101] offset:2048
	global_load_dwordx4 v[140:143], v180, s[100:101] offset:2064
	v_mov_b32_e32 v182, 0x358637bd
	global_load_dwordx4 v[0:3], v178, s[78:79]
	global_load_dwordx4 v[4:7], v178, s[78:79] offset:1024
	global_load_dwordx4 v[8:11], v179, s[78:79]
	global_load_dwordx4 v[12:15], v179, s[78:79] offset:1024
	v_add_u32_e32 v178, 0x400000, v178
	v_add_u32_e32 v179, 0x400000, v179
	global_load_dwordx4 v[16:19], v178, s[78:79]
	global_load_dwordx4 v[20:23], v178, s[78:79] offset:1024
	global_load_dwordx4 v[24:27], v179, s[78:79]
	global_load_dwordx4 v[28:31], v179, s[78:79] offset:1024
	v_add_u32_e32 v178, 0x400000, v178
	v_add_u32_e32 v179, 0x400000, v179
	global_load_dwordx4 v[32:35], v178, s[78:79]
	global_load_dwordx4 v[36:39], v178, s[78:79] offset:1024
	global_load_dwordx4 v[40:43], v179, s[78:79]
	global_load_dwordx4 v[44:47], v179, s[78:79] offset:1024
	v_add_u32_e32 v178, 0x400000, v178
	v_add_u32_e32 v179, 0x400000, v179
	global_load_dwordx4 v[48:51], v178, s[78:79]
	global_load_dwordx4 v[52:55], v178, s[78:79] offset:1024
	global_load_dwordx4 v[56:59], v179, s[78:79]
	global_load_dwordx4 v[60:63], v179, s[78:79] offset:1024
	v_add_u32_e32 v178, 0x400000, v178
	v_add_u32_e32 v179, 0x400000, v179
	global_load_dwordx4 v[64:67], v178, s[78:79]
	global_load_dwordx4 v[68:71], v178, s[78:79] offset:1024
	global_load_dwordx4 v[72:75], v179, s[78:79]
	global_load_dwordx4 v[76:79], v179, s[78:79] offset:1024
	v_add_u32_e32 v178, 0x400000, v178
	v_add_u32_e32 v179, 0x400000, v179
	global_load_dwordx4 v[80:83], v178, s[78:79]
	global_load_dwordx4 v[84:87], v178, s[78:79] offset:1024
	global_load_dwordx4 v[88:91], v179, s[78:79]
	global_load_dwordx4 v[92:95], v179, s[78:79] offset:1024
	v_add_u32_e32 v178, 0x400000, v178
	v_add_u32_e32 v179, 0x400000, v179
	global_load_dwordx4 v[96:99], v178, s[78:79]
	global_load_dwordx4 v[100:103], v178, s[78:79] offset:1024
	global_load_dwordx4 v[104:107], v179, s[78:79]
	global_load_dwordx4 v[108:111], v179, s[78:79] offset:1024
	v_add_u32_e32 v178, 0x400000, v178
	v_add_u32_e32 v179, 0x400000, v179
	global_load_dwordx4 v[112:115], v178, s[78:79]
	global_load_dwordx4 v[116:119], v178, s[78:79] offset:1024
	global_load_dwordx4 v[120:123], v179, s[78:79]
	global_load_dwordx4 v[124:127], v179, s[78:79] offset:1024
	v_mov_b32_e32 v183, s98
	v_lshlrev_b32_e32 v237, 2, v183
	v_add_u32_e32 v237, 0x10000, v237
	v_mov_b32_e32 v179, v183
	s_waitcnt vmcnt(28)
	v_lshlrev_b32_e32 v144, 16, v0
	v_and_b32_e32 v145, 0xffff0000, v0
	v_lshlrev_b32_e32 v146, 16, v1
	v_and_b32_e32 v147, 0xffff0000, v1
	v_lshlrev_b32_e32 v148, 16, v2
	v_and_b32_e32 v149, 0xffff0000, v2
	v_lshlrev_b32_e32 v150, 16, v3
	v_and_b32_e32 v151, 0xffff0000, v3
	v_lshlrev_b32_e32 v152, 16, v4
	v_and_b32_e32 v153, 0xffff0000, v4
	v_lshlrev_b32_e32 v154, 16, v5
	v_and_b32_e32 v155, 0xffff0000, v5
	v_lshlrev_b32_e32 v156, 16, v6
	v_and_b32_e32 v157, 0xffff0000, v6
	v_lshlrev_b32_e32 v158, 16, v7
	v_and_b32_e32 v159, 0xffff0000, v7
	v_lshlrev_b32_e32 v160, 16, v8
	v_and_b32_e32 v161, 0xffff0000, v8
	v_lshlrev_b32_e32 v162, 16, v9
	v_and_b32_e32 v163, 0xffff0000, v9
	v_lshlrev_b32_e32 v164, 16, v10
	v_and_b32_e32 v165, 0xffff0000, v10
	v_lshlrev_b32_e32 v166, 16, v11
	v_and_b32_e32 v167, 0xffff0000, v11
	v_lshlrev_b32_e32 v168, 16, v12
	v_and_b32_e32 v169, 0xffff0000, v12
	v_lshlrev_b32_e32 v170, 16, v13
	v_and_b32_e32 v171, 0xffff0000, v13
	v_lshlrev_b32_e32 v172, 16, v14
	v_and_b32_e32 v173, 0xffff0000, v14
	v_lshlrev_b32_e32 v174, 16, v15
	v_and_b32_e32 v175, 0xffff0000, v15
	v_pk_mul_f32 v[252:253], v[160:161], v[160:161]
	v_pk_mul_f32 v[254:255], v[162:163], v[162:163]
	v_pk_fma_f32 v[252:253], v[164:165], v[164:165], v[252:253]
	v_pk_fma_f32 v[254:255], v[166:167], v[166:167], v[254:255]
	v_pk_fma_f32 v[252:253], v[168:169], v[168:169], v[252:253]
	v_pk_fma_f32 v[254:255], v[170:171], v[170:171], v[254:255]
	v_pk_fma_f32 v[252:253], v[172:173], v[172:173], v[252:253]
	v_pk_fma_f32 v[254:255], v[174:175], v[174:175], v[254:255]
	v_pk_add_f32 v[252:253], v[252:253], v[254:255]
	s_nop 0
	v_add_f32_e32 v183, v252, v253
	s_nop 1
	v_add_f32_dpp v183, v183, v183 quad_perm:[1,0,3,2] row_mask:0xf bank_mask:0xf bound_ctrl:1
	s_nop 1
	v_add_f32_dpp v183, v183, v183 quad_perm:[2,3,0,1] row_mask:0xf bank_mask:0xf bound_ctrl:1
	s_nop 1
	v_add_f32_dpp v183, v183, v183 row_half_mirror row_mask:0xf bank_mask:0xf bound_ctrl:1
	s_nop 1
	v_add_f32_dpp v183, v183, v183 row_mirror row_mask:0xf bank_mask:0xf bound_ctrl:1
	s_nop 1
	v_readlane_b32 s98, v183, 0
	v_readlane_b32 s99, v183, 16
	v_readlane_b32 s100, v183, 32
	v_readlane_b32 s101, v183, 48
	s_nop 1
	v_mov_b32_e32 v183, s98
	v_add_f32_e32 v183, s99, v183
	v_add_f32_e32 v183, s100, v183
	v_add_f32_e32 v183, s101, v183
	v_fmamk_f32 v183, v183, 0x3a800000, v182
	v_cmp_gt_f32_e32 vcc, 0x800000, v183
	v_mul_f32_e32 v181, 0x4b800000, v183
	s_nop 1
	v_cndmask_b32_e32 v183, v183, v181, vcc
	v_rsq_f32_e32 v183, v183
	s_nop 0
	v_mul_f32_e32 v181, 0x45800000, v183
	v_cndmask_b32_e32 v184, v183, v181, vcc
	v_mov_b32_e32 v185, v184
	v_pk_mul_f32 v[160:161], v[160:161], v[184:185]
	v_pk_mul_f32 v[162:163], v[162:163], v[184:185]
	v_pk_mul_f32 v[164:165], v[164:165], v[184:185]
	v_pk_mul_f32 v[166:167], v[166:167], v[184:185]
	v_pk_mul_f32 v[168:169], v[168:169], v[184:185]
	v_pk_mul_f32 v[170:171], v[170:171], v[184:185]
	v_pk_mul_f32 v[172:173], v[172:173], v[184:185]
	v_pk_mul_f32 v[174:175], v[174:175], v[184:185]
	v_pk_fma_f32 v[144:145], v[160:161], v[128:129], v[144:145]
	v_pk_fma_f32 v[146:147], v[162:163], v[130:131], v[146:147]
	v_pk_fma_f32 v[148:149], v[164:165], v[132:133], v[148:149]
	v_pk_fma_f32 v[150:151], v[166:167], v[134:135], v[150:151]
	v_pk_fma_f32 v[152:153], v[168:169], v[136:137], v[152:153]
	v_pk_fma_f32 v[154:155], v[170:171], v[138:139], v[154:155]
	v_pk_fma_f32 v[156:157], v[172:173], v[140:141], v[156:157]
	v_pk_fma_f32 v[158:159], v[174:175], v[142:143], v[158:159]
	v_pk_mul_f32 v[252:253], v[144:145], v[144:145]
	v_pk_mul_f32 v[254:255], v[146:147], v[146:147]
	v_pk_fma_f32 v[252:253], v[148:149], v[148:149], v[252:253]
	v_pk_fma_f32 v[254:255], v[150:151], v[150:151], v[254:255]
	v_pk_fma_f32 v[252:253], v[152:153], v[152:153], v[252:253]
	v_pk_fma_f32 v[254:255], v[154:155], v[154:155], v[254:255]
	v_pk_fma_f32 v[252:253], v[156:157], v[156:157], v[252:253]
	v_pk_fma_f32 v[254:255], v[158:159], v[158:159], v[254:255]
	v_pk_add_f32 v[252:253], v[252:253], v[254:255]
	s_nop 0
	v_add_f32_e32 v183, v252, v253
	s_nop 1
	v_add_f32_dpp v183, v183, v183 quad_perm:[1,0,3,2] row_mask:0xf bank_mask:0xf bound_ctrl:1
	s_nop 1
	v_add_f32_dpp v183, v183, v183 quad_perm:[2,3,0,1] row_mask:0xf bank_mask:0xf bound_ctrl:1
	s_nop 1
	v_add_f32_dpp v183, v183, v183 row_half_mirror row_mask:0xf bank_mask:0xf bound_ctrl:1
	s_nop 1
	v_add_f32_dpp v183, v183, v183 row_mirror row_mask:0xf bank_mask:0xf bound_ctrl:1
	s_nop 1
	v_readlane_b32 s98, v183, 0
	v_readlane_b32 s99, v183, 16
	v_readlane_b32 s100, v183, 32
	v_readlane_b32 s101, v183, 48
	s_nop 1
	v_mov_b32_e32 v183, s98
	v_add_f32_e32 v183, s99, v183
	v_add_f32_e32 v183, s100, v183
	v_add_f32_e32 v183, s101, v183
	v_fmamk_f32 v183, v183, 0x3a800000, v182
	v_cmp_gt_f32_e32 vcc, 0x800000, v183
	v_mul_f32_e32 v181, 0x4b800000, v183
	s_nop 1
	v_cndmask_b32_e32 v183, v183, v181, vcc
	v_rsq_f32_e32 v183, v183
	s_nop 0
	v_mul_f32_e32 v181, 0x45800000, v183
	v_cndmask_b32_e32 v184, v183, v181, vcc
	v_mov_b32_e32 v185, v184
	v_cvt_pk_bf16_f32 v0, v144, v145
	v_cvt_pk_bf16_f32 v1, v146, v147
	v_cvt_pk_bf16_f32 v2, v148, v149
	v_cvt_pk_bf16_f32 v3, v150, v151
	v_cvt_pk_bf16_f32 v4, v152, v153
	v_cvt_pk_bf16_f32 v5, v154, v155
	v_cvt_pk_bf16_f32 v6, v156, v157
	v_cvt_pk_bf16_f32 v7, v158, v159
	v_add_u32_e32 v181, 0x1800000, v177
	global_store_dwordx4 v181, v[0:3], s[78:79]
	global_store_dwordx4 v181, v[4:7], s[78:79] offset:1024
	v_add_u32_e32 v236, 0x0, v237
	s_mov_b64 exec, 1
	global_store_dword v236, v184, s[78:79]
	s_mov_b64 exec, -1
	s_waitcnt vmcnt(24)
	v_lshlrev_b32_e32 v144, 16, v16
	v_and_b32_e32 v145, 0xffff0000, v16
	v_lshlrev_b32_e32 v146, 16, v17
	v_and_b32_e32 v147, 0xffff0000, v17
	v_lshlrev_b32_e32 v148, 16, v18
	v_and_b32_e32 v149, 0xffff0000, v18
	v_lshlrev_b32_e32 v150, 16, v19
	v_and_b32_e32 v151, 0xffff0000, v19
	v_lshlrev_b32_e32 v152, 16, v20
	v_and_b32_e32 v153, 0xffff0000, v20
	v_lshlrev_b32_e32 v154, 16, v21
	v_and_b32_e32 v155, 0xffff0000, v21
	v_lshlrev_b32_e32 v156, 16, v22
	v_and_b32_e32 v157, 0xffff0000, v22
	v_lshlrev_b32_e32 v158, 16, v23
	v_and_b32_e32 v159, 0xffff0000, v23
	v_lshlrev_b32_e32 v160, 16, v24
	v_and_b32_e32 v161, 0xffff0000, v24
	v_lshlrev_b32_e32 v162, 16, v25
	v_and_b32_e32 v163, 0xffff0000, v25
	v_lshlrev_b32_e32 v164, 16, v26
	v_and_b32_e32 v165, 0xffff0000, v26
	v_lshlrev_b32_e32 v166, 16, v27
	v_and_b32_e32 v167, 0xffff0000, v27
	v_lshlrev_b32_e32 v168, 16, v28
	v_and_b32_e32 v169, 0xffff0000, v28
	v_lshlrev_b32_e32 v170, 16, v29
	v_and_b32_e32 v171, 0xffff0000, v29
	v_lshlrev_b32_e32 v172, 16, v30
	v_and_b32_e32 v173, 0xffff0000, v30
	v_lshlrev_b32_e32 v174, 16, v31
	v_and_b32_e32 v175, 0xffff0000, v31
	v_pk_mul_f32 v[252:253], v[160:161], v[160:161]
	v_pk_mul_f32 v[254:255], v[162:163], v[162:163]
	v_pk_fma_f32 v[252:253], v[164:165], v[164:165], v[252:253]
	v_pk_fma_f32 v[254:255], v[166:167], v[166:167], v[254:255]
	v_pk_fma_f32 v[252:253], v[168:169], v[168:169], v[252:253]
	v_pk_fma_f32 v[254:255], v[170:171], v[170:171], v[254:255]
	v_pk_fma_f32 v[252:253], v[172:173], v[172:173], v[252:253]
	v_pk_fma_f32 v[254:255], v[174:175], v[174:175], v[254:255]
	v_pk_add_f32 v[252:253], v[252:253], v[254:255]
	s_nop 0
	v_add_f32_e32 v183, v252, v253
	s_nop 1
	v_add_f32_dpp v183, v183, v183 quad_perm:[1,0,3,2] row_mask:0xf bank_mask:0xf bound_ctrl:1
	s_nop 1
	v_add_f32_dpp v183, v183, v183 quad_perm:[2,3,0,1] row_mask:0xf bank_mask:0xf bound_ctrl:1
	s_nop 1
	v_add_f32_dpp v183, v183, v183 row_half_mirror row_mask:0xf bank_mask:0xf bound_ctrl:1
	s_nop 1
	v_add_f32_dpp v183, v183, v183 row_mirror row_mask:0xf bank_mask:0xf bound_ctrl:1
	s_nop 1
	v_readlane_b32 s98, v183, 0
	v_readlane_b32 s99, v183, 16
	v_readlane_b32 s100, v183, 32
	v_readlane_b32 s101, v183, 48
	s_nop 1
	v_mov_b32_e32 v183, s98
	v_add_f32_e32 v183, s99, v183
	v_add_f32_e32 v183, s100, v183
	v_add_f32_e32 v183, s101, v183
	v_fmamk_f32 v183, v183, 0x3a800000, v182
	v_cmp_gt_f32_e32 vcc, 0x800000, v183
	v_mul_f32_e32 v181, 0x4b800000, v183
	s_nop 1
	v_cndmask_b32_e32 v183, v183, v181, vcc
	v_rsq_f32_e32 v183, v183
	s_nop 0
	v_mul_f32_e32 v181, 0x45800000, v183
	v_cndmask_b32_e32 v184, v183, v181, vcc
	v_mov_b32_e32 v185, v184
	v_pk_mul_f32 v[160:161], v[160:161], v[184:185]
	v_pk_mul_f32 v[162:163], v[162:163], v[184:185]
	v_pk_mul_f32 v[164:165], v[164:165], v[184:185]
	v_pk_mul_f32 v[166:167], v[166:167], v[184:185]
	v_pk_mul_f32 v[168:169], v[168:169], v[184:185]
	v_pk_mul_f32 v[170:171], v[170:171], v[184:185]
	v_pk_mul_f32 v[172:173], v[172:173], v[184:185]
	v_pk_mul_f32 v[174:175], v[174:175], v[184:185]
	v_pk_fma_f32 v[144:145], v[160:161], v[128:129], v[144:145]
	v_pk_fma_f32 v[146:147], v[162:163], v[130:131], v[146:147]
	v_pk_fma_f32 v[148:149], v[164:165], v[132:133], v[148:149]
	v_pk_fma_f32 v[150:151], v[166:167], v[134:135], v[150:151]
	v_pk_fma_f32 v[152:153], v[168:169], v[136:137], v[152:153]
	v_pk_fma_f32 v[154:155], v[170:171], v[138:139], v[154:155]
	v_pk_fma_f32 v[156:157], v[172:173], v[140:141], v[156:157]
	v_pk_fma_f32 v[158:159], v[174:175], v[142:143], v[158:159]
	v_pk_mul_f32 v[252:253], v[144:145], v[144:145]
	v_pk_mul_f32 v[254:255], v[146:147], v[146:147]
	v_pk_fma_f32 v[252:253], v[148:149], v[148:149], v[252:253]
	v_pk_fma_f32 v[254:255], v[150:151], v[150:151], v[254:255]
	v_pk_fma_f32 v[252:253], v[152:153], v[152:153], v[252:253]
	v_pk_fma_f32 v[254:255], v[154:155], v[154:155], v[254:255]
	v_pk_fma_f32 v[252:253], v[156:157], v[156:157], v[252:253]
	v_pk_fma_f32 v[254:255], v[158:159], v[158:159], v[254:255]
	v_pk_add_f32 v[252:253], v[252:253], v[254:255]
	s_nop 0
	v_add_f32_e32 v183, v252, v253
	s_nop 1
	v_add_f32_dpp v183, v183, v183 quad_perm:[1,0,3,2] row_mask:0xf bank_mask:0xf bound_ctrl:1
	s_nop 1
	v_add_f32_dpp v183, v183, v183 quad_perm:[2,3,0,1] row_mask:0xf bank_mask:0xf bound_ctrl:1
	s_nop 1
	v_add_f32_dpp v183, v183, v183 row_half_mirror row_mask:0xf bank_mask:0xf bound_ctrl:1
	s_nop 1
	v_add_f32_dpp v183, v183, v183 row_mirror row_mask:0xf bank_mask:0xf bound_ctrl:1
	s_nop 1
	v_readlane_b32 s98, v183, 0
	v_readlane_b32 s99, v183, 16
	v_readlane_b32 s100, v183, 32
	v_readlane_b32 s101, v183, 48
	s_nop 1
	v_mov_b32_e32 v183, s98
	v_add_f32_e32 v183, s99, v183
	v_add_f32_e32 v183, s100, v183
	v_add_f32_e32 v183, s101, v183
	v_fmamk_f32 v183, v183, 0x3a800000, v182
	v_cmp_gt_f32_e32 vcc, 0x800000, v183
	v_mul_f32_e32 v181, 0x4b800000, v183
	s_nop 1
	v_cndmask_b32_e32 v183, v183, v181, vcc
	v_rsq_f32_e32 v183, v183
	s_nop 0
	v_mul_f32_e32 v181, 0x45800000, v183
	v_cndmask_b32_e32 v184, v183, v181, vcc
	v_mov_b32_e32 v185, v184
	v_cvt_pk_bf16_f32 v16, v144, v145
	v_cvt_pk_bf16_f32 v17, v146, v147
	v_cvt_pk_bf16_f32 v18, v148, v149
	v_cvt_pk_bf16_f32 v19, v150, v151
	v_cvt_pk_bf16_f32 v20, v152, v153
	v_cvt_pk_bf16_f32 v21, v154, v155
	v_cvt_pk_bf16_f32 v22, v156, v157
	v_cvt_pk_bf16_f32 v23, v158, v159
	v_add_u32_e32 v181, 0x1c00000, v177
	global_store_dwordx4 v181, v[16:19], s[78:79]
	global_store_dwordx4 v181, v[20:23], s[78:79] offset:1024
	v_add_u32_e32 v236, 0x2000, v237
	s_mov_b64 exec, 1
	global_store_dword v236, v184, s[78:79]
	s_mov_b64 exec, -1
	s_waitcnt vmcnt(20)
	v_lshlrev_b32_e32 v144, 16, v32
	v_and_b32_e32 v145, 0xffff0000, v32
	v_lshlrev_b32_e32 v146, 16, v33
	v_and_b32_e32 v147, 0xffff0000, v33
	v_lshlrev_b32_e32 v148, 16, v34
	v_and_b32_e32 v149, 0xffff0000, v34
	v_lshlrev_b32_e32 v150, 16, v35
	v_and_b32_e32 v151, 0xffff0000, v35
	v_lshlrev_b32_e32 v152, 16, v36
	v_and_b32_e32 v153, 0xffff0000, v36
	v_lshlrev_b32_e32 v154, 16, v37
	v_and_b32_e32 v155, 0xffff0000, v37
	v_lshlrev_b32_e32 v156, 16, v38
	v_and_b32_e32 v157, 0xffff0000, v38
	v_lshlrev_b32_e32 v158, 16, v39
	v_and_b32_e32 v159, 0xffff0000, v39
	v_lshlrev_b32_e32 v160, 16, v40
	v_and_b32_e32 v161, 0xffff0000, v40
	v_lshlrev_b32_e32 v162, 16, v41
	v_and_b32_e32 v163, 0xffff0000, v41
	v_lshlrev_b32_e32 v164, 16, v42
	v_and_b32_e32 v165, 0xffff0000, v42
	v_lshlrev_b32_e32 v166, 16, v43
	v_and_b32_e32 v167, 0xffff0000, v43
	v_lshlrev_b32_e32 v168, 16, v44
	v_and_b32_e32 v169, 0xffff0000, v44
	v_lshlrev_b32_e32 v170, 16, v45
	v_and_b32_e32 v171, 0xffff0000, v45
	v_lshlrev_b32_e32 v172, 16, v46
	v_and_b32_e32 v173, 0xffff0000, v46
	v_lshlrev_b32_e32 v174, 16, v47
	v_and_b32_e32 v175, 0xffff0000, v47
	v_pk_mul_f32 v[252:253], v[160:161], v[160:161]
	v_pk_mul_f32 v[254:255], v[162:163], v[162:163]
	v_pk_fma_f32 v[252:253], v[164:165], v[164:165], v[252:253]
	v_pk_fma_f32 v[254:255], v[166:167], v[166:167], v[254:255]
	v_pk_fma_f32 v[252:253], v[168:169], v[168:169], v[252:253]
	v_pk_fma_f32 v[254:255], v[170:171], v[170:171], v[254:255]
	v_pk_fma_f32 v[252:253], v[172:173], v[172:173], v[252:253]
	v_pk_fma_f32 v[254:255], v[174:175], v[174:175], v[254:255]
	v_pk_add_f32 v[252:253], v[252:253], v[254:255]
	s_nop 0
	v_add_f32_e32 v183, v252, v253
	s_nop 1
	v_add_f32_dpp v183, v183, v183 quad_perm:[1,0,3,2] row_mask:0xf bank_mask:0xf bound_ctrl:1
	s_nop 1
	v_add_f32_dpp v183, v183, v183 quad_perm:[2,3,0,1] row_mask:0xf bank_mask:0xf bound_ctrl:1
	s_nop 1
	v_add_f32_dpp v183, v183, v183 row_half_mirror row_mask:0xf bank_mask:0xf bound_ctrl:1
	s_nop 1
	v_add_f32_dpp v183, v183, v183 row_mirror row_mask:0xf bank_mask:0xf bound_ctrl:1
	s_nop 1
	v_readlane_b32 s98, v183, 0
	v_readlane_b32 s99, v183, 16
	v_readlane_b32 s100, v183, 32
	v_readlane_b32 s101, v183, 48
	s_nop 1
	v_mov_b32_e32 v183, s98
	v_add_f32_e32 v183, s99, v183
	v_add_f32_e32 v183, s100, v183
	v_add_f32_e32 v183, s101, v183
	v_fmamk_f32 v183, v183, 0x3a800000, v182
	v_cmp_gt_f32_e32 vcc, 0x800000, v183
	v_mul_f32_e32 v181, 0x4b800000, v183
	s_nop 1
	v_cndmask_b32_e32 v183, v183, v181, vcc
	v_rsq_f32_e32 v183, v183
	s_nop 0
	v_mul_f32_e32 v181, 0x45800000, v183
	v_cndmask_b32_e32 v184, v183, v181, vcc
	v_mov_b32_e32 v185, v184
	v_pk_mul_f32 v[160:161], v[160:161], v[184:185]
	v_pk_mul_f32 v[162:163], v[162:163], v[184:185]
	v_pk_mul_f32 v[164:165], v[164:165], v[184:185]
	v_pk_mul_f32 v[166:167], v[166:167], v[184:185]
	v_pk_mul_f32 v[168:169], v[168:169], v[184:185]
	v_pk_mul_f32 v[170:171], v[170:171], v[184:185]
	v_pk_mul_f32 v[172:173], v[172:173], v[184:185]
	v_pk_mul_f32 v[174:175], v[174:175], v[184:185]
	v_pk_fma_f32 v[144:145], v[160:161], v[128:129], v[144:145]
	v_pk_fma_f32 v[146:147], v[162:163], v[130:131], v[146:147]
	v_pk_fma_f32 v[148:149], v[164:165], v[132:133], v[148:149]
	v_pk_fma_f32 v[150:151], v[166:167], v[134:135], v[150:151]
	v_pk_fma_f32 v[152:153], v[168:169], v[136:137], v[152:153]
	v_pk_fma_f32 v[154:155], v[170:171], v[138:139], v[154:155]
	v_pk_fma_f32 v[156:157], v[172:173], v[140:141], v[156:157]
	v_pk_fma_f32 v[158:159], v[174:175], v[142:143], v[158:159]
	v_pk_mul_f32 v[252:253], v[144:145], v[144:145]
	v_pk_mul_f32 v[254:255], v[146:147], v[146:147]
	v_pk_fma_f32 v[252:253], v[148:149], v[148:149], v[252:253]
	v_pk_fma_f32 v[254:255], v[150:151], v[150:151], v[254:255]
	v_pk_fma_f32 v[252:253], v[152:153], v[152:153], v[252:253]
	v_pk_fma_f32 v[254:255], v[154:155], v[154:155], v[254:255]
	v_pk_fma_f32 v[252:253], v[156:157], v[156:157], v[252:253]
	v_pk_fma_f32 v[254:255], v[158:159], v[158:159], v[254:255]
	v_pk_add_f32 v[252:253], v[252:253], v[254:255]
	s_nop 0
	v_add_f32_e32 v183, v252, v253
	s_nop 1
	v_add_f32_dpp v183, v183, v183 quad_perm:[1,0,3,2] row_mask:0xf bank_mask:0xf bound_ctrl:1
	s_nop 1
	v_add_f32_dpp v183, v183, v183 quad_perm:[2,3,0,1] row_mask:0xf bank_mask:0xf bound_ctrl:1
	s_nop 1
	v_add_f32_dpp v183, v183, v183 row_half_mirror row_mask:0xf bank_mask:0xf bound_ctrl:1
	s_nop 1
	v_add_f32_dpp v183, v183, v183 row_mirror row_mask:0xf bank_mask:0xf bound_ctrl:1
	s_nop 1
	v_readlane_b32 s98, v183, 0
	v_readlane_b32 s99, v183, 16
	v_readlane_b32 s100, v183, 32
	v_readlane_b32 s101, v183, 48
	s_nop 1
	v_mov_b32_e32 v183, s98
	v_add_f32_e32 v183, s99, v183
	v_add_f32_e32 v183, s100, v183
	v_add_f32_e32 v183, s101, v183
	v_fmamk_f32 v183, v183, 0x3a800000, v182
	v_cmp_gt_f32_e32 vcc, 0x800000, v183
	v_mul_f32_e32 v181, 0x4b800000, v183
	s_nop 1
	v_cndmask_b32_e32 v183, v183, v181, vcc
	v_rsq_f32_e32 v183, v183
	s_nop 0
	v_mul_f32_e32 v181, 0x45800000, v183
	v_cndmask_b32_e32 v184, v183, v181, vcc
	v_mov_b32_e32 v185, v184
	v_cvt_pk_bf16_f32 v32, v144, v145
	v_cvt_pk_bf16_f32 v33, v146, v147
	v_cvt_pk_bf16_f32 v34, v148, v149
	v_cvt_pk_bf16_f32 v35, v150, v151
	v_cvt_pk_bf16_f32 v36, v152, v153
	v_cvt_pk_bf16_f32 v37, v154, v155
	v_cvt_pk_bf16_f32 v38, v156, v157
	v_cvt_pk_bf16_f32 v39, v158, v159
	v_add_u32_e32 v181, 0x2000000, v177
	global_store_dwordx4 v181, v[32:35], s[78:79]
	global_store_dwordx4 v181, v[36:39], s[78:79] offset:1024
	v_add_u32_e32 v236, 0x4000, v237
	s_mov_b64 exec, 1
	global_store_dword v236, v184, s[78:79]
	s_mov_b64 exec, -1
	s_waitcnt vmcnt(16)
	v_lshlrev_b32_e32 v144, 16, v48
	v_and_b32_e32 v145, 0xffff0000, v48
	v_lshlrev_b32_e32 v146, 16, v49
	v_and_b32_e32 v147, 0xffff0000, v49
	v_lshlrev_b32_e32 v148, 16, v50
	v_and_b32_e32 v149, 0xffff0000, v50
	v_lshlrev_b32_e32 v150, 16, v51
	v_and_b32_e32 v151, 0xffff0000, v51
	v_lshlrev_b32_e32 v152, 16, v52
	v_and_b32_e32 v153, 0xffff0000, v52
	v_lshlrev_b32_e32 v154, 16, v53
	v_and_b32_e32 v155, 0xffff0000, v53
	v_lshlrev_b32_e32 v156, 16, v54
	v_and_b32_e32 v157, 0xffff0000, v54
	v_lshlrev_b32_e32 v158, 16, v55
	v_and_b32_e32 v159, 0xffff0000, v55
	v_lshlrev_b32_e32 v160, 16, v56
	v_and_b32_e32 v161, 0xffff0000, v56
	v_lshlrev_b32_e32 v162, 16, v57
	v_and_b32_e32 v163, 0xffff0000, v57
	v_lshlrev_b32_e32 v164, 16, v58
	v_and_b32_e32 v165, 0xffff0000, v58
	v_lshlrev_b32_e32 v166, 16, v59
	v_and_b32_e32 v167, 0xffff0000, v59
	v_lshlrev_b32_e32 v168, 16, v60
	v_and_b32_e32 v169, 0xffff0000, v60
	v_lshlrev_b32_e32 v170, 16, v61
	v_and_b32_e32 v171, 0xffff0000, v61
	v_lshlrev_b32_e32 v172, 16, v62
	v_and_b32_e32 v173, 0xffff0000, v62
	v_lshlrev_b32_e32 v174, 16, v63
	v_and_b32_e32 v175, 0xffff0000, v63
	v_pk_mul_f32 v[252:253], v[160:161], v[160:161]
	v_pk_mul_f32 v[254:255], v[162:163], v[162:163]
	v_pk_fma_f32 v[252:253], v[164:165], v[164:165], v[252:253]
	v_pk_fma_f32 v[254:255], v[166:167], v[166:167], v[254:255]
	v_pk_fma_f32 v[252:253], v[168:169], v[168:169], v[252:253]
	v_pk_fma_f32 v[254:255], v[170:171], v[170:171], v[254:255]
	v_pk_fma_f32 v[252:253], v[172:173], v[172:173], v[252:253]
	v_pk_fma_f32 v[254:255], v[174:175], v[174:175], v[254:255]
	v_pk_add_f32 v[252:253], v[252:253], v[254:255]
	s_nop 0
	v_add_f32_e32 v183, v252, v253
	s_nop 1
	v_add_f32_dpp v183, v183, v183 quad_perm:[1,0,3,2] row_mask:0xf bank_mask:0xf bound_ctrl:1
	s_nop 1
	v_add_f32_dpp v183, v183, v183 quad_perm:[2,3,0,1] row_mask:0xf bank_mask:0xf bound_ctrl:1
	s_nop 1
	v_add_f32_dpp v183, v183, v183 row_half_mirror row_mask:0xf bank_mask:0xf bound_ctrl:1
	s_nop 1
	v_add_f32_dpp v183, v183, v183 row_mirror row_mask:0xf bank_mask:0xf bound_ctrl:1
	s_nop 1
	v_readlane_b32 s98, v183, 0
	v_readlane_b32 s99, v183, 16
	v_readlane_b32 s100, v183, 32
	v_readlane_b32 s101, v183, 48
	s_nop 1
	v_mov_b32_e32 v183, s98
	v_add_f32_e32 v183, s99, v183
	v_add_f32_e32 v183, s100, v183
	v_add_f32_e32 v183, s101, v183
	v_fmamk_f32 v183, v183, 0x3a800000, v182
	v_cmp_gt_f32_e32 vcc, 0x800000, v183
	v_mul_f32_e32 v181, 0x4b800000, v183
	s_nop 1
	v_cndmask_b32_e32 v183, v183, v181, vcc
	v_rsq_f32_e32 v183, v183
	s_nop 0
	v_mul_f32_e32 v181, 0x45800000, v183
	v_cndmask_b32_e32 v184, v183, v181, vcc
	v_mov_b32_e32 v185, v184
	v_pk_mul_f32 v[160:161], v[160:161], v[184:185]
	v_pk_mul_f32 v[162:163], v[162:163], v[184:185]
	v_pk_mul_f32 v[164:165], v[164:165], v[184:185]
	v_pk_mul_f32 v[166:167], v[166:167], v[184:185]
	v_pk_mul_f32 v[168:169], v[168:169], v[184:185]
	v_pk_mul_f32 v[170:171], v[170:171], v[184:185]
	v_pk_mul_f32 v[172:173], v[172:173], v[184:185]
	v_pk_mul_f32 v[174:175], v[174:175], v[184:185]
	v_pk_fma_f32 v[144:145], v[160:161], v[128:129], v[144:145]
	v_pk_fma_f32 v[146:147], v[162:163], v[130:131], v[146:147]
	v_pk_fma_f32 v[148:149], v[164:165], v[132:133], v[148:149]
	v_pk_fma_f32 v[150:151], v[166:167], v[134:135], v[150:151]
	v_pk_fma_f32 v[152:153], v[168:169], v[136:137], v[152:153]
	v_pk_fma_f32 v[154:155], v[170:171], v[138:139], v[154:155]
	v_pk_fma_f32 v[156:157], v[172:173], v[140:141], v[156:157]
	v_pk_fma_f32 v[158:159], v[174:175], v[142:143], v[158:159]
	v_pk_mul_f32 v[252:253], v[144:145], v[144:145]
	v_pk_mul_f32 v[254:255], v[146:147], v[146:147]
	v_pk_fma_f32 v[252:253], v[148:149], v[148:149], v[252:253]
	v_pk_fma_f32 v[254:255], v[150:151], v[150:151], v[254:255]
	v_pk_fma_f32 v[252:253], v[152:153], v[152:153], v[252:253]
	v_pk_fma_f32 v[254:255], v[154:155], v[154:155], v[254:255]
	v_pk_fma_f32 v[252:253], v[156:157], v[156:157], v[252:253]
	v_pk_fma_f32 v[254:255], v[158:159], v[158:159], v[254:255]
	v_pk_add_f32 v[252:253], v[252:253], v[254:255]
	s_nop 0
	v_add_f32_e32 v183, v252, v253
	s_nop 1
	v_add_f32_dpp v183, v183, v183 quad_perm:[1,0,3,2] row_mask:0xf bank_mask:0xf bound_ctrl:1
	s_nop 1
	v_add_f32_dpp v183, v183, v183 quad_perm:[2,3,0,1] row_mask:0xf bank_mask:0xf bound_ctrl:1
	s_nop 1
	v_add_f32_dpp v183, v183, v183 row_half_mirror row_mask:0xf bank_mask:0xf bound_ctrl:1
	s_nop 1
	v_add_f32_dpp v183, v183, v183 row_mirror row_mask:0xf bank_mask:0xf bound_ctrl:1
	s_nop 1
	v_readlane_b32 s98, v183, 0
	v_readlane_b32 s99, v183, 16
	v_readlane_b32 s100, v183, 32
	v_readlane_b32 s101, v183, 48
	s_nop 1
	v_mov_b32_e32 v183, s98
	v_add_f32_e32 v183, s99, v183
	v_add_f32_e32 v183, s100, v183
	v_add_f32_e32 v183, s101, v183
	v_fmamk_f32 v183, v183, 0x3a800000, v182
	v_cmp_gt_f32_e32 vcc, 0x800000, v183
	v_mul_f32_e32 v181, 0x4b800000, v183
	s_nop 1
	v_cndmask_b32_e32 v183, v183, v181, vcc
	v_rsq_f32_e32 v183, v183
	s_nop 0
	v_mul_f32_e32 v181, 0x45800000, v183
	v_cndmask_b32_e32 v184, v183, v181, vcc
	v_mov_b32_e32 v185, v184
	v_cvt_pk_bf16_f32 v48, v144, v145
	v_cvt_pk_bf16_f32 v49, v146, v147
	v_cvt_pk_bf16_f32 v50, v148, v149
	v_cvt_pk_bf16_f32 v51, v150, v151
	v_cvt_pk_bf16_f32 v52, v152, v153
	v_cvt_pk_bf16_f32 v53, v154, v155
	v_cvt_pk_bf16_f32 v54, v156, v157
	v_cvt_pk_bf16_f32 v55, v158, v159
	v_add_u32_e32 v181, 0x2400000, v177
	global_store_dwordx4 v181, v[48:51], s[78:79]
	global_store_dwordx4 v181, v[52:55], s[78:79] offset:1024
	v_add_u32_e32 v236, 0x6000, v237
	s_mov_b64 exec, 1
	global_store_dword v236, v184, s[78:79]
	s_mov_b64 exec, -1
	s_waitcnt vmcnt(12)
	v_lshlrev_b32_e32 v144, 16, v64
	v_and_b32_e32 v145, 0xffff0000, v64
	v_lshlrev_b32_e32 v146, 16, v65
	v_and_b32_e32 v147, 0xffff0000, v65
	v_lshlrev_b32_e32 v148, 16, v66
	v_and_b32_e32 v149, 0xffff0000, v66
	v_lshlrev_b32_e32 v150, 16, v67
	v_and_b32_e32 v151, 0xffff0000, v67
	v_lshlrev_b32_e32 v152, 16, v68
	v_and_b32_e32 v153, 0xffff0000, v68
	v_lshlrev_b32_e32 v154, 16, v69
	v_and_b32_e32 v155, 0xffff0000, v69
	v_lshlrev_b32_e32 v156, 16, v70
	v_and_b32_e32 v157, 0xffff0000, v70
	v_lshlrev_b32_e32 v158, 16, v71
	v_and_b32_e32 v159, 0xffff0000, v71
	v_lshlrev_b32_e32 v160, 16, v72
	v_and_b32_e32 v161, 0xffff0000, v72
	v_lshlrev_b32_e32 v162, 16, v73
	v_and_b32_e32 v163, 0xffff0000, v73
	v_lshlrev_b32_e32 v164, 16, v74
	v_and_b32_e32 v165, 0xffff0000, v74
	v_lshlrev_b32_e32 v166, 16, v75
	v_and_b32_e32 v167, 0xffff0000, v75
	v_lshlrev_b32_e32 v168, 16, v76
	v_and_b32_e32 v169, 0xffff0000, v76
	v_lshlrev_b32_e32 v170, 16, v77
	v_and_b32_e32 v171, 0xffff0000, v77
	v_lshlrev_b32_e32 v172, 16, v78
	v_and_b32_e32 v173, 0xffff0000, v78
	v_lshlrev_b32_e32 v174, 16, v79
	v_and_b32_e32 v175, 0xffff0000, v79
	v_pk_mul_f32 v[252:253], v[160:161], v[160:161]
	v_pk_mul_f32 v[254:255], v[162:163], v[162:163]
	v_pk_fma_f32 v[252:253], v[164:165], v[164:165], v[252:253]
	v_pk_fma_f32 v[254:255], v[166:167], v[166:167], v[254:255]
	v_pk_fma_f32 v[252:253], v[168:169], v[168:169], v[252:253]
	v_pk_fma_f32 v[254:255], v[170:171], v[170:171], v[254:255]
	v_pk_fma_f32 v[252:253], v[172:173], v[172:173], v[252:253]
	v_pk_fma_f32 v[254:255], v[174:175], v[174:175], v[254:255]
	v_pk_add_f32 v[252:253], v[252:253], v[254:255]
	s_nop 0
	v_add_f32_e32 v183, v252, v253
	s_nop 1
	v_add_f32_dpp v183, v183, v183 quad_perm:[1,0,3,2] row_mask:0xf bank_mask:0xf bound_ctrl:1
	s_nop 1
	v_add_f32_dpp v183, v183, v183 quad_perm:[2,3,0,1] row_mask:0xf bank_mask:0xf bound_ctrl:1
	s_nop 1
	v_add_f32_dpp v183, v183, v183 row_half_mirror row_mask:0xf bank_mask:0xf bound_ctrl:1
	s_nop 1
	v_add_f32_dpp v183, v183, v183 row_mirror row_mask:0xf bank_mask:0xf bound_ctrl:1
	s_nop 1
	v_readlane_b32 s98, v183, 0
	v_readlane_b32 s99, v183, 16
	v_readlane_b32 s100, v183, 32
	v_readlane_b32 s101, v183, 48
	s_nop 1
	v_mov_b32_e32 v183, s98
	v_add_f32_e32 v183, s99, v183
	v_add_f32_e32 v183, s100, v183
	v_add_f32_e32 v183, s101, v183
	v_fmamk_f32 v183, v183, 0x3a800000, v182
	v_cmp_gt_f32_e32 vcc, 0x800000, v183
	v_mul_f32_e32 v181, 0x4b800000, v183
	s_nop 1
	v_cndmask_b32_e32 v183, v183, v181, vcc
	v_rsq_f32_e32 v183, v183
	s_nop 0
	v_mul_f32_e32 v181, 0x45800000, v183
	v_cndmask_b32_e32 v184, v183, v181, vcc
	v_mov_b32_e32 v185, v184
	v_pk_mul_f32 v[160:161], v[160:161], v[184:185]
	v_pk_mul_f32 v[162:163], v[162:163], v[184:185]
	v_pk_mul_f32 v[164:165], v[164:165], v[184:185]
	v_pk_mul_f32 v[166:167], v[166:167], v[184:185]
	v_pk_mul_f32 v[168:169], v[168:169], v[184:185]
	v_pk_mul_f32 v[170:171], v[170:171], v[184:185]
	v_pk_mul_f32 v[172:173], v[172:173], v[184:185]
	v_pk_mul_f32 v[174:175], v[174:175], v[184:185]
	v_pk_fma_f32 v[144:145], v[160:161], v[128:129], v[144:145]
	v_pk_fma_f32 v[146:147], v[162:163], v[130:131], v[146:147]
	v_pk_fma_f32 v[148:149], v[164:165], v[132:133], v[148:149]
	v_pk_fma_f32 v[150:151], v[166:167], v[134:135], v[150:151]
	v_pk_fma_f32 v[152:153], v[168:169], v[136:137], v[152:153]
	v_pk_fma_f32 v[154:155], v[170:171], v[138:139], v[154:155]
	v_pk_fma_f32 v[156:157], v[172:173], v[140:141], v[156:157]
	v_pk_fma_f32 v[158:159], v[174:175], v[142:143], v[158:159]
	v_pk_mul_f32 v[252:253], v[144:145], v[144:145]
	v_pk_mul_f32 v[254:255], v[146:147], v[146:147]
	v_pk_fma_f32 v[252:253], v[148:149], v[148:149], v[252:253]
	v_pk_fma_f32 v[254:255], v[150:151], v[150:151], v[254:255]
	v_pk_fma_f32 v[252:253], v[152:153], v[152:153], v[252:253]
	v_pk_fma_f32 v[254:255], v[154:155], v[154:155], v[254:255]
	v_pk_fma_f32 v[252:253], v[156:157], v[156:157], v[252:253]
	v_pk_fma_f32 v[254:255], v[158:159], v[158:159], v[254:255]
	v_pk_add_f32 v[252:253], v[252:253], v[254:255]
	s_nop 0
	v_add_f32_e32 v183, v252, v253
	s_nop 1
	v_add_f32_dpp v183, v183, v183 quad_perm:[1,0,3,2] row_mask:0xf bank_mask:0xf bound_ctrl:1
	s_nop 1
	v_add_f32_dpp v183, v183, v183 quad_perm:[2,3,0,1] row_mask:0xf bank_mask:0xf bound_ctrl:1
	s_nop 1
	v_add_f32_dpp v183, v183, v183 row_half_mirror row_mask:0xf bank_mask:0xf bound_ctrl:1
	s_nop 1
	v_add_f32_dpp v183, v183, v183 row_mirror row_mask:0xf bank_mask:0xf bound_ctrl:1
	s_nop 1
	v_readlane_b32 s98, v183, 0
	v_readlane_b32 s99, v183, 16
	v_readlane_b32 s100, v183, 32
	v_readlane_b32 s101, v183, 48
	s_nop 1
	v_mov_b32_e32 v183, s98
	v_add_f32_e32 v183, s99, v183
	v_add_f32_e32 v183, s100, v183
	v_add_f32_e32 v183, s101, v183
	v_fmamk_f32 v183, v183, 0x3a800000, v182
	v_cmp_gt_f32_e32 vcc, 0x800000, v183
	v_mul_f32_e32 v181, 0x4b800000, v183
	s_nop 1
	v_cndmask_b32_e32 v183, v183, v181, vcc
	v_rsq_f32_e32 v183, v183
	s_nop 0
	v_mul_f32_e32 v181, 0x45800000, v183
	v_cndmask_b32_e32 v184, v183, v181, vcc
	v_mov_b32_e32 v185, v184
	v_cvt_pk_bf16_f32 v64, v144, v145
	v_cvt_pk_bf16_f32 v65, v146, v147
	v_cvt_pk_bf16_f32 v66, v148, v149
	v_cvt_pk_bf16_f32 v67, v150, v151
	v_cvt_pk_bf16_f32 v68, v152, v153
	v_cvt_pk_bf16_f32 v69, v154, v155
	v_cvt_pk_bf16_f32 v70, v156, v157
	v_cvt_pk_bf16_f32 v71, v158, v159
	v_add_u32_e32 v181, 0x2800000, v177
	global_store_dwordx4 v181, v[64:67], s[78:79]
	global_store_dwordx4 v181, v[68:71], s[78:79] offset:1024
	v_add_u32_e32 v236, 0x8000, v237
	s_mov_b64 exec, 1
	global_store_dword v236, v184, s[78:79]
	s_mov_b64 exec, -1
	s_waitcnt vmcnt(8)
	v_lshlrev_b32_e32 v144, 16, v80
	v_and_b32_e32 v145, 0xffff0000, v80
	v_lshlrev_b32_e32 v146, 16, v81
	v_and_b32_e32 v147, 0xffff0000, v81
	v_lshlrev_b32_e32 v148, 16, v82
	v_and_b32_e32 v149, 0xffff0000, v82
	v_lshlrev_b32_e32 v150, 16, v83
	v_and_b32_e32 v151, 0xffff0000, v83
	v_lshlrev_b32_e32 v152, 16, v84
	v_and_b32_e32 v153, 0xffff0000, v84
	v_lshlrev_b32_e32 v154, 16, v85
	v_and_b32_e32 v155, 0xffff0000, v85
	v_lshlrev_b32_e32 v156, 16, v86
	v_and_b32_e32 v157, 0xffff0000, v86
	v_lshlrev_b32_e32 v158, 16, v87
	v_and_b32_e32 v159, 0xffff0000, v87
	v_lshlrev_b32_e32 v160, 16, v88
	v_and_b32_e32 v161, 0xffff0000, v88
	v_lshlrev_b32_e32 v162, 16, v89
	v_and_b32_e32 v163, 0xffff0000, v89
	v_lshlrev_b32_e32 v164, 16, v90
	v_and_b32_e32 v165, 0xffff0000, v90
	v_lshlrev_b32_e32 v166, 16, v91
	v_and_b32_e32 v167, 0xffff0000, v91
	v_lshlrev_b32_e32 v168, 16, v92
	v_and_b32_e32 v169, 0xffff0000, v92
	v_lshlrev_b32_e32 v170, 16, v93
	v_and_b32_e32 v171, 0xffff0000, v93
	v_lshlrev_b32_e32 v172, 16, v94
	v_and_b32_e32 v173, 0xffff0000, v94
	v_lshlrev_b32_e32 v174, 16, v95
	v_and_b32_e32 v175, 0xffff0000, v95
	v_pk_mul_f32 v[252:253], v[160:161], v[160:161]
	v_pk_mul_f32 v[254:255], v[162:163], v[162:163]
	v_pk_fma_f32 v[252:253], v[164:165], v[164:165], v[252:253]
	v_pk_fma_f32 v[254:255], v[166:167], v[166:167], v[254:255]
	v_pk_fma_f32 v[252:253], v[168:169], v[168:169], v[252:253]
	v_pk_fma_f32 v[254:255], v[170:171], v[170:171], v[254:255]
	v_pk_fma_f32 v[252:253], v[172:173], v[172:173], v[252:253]
	v_pk_fma_f32 v[254:255], v[174:175], v[174:175], v[254:255]
	v_pk_add_f32 v[252:253], v[252:253], v[254:255]
	s_nop 0
	v_add_f32_e32 v183, v252, v253
	s_nop 1
	v_add_f32_dpp v183, v183, v183 quad_perm:[1,0,3,2] row_mask:0xf bank_mask:0xf bound_ctrl:1
	s_nop 1
	v_add_f32_dpp v183, v183, v183 quad_perm:[2,3,0,1] row_mask:0xf bank_mask:0xf bound_ctrl:1
	s_nop 1
	v_add_f32_dpp v183, v183, v183 row_half_mirror row_mask:0xf bank_mask:0xf bound_ctrl:1
	s_nop 1
	v_add_f32_dpp v183, v183, v183 row_mirror row_mask:0xf bank_mask:0xf bound_ctrl:1
	s_nop 1
	v_readlane_b32 s98, v183, 0
	v_readlane_b32 s99, v183, 16
	v_readlane_b32 s100, v183, 32
	v_readlane_b32 s101, v183, 48
	s_nop 1
	v_mov_b32_e32 v183, s98
	v_add_f32_e32 v183, s99, v183
	v_add_f32_e32 v183, s100, v183
	v_add_f32_e32 v183, s101, v183
	v_fmamk_f32 v183, v183, 0x3a800000, v182
	v_cmp_gt_f32_e32 vcc, 0x800000, v183
	v_mul_f32_e32 v181, 0x4b800000, v183
	s_nop 1
	v_cndmask_b32_e32 v183, v183, v181, vcc
	v_rsq_f32_e32 v183, v183
	s_nop 0
	v_mul_f32_e32 v181, 0x45800000, v183
	v_cndmask_b32_e32 v184, v183, v181, vcc
	v_mov_b32_e32 v185, v184
	v_pk_mul_f32 v[160:161], v[160:161], v[184:185]
	v_pk_mul_f32 v[162:163], v[162:163], v[184:185]
	v_pk_mul_f32 v[164:165], v[164:165], v[184:185]
	v_pk_mul_f32 v[166:167], v[166:167], v[184:185]
	v_pk_mul_f32 v[168:169], v[168:169], v[184:185]
	v_pk_mul_f32 v[170:171], v[170:171], v[184:185]
	v_pk_mul_f32 v[172:173], v[172:173], v[184:185]
	v_pk_mul_f32 v[174:175], v[174:175], v[184:185]
	v_pk_fma_f32 v[144:145], v[160:161], v[128:129], v[144:145]
	v_pk_fma_f32 v[146:147], v[162:163], v[130:131], v[146:147]
	v_pk_fma_f32 v[148:149], v[164:165], v[132:133], v[148:149]
	v_pk_fma_f32 v[150:151], v[166:167], v[134:135], v[150:151]
	v_pk_fma_f32 v[152:153], v[168:169], v[136:137], v[152:153]
	v_pk_fma_f32 v[154:155], v[170:171], v[138:139], v[154:155]
	v_pk_fma_f32 v[156:157], v[172:173], v[140:141], v[156:157]
	v_pk_fma_f32 v[158:159], v[174:175], v[142:143], v[158:159]
	v_pk_mul_f32 v[252:253], v[144:145], v[144:145]
	v_pk_mul_f32 v[254:255], v[146:147], v[146:147]
	v_pk_fma_f32 v[252:253], v[148:149], v[148:149], v[252:253]
	v_pk_fma_f32 v[254:255], v[150:151], v[150:151], v[254:255]
	v_pk_fma_f32 v[252:253], v[152:153], v[152:153], v[252:253]
	v_pk_fma_f32 v[254:255], v[154:155], v[154:155], v[254:255]
	v_pk_fma_f32 v[252:253], v[156:157], v[156:157], v[252:253]
	v_pk_fma_f32 v[254:255], v[158:159], v[158:159], v[254:255]
	v_pk_add_f32 v[252:253], v[252:253], v[254:255]
	s_nop 0
	v_add_f32_e32 v183, v252, v253
	s_nop 1
	v_add_f32_dpp v183, v183, v183 quad_perm:[1,0,3,2] row_mask:0xf bank_mask:0xf bound_ctrl:1
	s_nop 1
	v_add_f32_dpp v183, v183, v183 quad_perm:[2,3,0,1] row_mask:0xf bank_mask:0xf bound_ctrl:1
	s_nop 1
	v_add_f32_dpp v183, v183, v183 row_half_mirror row_mask:0xf bank_mask:0xf bound_ctrl:1
	s_nop 1
	v_add_f32_dpp v183, v183, v183 row_mirror row_mask:0xf bank_mask:0xf bound_ctrl:1
	s_nop 1
	v_readlane_b32 s98, v183, 0
	v_readlane_b32 s99, v183, 16
	v_readlane_b32 s100, v183, 32
	v_readlane_b32 s101, v183, 48
	s_nop 1
	v_mov_b32_e32 v183, s98
	v_add_f32_e32 v183, s99, v183
	v_add_f32_e32 v183, s100, v183
	v_add_f32_e32 v183, s101, v183
	v_fmamk_f32 v183, v183, 0x3a800000, v182
	v_cmp_gt_f32_e32 vcc, 0x800000, v183
	v_mul_f32_e32 v181, 0x4b800000, v183
	s_nop 1
	v_cndmask_b32_e32 v183, v183, v181, vcc
	v_rsq_f32_e32 v183, v183
	s_nop 0
	v_mul_f32_e32 v181, 0x45800000, v183
	v_cndmask_b32_e32 v184, v183, v181, vcc
	v_mov_b32_e32 v185, v184
	v_cvt_pk_bf16_f32 v80, v144, v145
	v_cvt_pk_bf16_f32 v81, v146, v147
	v_cvt_pk_bf16_f32 v82, v148, v149
	v_cvt_pk_bf16_f32 v83, v150, v151
	v_cvt_pk_bf16_f32 v84, v152, v153
	v_cvt_pk_bf16_f32 v85, v154, v155
	v_cvt_pk_bf16_f32 v86, v156, v157
	v_cvt_pk_bf16_f32 v87, v158, v159
	v_add_u32_e32 v181, 0x2c00000, v177
	global_store_dwordx4 v181, v[80:83], s[78:79]
	global_store_dwordx4 v181, v[84:87], s[78:79] offset:1024
	v_add_u32_e32 v236, 0xa000, v237
	s_mov_b64 exec, 1
	global_store_dword v236, v184, s[78:79]
	s_mov_b64 exec, -1
	s_waitcnt vmcnt(4)
	v_lshlrev_b32_e32 v144, 16, v96
	v_and_b32_e32 v145, 0xffff0000, v96
	v_lshlrev_b32_e32 v146, 16, v97
	v_and_b32_e32 v147, 0xffff0000, v97
	v_lshlrev_b32_e32 v148, 16, v98
	v_and_b32_e32 v149, 0xffff0000, v98
	v_lshlrev_b32_e32 v150, 16, v99
	v_and_b32_e32 v151, 0xffff0000, v99
	v_lshlrev_b32_e32 v152, 16, v100
	v_and_b32_e32 v153, 0xffff0000, v100
	v_lshlrev_b32_e32 v154, 16, v101
	v_and_b32_e32 v155, 0xffff0000, v101
	v_lshlrev_b32_e32 v156, 16, v102
	v_and_b32_e32 v157, 0xffff0000, v102
	v_lshlrev_b32_e32 v158, 16, v103
	v_and_b32_e32 v159, 0xffff0000, v103
	v_lshlrev_b32_e32 v160, 16, v104
	v_and_b32_e32 v161, 0xffff0000, v104
	v_lshlrev_b32_e32 v162, 16, v105
	v_and_b32_e32 v163, 0xffff0000, v105
	v_lshlrev_b32_e32 v164, 16, v106
	v_and_b32_e32 v165, 0xffff0000, v106
	v_lshlrev_b32_e32 v166, 16, v107
	v_and_b32_e32 v167, 0xffff0000, v107
	v_lshlrev_b32_e32 v168, 16, v108
	v_and_b32_e32 v169, 0xffff0000, v108
	v_lshlrev_b32_e32 v170, 16, v109
	v_and_b32_e32 v171, 0xffff0000, v109
	v_lshlrev_b32_e32 v172, 16, v110
	v_and_b32_e32 v173, 0xffff0000, v110
	v_lshlrev_b32_e32 v174, 16, v111
	v_and_b32_e32 v175, 0xffff0000, v111
	v_pk_mul_f32 v[252:253], v[160:161], v[160:161]
	v_pk_mul_f32 v[254:255], v[162:163], v[162:163]
	v_pk_fma_f32 v[252:253], v[164:165], v[164:165], v[252:253]
	v_pk_fma_f32 v[254:255], v[166:167], v[166:167], v[254:255]
	v_pk_fma_f32 v[252:253], v[168:169], v[168:169], v[252:253]
	v_pk_fma_f32 v[254:255], v[170:171], v[170:171], v[254:255]
	v_pk_fma_f32 v[252:253], v[172:173], v[172:173], v[252:253]
	v_pk_fma_f32 v[254:255], v[174:175], v[174:175], v[254:255]
	v_pk_add_f32 v[252:253], v[252:253], v[254:255]
	s_nop 0
	v_add_f32_e32 v183, v252, v253
	s_nop 1
	v_add_f32_dpp v183, v183, v183 quad_perm:[1,0,3,2] row_mask:0xf bank_mask:0xf bound_ctrl:1
	s_nop 1
	v_add_f32_dpp v183, v183, v183 quad_perm:[2,3,0,1] row_mask:0xf bank_mask:0xf bound_ctrl:1
	s_nop 1
	v_add_f32_dpp v183, v183, v183 row_half_mirror row_mask:0xf bank_mask:0xf bound_ctrl:1
	s_nop 1
	v_add_f32_dpp v183, v183, v183 row_mirror row_mask:0xf bank_mask:0xf bound_ctrl:1
	s_nop 1
	v_readlane_b32 s98, v183, 0
	v_readlane_b32 s99, v183, 16
	v_readlane_b32 s100, v183, 32
	v_readlane_b32 s101, v183, 48
	s_nop 1
	v_mov_b32_e32 v183, s98
	v_add_f32_e32 v183, s99, v183
	v_add_f32_e32 v183, s100, v183
	v_add_f32_e32 v183, s101, v183
	v_fmamk_f32 v183, v183, 0x3a800000, v182
	v_cmp_gt_f32_e32 vcc, 0x800000, v183
	v_mul_f32_e32 v181, 0x4b800000, v183
	s_nop 1
	v_cndmask_b32_e32 v183, v183, v181, vcc
	v_rsq_f32_e32 v183, v183
	s_nop 0
	v_mul_f32_e32 v181, 0x45800000, v183
	v_cndmask_b32_e32 v184, v183, v181, vcc
	v_mov_b32_e32 v185, v184
	v_pk_mul_f32 v[160:161], v[160:161], v[184:185]
	v_pk_mul_f32 v[162:163], v[162:163], v[184:185]
	v_pk_mul_f32 v[164:165], v[164:165], v[184:185]
	v_pk_mul_f32 v[166:167], v[166:167], v[184:185]
	v_pk_mul_f32 v[168:169], v[168:169], v[184:185]
	v_pk_mul_f32 v[170:171], v[170:171], v[184:185]
	v_pk_mul_f32 v[172:173], v[172:173], v[184:185]
	v_pk_mul_f32 v[174:175], v[174:175], v[184:185]
	v_pk_fma_f32 v[144:145], v[160:161], v[128:129], v[144:145]
	v_pk_fma_f32 v[146:147], v[162:163], v[130:131], v[146:147]
	v_pk_fma_f32 v[148:149], v[164:165], v[132:133], v[148:149]
	v_pk_fma_f32 v[150:151], v[166:167], v[134:135], v[150:151]
	v_pk_fma_f32 v[152:153], v[168:169], v[136:137], v[152:153]
	v_pk_fma_f32 v[154:155], v[170:171], v[138:139], v[154:155]
	v_pk_fma_f32 v[156:157], v[172:173], v[140:141], v[156:157]
	v_pk_fma_f32 v[158:159], v[174:175], v[142:143], v[158:159]
	v_pk_mul_f32 v[252:253], v[144:145], v[144:145]
	v_pk_mul_f32 v[254:255], v[146:147], v[146:147]
	v_pk_fma_f32 v[252:253], v[148:149], v[148:149], v[252:253]
	v_pk_fma_f32 v[254:255], v[150:151], v[150:151], v[254:255]
	v_pk_fma_f32 v[252:253], v[152:153], v[152:153], v[252:253]
	v_pk_fma_f32 v[254:255], v[154:155], v[154:155], v[254:255]
	v_pk_fma_f32 v[252:253], v[156:157], v[156:157], v[252:253]
	v_pk_fma_f32 v[254:255], v[158:159], v[158:159], v[254:255]
	v_pk_add_f32 v[252:253], v[252:253], v[254:255]
	s_nop 0
	v_add_f32_e32 v183, v252, v253
	s_nop 1
	v_add_f32_dpp v183, v183, v183 quad_perm:[1,0,3,2] row_mask:0xf bank_mask:0xf bound_ctrl:1
	s_nop 1
	v_add_f32_dpp v183, v183, v183 quad_perm:[2,3,0,1] row_mask:0xf bank_mask:0xf bound_ctrl:1
	s_nop 1
	v_add_f32_dpp v183, v183, v183 row_half_mirror row_mask:0xf bank_mask:0xf bound_ctrl:1
	s_nop 1
	v_add_f32_dpp v183, v183, v183 row_mirror row_mask:0xf bank_mask:0xf bound_ctrl:1
	s_nop 1
	v_readlane_b32 s98, v183, 0
	v_readlane_b32 s99, v183, 16
	v_readlane_b32 s100, v183, 32
	v_readlane_b32 s101, v183, 48
	s_nop 1
	v_mov_b32_e32 v183, s98
	v_add_f32_e32 v183, s99, v183
	v_add_f32_e32 v183, s100, v183
	v_add_f32_e32 v183, s101, v183
	v_fmamk_f32 v183, v183, 0x3a800000, v182
	v_cmp_gt_f32_e32 vcc, 0x800000, v183
	v_mul_f32_e32 v181, 0x4b800000, v183
	s_nop 1
	v_cndmask_b32_e32 v183, v183, v181, vcc
	v_rsq_f32_e32 v183, v183
	s_nop 0
	v_mul_f32_e32 v181, 0x45800000, v183
	v_cndmask_b32_e32 v184, v183, v181, vcc
	v_mov_b32_e32 v185, v184
	v_cvt_pk_bf16_f32 v96, v144, v145
	v_cvt_pk_bf16_f32 v97, v146, v147
	v_cvt_pk_bf16_f32 v98, v148, v149
	v_cvt_pk_bf16_f32 v99, v150, v151
	v_cvt_pk_bf16_f32 v100, v152, v153
	v_cvt_pk_bf16_f32 v101, v154, v155
	v_cvt_pk_bf16_f32 v102, v156, v157
	v_cvt_pk_bf16_f32 v103, v158, v159
	v_add_u32_e32 v181, 0x3000000, v177
	global_store_dwordx4 v181, v[96:99], s[78:79]
	global_store_dwordx4 v181, v[100:103], s[78:79] offset:1024
	v_add_u32_e32 v236, 0xc000, v237
	s_mov_b64 exec, 1
	global_store_dword v236, v184, s[78:79]
	s_mov_b64 exec, -1
	s_waitcnt vmcnt(0)
	v_lshlrev_b32_e32 v144, 16, v112
	v_and_b32_e32 v145, 0xffff0000, v112
	v_lshlrev_b32_e32 v146, 16, v113
	v_and_b32_e32 v147, 0xffff0000, v113
	v_lshlrev_b32_e32 v148, 16, v114
	v_and_b32_e32 v149, 0xffff0000, v114
	v_lshlrev_b32_e32 v150, 16, v115
	v_and_b32_e32 v151, 0xffff0000, v115
	v_lshlrev_b32_e32 v152, 16, v116
	v_and_b32_e32 v153, 0xffff0000, v116
	v_lshlrev_b32_e32 v154, 16, v117
	v_and_b32_e32 v155, 0xffff0000, v117
	v_lshlrev_b32_e32 v156, 16, v118
	v_and_b32_e32 v157, 0xffff0000, v118
	v_lshlrev_b32_e32 v158, 16, v119
	v_and_b32_e32 v159, 0xffff0000, v119
	v_lshlrev_b32_e32 v160, 16, v120
	v_and_b32_e32 v161, 0xffff0000, v120
	v_lshlrev_b32_e32 v162, 16, v121
	v_and_b32_e32 v163, 0xffff0000, v121
	v_lshlrev_b32_e32 v164, 16, v122
	v_and_b32_e32 v165, 0xffff0000, v122
	v_lshlrev_b32_e32 v166, 16, v123
	v_and_b32_e32 v167, 0xffff0000, v123
	v_lshlrev_b32_e32 v168, 16, v124
	v_and_b32_e32 v169, 0xffff0000, v124
	v_lshlrev_b32_e32 v170, 16, v125
	v_and_b32_e32 v171, 0xffff0000, v125
	v_lshlrev_b32_e32 v172, 16, v126
	v_and_b32_e32 v173, 0xffff0000, v126
	v_lshlrev_b32_e32 v174, 16, v127
	v_and_b32_e32 v175, 0xffff0000, v127
	v_pk_mul_f32 v[252:253], v[160:161], v[160:161]
	v_pk_mul_f32 v[254:255], v[162:163], v[162:163]
	v_pk_fma_f32 v[252:253], v[164:165], v[164:165], v[252:253]
	v_pk_fma_f32 v[254:255], v[166:167], v[166:167], v[254:255]
	v_pk_fma_f32 v[252:253], v[168:169], v[168:169], v[252:253]
	v_pk_fma_f32 v[254:255], v[170:171], v[170:171], v[254:255]
	v_pk_fma_f32 v[252:253], v[172:173], v[172:173], v[252:253]
	v_pk_fma_f32 v[254:255], v[174:175], v[174:175], v[254:255]
	v_pk_add_f32 v[252:253], v[252:253], v[254:255]
	s_nop 0
	v_add_f32_e32 v183, v252, v253
	s_nop 1
	v_add_f32_dpp v183, v183, v183 quad_perm:[1,0,3,2] row_mask:0xf bank_mask:0xf bound_ctrl:1
	s_nop 1
	v_add_f32_dpp v183, v183, v183 quad_perm:[2,3,0,1] row_mask:0xf bank_mask:0xf bound_ctrl:1
	s_nop 1
	v_add_f32_dpp v183, v183, v183 row_half_mirror row_mask:0xf bank_mask:0xf bound_ctrl:1
	s_nop 1
	v_add_f32_dpp v183, v183, v183 row_mirror row_mask:0xf bank_mask:0xf bound_ctrl:1
	s_nop 1
	v_readlane_b32 s98, v183, 0
	v_readlane_b32 s99, v183, 16
	v_readlane_b32 s100, v183, 32
	v_readlane_b32 s101, v183, 48
	s_nop 1
	v_mov_b32_e32 v183, s98
	v_add_f32_e32 v183, s99, v183
	v_add_f32_e32 v183, s100, v183
	v_add_f32_e32 v183, s101, v183
	v_fmamk_f32 v183, v183, 0x3a800000, v182
	v_cmp_gt_f32_e32 vcc, 0x800000, v183
	v_mul_f32_e32 v181, 0x4b800000, v183
	s_nop 1
	v_cndmask_b32_e32 v183, v183, v181, vcc
	v_rsq_f32_e32 v183, v183
	s_nop 0
	v_mul_f32_e32 v181, 0x45800000, v183
	v_cndmask_b32_e32 v184, v183, v181, vcc
	v_mov_b32_e32 v185, v184
	v_pk_mul_f32 v[160:161], v[160:161], v[184:185]
	v_pk_mul_f32 v[162:163], v[162:163], v[184:185]
	v_pk_mul_f32 v[164:165], v[164:165], v[184:185]
	v_pk_mul_f32 v[166:167], v[166:167], v[184:185]
	v_pk_mul_f32 v[168:169], v[168:169], v[184:185]
	v_pk_mul_f32 v[170:171], v[170:171], v[184:185]
	v_pk_mul_f32 v[172:173], v[172:173], v[184:185]
	v_pk_mul_f32 v[174:175], v[174:175], v[184:185]
	v_pk_fma_f32 v[144:145], v[160:161], v[128:129], v[144:145]
	v_pk_fma_f32 v[146:147], v[162:163], v[130:131], v[146:147]
	v_pk_fma_f32 v[148:149], v[164:165], v[132:133], v[148:149]
	v_pk_fma_f32 v[150:151], v[166:167], v[134:135], v[150:151]
	v_pk_fma_f32 v[152:153], v[168:169], v[136:137], v[152:153]
	v_pk_fma_f32 v[154:155], v[170:171], v[138:139], v[154:155]
	v_pk_fma_f32 v[156:157], v[172:173], v[140:141], v[156:157]
	v_pk_fma_f32 v[158:159], v[174:175], v[142:143], v[158:159]
	v_pk_mul_f32 v[252:253], v[144:145], v[144:145]
	v_pk_mul_f32 v[254:255], v[146:147], v[146:147]
	v_pk_fma_f32 v[252:253], v[148:149], v[148:149], v[252:253]
	v_pk_fma_f32 v[254:255], v[150:151], v[150:151], v[254:255]
	v_pk_fma_f32 v[252:253], v[152:153], v[152:153], v[252:253]
	v_pk_fma_f32 v[254:255], v[154:155], v[154:155], v[254:255]
	v_pk_fma_f32 v[252:253], v[156:157], v[156:157], v[252:253]
	v_pk_fma_f32 v[254:255], v[158:159], v[158:159], v[254:255]
	v_pk_add_f32 v[252:253], v[252:253], v[254:255]
	s_nop 0
	v_add_f32_e32 v183, v252, v253
	s_nop 1
	v_add_f32_dpp v183, v183, v183 quad_perm:[1,0,3,2] row_mask:0xf bank_mask:0xf bound_ctrl:1
	s_nop 1
	v_add_f32_dpp v183, v183, v183 quad_perm:[2,3,0,1] row_mask:0xf bank_mask:0xf bound_ctrl:1
	s_nop 1
	v_add_f32_dpp v183, v183, v183 row_half_mirror row_mask:0xf bank_mask:0xf bound_ctrl:1
	s_nop 1
	v_add_f32_dpp v183, v183, v183 row_mirror row_mask:0xf bank_mask:0xf bound_ctrl:1
	s_nop 1
	v_readlane_b32 s98, v183, 0
	v_readlane_b32 s99, v183, 16
	v_readlane_b32 s100, v183, 32
	v_readlane_b32 s101, v183, 48
	s_nop 1
	v_mov_b32_e32 v183, s98
	v_add_f32_e32 v183, s99, v183
	v_add_f32_e32 v183, s100, v183
	v_add_f32_e32 v183, s101, v183
	v_fmamk_f32 v183, v183, 0x3a800000, v182
	v_cmp_gt_f32_e32 vcc, 0x800000, v183
	v_mul_f32_e32 v181, 0x4b800000, v183
	s_nop 1
	v_cndmask_b32_e32 v183, v183, v181, vcc
	v_rsq_f32_e32 v183, v183
	s_nop 0
	v_mul_f32_e32 v181, 0x45800000, v183
	v_cndmask_b32_e32 v184, v183, v181, vcc
	v_mov_b32_e32 v185, v184
	v_cvt_pk_bf16_f32 v112, v144, v145
	v_cvt_pk_bf16_f32 v113, v146, v147
	v_cvt_pk_bf16_f32 v114, v148, v149
	v_cvt_pk_bf16_f32 v115, v150, v151
	v_cvt_pk_bf16_f32 v116, v152, v153
	v_cvt_pk_bf16_f32 v117, v154, v155
	v_cvt_pk_bf16_f32 v118, v156, v157
	v_cvt_pk_bf16_f32 v119, v158, v159
	v_add_u32_e32 v181, 0x3400000, v177
	global_store_dwordx4 v181, v[112:115], s[78:79]
	global_store_dwordx4 v181, v[116:119], s[78:79] offset:1024
	v_add_u32_e32 v236, 0xe000, v237
	s_mov_b64 exec, 1
	global_store_dword v236, v184, s[78:79]
	s_mov_b64 exec, -1
	v_readfirstlane_b32 s98, v179
	s_nop 3
	s_cmp_ge_u32 s98, 512
	s_cbranch_scc1 .Lmyxupd_done_1
	v_add_u32_e32 v181, 0x3800000, v177
	global_load_dwordx4 v[0:3], v181, s[78:79]
	global_load_dwordx4 v[4:7], v181, s[78:79] offset:1024
	v_lshl_add_u32 v183, v179, 12, v180
	v_add_u32_e32 v183, 0xbf00000, v183
	v_add_u32_e32 v181, 0x0, v183
	global_load_dwordx4 v[8:11], v181, s[78:79]
	global_load_dwordx4 v[12:15], v181, s[78:79] offset:16
	global_load_dwordx4 v[16:19], v181, s[78:79] offset:2048
	global_load_dwordx4 v[20:23], v181, s[78:79] offset:2064
	v_add_u32_e32 v181, 0x200000, v183
	global_load_dwordx4 v[24:27], v181, s[78:79]
	global_load_dwordx4 v[28:31], v181, s[78:79] offset:16
	global_load_dwordx4 v[32:35], v181, s[78:79] offset:2048
	global_load_dwordx4 v[36:39], v181, s[78:79] offset:2064
	v_add_u32_e32 v181, 0x400000, v183
	global_load_dwordx4 v[40:43], v181, s[78:79]
	global_load_dwordx4 v[44:47], v181, s[78:79] offset:16
	global_load_dwordx4 v[48:51], v181, s[78:79] offset:2048
	global_load_dwordx4 v[52:55], v181, s[78:79] offset:2064
	v_add_u32_e32 v181, 0x600000, v183
	global_load_dwordx4 v[56:59], v181, s[78:79]
	global_load_dwordx4 v[60:63], v181, s[78:79] offset:16
	global_load_dwordx4 v[64:67], v181, s[78:79] offset:2048
	global_load_dwordx4 v[68:71], v181, s[78:79] offset:2064
	v_add_u32_e32 v181, 0x800000, v183
	global_load_dwordx4 v[72:75], v181, s[78:79]
	global_load_dwordx4 v[76:79], v181, s[78:79] offset:16
	global_load_dwordx4 v[80:83], v181, s[78:79] offset:2048
	global_load_dwordx4 v[84:87], v181, s[78:79] offset:2064
	v_add_u32_e32 v181, 0xa00000, v183
	global_load_dwordx4 v[88:91], v181, s[78:79]
	global_load_dwordx4 v[92:95], v181, s[78:79] offset:16
	global_load_dwordx4 v[96:99], v181, s[78:79] offset:2048
	global_load_dwordx4 v[100:103], v181, s[78:79] offset:2064
	s_waitcnt vmcnt(20)
	v_pk_add_f32 v[160:161], v[8:9], 0 op_sel_hi:[1,0]
	v_pk_add_f32 v[162:163], v[10:11], 0 op_sel_hi:[1,0]
	v_pk_add_f32 v[164:165], v[12:13], 0 op_sel_hi:[1,0]
	v_pk_add_f32 v[166:167], v[14:15], 0 op_sel_hi:[1,0]
	v_pk_add_f32 v[168:169], v[16:17], 0 op_sel_hi:[1,0]
	v_pk_add_f32 v[170:171], v[18:19], 0 op_sel_hi:[1,0]
	v_pk_add_f32 v[172:173], v[20:21], 0 op_sel_hi:[1,0]
	v_pk_add_f32 v[174:175], v[22:23], 0 op_sel_hi:[1,0]
	s_waitcnt vmcnt(16)
	v_pk_add_f32 v[160:161], v[160:161], v[24:25]
	v_pk_add_f32 v[162:163], v[162:163], v[26:27]
	v_pk_add_f32 v[164:165], v[164:165], v[28:29]
	v_pk_add_f32 v[166:167], v[166:167], v[30:31]
	v_pk_add_f32 v[168:169], v[168:169], v[32:33]
	v_pk_add_f32 v[170:171], v[170:171], v[34:35]
	v_pk_add_f32 v[172:173], v[172:173], v[36:37]
	v_pk_add_f32 v[174:175], v[174:175], v[38:39]
	s_waitcnt vmcnt(12)
	v_pk_add_f32 v[160:161], v[160:161], v[40:41]
	v_pk_add_f32 v[162:163], v[162:163], v[42:43]
	v_pk_add_f32 v[164:165], v[164:165], v[44:45]
	v_pk_add_f32 v[166:167], v[166:167], v[46:47]
	v_pk_add_f32 v[168:169], v[168:169], v[48:49]
	v_pk_add_f32 v[170:171], v[170:171], v[50:51]
	v_pk_add_f32 v[172:173], v[172:173], v[52:53]
	v_pk_add_f32 v[174:175], v[174:175], v[54:55]
	s_waitcnt vmcnt(8)
	v_pk_add_f32 v[160:161], v[160:161], v[56:57]
	v_pk_add_f32 v[162:163], v[162:163], v[58:59]
	v_pk_add_f32 v[164:165], v[164:165], v[60:61]
	v_pk_add_f32 v[166:167], v[166:167], v[62:63]
	v_pk_add_f32 v[168:169], v[168:169], v[64:65]
	v_pk_add_f32 v[170:171], v[170:171], v[66:67]
	v_pk_add_f32 v[172:173], v[172:173], v[68:69]
	v_pk_add_f32 v[174:175], v[174:175], v[70:71]
	s_waitcnt vmcnt(4)
	v_pk_add_f32 v[160:161], v[160:161], v[72:73]
	v_pk_add_f32 v[162:163], v[162:163], v[74:75]
	v_pk_add_f32 v[164:165], v[164:165], v[76:77]
	v_pk_add_f32 v[166:167], v[166:167], v[78:79]
	v_pk_add_f32 v[168:169], v[168:169], v[80:81]
	v_pk_add_f32 v[170:171], v[170:171], v[82:83]
	v_pk_add_f32 v[172:173], v[172:173], v[84:85]
	v_pk_add_f32 v[174:175], v[174:175], v[86:87]
	s_waitcnt vmcnt(0)
	v_pk_add_f32 v[160:161], v[160:161], v[88:89]
	v_pk_add_f32 v[162:163], v[162:163], v[90:91]
	v_pk_add_f32 v[164:165], v[164:165], v[92:93]
	v_pk_add_f32 v[166:167], v[166:167], v[94:95]
	v_pk_add_f32 v[168:169], v[168:169], v[96:97]
	v_pk_add_f32 v[170:171], v[170:171], v[98:99]
	v_pk_add_f32 v[172:173], v[172:173], v[100:101]
	v_pk_add_f32 v[174:175], v[174:175], v[102:103]
	v_lshlrev_b32_e32 v144, 16, v0
	v_and_b32_e32 v145, 0xffff0000, v0
	v_lshlrev_b32_e32 v146, 16, v1
	v_and_b32_e32 v147, 0xffff0000, v1
	v_lshlrev_b32_e32 v148, 16, v2
	v_and_b32_e32 v149, 0xffff0000, v2
	v_lshlrev_b32_e32 v150, 16, v3
	v_and_b32_e32 v151, 0xffff0000, v3
	v_lshlrev_b32_e32 v152, 16, v4
	v_and_b32_e32 v153, 0xffff0000, v4
	v_lshlrev_b32_e32 v154, 16, v5
	v_and_b32_e32 v155, 0xffff0000, v5
	v_lshlrev_b32_e32 v156, 16, v6
	v_and_b32_e32 v157, 0xffff0000, v6
	v_lshlrev_b32_e32 v158, 16, v7
	v_and_b32_e32 v159, 0xffff0000, v7
	v_add_u32_e32 v181, 0xc00000, v183
	global_load_dwordx4 v[8:11], v181, s[78:79]
	global_load_dwordx4 v[12:15], v181, s[78:79] offset:16
	global_load_dwordx4 v[16:19], v181, s[78:79] offset:2048
	global_load_dwordx4 v[20:23], v181, s[78:79] offset:2064
	v_add_u32_e32 v181, 0xe00000, v183
	global_load_dwordx4 v[24:27], v181, s[78:79]
	global_load_dwordx4 v[28:31], v181, s[78:79] offset:16
	global_load_dwordx4 v[32:35], v181, s[78:79] offset:2048
	global_load_dwordx4 v[36:39], v181, s[78:79] offset:2064
	v_add_u32_e32 v181, 0x1000000, v183
	global_load_dwordx4 v[40:43], v181, s[78:79]
	global_load_dwordx4 v[44:47], v181, s[78:79] offset:16
	global_load_dwordx4 v[48:51], v181, s[78:79] offset:2048
	global_load_dwordx4 v[52:55], v181, s[78:79] offset:2064
	v_add_u32_e32 v181, 0x1200000, v183
	global_load_dwordx4 v[56:59], v181, s[78:79]
	global_load_dwordx4 v[60:63], v181, s[78:79] offset:16
	global_load_dwordx4 v[64:67], v181, s[78:79] offset:2048
	global_load_dwordx4 v[68:71], v181, s[78:79] offset:2064
	v_add_u32_e32 v181, 0x1400000, v183
	global_load_dwordx4 v[72:75], v181, s[78:79]
	global_load_dwordx4 v[76:79], v181, s[78:79] offset:16
	global_load_dwordx4 v[80:83], v181, s[78:79] offset:2048
	global_load_dwordx4 v[84:87], v181, s[78:79] offset:2064
	s_waitcnt vmcnt(16)
	v_pk_add_f32 v[160:161], v[160:161], v[8:9]
	v_pk_add_f32 v[162:163], v[162:163], v[10:11]
	v_pk_add_f32 v[164:165], v[164:165], v[12:13]
	v_pk_add_f32 v[166:167], v[166:167], v[14:15]
	v_pk_add_f32 v[168:169], v[168:169], v[16:17]
	v_pk_add_f32 v[170:171], v[170:171], v[18:19]
	v_pk_add_f32 v[172:173], v[172:173], v[20:21]
	v_pk_add_f32 v[174:175], v[174:175], v[22:23]
	s_waitcnt vmcnt(12)
	v_pk_add_f32 v[160:161], v[160:161], v[24:25]
	v_pk_add_f32 v[162:163], v[162:163], v[26:27]
	v_pk_add_f32 v[164:165], v[164:165], v[28:29]
	v_pk_add_f32 v[166:167], v[166:167], v[30:31]
	v_pk_add_f32 v[168:169], v[168:169], v[32:33]
	v_pk_add_f32 v[170:171], v[170:171], v[34:35]
	v_pk_add_f32 v[172:173], v[172:173], v[36:37]
	v_pk_add_f32 v[174:175], v[174:175], v[38:39]
	s_waitcnt vmcnt(8)
	v_pk_add_f32 v[160:161], v[160:161], v[40:41]
	v_pk_add_f32 v[162:163], v[162:163], v[42:43]
	v_pk_add_f32 v[164:165], v[164:165], v[44:45]
	v_pk_add_f32 v[166:167], v[166:167], v[46:47]
	v_pk_add_f32 v[168:169], v[168:169], v[48:49]
	v_pk_add_f32 v[170:171], v[170:171], v[50:51]
	v_pk_add_f32 v[172:173], v[172:173], v[52:53]
	v_pk_add_f32 v[174:175], v[174:175], v[54:55]
	s_waitcnt vmcnt(4)
	v_pk_add_f32 v[160:161], v[160:161], v[56:57]
	v_pk_add_f32 v[162:163], v[162:163], v[58:59]
	v_pk_add_f32 v[164:165], v[164:165], v[60:61]
	v_pk_add_f32 v[166:167], v[166:167], v[62:63]
	v_pk_add_f32 v[168:169], v[168:169], v[64:65]
	v_pk_add_f32 v[170:171], v[170:171], v[66:67]
	v_pk_add_f32 v[172:173], v[172:173], v[68:69]
	v_pk_add_f32 v[174:175], v[174:175], v[70:71]
	s_waitcnt vmcnt(0)
	v_pk_add_f32 v[160:161], v[160:161], v[72:73]
	v_pk_add_f32 v[162:163], v[162:163], v[74:75]
	v_pk_add_f32 v[164:165], v[164:165], v[76:77]
	v_pk_add_f32 v[166:167], v[166:167], v[78:79]
	v_pk_add_f32 v[168:169], v[168:169], v[80:81]
	v_pk_add_f32 v[170:171], v[170:171], v[82:83]
	v_pk_add_f32 v[172:173], v[172:173], v[84:85]
	v_pk_add_f32 v[174:175], v[174:175], v[86:87]
	v_pk_mul_f32 v[252:253], v[160:161], v[160:161]
	v_pk_mul_f32 v[254:255], v[162:163], v[162:163]
	v_pk_fma_f32 v[252:253], v[164:165], v[164:165], v[252:253]
	v_pk_fma_f32 v[254:255], v[166:167], v[166:167], v[254:255]
	v_pk_fma_f32 v[252:253], v[168:169], v[168:169], v[252:253]
	v_pk_fma_f32 v[254:255], v[170:171], v[170:171], v[254:255]
	v_pk_fma_f32 v[252:253], v[172:173], v[172:173], v[252:253]
	v_pk_fma_f32 v[254:255], v[174:175], v[174:175], v[254:255]
	v_pk_add_f32 v[252:253], v[252:253], v[254:255]
	s_nop 0
	v_add_f32_e32 v183, v252, v253
	s_nop 1
	v_add_f32_dpp v183, v183, v183 quad_perm:[1,0,3,2] row_mask:0xf bank_mask:0xf bound_ctrl:1
	s_nop 1
	v_add_f32_dpp v183, v183, v183 quad_perm:[2,3,0,1] row_mask:0xf bank_mask:0xf bound_ctrl:1
	s_nop 1
	v_add_f32_dpp v183, v183, v183 row_half_mirror row_mask:0xf bank_mask:0xf bound_ctrl:1
	s_nop 1
	v_add_f32_dpp v183, v183, v183 row_mirror row_mask:0xf bank_mask:0xf bound_ctrl:1
	s_nop 1
	v_readlane_b32 s98, v183, 0
	v_readlane_b32 s99, v183, 16
	v_readlane_b32 s100, v183, 32
	v_readlane_b32 s101, v183, 48
	s_nop 1
	v_mov_b32_e32 v183, s98
	v_add_f32_e32 v183, s99, v183
	v_add_f32_e32 v183, s100, v183
	v_add_f32_e32 v183, s101, v183
	v_fmamk_f32 v183, v183, 0x3a800000, v182
	v_cmp_gt_f32_e32 vcc, 0x800000, v183
	v_mul_f32_e32 v181, 0x4b800000, v183
	s_nop 1
	v_cndmask_b32_e32 v183, v183, v181, vcc
	v_rsq_f32_e32 v183, v183
	s_nop 0
	v_mul_f32_e32 v181, 0x45800000, v183
	v_cndmask_b32_e32 v184, v183, v181, vcc
	v_mov_b32_e32 v185, v184
	v_pk_mul_f32 v[160:161], v[160:161], v[184:185]
	v_pk_mul_f32 v[162:163], v[162:163], v[184:185]
	v_pk_mul_f32 v[164:165], v[164:165], v[184:185]
	v_pk_mul_f32 v[166:167], v[166:167], v[184:185]
	v_pk_mul_f32 v[168:169], v[168:169], v[184:185]
	v_pk_mul_f32 v[170:171], v[170:171], v[184:185]
	v_pk_mul_f32 v[172:173], v[172:173], v[184:185]
	v_pk_mul_f32 v[174:175], v[174:175], v[184:185]
	v_pk_fma_f32 v[144:145], v[160:161], v[128:129], v[144:145]
	v_pk_fma_f32 v[146:147], v[162:163], v[130:131], v[146:147]
	v_pk_fma_f32 v[148:149], v[164:165], v[132:133], v[148:149]
	v_pk_fma_f32 v[150:151], v[166:167], v[134:135], v[150:151]
	v_pk_fma_f32 v[152:153], v[168:169], v[136:137], v[152:153]
	v_pk_fma_f32 v[154:155], v[170:171], v[138:139], v[154:155]
	v_pk_fma_f32 v[156:157], v[172:173], v[140:141], v[156:157]
	v_pk_fma_f32 v[158:159], v[174:175], v[142:143], v[158:159]
	v_pk_mul_f32 v[252:253], v[144:145], v[144:145]
	v_pk_mul_f32 v[254:255], v[146:147], v[146:147]
	v_pk_fma_f32 v[252:253], v[148:149], v[148:149], v[252:253]
	v_pk_fma_f32 v[254:255], v[150:151], v[150:151], v[254:255]
	v_pk_fma_f32 v[252:253], v[152:153], v[152:153], v[252:253]
	v_pk_fma_f32 v[254:255], v[154:155], v[154:155], v[254:255]
	v_pk_fma_f32 v[252:253], v[156:157], v[156:157], v[252:253]
	v_pk_fma_f32 v[254:255], v[158:159], v[158:159], v[254:255]
	v_pk_add_f32 v[252:253], v[252:253], v[254:255]
	s_nop 0
	v_add_f32_e32 v183, v252, v253
	s_nop 1
	v_add_f32_dpp v183, v183, v183 quad_perm:[1,0,3,2] row_mask:0xf bank_mask:0xf bound_ctrl:1
	s_nop 1
	v_add_f32_dpp v183, v183, v183 quad_perm:[2,3,0,1] row_mask:0xf bank_mask:0xf bound_ctrl:1
	s_nop 1
	v_add_f32_dpp v183, v183, v183 row_half_mirror row_mask:0xf bank_mask:0xf bound_ctrl:1
	s_nop 1
	v_add_f32_dpp v183, v183, v183 row_mirror row_mask:0xf bank_mask:0xf bound_ctrl:1
	s_nop 1
	v_readlane_b32 s98, v183, 0
	v_readlane_b32 s99, v183, 16
	v_readlane_b32 s100, v183, 32
	v_readlane_b32 s101, v183, 48
	s_nop 1
	v_mov_b32_e32 v183, s98
	v_add_f32_e32 v183, s99, v183
	v_add_f32_e32 v183, s100, v183
	v_add_f32_e32 v183, s101, v183
	v_fmamk_f32 v183, v183, 0x3a800000, v182
	v_cmp_gt_f32_e32 vcc, 0x800000, v183
	v_mul_f32_e32 v181, 0x4b800000, v183
	s_nop 1
	v_cndmask_b32_e32 v183, v183, v181, vcc
	v_rsq_f32_e32 v183, v183
	s_nop 0
	v_mul_f32_e32 v181, 0x45800000, v183
	v_cndmask_b32_e32 v184, v183, v181, vcc
	v_mov_b32_e32 v185, v184
	v_cvt_pk_bf16_f32 v0, v144, v145
	v_cvt_pk_bf16_f32 v1, v146, v147
	v_cvt_pk_bf16_f32 v2, v148, v149
	v_cvt_pk_bf16_f32 v3, v150, v151
	v_cvt_pk_bf16_f32 v4, v152, v153
	v_cvt_pk_bf16_f32 v5, v154, v155
	v_cvt_pk_bf16_f32 v6, v156, v157
	v_cvt_pk_bf16_f32 v7, v158, v159
	v_add_u32_e32 v181, 0x3800000, v177
	global_store_dwordx4 v181, v[0:3], s[78:79]
	global_store_dwordx4 v181, v[4:7], s[78:79] offset:1024
	v_add_u32_e32 v236, 0x10000, v237
	s_mov_b64 exec, 1
	global_store_dword v236, v184, s[78:79]
	s_mov_b64 exec, -1
.Lmyxupd_done_1:
.LBB0_740:
	v_readlane_b32 s86, v235, 56
	v_readlane_b32 s90, v235, 59
	v_readlane_b32 s87, v235, 57
	v_readlane_b32 s82, v235, 58
	v_readlane_b32 s91, v235, 60
	v_readlane_b32 s33, v234, 3

.LBB0_1154:
	v_readlane_b32 s0, v235, 52
	v_readlane_b32 s1, v235, 53
	s_and_b64 vcc, exec, s[0:1]
	s_waitcnt lgkmcnt(0)
	s_barrier
	v_mbcnt_lo_u32_b32 v0, -1, 0
	v_mbcnt_hi_u32_b32 v0, -1, v0
	s_cbranch_vccnz .LBB0_1174
	v_lshlrev_b32_e32 v2, 3, v0
	v_ashrrev_i32_e32 v3, 31, v2
	v_readlane_b32 s4, v235, 4
	v_lshlrev_b64 v[4:5], 1, v[2:3]
	v_lshlrev_b64 v[2:3], 2, v[2:3]
	v_readlane_b32 s14, v235, 14
	v_readlane_b32 s15, v235, 15
	v_lshl_add_u64 v[62:63], s[90:91], 0, v[2:3]
	v_readlane_b32 s5, v235, 5
	v_readlane_b32 s6, v235, 6
	v_readlane_b32 s7, v235, 7
	v_readlane_b32 s8, v235, 8
	v_readlane_b32 s9, v235, 9
	v_readlane_b32 s10, v235, 10
	v_readlane_b32 s11, v235, 11
	v_readlane_b32 s12, v235, 12
	v_readlane_b32 s13, v235, 13
	v_readlane_b32 s16, v235, 16
	v_readlane_b32 s17, v235, 17
	v_readlane_b32 s18, v235, 18
	v_readlane_b32 s19, v235, 19
	v_lshl_add_u64 v[2:3], s[14:15], 0, v[2:3]
	s_mov_b64 s[0:1], 0x1000
	v_lshl_add_u64 v[60:61], s[86:87], 0, v[4:5]
	v_lshl_add_u64 v[64:65], s[54:55], 0, v[4:5]
	v_lshl_add_u64 v[66:67], v[2:3], 0, s[0:1]
	s_mov_b32 s1, 0
	v_cmp_eq_u32_e64 s[12:13], 0, v0
	s_mov_b64 s[4:5], 0x200000
	s_mov_b64 s[6:7], 0x200800
	s_mov_b64 s[8:9], 0x400000
	s_mov_b64 s[10:11], 0x400800
	s_mov_b64 s[14:15], 0x600000
	s_mov_b64 s[16:17], 0x600800
	s_mov_b64 s[18:19], 0x800000
	s_mov_b32 s48, 0x800000
	s_mov_b64 s[20:21], 0x800800
	s_mov_b64 s[22:23], 0xa00000
	s_mov_b64 s[24:25], 0xa00800
	s_mov_b64 s[26:27], 0xc00000
	s_mov_b64 s[28:29], 0xc00800
	s_mov_b64 s[36:37], 0xe00000
	s_mov_b64 s[38:39], 0xe00800
	v_mov_b32_e32 v104, 0
	v_mov_b32_e32 v105, 0x358637bd
	v_readlane_b32 s42, v235, 61
	v_readlane_b32 s43, v235, 62
	v_mbcnt_lo_u32_b32 v176, -1, 0
	v_mbcnt_hi_u32_b32 v176, -1, v176
	v_readlane_b32 s98, v235, 49
	v_readlane_b32 s99, v235, 20
	v_readlane_b32 s100, v235, 14
	v_readlane_b32 s101, v235, 15
	s_nop 3
	s_lshr_b32 vcc_lo, s98, 3
	s_and_b32 vcc_hi, vcc_lo, 7
	s_lshl_b32 vcc_hi, vcc_hi, 8
	s_lshr_b32 vcc_lo, vcc_lo, 3
	s_lshl_b32 vcc_lo, vcc_lo, 3
	s_add_i32 s98, vcc_hi, vcc_lo
	s_add_i32 s98, s98, s99
	v_lshlrev_b32_e32 v177, 4, v176
	s_lshl_b32 s99, s98, 11
	v_add_u32_e32 v177, s99, v177
	v_add_u32_e32 v178, 0x1800000, v177
	v_add_u32_e32 v179, 0x9e00000, v177
	v_lshlrev_b32_e32 v180, 5, v176
	v_add_u32_e32 v181, 0x1000, v180
	global_load_dwordx4 v[128:131], v181, s[100:101]
	global_load_dwordx4 v[132:135], v181, s[100:101] offset:16
	global_load_dwordx4 v[136:139], v181, s[100:101] offset:2048
	global_load_dwordx4 v[140:143], v181, s[100:101] offset:2064
	v_mov_b32_e32 v182, 0x358637bd
	global_load_dwordx4 v[0:3], v178, s[78:79]
	global_load_dwordx4 v[4:7], v178, s[78:79] offset:1024
	global_load_dwordx4 v[8:11], v179, s[78:79]
	global_load_dwordx4 v[12:15], v179, s[78:79] offset:1024
	v_add_u32_e32 v178, 0x400000, v178
	v_add_u32_e32 v179, 0x400000, v179
	global_load_dwordx4 v[16:19], v178, s[78:79]
	global_load_dwordx4 v[20:23], v178, s[78:79] offset:1024
	global_load_dwordx4 v[24:27], v179, s[78:79]
	global_load_dwordx4 v[28:31], v179, s[78:79] offset:1024
	v_add_u32_e32 v178, 0x400000, v178
	v_add_u32_e32 v179, 0x400000, v179
	global_load_dwordx4 v[32:35], v178, s[78:79]
	global_load_dwordx4 v[36:39], v178, s[78:79] offset:1024
	global_load_dwordx4 v[40:43], v179, s[78:79]
	global_load_dwordx4 v[44:47], v179, s[78:79] offset:1024
	v_add_u32_e32 v178, 0x400000, v178
	v_add_u32_e32 v179, 0x400000, v179
	global_load_dwordx4 v[48:51], v178, s[78:79]
	global_load_dwordx4 v[52:55], v178, s[78:79] offset:1024
	global_load_dwordx4 v[56:59], v179, s[78:79]
	global_load_dwordx4 v[60:63], v179, s[78:79] offset:1024
	v_add_u32_e32 v178, 0x400000, v178
	v_add_u32_e32 v179, 0x400000, v179
	global_load_dwordx4 v[64:67], v178, s[78:79]
	global_load_dwordx4 v[68:71], v178, s[78:79] offset:1024
	global_load_dwordx4 v[72:75], v179, s[78:79]
	global_load_dwordx4 v[76:79], v179, s[78:79] offset:1024
	v_add_u32_e32 v178, 0x400000, v178
	v_add_u32_e32 v179, 0x400000, v179
	global_load_dwordx4 v[80:83], v178, s[78:79]
	global_load_dwordx4 v[84:87], v178, s[78:79] offset:1024
	global_load_dwordx4 v[88:91], v179, s[78:79]
	global_load_dwordx4 v[92:95], v179, s[78:79] offset:1024
	v_add_u32_e32 v178, 0x400000, v178
	v_add_u32_e32 v179, 0x400000, v179
	global_load_dwordx4 v[96:99], v178, s[78:79]
	global_load_dwordx4 v[100:103], v178, s[78:79] offset:1024
	global_load_dwordx4 v[104:107], v179, s[78:79]
	global_load_dwordx4 v[108:111], v179, s[78:79] offset:1024
	v_add_u32_e32 v178, 0x400000, v178
	v_add_u32_e32 v179, 0x400000, v179
	global_load_dwordx4 v[112:115], v178, s[78:79]
	global_load_dwordx4 v[116:119], v178, s[78:79] offset:1024
	global_load_dwordx4 v[120:123], v179, s[78:79]
	global_load_dwordx4 v[124:127], v179, s[78:79] offset:1024
	v_mov_b32_e32 v183, s98
	v_lshlrev_b32_e32 v237, 2, v183
	v_add_u32_e32 v237, 0x10000, v237
	v_mov_b32_e32 v179, v183
	s_waitcnt vmcnt(28)
	v_lshlrev_b32_e32 v144, 16, v0
	v_and_b32_e32 v145, 0xffff0000, v0
	v_lshlrev_b32_e32 v146, 16, v1
	v_and_b32_e32 v147, 0xffff0000, v1
	v_lshlrev_b32_e32 v148, 16, v2
	v_and_b32_e32 v149, 0xffff0000, v2
	v_lshlrev_b32_e32 v150, 16, v3
	v_and_b32_e32 v151, 0xffff0000, v3
	v_lshlrev_b32_e32 v152, 16, v4
	v_and_b32_e32 v153, 0xffff0000, v4
	v_lshlrev_b32_e32 v154, 16, v5
	v_and_b32_e32 v155, 0xffff0000, v5
	v_lshlrev_b32_e32 v156, 16, v6
	v_and_b32_e32 v157, 0xffff0000, v6
	v_lshlrev_b32_e32 v158, 16, v7
	v_and_b32_e32 v159, 0xffff0000, v7
	v_lshlrev_b32_e32 v160, 16, v8
	v_and_b32_e32 v161, 0xffff0000, v8
	v_lshlrev_b32_e32 v162, 16, v9
	v_and_b32_e32 v163, 0xffff0000, v9
	v_lshlrev_b32_e32 v164, 16, v10
	v_and_b32_e32 v165, 0xffff0000, v10
	v_lshlrev_b32_e32 v166, 16, v11
	v_and_b32_e32 v167, 0xffff0000, v11
	v_lshlrev_b32_e32 v168, 16, v12
	v_and_b32_e32 v169, 0xffff0000, v12
	v_lshlrev_b32_e32 v170, 16, v13
	v_and_b32_e32 v171, 0xffff0000, v13
	v_lshlrev_b32_e32 v172, 16, v14
	v_and_b32_e32 v173, 0xffff0000, v14
	v_lshlrev_b32_e32 v174, 16, v15
	v_and_b32_e32 v175, 0xffff0000, v15
	v_pk_mul_f32 v[252:253], v[160:161], v[160:161]
	v_pk_mul_f32 v[254:255], v[162:163], v[162:163]
	v_pk_fma_f32 v[252:253], v[164:165], v[164:165], v[252:253]
	v_pk_fma_f32 v[254:255], v[166:167], v[166:167], v[254:255]
	v_pk_fma_f32 v[252:253], v[168:169], v[168:169], v[252:253]
	v_pk_fma_f32 v[254:255], v[170:171], v[170:171], v[254:255]
	v_pk_fma_f32 v[252:253], v[172:173], v[172:173], v[252:253]
	v_pk_fma_f32 v[254:255], v[174:175], v[174:175], v[254:255]
	v_pk_add_f32 v[252:253], v[252:253], v[254:255]
	s_nop 0
	v_add_f32_e32 v183, v252, v253
	s_nop 1
	v_add_f32_dpp v183, v183, v183 quad_perm:[1,0,3,2] row_mask:0xf bank_mask:0xf bound_ctrl:1
	s_nop 1
	v_add_f32_dpp v183, v183, v183 quad_perm:[2,3,0,1] row_mask:0xf bank_mask:0xf bound_ctrl:1
	s_nop 1
	v_add_f32_dpp v183, v183, v183 row_half_mirror row_mask:0xf bank_mask:0xf bound_ctrl:1
	s_nop 1
	v_add_f32_dpp v183, v183, v183 row_mirror row_mask:0xf bank_mask:0xf bound_ctrl:1
	s_nop 1
	v_readlane_b32 s98, v183, 0
	v_readlane_b32 s99, v183, 16
	v_readlane_b32 s100, v183, 32
	v_readlane_b32 s101, v183, 48
	s_nop 1
	v_mov_b32_e32 v183, s98
	v_add_f32_e32 v183, s99, v183
	v_add_f32_e32 v183, s100, v183
	v_add_f32_e32 v183, s101, v183
	v_fmamk_f32 v183, v183, 0x3a800000, v182
	v_cmp_gt_f32_e32 vcc, 0x800000, v183
	v_mul_f32_e32 v181, 0x4b800000, v183
	s_nop 1
	v_cndmask_b32_e32 v183, v183, v181, vcc
	v_rsq_f32_e32 v183, v183
	s_nop 0
	v_mul_f32_e32 v181, 0x45800000, v183
	v_cndmask_b32_e32 v184, v183, v181, vcc
	v_mov_b32_e32 v185, v184
	v_pk_mul_f32 v[160:161], v[160:161], v[184:185]
	v_pk_mul_f32 v[162:163], v[162:163], v[184:185]
	v_pk_mul_f32 v[164:165], v[164:165], v[184:185]
	v_pk_mul_f32 v[166:167], v[166:167], v[184:185]
	v_pk_mul_f32 v[168:169], v[168:169], v[184:185]
	v_pk_mul_f32 v[170:171], v[170:171], v[184:185]
	v_pk_mul_f32 v[172:173], v[172:173], v[184:185]
	v_pk_mul_f32 v[174:175], v[174:175], v[184:185]
	v_pk_fma_f32 v[144:145], v[160:161], v[128:129], v[144:145]
	v_pk_fma_f32 v[146:147], v[162:163], v[130:131], v[146:147]
	v_pk_fma_f32 v[148:149], v[164:165], v[132:133], v[148:149]
	v_pk_fma_f32 v[150:151], v[166:167], v[134:135], v[150:151]
	v_pk_fma_f32 v[152:153], v[168:169], v[136:137], v[152:153]
	v_pk_fma_f32 v[154:155], v[170:171], v[138:139], v[154:155]
	v_pk_fma_f32 v[156:157], v[172:173], v[140:141], v[156:157]
	v_pk_fma_f32 v[158:159], v[174:175], v[142:143], v[158:159]
	v_pk_mul_f32 v[252:253], v[144:145], v[144:145]
	v_pk_mul_f32 v[254:255], v[146:147], v[146:147]
	v_pk_fma_f32 v[252:253], v[148:149], v[148:149], v[252:253]
	v_pk_fma_f32 v[254:255], v[150:151], v[150:151], v[254:255]
	v_pk_fma_f32 v[252:253], v[152:153], v[152:153], v[252:253]
	v_pk_fma_f32 v[254:255], v[154:155], v[154:155], v[254:255]
	v_pk_fma_f32 v[252:253], v[156:157], v[156:157], v[252:253]
	v_pk_fma_f32 v[254:255], v[158:159], v[158:159], v[254:255]
	v_pk_add_f32 v[252:253], v[252:253], v[254:255]
	s_nop 0
	v_add_f32_e32 v183, v252, v253
	s_nop 1
	v_add_f32_dpp v183, v183, v183 quad_perm:[1,0,3,2] row_mask:0xf bank_mask:0xf bound_ctrl:1
	s_nop 1
	v_add_f32_dpp v183, v183, v183 quad_perm:[2,3,0,1] row_mask:0xf bank_mask:0xf bound_ctrl:1
	s_nop 1
	v_add_f32_dpp v183, v183, v183 row_half_mirror row_mask:0xf bank_mask:0xf bound_ctrl:1
	s_nop 1
	v_add_f32_dpp v183, v183, v183 row_mirror row_mask:0xf bank_mask:0xf bound_ctrl:1
	s_nop 1
	v_readlane_b32 s98, v183, 0
	v_readlane_b32 s99, v183, 16
	v_readlane_b32 s100, v183, 32
	v_readlane_b32 s101, v183, 48
	s_nop 1
	v_mov_b32_e32 v183, s98
	v_add_f32_e32 v183, s99, v183
	v_add_f32_e32 v183, s100, v183
	v_add_f32_e32 v183, s101, v183
	v_fmamk_f32 v183, v183, 0x3a800000, v182
	v_cmp_gt_f32_e32 vcc, 0x800000, v183
	v_mul_f32_e32 v181, 0x4b800000, v183
	s_nop 1
	v_cndmask_b32_e32 v183, v183, v181, vcc
	v_rsq_f32_e32 v183, v183
	s_nop 0
	v_mul_f32_e32 v181, 0x45800000, v183
	v_cndmask_b32_e32 v184, v183, v181, vcc
	v_mov_b32_e32 v185, v184
	v_cvt_pk_bf16_f32 v0, v144, v145
	v_cvt_pk_bf16_f32 v1, v146, v147
	v_cvt_pk_bf16_f32 v2, v148, v149
	v_cvt_pk_bf16_f32 v3, v150, v151
	v_cvt_pk_bf16_f32 v4, v152, v153
	v_cvt_pk_bf16_f32 v5, v154, v155
	v_cvt_pk_bf16_f32 v6, v156, v157
	v_cvt_pk_bf16_f32 v7, v158, v159
	v_add_u32_e32 v181, 0x1800000, v177
	global_store_dwordx4 v181, v[0:3], s[78:79]
	global_store_dwordx4 v181, v[4:7], s[78:79] offset:1024
	v_add_u32_e32 v236, 0x0, v237
	s_mov_b64 exec, 1
	global_store_dword v236, v184, s[78:79]
	s_mov_b64 exec, -1
	s_waitcnt vmcnt(24)
	v_lshlrev_b32_e32 v144, 16, v16
	v_and_b32_e32 v145, 0xffff0000, v16
	v_lshlrev_b32_e32 v146, 16, v17
	v_and_b32_e32 v147, 0xffff0000, v17
	v_lshlrev_b32_e32 v148, 16, v18
	v_and_b32_e32 v149, 0xffff0000, v18
	v_lshlrev_b32_e32 v150, 16, v19
	v_and_b32_e32 v151, 0xffff0000, v19
	v_lshlrev_b32_e32 v152, 16, v20
	v_and_b32_e32 v153, 0xffff0000, v20
	v_lshlrev_b32_e32 v154, 16, v21
	v_and_b32_e32 v155, 0xffff0000, v21
	v_lshlrev_b32_e32 v156, 16, v22
	v_and_b32_e32 v157, 0xffff0000, v22
	v_lshlrev_b32_e32 v158, 16, v23
	v_and_b32_e32 v159, 0xffff0000, v23
	v_lshlrev_b32_e32 v160, 16, v24
	v_and_b32_e32 v161, 0xffff0000, v24
	v_lshlrev_b32_e32 v162, 16, v25
	v_and_b32_e32 v163, 0xffff0000, v25
	v_lshlrev_b32_e32 v164, 16, v26
	v_and_b32_e32 v165, 0xffff0000, v26
	v_lshlrev_b32_e32 v166, 16, v27
	v_and_b32_e32 v167, 0xffff0000, v27
	v_lshlrev_b32_e32 v168, 16, v28
	v_and_b32_e32 v169, 0xffff0000, v28
	v_lshlrev_b32_e32 v170, 16, v29
	v_and_b32_e32 v171, 0xffff0000, v29
	v_lshlrev_b32_e32 v172, 16, v30
	v_and_b32_e32 v173, 0xffff0000, v30
	v_lshlrev_b32_e32 v174, 16, v31
	v_and_b32_e32 v175, 0xffff0000, v31
	v_pk_mul_f32 v[252:253], v[160:161], v[160:161]
	v_pk_mul_f32 v[254:255], v[162:163], v[162:163]
	v_pk_fma_f32 v[252:253], v[164:165], v[164:165], v[252:253]
	v_pk_fma_f32 v[254:255], v[166:167], v[166:167], v[254:255]
	v_pk_fma_f32 v[252:253], v[168:169], v[168:169], v[252:253]
	v_pk_fma_f32 v[254:255], v[170:171], v[170:171], v[254:255]
	v_pk_fma_f32 v[252:253], v[172:173], v[172:173], v[252:253]
	v_pk_fma_f32 v[254:255], v[174:175], v[174:175], v[254:255]
	v_pk_add_f32 v[252:253], v[252:253], v[254:255]
	s_nop 0
	v_add_f32_e32 v183, v252, v253
	s_nop 1
	v_add_f32_dpp v183, v183, v183 quad_perm:[1,0,3,2] row_mask:0xf bank_mask:0xf bound_ctrl:1
	s_nop 1
	v_add_f32_dpp v183, v183, v183 quad_perm:[2,3,0,1] row_mask:0xf bank_mask:0xf bound_ctrl:1
	s_nop 1
	v_add_f32_dpp v183, v183, v183 row_half_mirror row_mask:0xf bank_mask:0xf bound_ctrl:1
	s_nop 1
	v_add_f32_dpp v183, v183, v183 row_mirror row_mask:0xf bank_mask:0xf bound_ctrl:1
	s_nop 1
	v_readlane_b32 s98, v183, 0
	v_readlane_b32 s99, v183, 16
	v_readlane_b32 s100, v183, 32
	v_readlane_b32 s101, v183, 48
	s_nop 1
	v_mov_b32_e32 v183, s98
	v_add_f32_e32 v183, s99, v183
	v_add_f32_e32 v183, s100, v183
	v_add_f32_e32 v183, s101, v183
	v_fmamk_f32 v183, v183, 0x3a800000, v182
	v_cmp_gt_f32_e32 vcc, 0x800000, v183
	v_mul_f32_e32 v181, 0x4b800000, v183
	s_nop 1
	v_cndmask_b32_e32 v183, v183, v181, vcc
	v_rsq_f32_e32 v183, v183
	s_nop 0
	v_mul_f32_e32 v181, 0x45800000, v183
	v_cndmask_b32_e32 v184, v183, v181, vcc
	v_mov_b32_e32 v185, v184
	v_pk_mul_f32 v[160:161], v[160:161], v[184:185]
	v_pk_mul_f32 v[162:163], v[162:163], v[184:185]
	v_pk_mul_f32 v[164:165], v[164:165], v[184:185]
	v_pk_mul_f32 v[166:167], v[166:167], v[184:185]
	v_pk_mul_f32 v[168:169], v[168:169], v[184:185]
	v_pk_mul_f32 v[170:171], v[170:171], v[184:185]
	v_pk_mul_f32 v[172:173], v[172:173], v[184:185]
	v_pk_mul_f32 v[174:175], v[174:175], v[184:185]
	v_pk_fma_f32 v[144:145], v[160:161], v[128:129], v[144:145]
	v_pk_fma_f32 v[146:147], v[162:163], v[130:131], v[146:147]
	v_pk_fma_f32 v[148:149], v[164:165], v[132:133], v[148:149]
	v_pk_fma_f32 v[150:151], v[166:167], v[134:135], v[150:151]
	v_pk_fma_f32 v[152:153], v[168:169], v[136:137], v[152:153]
	v_pk_fma_f32 v[154:155], v[170:171], v[138:139], v[154:155]
	v_pk_fma_f32 v[156:157], v[172:173], v[140:141], v[156:157]
	v_pk_fma_f32 v[158:159], v[174:175], v[142:143], v[158:159]
	v_pk_mul_f32 v[252:253], v[144:145], v[144:145]
	v_pk_mul_f32 v[254:255], v[146:147], v[146:147]
	v_pk_fma_f32 v[252:253], v[148:149], v[148:149], v[252:253]
	v_pk_fma_f32 v[254:255], v[150:151], v[150:151], v[254:255]
	v_pk_fma_f32 v[252:253], v[152:153], v[152:153], v[252:253]
	v_pk_fma_f32 v[254:255], v[154:155], v[154:155], v[254:255]
	v_pk_fma_f32 v[252:253], v[156:157], v[156:157], v[252:253]
	v_pk_fma_f32 v[254:255], v[158:159], v[158:159], v[254:255]
	v_pk_add_f32 v[252:253], v[252:253], v[254:255]
	s_nop 0
	v_add_f32_e32 v183, v252, v253
	s_nop 1
	v_add_f32_dpp v183, v183, v183 quad_perm:[1,0,3,2] row_mask:0xf bank_mask:0xf bound_ctrl:1
	s_nop 1
	v_add_f32_dpp v183, v183, v183 quad_perm:[2,3,0,1] row_mask:0xf bank_mask:0xf bound_ctrl:1
	s_nop 1
	v_add_f32_dpp v183, v183, v183 row_half_mirror row_mask:0xf bank_mask:0xf bound_ctrl:1
	s_nop 1
	v_add_f32_dpp v183, v183, v183 row_mirror row_mask:0xf bank_mask:0xf bound_ctrl:1
	s_nop 1
	v_readlane_b32 s98, v183, 0
	v_readlane_b32 s99, v183, 16
	v_readlane_b32 s100, v183, 32
	v_readlane_b32 s101, v183, 48
	s_nop 1
	v_mov_b32_e32 v183, s98
	v_add_f32_e32 v183, s99, v183
	v_add_f32_e32 v183, s100, v183
	v_add_f32_e32 v183, s101, v183
	v_fmamk_f32 v183, v183, 0x3a800000, v182
	v_cmp_gt_f32_e32 vcc, 0x800000, v183
	v_mul_f32_e32 v181, 0x4b800000, v183
	s_nop 1
	v_cndmask_b32_e32 v183, v183, v181, vcc
	v_rsq_f32_e32 v183, v183
	s_nop 0
	v_mul_f32_e32 v181, 0x45800000, v183
	v_cndmask_b32_e32 v184, v183, v181, vcc
	v_mov_b32_e32 v185, v184
	v_cvt_pk_bf16_f32 v16, v144, v145
	v_cvt_pk_bf16_f32 v17, v146, v147
	v_cvt_pk_bf16_f32 v18, v148, v149
	v_cvt_pk_bf16_f32 v19, v150, v151
	v_cvt_pk_bf16_f32 v20, v152, v153
	v_cvt_pk_bf16_f32 v21, v154, v155
	v_cvt_pk_bf16_f32 v22, v156, v157
	v_cvt_pk_bf16_f32 v23, v158, v159
	v_add_u32_e32 v181, 0x1c00000, v177
	global_store_dwordx4 v181, v[16:19], s[78:79]
	global_store_dwordx4 v181, v[20:23], s[78:79] offset:1024
	v_add_u32_e32 v236, 0x2000, v237
	s_mov_b64 exec, 1
	global_store_dword v236, v184, s[78:79]
	s_mov_b64 exec, -1
	s_waitcnt vmcnt(20)
	v_lshlrev_b32_e32 v144, 16, v32
	v_and_b32_e32 v145, 0xffff0000, v32
	v_lshlrev_b32_e32 v146, 16, v33
	v_and_b32_e32 v147, 0xffff0000, v33
	v_lshlrev_b32_e32 v148, 16, v34
	v_and_b32_e32 v149, 0xffff0000, v34
	v_lshlrev_b32_e32 v150, 16, v35
	v_and_b32_e32 v151, 0xffff0000, v35
	v_lshlrev_b32_e32 v152, 16, v36
	v_and_b32_e32 v153, 0xffff0000, v36
	v_lshlrev_b32_e32 v154, 16, v37
	v_and_b32_e32 v155, 0xffff0000, v37
	v_lshlrev_b32_e32 v156, 16, v38
	v_and_b32_e32 v157, 0xffff0000, v38
	v_lshlrev_b32_e32 v158, 16, v39
	v_and_b32_e32 v159, 0xffff0000, v39
	v_lshlrev_b32_e32 v160, 16, v40
	v_and_b32_e32 v161, 0xffff0000, v40
	v_lshlrev_b32_e32 v162, 16, v41
	v_and_b32_e32 v163, 0xffff0000, v41
	v_lshlrev_b32_e32 v164, 16, v42
	v_and_b32_e32 v165, 0xffff0000, v42
	v_lshlrev_b32_e32 v166, 16, v43
	v_and_b32_e32 v167, 0xffff0000, v43
	v_lshlrev_b32_e32 v168, 16, v44
	v_and_b32_e32 v169, 0xffff0000, v44
	v_lshlrev_b32_e32 v170, 16, v45
	v_and_b32_e32 v171, 0xffff0000, v45
	v_lshlrev_b32_e32 v172, 16, v46
	v_and_b32_e32 v173, 0xffff0000, v46
	v_lshlrev_b32_e32 v174, 16, v47
	v_and_b32_e32 v175, 0xffff0000, v47
	v_pk_mul_f32 v[252:253], v[160:161], v[160:161]
	v_pk_mul_f32 v[254:255], v[162:163], v[162:163]
	v_pk_fma_f32 v[252:253], v[164:165], v[164:165], v[252:253]
	v_pk_fma_f32 v[254:255], v[166:167], v[166:167], v[254:255]
	v_pk_fma_f32 v[252:253], v[168:169], v[168:169], v[252:253]
	v_pk_fma_f32 v[254:255], v[170:171], v[170:171], v[254:255]
	v_pk_fma_f32 v[252:253], v[172:173], v[172:173], v[252:253]
	v_pk_fma_f32 v[254:255], v[174:175], v[174:175], v[254:255]
	v_pk_add_f32 v[252:253], v[252:253], v[254:255]
	s_nop 0
	v_add_f32_e32 v183, v252, v253
	s_nop 1
	v_add_f32_dpp v183, v183, v183 quad_perm:[1,0,3,2] row_mask:0xf bank_mask:0xf bound_ctrl:1
	s_nop 1
	v_add_f32_dpp v183, v183, v183 quad_perm:[2,3,0,1] row_mask:0xf bank_mask:0xf bound_ctrl:1
	s_nop 1
	v_add_f32_dpp v183, v183, v183 row_half_mirror row_mask:0xf bank_mask:0xf bound_ctrl:1
	s_nop 1
	v_add_f32_dpp v183, v183, v183 row_mirror row_mask:0xf bank_mask:0xf bound_ctrl:1
	s_nop 1
	v_readlane_b32 s98, v183, 0
	v_readlane_b32 s99, v183, 16
	v_readlane_b32 s100, v183, 32
	v_readlane_b32 s101, v183, 48
	s_nop 1
	v_mov_b32_e32 v183, s98
	v_add_f32_e32 v183, s99, v183
	v_add_f32_e32 v183, s100, v183
	v_add_f32_e32 v183, s101, v183
	v_fmamk_f32 v183, v183, 0x3a800000, v182
	v_cmp_gt_f32_e32 vcc, 0x800000, v183
	v_mul_f32_e32 v181, 0x4b800000, v183
	s_nop 1
	v_cndmask_b32_e32 v183, v183, v181, vcc
	v_rsq_f32_e32 v183, v183
	s_nop 0
	v_mul_f32_e32 v181, 0x45800000, v183
	v_cndmask_b32_e32 v184, v183, v181, vcc
	v_mov_b32_e32 v185, v184
	v_pk_mul_f32 v[160:161], v[160:161], v[184:185]
	v_pk_mul_f32 v[162:163], v[162:163], v[184:185]
	v_pk_mul_f32 v[164:165], v[164:165], v[184:185]
	v_pk_mul_f32 v[166:167], v[166:167], v[184:185]
	v_pk_mul_f32 v[168:169], v[168:169], v[184:185]
	v_pk_mul_f32 v[170:171], v[170:171], v[184:185]
	v_pk_mul_f32 v[172:173], v[172:173], v[184:185]
	v_pk_mul_f32 v[174:175], v[174:175], v[184:185]
	v_pk_fma_f32 v[144:145], v[160:161], v[128:129], v[144:145]
	v_pk_fma_f32 v[146:147], v[162:163], v[130:131], v[146:147]
	v_pk_fma_f32 v[148:149], v[164:165], v[132:133], v[148:149]
	v_pk_fma_f32 v[150:151], v[166:167], v[134:135], v[150:151]
	v_pk_fma_f32 v[152:153], v[168:169], v[136:137], v[152:153]
	v_pk_fma_f32 v[154:155], v[170:171], v[138:139], v[154:155]
	v_pk_fma_f32 v[156:157], v[172:173], v[140:141], v[156:157]
	v_pk_fma_f32 v[158:159], v[174:175], v[142:143], v[158:159]
	v_pk_mul_f32 v[252:253], v[144:145], v[144:145]
	v_pk_mul_f32 v[254:255], v[146:147], v[146:147]
	v_pk_fma_f32 v[252:253], v[148:149], v[148:149], v[252:253]
	v_pk_fma_f32 v[254:255], v[150:151], v[150:151], v[254:255]
	v_pk_fma_f32 v[252:253], v[152:153], v[152:153], v[252:253]
	v_pk_fma_f32 v[254:255], v[154:155], v[154:155], v[254:255]
	v_pk_fma_f32 v[252:253], v[156:157], v[156:157], v[252:253]
	v_pk_fma_f32 v[254:255], v[158:159], v[158:159], v[254:255]
	v_pk_add_f32 v[252:253], v[252:253], v[254:255]
	s_nop 0
	v_add_f32_e32 v183, v252, v253
	s_nop 1
	v_add_f32_dpp v183, v183, v183 quad_perm:[1,0,3,2] row_mask:0xf bank_mask:0xf bound_ctrl:1
	s_nop 1
	v_add_f32_dpp v183, v183, v183 quad_perm:[2,3,0,1] row_mask:0xf bank_mask:0xf bound_ctrl:1
	s_nop 1
	v_add_f32_dpp v183, v183, v183 row_half_mirror row_mask:0xf bank_mask:0xf bound_ctrl:1
	s_nop 1
	v_add_f32_dpp v183, v183, v183 row_mirror row_mask:0xf bank_mask:0xf bound_ctrl:1
	s_nop 1
	v_readlane_b32 s98, v183, 0
	v_readlane_b32 s99, v183, 16
	v_readlane_b32 s100, v183, 32
	v_readlane_b32 s101, v183, 48
	s_nop 1
	v_mov_b32_e32 v183, s98
	v_add_f32_e32 v183, s99, v183
	v_add_f32_e32 v183, s100, v183
	v_add_f32_e32 v183, s101, v183
	v_fmamk_f32 v183, v183, 0x3a800000, v182
	v_cmp_gt_f32_e32 vcc, 0x800000, v183
	v_mul_f32_e32 v181, 0x4b800000, v183
	s_nop 1
	v_cndmask_b32_e32 v183, v183, v181, vcc
	v_rsq_f32_e32 v183, v183
	s_nop 0
	v_mul_f32_e32 v181, 0x45800000, v183
	v_cndmask_b32_e32 v184, v183, v181, vcc
	v_mov_b32_e32 v185, v184
	v_cvt_pk_bf16_f32 v32, v144, v145
	v_cvt_pk_bf16_f32 v33, v146, v147
	v_cvt_pk_bf16_f32 v34, v148, v149
	v_cvt_pk_bf16_f32 v35, v150, v151
	v_cvt_pk_bf16_f32 v36, v152, v153
	v_cvt_pk_bf16_f32 v37, v154, v155
	v_cvt_pk_bf16_f32 v38, v156, v157
	v_cvt_pk_bf16_f32 v39, v158, v159
	v_add_u32_e32 v181, 0x2000000, v177
	global_store_dwordx4 v181, v[32:35], s[78:79]
	global_store_dwordx4 v181, v[36:39], s[78:79] offset:1024
	v_add_u32_e32 v236, 0x4000, v237
	s_mov_b64 exec, 1
	global_store_dword v236, v184, s[78:79]
	s_mov_b64 exec, -1
	s_waitcnt vmcnt(16)
	v_lshlrev_b32_e32 v144, 16, v48
	v_and_b32_e32 v145, 0xffff0000, v48
	v_lshlrev_b32_e32 v146, 16, v49
	v_and_b32_e32 v147, 0xffff0000, v49
	v_lshlrev_b32_e32 v148, 16, v50
	v_and_b32_e32 v149, 0xffff0000, v50
	v_lshlrev_b32_e32 v150, 16, v51
	v_and_b32_e32 v151, 0xffff0000, v51
	v_lshlrev_b32_e32 v152, 16, v52
	v_and_b32_e32 v153, 0xffff0000, v52
	v_lshlrev_b32_e32 v154, 16, v53
	v_and_b32_e32 v155, 0xffff0000, v53
	v_lshlrev_b32_e32 v156, 16, v54
	v_and_b32_e32 v157, 0xffff0000, v54
	v_lshlrev_b32_e32 v158, 16, v55
	v_and_b32_e32 v159, 0xffff0000, v55
	v_lshlrev_b32_e32 v160, 16, v56
	v_and_b32_e32 v161, 0xffff0000, v56
	v_lshlrev_b32_e32 v162, 16, v57
	v_and_b32_e32 v163, 0xffff0000, v57
	v_lshlrev_b32_e32 v164, 16, v58
	v_and_b32_e32 v165, 0xffff0000, v58
	v_lshlrev_b32_e32 v166, 16, v59
	v_and_b32_e32 v167, 0xffff0000, v59
	v_lshlrev_b32_e32 v168, 16, v60
	v_and_b32_e32 v169, 0xffff0000, v60
	v_lshlrev_b32_e32 v170, 16, v61
	v_and_b32_e32 v171, 0xffff0000, v61
	v_lshlrev_b32_e32 v172, 16, v62
	v_and_b32_e32 v173, 0xffff0000, v62
	v_lshlrev_b32_e32 v174, 16, v63
	v_and_b32_e32 v175, 0xffff0000, v63
	v_pk_mul_f32 v[252:253], v[160:161], v[160:161]
	v_pk_mul_f32 v[254:255], v[162:163], v[162:163]
	v_pk_fma_f32 v[252:253], v[164:165], v[164:165], v[252:253]
	v_pk_fma_f32 v[254:255], v[166:167], v[166:167], v[254:255]
	v_pk_fma_f32 v[252:253], v[168:169], v[168:169], v[252:253]
	v_pk_fma_f32 v[254:255], v[170:171], v[170:171], v[254:255]
	v_pk_fma_f32 v[252:253], v[172:173], v[172:173], v[252:253]
	v_pk_fma_f32 v[254:255], v[174:175], v[174:175], v[254:255]
	v_pk_add_f32 v[252:253], v[252:253], v[254:255]
	s_nop 0
	v_add_f32_e32 v183, v252, v253
	s_nop 1
	v_add_f32_dpp v183, v183, v183 quad_perm:[1,0,3,2] row_mask:0xf bank_mask:0xf bound_ctrl:1
	s_nop 1
	v_add_f32_dpp v183, v183, v183 quad_perm:[2,3,0,1] row_mask:0xf bank_mask:0xf bound_ctrl:1
	s_nop 1
	v_add_f32_dpp v183, v183, v183 row_half_mirror row_mask:0xf bank_mask:0xf bound_ctrl:1
	s_nop 1
	v_add_f32_dpp v183, v183, v183 row_mirror row_mask:0xf bank_mask:0xf bound_ctrl:1
	s_nop 1
	v_readlane_b32 s98, v183, 0
	v_readlane_b32 s99, v183, 16
	v_readlane_b32 s100, v183, 32
	v_readlane_b32 s101, v183, 48
	s_nop 1
	v_mov_b32_e32 v183, s98
	v_add_f32_e32 v183, s99, v183
	v_add_f32_e32 v183, s100, v183
	v_add_f32_e32 v183, s101, v183
	v_fmamk_f32 v183, v183, 0x3a800000, v182
	v_cmp_gt_f32_e32 vcc, 0x800000, v183
	v_mul_f32_e32 v181, 0x4b800000, v183
	s_nop 1
	v_cndmask_b32_e32 v183, v183, v181, vcc
	v_rsq_f32_e32 v183, v183
	s_nop 0
	v_mul_f32_e32 v181, 0x45800000, v183
	v_cndmask_b32_e32 v184, v183, v181, vcc
	v_mov_b32_e32 v185, v184
	v_pk_mul_f32 v[160:161], v[160:161], v[184:185]
	v_pk_mul_f32 v[162:163], v[162:163], v[184:185]
	v_pk_mul_f32 v[164:165], v[164:165], v[184:185]
	v_pk_mul_f32 v[166:167], v[166:167], v[184:185]
	v_pk_mul_f32 v[168:169], v[168:169], v[184:185]
	v_pk_mul_f32 v[170:171], v[170:171], v[184:185]
	v_pk_mul_f32 v[172:173], v[172:173], v[184:185]
	v_pk_mul_f32 v[174:175], v[174:175], v[184:185]
	v_pk_fma_f32 v[144:145], v[160:161], v[128:129], v[144:145]
	v_pk_fma_f32 v[146:147], v[162:163], v[130:131], v[146:147]
	v_pk_fma_f32 v[148:149], v[164:165], v[132:133], v[148:149]
	v_pk_fma_f32 v[150:151], v[166:167], v[134:135], v[150:151]
	v_pk_fma_f32 v[152:153], v[168:169], v[136:137], v[152:153]
	v_pk_fma_f32 v[154:155], v[170:171], v[138:139], v[154:155]
	v_pk_fma_f32 v[156:157], v[172:173], v[140:141], v[156:157]
	v_pk_fma_f32 v[158:159], v[174:175], v[142:143], v[158:159]
	v_pk_mul_f32 v[252:253], v[144:145], v[144:145]
	v_pk_mul_f32 v[254:255], v[146:147], v[146:147]
	v_pk_fma_f32 v[252:253], v[148:149], v[148:149], v[252:253]
	v_pk_fma_f32 v[254:255], v[150:151], v[150:151], v[254:255]
	v_pk_fma_f32 v[252:253], v[152:153], v[152:153], v[252:253]
	v_pk_fma_f32 v[254:255], v[154:155], v[154:155], v[254:255]
	v_pk_fma_f32 v[252:253], v[156:157], v[156:157], v[252:253]
	v_pk_fma_f32 v[254:255], v[158:159], v[158:159], v[254:255]
	v_pk_add_f32 v[252:253], v[252:253], v[254:255]
	s_nop 0
	v_add_f32_e32 v183, v252, v253
	s_nop 1
	v_add_f32_dpp v183, v183, v183 quad_perm:[1,0,3,2] row_mask:0xf bank_mask:0xf bound_ctrl:1
	s_nop 1
	v_add_f32_dpp v183, v183, v183 quad_perm:[2,3,0,1] row_mask:0xf bank_mask:0xf bound_ctrl:1
	s_nop 1
	v_add_f32_dpp v183, v183, v183 row_half_mirror row_mask:0xf bank_mask:0xf bound_ctrl:1
	s_nop 1
	v_add_f32_dpp v183, v183, v183 row_mirror row_mask:0xf bank_mask:0xf bound_ctrl:1
	s_nop 1
	v_readlane_b32 s98, v183, 0
	v_readlane_b32 s99, v183, 16
	v_readlane_b32 s100, v183, 32
	v_readlane_b32 s101, v183, 48
	s_nop 1
	v_mov_b32_e32 v183, s98
	v_add_f32_e32 v183, s99, v183
	v_add_f32_e32 v183, s100, v183
	v_add_f32_e32 v183, s101, v183
	v_fmamk_f32 v183, v183, 0x3a800000, v182
	v_cmp_gt_f32_e32 vcc, 0x800000, v183
	v_mul_f32_e32 v181, 0x4b800000, v183
	s_nop 1
	v_cndmask_b32_e32 v183, v183, v181, vcc
	v_rsq_f32_e32 v183, v183
	s_nop 0
	v_mul_f32_e32 v181, 0x45800000, v183
	v_cndmask_b32_e32 v184, v183, v181, vcc
	v_mov_b32_e32 v185, v184
	v_cvt_pk_bf16_f32 v48, v144, v145
	v_cvt_pk_bf16_f32 v49, v146, v147
	v_cvt_pk_bf16_f32 v50, v148, v149
	v_cvt_pk_bf16_f32 v51, v150, v151
	v_cvt_pk_bf16_f32 v52, v152, v153
	v_cvt_pk_bf16_f32 v53, v154, v155
	v_cvt_pk_bf16_f32 v54, v156, v157
	v_cvt_pk_bf16_f32 v55, v158, v159
	v_add_u32_e32 v181, 0x2400000, v177
	global_store_dwordx4 v181, v[48:51], s[78:79]
	global_store_dwordx4 v181, v[52:55], s[78:79] offset:1024
	v_add_u32_e32 v236, 0x6000, v237
	s_mov_b64 exec, 1
	global_store_dword v236, v184, s[78:79]
	s_mov_b64 exec, -1
	s_waitcnt vmcnt(12)
	v_lshlrev_b32_e32 v144, 16, v64
	v_and_b32_e32 v145, 0xffff0000, v64
	v_lshlrev_b32_e32 v146, 16, v65
	v_and_b32_e32 v147, 0xffff0000, v65
	v_lshlrev_b32_e32 v148, 16, v66
	v_and_b32_e32 v149, 0xffff0000, v66
	v_lshlrev_b32_e32 v150, 16, v67
	v_and_b32_e32 v151, 0xffff0000, v67
	v_lshlrev_b32_e32 v152, 16, v68
	v_and_b32_e32 v153, 0xffff0000, v68
	v_lshlrev_b32_e32 v154, 16, v69
	v_and_b32_e32 v155, 0xffff0000, v69
	v_lshlrev_b32_e32 v156, 16, v70
	v_and_b32_e32 v157, 0xffff0000, v70
	v_lshlrev_b32_e32 v158, 16, v71
	v_and_b32_e32 v159, 0xffff0000, v71
	v_lshlrev_b32_e32 v160, 16, v72
	v_and_b32_e32 v161, 0xffff0000, v72
	v_lshlrev_b32_e32 v162, 16, v73
	v_and_b32_e32 v163, 0xffff0000, v73
	v_lshlrev_b32_e32 v164, 16, v74
	v_and_b32_e32 v165, 0xffff0000, v74
	v_lshlrev_b32_e32 v166, 16, v75
	v_and_b32_e32 v167, 0xffff0000, v75
	v_lshlrev_b32_e32 v168, 16, v76
	v_and_b32_e32 v169, 0xffff0000, v76
	v_lshlrev_b32_e32 v170, 16, v77
	v_and_b32_e32 v171, 0xffff0000, v77
	v_lshlrev_b32_e32 v172, 16, v78
	v_and_b32_e32 v173, 0xffff0000, v78
	v_lshlrev_b32_e32 v174, 16, v79
	v_and_b32_e32 v175, 0xffff0000, v79
	v_pk_mul_f32 v[252:253], v[160:161], v[160:161]
	v_pk_mul_f32 v[254:255], v[162:163], v[162:163]
	v_pk_fma_f32 v[252:253], v[164:165], v[164:165], v[252:253]
	v_pk_fma_f32 v[254:255], v[166:167], v[166:167], v[254:255]
	v_pk_fma_f32 v[252:253], v[168:169], v[168:169], v[252:253]
	v_pk_fma_f32 v[254:255], v[170:171], v[170:171], v[254:255]
	v_pk_fma_f32 v[252:253], v[172:173], v[172:173], v[252:253]
	v_pk_fma_f32 v[254:255], v[174:175], v[174:175], v[254:255]
	v_pk_add_f32 v[252:253], v[252:253], v[254:255]
	s_nop 0
	v_add_f32_e32 v183, v252, v253
	s_nop 1
	v_add_f32_dpp v183, v183, v183 quad_perm:[1,0,3,2] row_mask:0xf bank_mask:0xf bound_ctrl:1
	s_nop 1
	v_add_f32_dpp v183, v183, v183 quad_perm:[2,3,0,1] row_mask:0xf bank_mask:0xf bound_ctrl:1
	s_nop 1
	v_add_f32_dpp v183, v183, v183 row_half_mirror row_mask:0xf bank_mask:0xf bound_ctrl:1
	s_nop 1
	v_add_f32_dpp v183, v183, v183 row_mirror row_mask:0xf bank_mask:0xf bound_ctrl:1
	s_nop 1
	v_readlane_b32 s98, v183, 0
	v_readlane_b32 s99, v183, 16
	v_readlane_b32 s100, v183, 32
	v_readlane_b32 s101, v183, 48
	s_nop 1
	v_mov_b32_e32 v183, s98
	v_add_f32_e32 v183, s99, v183
	v_add_f32_e32 v183, s100, v183
	v_add_f32_e32 v183, s101, v183
	v_fmamk_f32 v183, v183, 0x3a800000, v182
	v_cmp_gt_f32_e32 vcc, 0x800000, v183
	v_mul_f32_e32 v181, 0x4b800000, v183
	s_nop 1
	v_cndmask_b32_e32 v183, v183, v181, vcc
	v_rsq_f32_e32 v183, v183
	s_nop 0
	v_mul_f32_e32 v181, 0x45800000, v183
	v_cndmask_b32_e32 v184, v183, v181, vcc
	v_mov_b32_e32 v185, v184
	v_pk_mul_f32 v[160:161], v[160:161], v[184:185]
	v_pk_mul_f32 v[162:163], v[162:163], v[184:185]
	v_pk_mul_f32 v[164:165], v[164:165], v[184:185]
	v_pk_mul_f32 v[166:167], v[166:167], v[184:185]
	v_pk_mul_f32 v[168:169], v[168:169], v[184:185]
	v_pk_mul_f32 v[170:171], v[170:171], v[184:185]
	v_pk_mul_f32 v[172:173], v[172:173], v[184:185]
	v_pk_mul_f32 v[174:175], v[174:175], v[184:185]
	v_pk_fma_f32 v[144:145], v[160:161], v[128:129], v[144:145]
	v_pk_fma_f32 v[146:147], v[162:163], v[130:131], v[146:147]
	v_pk_fma_f32 v[148:149], v[164:165], v[132:133], v[148:149]
	v_pk_fma_f32 v[150:151], v[166:167], v[134:135], v[150:151]
	v_pk_fma_f32 v[152:153], v[168:169], v[136:137], v[152:153]
	v_pk_fma_f32 v[154:155], v[170:171], v[138:139], v[154:155]
	v_pk_fma_f32 v[156:157], v[172:173], v[140:141], v[156:157]
	v_pk_fma_f32 v[158:159], v[174:175], v[142:143], v[158:159]
	v_pk_mul_f32 v[252:253], v[144:145], v[144:145]
	v_pk_mul_f32 v[254:255], v[146:147], v[146:147]
	v_pk_fma_f32 v[252:253], v[148:149], v[148:149], v[252:253]
	v_pk_fma_f32 v[254:255], v[150:151], v[150:151], v[254:255]
	v_pk_fma_f32 v[252:253], v[152:153], v[152:153], v[252:253]
	v_pk_fma_f32 v[254:255], v[154:155], v[154:155], v[254:255]
	v_pk_fma_f32 v[252:253], v[156:157], v[156:157], v[252:253]
	v_pk_fma_f32 v[254:255], v[158:159], v[158:159], v[254:255]
	v_pk_add_f32 v[252:253], v[252:253], v[254:255]
	s_nop 0
	v_add_f32_e32 v183, v252, v253
	s_nop 1
	v_add_f32_dpp v183, v183, v183 quad_perm:[1,0,3,2] row_mask:0xf bank_mask:0xf bound_ctrl:1
	s_nop 1
	v_add_f32_dpp v183, v183, v183 quad_perm:[2,3,0,1] row_mask:0xf bank_mask:0xf bound_ctrl:1
	s_nop 1
	v_add_f32_dpp v183, v183, v183 row_half_mirror row_mask:0xf bank_mask:0xf bound_ctrl:1
	s_nop 1
	v_add_f32_dpp v183, v183, v183 row_mirror row_mask:0xf bank_mask:0xf bound_ctrl:1
	s_nop 1
	v_readlane_b32 s98, v183, 0
	v_readlane_b32 s99, v183, 16
	v_readlane_b32 s100, v183, 32
	v_readlane_b32 s101, v183, 48
	s_nop 1
	v_mov_b32_e32 v183, s98
	v_add_f32_e32 v183, s99, v183
	v_add_f32_e32 v183, s100, v183
	v_add_f32_e32 v183, s101, v183
	v_fmamk_f32 v183, v183, 0x3a800000, v182
	v_cmp_gt_f32_e32 vcc, 0x800000, v183
	v_mul_f32_e32 v181, 0x4b800000, v183
	s_nop 1
	v_cndmask_b32_e32 v183, v183, v181, vcc
	v_rsq_f32_e32 v183, v183
	s_nop 0
	v_mul_f32_e32 v181, 0x45800000, v183
	v_cndmask_b32_e32 v184, v183, v181, vcc
	v_mov_b32_e32 v185, v184
	v_cvt_pk_bf16_f32 v64, v144, v145
	v_cvt_pk_bf16_f32 v65, v146, v147
	v_cvt_pk_bf16_f32 v66, v148, v149
	v_cvt_pk_bf16_f32 v67, v150, v151
	v_cvt_pk_bf16_f32 v68, v152, v153
	v_cvt_pk_bf16_f32 v69, v154, v155
	v_cvt_pk_bf16_f32 v70, v156, v157
	v_cvt_pk_bf16_f32 v71, v158, v159
	v_add_u32_e32 v181, 0x2800000, v177
	global_store_dwordx4 v181, v[64:67], s[78:79]
	global_store_dwordx4 v181, v[68:71], s[78:79] offset:1024
	v_add_u32_e32 v236, 0x8000, v237
	s_mov_b64 exec, 1
	global_store_dword v236, v184, s[78:79]
	s_mov_b64 exec, -1
	s_waitcnt vmcnt(8)
	v_lshlrev_b32_e32 v144, 16, v80
	v_and_b32_e32 v145, 0xffff0000, v80
	v_lshlrev_b32_e32 v146, 16, v81
	v_and_b32_e32 v147, 0xffff0000, v81
	v_lshlrev_b32_e32 v148, 16, v82
	v_and_b32_e32 v149, 0xffff0000, v82
	v_lshlrev_b32_e32 v150, 16, v83
	v_and_b32_e32 v151, 0xffff0000, v83
	v_lshlrev_b32_e32 v152, 16, v84
	v_and_b32_e32 v153, 0xffff0000, v84
	v_lshlrev_b32_e32 v154, 16, v85
	v_and_b32_e32 v155, 0xffff0000, v85
	v_lshlrev_b32_e32 v156, 16, v86
	v_and_b32_e32 v157, 0xffff0000, v86
	v_lshlrev_b32_e32 v158, 16, v87
	v_and_b32_e32 v159, 0xffff0000, v87
	v_lshlrev_b32_e32 v160, 16, v88
	v_and_b32_e32 v161, 0xffff0000, v88
	v_lshlrev_b32_e32 v162, 16, v89
	v_and_b32_e32 v163, 0xffff0000, v89
	v_lshlrev_b32_e32 v164, 16, v90
	v_and_b32_e32 v165, 0xffff0000, v90
	v_lshlrev_b32_e32 v166, 16, v91
	v_and_b32_e32 v167, 0xffff0000, v91
	v_lshlrev_b32_e32 v168, 16, v92
	v_and_b32_e32 v169, 0xffff0000, v92
	v_lshlrev_b32_e32 v170, 16, v93
	v_and_b32_e32 v171, 0xffff0000, v93
	v_lshlrev_b32_e32 v172, 16, v94
	v_and_b32_e32 v173, 0xffff0000, v94
	v_lshlrev_b32_e32 v174, 16, v95
	v_and_b32_e32 v175, 0xffff0000, v95
	v_pk_mul_f32 v[252:253], v[160:161], v[160:161]
	v_pk_mul_f32 v[254:255], v[162:163], v[162:163]
	v_pk_fma_f32 v[252:253], v[164:165], v[164:165], v[252:253]
	v_pk_fma_f32 v[254:255], v[166:167], v[166:167], v[254:255]
	v_pk_fma_f32 v[252:253], v[168:169], v[168:169], v[252:253]
	v_pk_fma_f32 v[254:255], v[170:171], v[170:171], v[254:255]
	v_pk_fma_f32 v[252:253], v[172:173], v[172:173], v[252:253]
	v_pk_fma_f32 v[254:255], v[174:175], v[174:175], v[254:255]
	v_pk_add_f32 v[252:253], v[252:253], v[254:255]
	s_nop 0
	v_add_f32_e32 v183, v252, v253
	s_nop 1
	v_add_f32_dpp v183, v183, v183 quad_perm:[1,0,3,2] row_mask:0xf bank_mask:0xf bound_ctrl:1
	s_nop 1
	v_add_f32_dpp v183, v183, v183 quad_perm:[2,3,0,1] row_mask:0xf bank_mask:0xf bound_ctrl:1
	s_nop 1
	v_add_f32_dpp v183, v183, v183 row_half_mirror row_mask:0xf bank_mask:0xf bound_ctrl:1
	s_nop 1
	v_add_f32_dpp v183, v183, v183 row_mirror row_mask:0xf bank_mask:0xf bound_ctrl:1
	s_nop 1
	v_readlane_b32 s98, v183, 0
	v_readlane_b32 s99, v183, 16
	v_readlane_b32 s100, v183, 32
	v_readlane_b32 s101, v183, 48
	s_nop 1
	v_mov_b32_e32 v183, s98
	v_add_f32_e32 v183, s99, v183
	v_add_f32_e32 v183, s100, v183
	v_add_f32_e32 v183, s101, v183
	v_fmamk_f32 v183, v183, 0x3a800000, v182
	v_cmp_gt_f32_e32 vcc, 0x800000, v183
	v_mul_f32_e32 v181, 0x4b800000, v183
	s_nop 1
	v_cndmask_b32_e32 v183, v183, v181, vcc
	v_rsq_f32_e32 v183, v183
	s_nop 0
	v_mul_f32_e32 v181, 0x45800000, v183
	v_cndmask_b32_e32 v184, v183, v181, vcc
	v_mov_b32_e32 v185, v184
	v_pk_mul_f32 v[160:161], v[160:161], v[184:185]
	v_pk_mul_f32 v[162:163], v[162:163], v[184:185]
	v_pk_mul_f32 v[164:165], v[164:165], v[184:185]
	v_pk_mul_f32 v[166:167], v[166:167], v[184:185]
	v_pk_mul_f32 v[168:169], v[168:169], v[184:185]
	v_pk_mul_f32 v[170:171], v[170:171], v[184:185]
	v_pk_mul_f32 v[172:173], v[172:173], v[184:185]
	v_pk_mul_f32 v[174:175], v[174:175], v[184:185]
	v_pk_fma_f32 v[144:145], v[160:161], v[128:129], v[144:145]
	v_pk_fma_f32 v[146:147], v[162:163], v[130:131], v[146:147]
	v_pk_fma_f32 v[148:149], v[164:165], v[132:133], v[148:149]
	v_pk_fma_f32 v[150:151], v[166:167], v[134:135], v[150:151]
	v_pk_fma_f32 v[152:153], v[168:169], v[136:137], v[152:153]
	v_pk_fma_f32 v[154:155], v[170:171], v[138:139], v[154:155]
	v_pk_fma_f32 v[156:157], v[172:173], v[140:141], v[156:157]
	v_pk_fma_f32 v[158:159], v[174:175], v[142:143], v[158:159]
	v_pk_mul_f32 v[252:253], v[144:145], v[144:145]
	v_pk_mul_f32 v[254:255], v[146:147], v[146:147]
	v_pk_fma_f32 v[252:253], v[148:149], v[148:149], v[252:253]
	v_pk_fma_f32 v[254:255], v[150:151], v[150:151], v[254:255]
	v_pk_fma_f32 v[252:253], v[152:153], v[152:153], v[252:253]
	v_pk_fma_f32 v[254:255], v[154:155], v[154:155], v[254:255]
	v_pk_fma_f32 v[252:253], v[156:157], v[156:157], v[252:253]
	v_pk_fma_f32 v[254:255], v[158:159], v[158:159], v[254:255]
	v_pk_add_f32 v[252:253], v[252:253], v[254:255]
	s_nop 0
	v_add_f32_e32 v183, v252, v253
	s_nop 1
	v_add_f32_dpp v183, v183, v183 quad_perm:[1,0,3,2] row_mask:0xf bank_mask:0xf bound_ctrl:1
	s_nop 1
	v_add_f32_dpp v183, v183, v183 quad_perm:[2,3,0,1] row_mask:0xf bank_mask:0xf bound_ctrl:1
	s_nop 1
	v_add_f32_dpp v183, v183, v183 row_half_mirror row_mask:0xf bank_mask:0xf bound_ctrl:1
	s_nop 1
	v_add_f32_dpp v183, v183, v183 row_mirror row_mask:0xf bank_mask:0xf bound_ctrl:1
	s_nop 1
	v_readlane_b32 s98, v183, 0
	v_readlane_b32 s99, v183, 16
	v_readlane_b32 s100, v183, 32
	v_readlane_b32 s101, v183, 48
	s_nop 1
	v_mov_b32_e32 v183, s98
	v_add_f32_e32 v183, s99, v183
	v_add_f32_e32 v183, s100, v183
	v_add_f32_e32 v183, s101, v183
	v_fmamk_f32 v183, v183, 0x3a800000, v182
	v_cmp_gt_f32_e32 vcc, 0x800000, v183
	v_mul_f32_e32 v181, 0x4b800000, v183
	s_nop 1
	v_cndmask_b32_e32 v183, v183, v181, vcc
	v_rsq_f32_e32 v183, v183
	s_nop 0
	v_mul_f32_e32 v181, 0x45800000, v183
	v_cndmask_b32_e32 v184, v183, v181, vcc
	v_mov_b32_e32 v185, v184
	v_cvt_pk_bf16_f32 v80, v144, v145
	v_cvt_pk_bf16_f32 v81, v146, v147
	v_cvt_pk_bf16_f32 v82, v148, v149
	v_cvt_pk_bf16_f32 v83, v150, v151
	v_cvt_pk_bf16_f32 v84, v152, v153
	v_cvt_pk_bf16_f32 v85, v154, v155
	v_cvt_pk_bf16_f32 v86, v156, v157
	v_cvt_pk_bf16_f32 v87, v158, v159
	v_add_u32_e32 v181, 0x2c00000, v177
	global_store_dwordx4 v181, v[80:83], s[78:79]
	global_store_dwordx4 v181, v[84:87], s[78:79] offset:1024
	v_add_u32_e32 v236, 0xa000, v237
	s_mov_b64 exec, 1
	global_store_dword v236, v184, s[78:79]
	s_mov_b64 exec, -1
	s_waitcnt vmcnt(4)
	v_lshlrev_b32_e32 v144, 16, v96
	v_and_b32_e32 v145, 0xffff0000, v96
	v_lshlrev_b32_e32 v146, 16, v97
	v_and_b32_e32 v147, 0xffff0000, v97
	v_lshlrev_b32_e32 v148, 16, v98
	v_and_b32_e32 v149, 0xffff0000, v98
	v_lshlrev_b32_e32 v150, 16, v99
	v_and_b32_e32 v151, 0xffff0000, v99
	v_lshlrev_b32_e32 v152, 16, v100
	v_and_b32_e32 v153, 0xffff0000, v100
	v_lshlrev_b32_e32 v154, 16, v101
	v_and_b32_e32 v155, 0xffff0000, v101
	v_lshlrev_b32_e32 v156, 16, v102
	v_and_b32_e32 v157, 0xffff0000, v102
	v_lshlrev_b32_e32 v158, 16, v103
	v_and_b32_e32 v159, 0xffff0000, v103
	v_lshlrev_b32_e32 v160, 16, v104
	v_and_b32_e32 v161, 0xffff0000, v104
	v_lshlrev_b32_e32 v162, 16, v105
	v_and_b32_e32 v163, 0xffff0000, v105
	v_lshlrev_b32_e32 v164, 16, v106
	v_and_b32_e32 v165, 0xffff0000, v106
	v_lshlrev_b32_e32 v166, 16, v107
	v_and_b32_e32 v167, 0xffff0000, v107
	v_lshlrev_b32_e32 v168, 16, v108
	v_and_b32_e32 v169, 0xffff0000, v108
	v_lshlrev_b32_e32 v170, 16, v109
	v_and_b32_e32 v171, 0xffff0000, v109
	v_lshlrev_b32_e32 v172, 16, v110
	v_and_b32_e32 v173, 0xffff0000, v110
	v_lshlrev_b32_e32 v174, 16, v111
	v_and_b32_e32 v175, 0xffff0000, v111
	v_pk_mul_f32 v[252:253], v[160:161], v[160:161]
	v_pk_mul_f32 v[254:255], v[162:163], v[162:163]
	v_pk_fma_f32 v[252:253], v[164:165], v[164:165], v[252:253]
	v_pk_fma_f32 v[254:255], v[166:167], v[166:167], v[254:255]
	v_pk_fma_f32 v[252:253], v[168:169], v[168:169], v[252:253]
	v_pk_fma_f32 v[254:255], v[170:171], v[170:171], v[254:255]
	v_pk_fma_f32 v[252:253], v[172:173], v[172:173], v[252:253]
	v_pk_fma_f32 v[254:255], v[174:175], v[174:175], v[254:255]
	v_pk_add_f32 v[252:253], v[252:253], v[254:255]
	s_nop 0
	v_add_f32_e32 v183, v252, v253
	s_nop 1
	v_add_f32_dpp v183, v183, v183 quad_perm:[1,0,3,2] row_mask:0xf bank_mask:0xf bound_ctrl:1
	s_nop 1
	v_add_f32_dpp v183, v183, v183 quad_perm:[2,3,0,1] row_mask:0xf bank_mask:0xf bound_ctrl:1
	s_nop 1
	v_add_f32_dpp v183, v183, v183 row_half_mirror row_mask:0xf bank_mask:0xf bound_ctrl:1
	s_nop 1
	v_add_f32_dpp v183, v183, v183 row_mirror row_mask:0xf bank_mask:0xf bound_ctrl:1
	s_nop 1
	v_readlane_b32 s98, v183, 0
	v_readlane_b32 s99, v183, 16
	v_readlane_b32 s100, v183, 32
	v_readlane_b32 s101, v183, 48
	s_nop 1
	v_mov_b32_e32 v183, s98
	v_add_f32_e32 v183, s99, v183
	v_add_f32_e32 v183, s100, v183
	v_add_f32_e32 v183, s101, v183
	v_fmamk_f32 v183, v183, 0x3a800000, v182
	v_cmp_gt_f32_e32 vcc, 0x800000, v183
	v_mul_f32_e32 v181, 0x4b800000, v183
	s_nop 1
	v_cndmask_b32_e32 v183, v183, v181, vcc
	v_rsq_f32_e32 v183, v183
	s_nop 0
	v_mul_f32_e32 v181, 0x45800000, v183
	v_cndmask_b32_e32 v184, v183, v181, vcc
	v_mov_b32_e32 v185, v184
	v_pk_mul_f32 v[160:161], v[160:161], v[184:185]
	v_pk_mul_f32 v[162:163], v[162:163], v[184:185]
	v_pk_mul_f32 v[164:165], v[164:165], v[184:185]
	v_pk_mul_f32 v[166:167], v[166:167], v[184:185]
	v_pk_mul_f32 v[168:169], v[168:169], v[184:185]
	v_pk_mul_f32 v[170:171], v[170:171], v[184:185]
	v_pk_mul_f32 v[172:173], v[172:173], v[184:185]
	v_pk_mul_f32 v[174:175], v[174:175], v[184:185]
	v_pk_fma_f32 v[144:145], v[160:161], v[128:129], v[144:145]
	v_pk_fma_f32 v[146:147], v[162:163], v[130:131], v[146:147]
	v_pk_fma_f32 v[148:149], v[164:165], v[132:133], v[148:149]
	v_pk_fma_f32 v[150:151], v[166:167], v[134:135], v[150:151]
	v_pk_fma_f32 v[152:153], v[168:169], v[136:137], v[152:153]
	v_pk_fma_f32 v[154:155], v[170:171], v[138:139], v[154:155]
	v_pk_fma_f32 v[156:157], v[172:173], v[140:141], v[156:157]
	v_pk_fma_f32 v[158:159], v[174:175], v[142:143], v[158:159]
	v_pk_mul_f32 v[252:253], v[144:145], v[144:145]
	v_pk_mul_f32 v[254:255], v[146:147], v[146:147]
	v_pk_fma_f32 v[252:253], v[148:149], v[148:149], v[252:253]
	v_pk_fma_f32 v[254:255], v[150:151], v[150:151], v[254:255]
	v_pk_fma_f32 v[252:253], v[152:153], v[152:153], v[252:253]
	v_pk_fma_f32 v[254:255], v[154:155], v[154:155], v[254:255]
	v_pk_fma_f32 v[252:253], v[156:157], v[156:157], v[252:253]
	v_pk_fma_f32 v[254:255], v[158:159], v[158:159], v[254:255]
	v_pk_add_f32 v[252:253], v[252:253], v[254:255]
	s_nop 0
	v_add_f32_e32 v183, v252, v253
	s_nop 1
	v_add_f32_dpp v183, v183, v183 quad_perm:[1,0,3,2] row_mask:0xf bank_mask:0xf bound_ctrl:1
	s_nop 1
	v_add_f32_dpp v183, v183, v183 quad_perm:[2,3,0,1] row_mask:0xf bank_mask:0xf bound_ctrl:1
	s_nop 1
	v_add_f32_dpp v183, v183, v183 row_half_mirror row_mask:0xf bank_mask:0xf bound_ctrl:1
	s_nop 1
	v_add_f32_dpp v183, v183, v183 row_mirror row_mask:0xf bank_mask:0xf bound_ctrl:1
	s_nop 1
	v_readlane_b32 s98, v183, 0
	v_readlane_b32 s99, v183, 16
	v_readlane_b32 s100, v183, 32
	v_readlane_b32 s101, v183, 48
	s_nop 1
	v_mov_b32_e32 v183, s98
	v_add_f32_e32 v183, s99, v183
	v_add_f32_e32 v183, s100, v183
	v_add_f32_e32 v183, s101, v183
	v_fmamk_f32 v183, v183, 0x3a800000, v182
	v_cmp_gt_f32_e32 vcc, 0x800000, v183
	v_mul_f32_e32 v181, 0x4b800000, v183
	s_nop 1
	v_cndmask_b32_e32 v183, v183, v181, vcc
	v_rsq_f32_e32 v183, v183
	s_nop 0
	v_mul_f32_e32 v181, 0x45800000, v183
	v_cndmask_b32_e32 v184, v183, v181, vcc
	v_mov_b32_e32 v185, v184
	v_cvt_pk_bf16_f32 v96, v144, v145
	v_cvt_pk_bf16_f32 v97, v146, v147
	v_cvt_pk_bf16_f32 v98, v148, v149
	v_cvt_pk_bf16_f32 v99, v150, v151
	v_cvt_pk_bf16_f32 v100, v152, v153
	v_cvt_pk_bf16_f32 v101, v154, v155
	v_cvt_pk_bf16_f32 v102, v156, v157
	v_cvt_pk_bf16_f32 v103, v158, v159
	v_add_u32_e32 v181, 0x3000000, v177
	global_store_dwordx4 v181, v[96:99], s[78:79]
	global_store_dwordx4 v181, v[100:103], s[78:79] offset:1024
	v_add_u32_e32 v236, 0xc000, v237
	s_mov_b64 exec, 1
	global_store_dword v236, v184, s[78:79]
	s_mov_b64 exec, -1
	s_waitcnt vmcnt(0)
	v_lshlrev_b32_e32 v144, 16, v112
	v_and_b32_e32 v145, 0xffff0000, v112
	v_lshlrev_b32_e32 v146, 16, v113
	v_and_b32_e32 v147, 0xffff0000, v113
	v_lshlrev_b32_e32 v148, 16, v114
	v_and_b32_e32 v149, 0xffff0000, v114
	v_lshlrev_b32_e32 v150, 16, v115
	v_and_b32_e32 v151, 0xffff0000, v115
	v_lshlrev_b32_e32 v152, 16, v116
	v_and_b32_e32 v153, 0xffff0000, v116
	v_lshlrev_b32_e32 v154, 16, v117
	v_and_b32_e32 v155, 0xffff0000, v117
	v_lshlrev_b32_e32 v156, 16, v118
	v_and_b32_e32 v157, 0xffff0000, v118
	v_lshlrev_b32_e32 v158, 16, v119
	v_and_b32_e32 v159, 0xffff0000, v119
	v_lshlrev_b32_e32 v160, 16, v120
	v_and_b32_e32 v161, 0xffff0000, v120
	v_lshlrev_b32_e32 v162, 16, v121
	v_and_b32_e32 v163, 0xffff0000, v121
	v_lshlrev_b32_e32 v164, 16, v122
	v_and_b32_e32 v165, 0xffff0000, v122
	v_lshlrev_b32_e32 v166, 16, v123
	v_and_b32_e32 v167, 0xffff0000, v123
	v_lshlrev_b32_e32 v168, 16, v124
	v_and_b32_e32 v169, 0xffff0000, v124
	v_lshlrev_b32_e32 v170, 16, v125
	v_and_b32_e32 v171, 0xffff0000, v125
	v_lshlrev_b32_e32 v172, 16, v126
	v_and_b32_e32 v173, 0xffff0000, v126
	v_lshlrev_b32_e32 v174, 16, v127
	v_and_b32_e32 v175, 0xffff0000, v127
	v_pk_mul_f32 v[252:253], v[160:161], v[160:161]
	v_pk_mul_f32 v[254:255], v[162:163], v[162:163]
	v_pk_fma_f32 v[252:253], v[164:165], v[164:165], v[252:253]
	v_pk_fma_f32 v[254:255], v[166:167], v[166:167], v[254:255]
	v_pk_fma_f32 v[252:253], v[168:169], v[168:169], v[252:253]
	v_pk_fma_f32 v[254:255], v[170:171], v[170:171], v[254:255]
	v_pk_fma_f32 v[252:253], v[172:173], v[172:173], v[252:253]
	v_pk_fma_f32 v[254:255], v[174:175], v[174:175], v[254:255]
	v_pk_add_f32 v[252:253], v[252:253], v[254:255]
	s_nop 0
	v_add_f32_e32 v183, v252, v253
	s_nop 1
	v_add_f32_dpp v183, v183, v183 quad_perm:[1,0,3,2] row_mask:0xf bank_mask:0xf bound_ctrl:1
	s_nop 1
	v_add_f32_dpp v183, v183, v183 quad_perm:[2,3,0,1] row_mask:0xf bank_mask:0xf bound_ctrl:1
	s_nop 1
	v_add_f32_dpp v183, v183, v183 row_half_mirror row_mask:0xf bank_mask:0xf bound_ctrl:1
	s_nop 1
	v_add_f32_dpp v183, v183, v183 row_mirror row_mask:0xf bank_mask:0xf bound_ctrl:1
	s_nop 1
	v_readlane_b32 s98, v183, 0
	v_readlane_b32 s99, v183, 16
	v_readlane_b32 s100, v183, 32
	v_readlane_b32 s101, v183, 48
	s_nop 1
	v_mov_b32_e32 v183, s98
	v_add_f32_e32 v183, s99, v183
	v_add_f32_e32 v183, s100, v183
	v_add_f32_e32 v183, s101, v183
	v_fmamk_f32 v183, v183, 0x3a800000, v182
	v_cmp_gt_f32_e32 vcc, 0x800000, v183
	v_mul_f32_e32 v181, 0x4b800000, v183
	s_nop 1
	v_cndmask_b32_e32 v183, v183, v181, vcc
	v_rsq_f32_e32 v183, v183
	s_nop 0
	v_mul_f32_e32 v181, 0x45800000, v183
	v_cndmask_b32_e32 v184, v183, v181, vcc
	v_mov_b32_e32 v185, v184
	v_pk_mul_f32 v[160:161], v[160:161], v[184:185]
	v_pk_mul_f32 v[162:163], v[162:163], v[184:185]
	v_pk_mul_f32 v[164:165], v[164:165], v[184:185]
	v_pk_mul_f32 v[166:167], v[166:167], v[184:185]
	v_pk_mul_f32 v[168:169], v[168:169], v[184:185]
	v_pk_mul_f32 v[170:171], v[170:171], v[184:185]
	v_pk_mul_f32 v[172:173], v[172:173], v[184:185]
	v_pk_mul_f32 v[174:175], v[174:175], v[184:185]
	v_pk_fma_f32 v[144:145], v[160:161], v[128:129], v[144:145]
	v_pk_fma_f32 v[146:147], v[162:163], v[130:131], v[146:147]
	v_pk_fma_f32 v[148:149], v[164:165], v[132:133], v[148:149]
	v_pk_fma_f32 v[150:151], v[166:167], v[134:135], v[150:151]
	v_pk_fma_f32 v[152:153], v[168:169], v[136:137], v[152:153]
	v_pk_fma_f32 v[154:155], v[170:171], v[138:139], v[154:155]
	v_pk_fma_f32 v[156:157], v[172:173], v[140:141], v[156:157]
	v_pk_fma_f32 v[158:159], v[174:175], v[142:143], v[158:159]
	v_pk_mul_f32 v[252:253], v[144:145], v[144:145]
	v_pk_mul_f32 v[254:255], v[146:147], v[146:147]
	v_pk_fma_f32 v[252:253], v[148:149], v[148:149], v[252:253]
	v_pk_fma_f32 v[254:255], v[150:151], v[150:151], v[254:255]
	v_pk_fma_f32 v[252:253], v[152:153], v[152:153], v[252:253]
	v_pk_fma_f32 v[254:255], v[154:155], v[154:155], v[254:255]
	v_pk_fma_f32 v[252:253], v[156:157], v[156:157], v[252:253]
	v_pk_fma_f32 v[254:255], v[158:159], v[158:159], v[254:255]
	v_pk_add_f32 v[252:253], v[252:253], v[254:255]
	s_nop 0
	v_add_f32_e32 v183, v252, v253
	s_nop 1
	v_add_f32_dpp v183, v183, v183 quad_perm:[1,0,3,2] row_mask:0xf bank_mask:0xf bound_ctrl:1
	s_nop 1
	v_add_f32_dpp v183, v183, v183 quad_perm:[2,3,0,1] row_mask:0xf bank_mask:0xf bound_ctrl:1
	s_nop 1
	v_add_f32_dpp v183, v183, v183 row_half_mirror row_mask:0xf bank_mask:0xf bound_ctrl:1
	s_nop 1
	v_add_f32_dpp v183, v183, v183 row_mirror row_mask:0xf bank_mask:0xf bound_ctrl:1
	s_nop 1
	v_readlane_b32 s98, v183, 0
	v_readlane_b32 s99, v183, 16
	v_readlane_b32 s100, v183, 32
	v_readlane_b32 s101, v183, 48
	s_nop 1
	v_mov_b32_e32 v183, s98
	v_add_f32_e32 v183, s99, v183
	v_add_f32_e32 v183, s100, v183
	v_add_f32_e32 v183, s101, v183
	v_fmamk_f32 v183, v183, 0x3a800000, v182
	v_cmp_gt_f32_e32 vcc, 0x800000, v183
	v_mul_f32_e32 v181, 0x4b800000, v183
	s_nop 1
	v_cndmask_b32_e32 v183, v183, v181, vcc
	v_rsq_f32_e32 v183, v183
	s_nop 0
	v_mul_f32_e32 v181, 0x45800000, v183
	v_cndmask_b32_e32 v184, v183, v181, vcc
	v_mov_b32_e32 v185, v184
	v_cvt_pk_bf16_f32 v112, v144, v145
	v_cvt_pk_bf16_f32 v113, v146, v147
	v_cvt_pk_bf16_f32 v114, v148, v149
	v_cvt_pk_bf16_f32 v115, v150, v151
	v_cvt_pk_bf16_f32 v116, v152, v153
	v_cvt_pk_bf16_f32 v117, v154, v155
	v_cvt_pk_bf16_f32 v118, v156, v157
	v_cvt_pk_bf16_f32 v119, v158, v159
	v_add_u32_e32 v181, 0x3400000, v177
	global_store_dwordx4 v181, v[112:115], s[78:79]
	global_store_dwordx4 v181, v[116:119], s[78:79] offset:1024
	v_add_u32_e32 v236, 0xe000, v237
	s_mov_b64 exec, 1
	global_store_dword v236, v184, s[78:79]
	s_mov_b64 exec, -1
	v_readfirstlane_b32 s98, v179
	s_nop 3
	s_cmp_ge_u32 s98, 512
	s_cbranch_scc1 .Lmyxupd_done_2
	v_add_u32_e32 v181, 0x3800000, v177
	global_load_dwordx4 v[0:3], v181, s[78:79]
	global_load_dwordx4 v[4:7], v181, s[78:79] offset:1024
	v_lshl_add_u32 v183, v179, 12, v180
	v_add_u32_e32 v183, 0xbf00000, v183
	v_add_u32_e32 v181, 0x0, v183
	global_load_dwordx4 v[8:11], v181, s[78:79]
	global_load_dwordx4 v[12:15], v181, s[78:79] offset:16
	global_load_dwordx4 v[16:19], v181, s[78:79] offset:2048
	global_load_dwordx4 v[20:23], v181, s[78:79] offset:2064
	v_add_u32_e32 v181, 0x200000, v183
	global_load_dwordx4 v[24:27], v181, s[78:79]
	global_load_dwordx4 v[28:31], v181, s[78:79] offset:16
	global_load_dwordx4 v[32:35], v181, s[78:79] offset:2048
	global_load_dwordx4 v[36:39], v181, s[78:79] offset:2064
	v_add_u32_e32 v181, 0x400000, v183
	global_load_dwordx4 v[40:43], v181, s[78:79]
	global_load_dwordx4 v[44:47], v181, s[78:79] offset:16
	global_load_dwordx4 v[48:51], v181, s[78:79] offset:2048
	global_load_dwordx4 v[52:55], v181, s[78:79] offset:2064
	v_add_u32_e32 v181, 0x600000, v183
	global_load_dwordx4 v[56:59], v181, s[78:79]
	global_load_dwordx4 v[60:63], v181, s[78:79] offset:16
	global_load_dwordx4 v[64:67], v181, s[78:79] offset:2048
	global_load_dwordx4 v[68:71], v181, s[78:79] offset:2064
	v_add_u32_e32 v181, 0x800000, v183
	global_load_dwordx4 v[72:75], v181, s[78:79]
	global_load_dwordx4 v[76:79], v181, s[78:79] offset:16
	global_load_dwordx4 v[80:83], v181, s[78:79] offset:2048
	global_load_dwordx4 v[84:87], v181, s[78:79] offset:2064
	v_add_u32_e32 v181, 0xa00000, v183
	global_load_dwordx4 v[88:91], v181, s[78:79]
	global_load_dwordx4 v[92:95], v181, s[78:79] offset:16
	global_load_dwordx4 v[96:99], v181, s[78:79] offset:2048
	global_load_dwordx4 v[100:103], v181, s[78:79] offset:2064
	s_waitcnt vmcnt(20)
	v_pk_add_f32 v[160:161], v[8:9], 0 op_sel_hi:[1,0]
	v_pk_add_f32 v[162:163], v[10:11], 0 op_sel_hi:[1,0]
	v_pk_add_f32 v[164:165], v[12:13], 0 op_sel_hi:[1,0]
	v_pk_add_f32 v[166:167], v[14:15], 0 op_sel_hi:[1,0]
	v_pk_add_f32 v[168:169], v[16:17], 0 op_sel_hi:[1,0]
	v_pk_add_f32 v[170:171], v[18:19], 0 op_sel_hi:[1,0]
	v_pk_add_f32 v[172:173], v[20:21], 0 op_sel_hi:[1,0]
	v_pk_add_f32 v[174:175], v[22:23], 0 op_sel_hi:[1,0]
	s_waitcnt vmcnt(16)
	v_pk_add_f32 v[160:161], v[160:161], v[24:25]
	v_pk_add_f32 v[162:163], v[162:163], v[26:27]
	v_pk_add_f32 v[164:165], v[164:165], v[28:29]
	v_pk_add_f32 v[166:167], v[166:167], v[30:31]
	v_pk_add_f32 v[168:169], v[168:169], v[32:33]
	v_pk_add_f32 v[170:171], v[170:171], v[34:35]
	v_pk_add_f32 v[172:173], v[172:173], v[36:37]
	v_pk_add_f32 v[174:175], v[174:175], v[38:39]
	s_waitcnt vmcnt(12)
	v_pk_add_f32 v[160:161], v[160:161], v[40:41]
	v_pk_add_f32 v[162:163], v[162:163], v[42:43]
	v_pk_add_f32 v[164:165], v[164:165], v[44:45]
	v_pk_add_f32 v[166:167], v[166:167], v[46:47]
	v_pk_add_f32 v[168:169], v[168:169], v[48:49]
	v_pk_add_f32 v[170:171], v[170:171], v[50:51]
	v_pk_add_f32 v[172:173], v[172:173], v[52:53]
	v_pk_add_f32 v[174:175], v[174:175], v[54:55]
	s_waitcnt vmcnt(8)
	v_pk_add_f32 v[160:161], v[160:161], v[56:57]
	v_pk_add_f32 v[162:163], v[162:163], v[58:59]
	v_pk_add_f32 v[164:165], v[164:165], v[60:61]
	v_pk_add_f32 v[166:167], v[166:167], v[62:63]
	v_pk_add_f32 v[168:169], v[168:169], v[64:65]
	v_pk_add_f32 v[170:171], v[170:171], v[66:67]
	v_pk_add_f32 v[172:173], v[172:173], v[68:69]
	v_pk_add_f32 v[174:175], v[174:175], v[70:71]
	s_waitcnt vmcnt(4)
	v_pk_add_f32 v[160:161], v[160:161], v[72:73]
	v_pk_add_f32 v[162:163], v[162:163], v[74:75]
	v_pk_add_f32 v[164:165], v[164:165], v[76:77]
	v_pk_add_f32 v[166:167], v[166:167], v[78:79]
	v_pk_add_f32 v[168:169], v[168:169], v[80:81]
	v_pk_add_f32 v[170:171], v[170:171], v[82:83]
	v_pk_add_f32 v[172:173], v[172:173], v[84:85]
	v_pk_add_f32 v[174:175], v[174:175], v[86:87]
	s_waitcnt vmcnt(0)
	v_pk_add_f32 v[160:161], v[160:161], v[88:89]
	v_pk_add_f32 v[162:163], v[162:163], v[90:91]
	v_pk_add_f32 v[164:165], v[164:165], v[92:93]
	v_pk_add_f32 v[166:167], v[166:167], v[94:95]
	v_pk_add_f32 v[168:169], v[168:169], v[96:97]
	v_pk_add_f32 v[170:171], v[170:171], v[98:99]
	v_pk_add_f32 v[172:173], v[172:173], v[100:101]
	v_pk_add_f32 v[174:175], v[174:175], v[102:103]
	v_lshlrev_b32_e32 v144, 16, v0
	v_and_b32_e32 v145, 0xffff0000, v0
	v_lshlrev_b32_e32 v146, 16, v1
	v_and_b32_e32 v147, 0xffff0000, v1
	v_lshlrev_b32_e32 v148, 16, v2
	v_and_b32_e32 v149, 0xffff0000, v2
	v_lshlrev_b32_e32 v150, 16, v3
	v_and_b32_e32 v151, 0xffff0000, v3
	v_lshlrev_b32_e32 v152, 16, v4
	v_and_b32_e32 v153, 0xffff0000, v4
	v_lshlrev_b32_e32 v154, 16, v5
	v_and_b32_e32 v155, 0xffff0000, v5
	v_lshlrev_b32_e32 v156, 16, v6
	v_and_b32_e32 v157, 0xffff0000, v6
	v_lshlrev_b32_e32 v158, 16, v7
	v_and_b32_e32 v159, 0xffff0000, v7
	v_add_u32_e32 v181, 0xc00000, v183
	global_load_dwordx4 v[8:11], v181, s[78:79]
	global_load_dwordx4 v[12:15], v181, s[78:79] offset:16
	global_load_dwordx4 v[16:19], v181, s[78:79] offset:2048
	global_load_dwordx4 v[20:23], v181, s[78:79] offset:2064
	v_add_u32_e32 v181, 0xe00000, v183
	global_load_dwordx4 v[24:27], v181, s[78:79]
	global_load_dwordx4 v[28:31], v181, s[78:79] offset:16
	global_load_dwordx4 v[32:35], v181, s[78:79] offset:2048
	global_load_dwordx4 v[36:39], v181, s[78:79] offset:2064
	s_waitcnt vmcnt(4)
	v_pk_add_f32 v[160:161], v[160:161], v[8:9]
	v_pk_add_f32 v[162:163], v[162:163], v[10:11]
	v_pk_add_f32 v[164:165], v[164:165], v[12:13]
	v_pk_add_f32 v[166:167], v[166:167], v[14:15]
	v_pk_add_f32 v[168:169], v[168:169], v[16:17]
	v_pk_add_f32 v[170:171], v[170:171], v[18:19]
	v_pk_add_f32 v[172:173], v[172:173], v[20:21]
	v_pk_add_f32 v[174:175], v[174:175], v[22:23]
	s_waitcnt vmcnt(0)
	v_pk_add_f32 v[160:161], v[160:161], v[24:25]
	v_pk_add_f32 v[162:163], v[162:163], v[26:27]
	v_pk_add_f32 v[164:165], v[164:165], v[28:29]
	v_pk_add_f32 v[166:167], v[166:167], v[30:31]
	v_pk_add_f32 v[168:169], v[168:169], v[32:33]
	v_pk_add_f32 v[170:171], v[170:171], v[34:35]
	v_pk_add_f32 v[172:173], v[172:173], v[36:37]
	v_pk_add_f32 v[174:175], v[174:175], v[38:39]
	v_pk_mul_f32 v[252:253], v[160:161], v[160:161]
	v_pk_mul_f32 v[254:255], v[162:163], v[162:163]
	v_pk_fma_f32 v[252:253], v[164:165], v[164:165], v[252:253]
	v_pk_fma_f32 v[254:255], v[166:167], v[166:167], v[254:255]
	v_pk_fma_f32 v[252:253], v[168:169], v[168:169], v[252:253]
	v_pk_fma_f32 v[254:255], v[170:171], v[170:171], v[254:255]
	v_pk_fma_f32 v[252:253], v[172:173], v[172:173], v[252:253]
	v_pk_fma_f32 v[254:255], v[174:175], v[174:175], v[254:255]
	v_pk_add_f32 v[252:253], v[252:253], v[254:255]
	s_nop 0
	v_add_f32_e32 v183, v252, v253
	s_nop 1
	v_add_f32_dpp v183, v183, v183 quad_perm:[1,0,3,2] row_mask:0xf bank_mask:0xf bound_ctrl:1
	s_nop 1
	v_add_f32_dpp v183, v183, v183 quad_perm:[2,3,0,1] row_mask:0xf bank_mask:0xf bound_ctrl:1
	s_nop 1
	v_add_f32_dpp v183, v183, v183 row_half_mirror row_mask:0xf bank_mask:0xf bound_ctrl:1
	s_nop 1
	v_add_f32_dpp v183, v183, v183 row_mirror row_mask:0xf bank_mask:0xf bound_ctrl:1
	s_nop 1
	v_readlane_b32 s98, v183, 0
	v_readlane_b32 s99, v183, 16
	v_readlane_b32 s100, v183, 32
	v_readlane_b32 s101, v183, 48
	s_nop 1
	v_mov_b32_e32 v183, s98
	v_add_f32_e32 v183, s99, v183
	v_add_f32_e32 v183, s100, v183
	v_add_f32_e32 v183, s101, v183
	v_fmamk_f32 v183, v183, 0x3a800000, v182
	v_cmp_gt_f32_e32 vcc, 0x800000, v183
	v_mul_f32_e32 v181, 0x4b800000, v183
	s_nop 1
	v_cndmask_b32_e32 v183, v183, v181, vcc
	v_rsq_f32_e32 v183, v183
	s_nop 0
	v_mul_f32_e32 v181, 0x45800000, v183
	v_cndmask_b32_e32 v184, v183, v181, vcc
	v_mov_b32_e32 v185, v184
	v_pk_mul_f32 v[160:161], v[160:161], v[184:185]
	v_pk_mul_f32 v[162:163], v[162:163], v[184:185]
	v_pk_mul_f32 v[164:165], v[164:165], v[184:185]
	v_pk_mul_f32 v[166:167], v[166:167], v[184:185]
	v_pk_mul_f32 v[168:169], v[168:169], v[184:185]
	v_pk_mul_f32 v[170:171], v[170:171], v[184:185]
	v_pk_mul_f32 v[172:173], v[172:173], v[184:185]
	v_pk_mul_f32 v[174:175], v[174:175], v[184:185]
	v_pk_fma_f32 v[144:145], v[160:161], v[128:129], v[144:145]
	v_pk_fma_f32 v[146:147], v[162:163], v[130:131], v[146:147]
	v_pk_fma_f32 v[148:149], v[164:165], v[132:133], v[148:149]
	v_pk_fma_f32 v[150:151], v[166:167], v[134:135], v[150:151]
	v_pk_fma_f32 v[152:153], v[168:169], v[136:137], v[152:153]
	v_pk_fma_f32 v[154:155], v[170:171], v[138:139], v[154:155]
	v_pk_fma_f32 v[156:157], v[172:173], v[140:141], v[156:157]
	v_pk_fma_f32 v[158:159], v[174:175], v[142:143], v[158:159]
	v_pk_mul_f32 v[252:253], v[144:145], v[144:145]
	v_pk_mul_f32 v[254:255], v[146:147], v[146:147]
	v_pk_fma_f32 v[252:253], v[148:149], v[148:149], v[252:253]
	v_pk_fma_f32 v[254:255], v[150:151], v[150:151], v[254:255]
	v_pk_fma_f32 v[252:253], v[152:153], v[152:153], v[252:253]
	v_pk_fma_f32 v[254:255], v[154:155], v[154:155], v[254:255]
	v_pk_fma_f32 v[252:253], v[156:157], v[156:157], v[252:253]
	v_pk_fma_f32 v[254:255], v[158:159], v[158:159], v[254:255]
	v_pk_add_f32 v[252:253], v[252:253], v[254:255]
	s_nop 0
	v_add_f32_e32 v183, v252, v253
	s_nop 1
	v_add_f32_dpp v183, v183, v183 quad_perm:[1,0,3,2] row_mask:0xf bank_mask:0xf bound_ctrl:1
	s_nop 1
	v_add_f32_dpp v183, v183, v183 quad_perm:[2,3,0,1] row_mask:0xf bank_mask:0xf bound_ctrl:1
	s_nop 1
	v_add_f32_dpp v183, v183, v183 row_half_mirror row_mask:0xf bank_mask:0xf bound_ctrl:1
	s_nop 1
	v_add_f32_dpp v183, v183, v183 row_mirror row_mask:0xf bank_mask:0xf bound_ctrl:1
	s_nop 1
	v_readlane_b32 s98, v183, 0
	v_readlane_b32 s99, v183, 16
	v_readlane_b32 s100, v183, 32
	v_readlane_b32 s101, v183, 48
	s_nop 1
	v_mov_b32_e32 v183, s98
	v_add_f32_e32 v183, s99, v183
	v_add_f32_e32 v183, s100, v183
	v_add_f32_e32 v183, s101, v183
	v_fmamk_f32 v183, v183, 0x3a800000, v182
	v_cmp_gt_f32_e32 vcc, 0x800000, v183
	v_mul_f32_e32 v181, 0x4b800000, v183
	s_nop 1
	v_cndmask_b32_e32 v183, v183, v181, vcc
	v_rsq_f32_e32 v183, v183
	s_nop 0
	v_mul_f32_e32 v181, 0x45800000, v183
	v_cndmask_b32_e32 v184, v183, v181, vcc
	v_mov_b32_e32 v185, v184
	v_cvt_pk_bf16_f32 v0, v144, v145
	v_cvt_pk_bf16_f32 v1, v146, v147
	v_cvt_pk_bf16_f32 v2, v148, v149
	v_cvt_pk_bf16_f32 v3, v150, v151
	v_cvt_pk_bf16_f32 v4, v152, v153
	v_cvt_pk_bf16_f32 v5, v154, v155
	v_cvt_pk_bf16_f32 v6, v156, v157
	v_cvt_pk_bf16_f32 v7, v158, v159
	v_add_u32_e32 v181, 0x3800000, v177
	global_store_dwordx4 v181, v[0:3], s[78:79]
	global_store_dwordx4 v181, v[4:7], s[78:79] offset:1024
	v_add_u32_e32 v236, 0x10000, v237
	s_mov_b64 exec, 1
	global_store_dword v236, v184, s[78:79]
	s_mov_b64 exec, -1
.Lmyxupd_done_2:
.LBB0_1173:
	v_readlane_b32 s33, v234, 3

.LBB0_1430:
	v_readlane_b32 s0, v235, 52
	v_readlane_b32 s1, v235, 53
	s_and_b64 vcc, exec, s[0:1]
	s_waitcnt lgkmcnt(0)
	s_barrier
	v_mbcnt_lo_u32_b32 v0, -1, 0
	v_mbcnt_hi_u32_b32 v0, -1, v0
	s_cbranch_vccnz .LBB0_1450
	v_lshlrev_b32_e32 v2, 3, v0
	v_readlane_b32 s4, v235, 4
	v_ashrrev_i32_e32 v3, 31, v2
	v_readlane_b32 s6, v235, 6
	v_readlane_b32 s7, v235, 7
	v_lshlrev_b64 v[4:5], 1, v[2:3]
	v_lshlrev_b64 v[2:3], 2, v[2:3]
	v_readlane_b32 s5, v235, 5
	v_readlane_b32 s10, v235, 10
	v_readlane_b32 s11, v235, 11
	v_readlane_b32 s18, v235, 18
	v_readlane_b32 s19, v235, 19
	v_readlane_b32 s6, v235, 61
	v_lshl_add_u64 v[154:155], s[90:91], 0, v[2:3]
	v_readlane_b32 s8, v235, 8
	v_lshl_add_u64 v[2:3], s[18:19], 0, v[2:3]
	s_mov_b64 s[0:1], 0x1000
	v_readlane_b32 s4, v235, 0
	v_readlane_b32 s7, v235, 62
	s_mov_b32 s10, s6
	s_ashr_i32 s11, s6, 31
	v_readlane_b32 s9, v235, 9
	v_lshl_add_u64 v[158:159], v[2:3], 0, s[0:1]
	s_lshl_b32 s4, s4, 4
	s_add_i32 s0, s6, 0xffffc000
	s_lshl_b64 s[6:7], s[10:11], 2
	s_mov_b32 s8, s10
	v_readlane_b32 s12, v235, 12
	v_readlane_b32 s13, v235, 13
	v_readlane_b32 s14, v235, 14
	v_readlane_b32 s15, v235, 15
	v_readlane_b32 s16, v235, 16
	v_readlane_b32 s17, v235, 17
	v_readlane_b32 s5, v235, 1
	s_add_u32 s80, s6, 0x10000
	v_writelane_b32 v235, s8, 61
	s_addc_u32 s12, s7, 0
	s_ashr_i32 s5, s4, 31
	v_writelane_b32 v235, s9, 62
	s_lshl_b64 s[8:9], s[10:11], 11
	v_lshl_add_u64 v[152:153], s[86:87], 0, v[4:5]
	v_lshl_add_u64 v[156:157], s[54:55], 0, v[4:5]
	s_mov_b32 s1, 0
	v_cmp_eq_u32_e64 s[16:17], 0, v0
	s_lshl_b64 s[6:7], s[4:5], 2
	v_lshl_add_u64 v[160:161], s[8:9], 0, v[4:5]
	s_lshl_b64 s[8:9], s[4:5], 11
	s_mov_b64 s[20:21], 0x600000
	s_mov_b64 s[22:23], 0x600800
	s_mov_b64 s[24:25], 0x800000
	s_mov_b32 s5, 0x800000
	s_mov_b64 s[26:27], 0x800800
	s_mov_b64 s[28:29], 0xa00000
	s_mov_b64 s[36:37], 0xa00800
	s_mov_b64 s[38:39], 0xc00000
	s_mov_b64 s[40:41], 0xc00800
	s_mov_b64 s[42:43], 0xe00000
	s_mov_b64 s[44:45], 0xe00800
	s_mov_b64 s[46:47], 0x1000000
	s_mov_b32 s13, 0x1000000
	s_mov_b64 s[48:49], 0x1000800
	s_mov_b64 s[50:51], 0x1200000
	s_mov_b32 s14, 0x1200000
	s_mov_b64 s[10:11], 0x1200800
	s_mov_b64 s[82:83], 0x1400000
	s_mov_b32 s15, 0x1400000
	s_mov_b64 s[90:91], 0x1400800
	v_mov_b32_e32 v215, 0
	v_mov_b32_e32 v216, 0x358637bd
	v_mbcnt_lo_u32_b32 v176, -1, 0
	v_mbcnt_hi_u32_b32 v176, -1, v176
	v_readlane_b32 s98, v235, 49
	v_readlane_b32 s99, v235, 20
	v_readlane_b32 s100, v235, 18
	v_readlane_b32 s101, v235, 19
	s_nop 3
	s_lshr_b32 vcc_lo, s98, 3
	s_and_b32 vcc_hi, vcc_lo, 7
	s_lshl_b32 vcc_hi, vcc_hi, 8
	s_lshr_b32 vcc_lo, vcc_lo, 3
	s_lshl_b32 vcc_lo, vcc_lo, 3
	s_add_i32 s98, vcc_hi, vcc_lo
	s_add_i32 s98, s98, s99
	v_lshlrev_b32_e32 v177, 4, v176
	s_lshl_b32 s99, s98, 11
	v_add_u32_e32 v177, s99, v177
	v_add_u32_e32 v178, 0x1800000, v177
	v_add_u32_e32 v179, 0x9e00000, v177
	v_lshlrev_b32_e32 v180, 5, v176
	v_add_u32_e32 v181, 0x1000, v180
	global_load_dwordx4 v[128:131], v181, s[100:101]
	global_load_dwordx4 v[132:135], v181, s[100:101] offset:16
	global_load_dwordx4 v[136:139], v181, s[100:101] offset:2048
	global_load_dwordx4 v[140:143], v181, s[100:101] offset:2064
	v_mov_b32_e32 v182, 0x358637bd
	global_load_dwordx4 v[0:3], v178, s[78:79]
	global_load_dwordx4 v[4:7], v178, s[78:79] offset:1024
	global_load_dwordx4 v[8:11], v179, s[78:79]
	global_load_dwordx4 v[12:15], v179, s[78:79] offset:1024
	v_add_u32_e32 v178, 0x400000, v178
	v_add_u32_e32 v179, 0x400000, v179
	global_load_dwordx4 v[16:19], v178, s[78:79]
	global_load_dwordx4 v[20:23], v178, s[78:79] offset:1024
	global_load_dwordx4 v[24:27], v179, s[78:79]
	global_load_dwordx4 v[28:31], v179, s[78:79] offset:1024
	v_add_u32_e32 v178, 0x400000, v178
	v_add_u32_e32 v179, 0x400000, v179
	global_load_dwordx4 v[32:35], v178, s[78:79]
	global_load_dwordx4 v[36:39], v178, s[78:79] offset:1024
	global_load_dwordx4 v[40:43], v179, s[78:79]
	global_load_dwordx4 v[44:47], v179, s[78:79] offset:1024
	v_add_u32_e32 v178, 0x400000, v178
	v_add_u32_e32 v179, 0x400000, v179
	global_load_dwordx4 v[48:51], v178, s[78:79]
	global_load_dwordx4 v[52:55], v178, s[78:79] offset:1024
	global_load_dwordx4 v[56:59], v179, s[78:79]
	global_load_dwordx4 v[60:63], v179, s[78:79] offset:1024
	v_add_u32_e32 v178, 0x400000, v178
	v_add_u32_e32 v179, 0x400000, v179
	global_load_dwordx4 v[64:67], v178, s[78:79]
	global_load_dwordx4 v[68:71], v178, s[78:79] offset:1024
	global_load_dwordx4 v[72:75], v179, s[78:79]
	global_load_dwordx4 v[76:79], v179, s[78:79] offset:1024
	v_add_u32_e32 v178, 0x400000, v178
	v_add_u32_e32 v179, 0x400000, v179
	global_load_dwordx4 v[80:83], v178, s[78:79]
	global_load_dwordx4 v[84:87], v178, s[78:79] offset:1024
	global_load_dwordx4 v[88:91], v179, s[78:79]
	global_load_dwordx4 v[92:95], v179, s[78:79] offset:1024
	v_add_u32_e32 v178, 0x400000, v178
	v_add_u32_e32 v179, 0x400000, v179
	global_load_dwordx4 v[96:99], v178, s[78:79]
	global_load_dwordx4 v[100:103], v178, s[78:79] offset:1024
	global_load_dwordx4 v[104:107], v179, s[78:79]
	global_load_dwordx4 v[108:111], v179, s[78:79] offset:1024
	v_add_u32_e32 v178, 0x400000, v178
	v_add_u32_e32 v179, 0x400000, v179
	global_load_dwordx4 v[112:115], v178, s[78:79]
	global_load_dwordx4 v[116:119], v178, s[78:79] offset:1024
	global_load_dwordx4 v[120:123], v179, s[78:79]
	global_load_dwordx4 v[124:127], v179, s[78:79] offset:1024
	v_mov_b32_e32 v183, s98
	v_lshlrev_b32_e32 v237, 2, v183
	v_add_u32_e32 v237, 0x10000, v237
	v_mov_b32_e32 v179, v183
	s_waitcnt vmcnt(28)
	v_lshlrev_b32_e32 v144, 16, v0
	v_and_b32_e32 v145, 0xffff0000, v0
	v_lshlrev_b32_e32 v146, 16, v1
	v_and_b32_e32 v147, 0xffff0000, v1
	v_lshlrev_b32_e32 v148, 16, v2
	v_and_b32_e32 v149, 0xffff0000, v2
	v_lshlrev_b32_e32 v150, 16, v3
	v_and_b32_e32 v151, 0xffff0000, v3
	v_lshlrev_b32_e32 v152, 16, v4
	v_and_b32_e32 v153, 0xffff0000, v4
	v_lshlrev_b32_e32 v154, 16, v5
	v_and_b32_e32 v155, 0xffff0000, v5
	v_lshlrev_b32_e32 v156, 16, v6
	v_and_b32_e32 v157, 0xffff0000, v6
	v_lshlrev_b32_e32 v158, 16, v7
	v_and_b32_e32 v159, 0xffff0000, v7
	v_lshlrev_b32_e32 v160, 16, v8
	v_and_b32_e32 v161, 0xffff0000, v8
	v_lshlrev_b32_e32 v162, 16, v9
	v_and_b32_e32 v163, 0xffff0000, v9
	v_lshlrev_b32_e32 v164, 16, v10
	v_and_b32_e32 v165, 0xffff0000, v10
	v_lshlrev_b32_e32 v166, 16, v11
	v_and_b32_e32 v167, 0xffff0000, v11
	v_lshlrev_b32_e32 v168, 16, v12
	v_and_b32_e32 v169, 0xffff0000, v12
	v_lshlrev_b32_e32 v170, 16, v13
	v_and_b32_e32 v171, 0xffff0000, v13
	v_lshlrev_b32_e32 v172, 16, v14
	v_and_b32_e32 v173, 0xffff0000, v14
	v_lshlrev_b32_e32 v174, 16, v15
	v_and_b32_e32 v175, 0xffff0000, v15
	v_pk_mul_f32 v[252:253], v[160:161], v[160:161]
	v_pk_mul_f32 v[254:255], v[162:163], v[162:163]
	v_pk_fma_f32 v[252:253], v[164:165], v[164:165], v[252:253]
	v_pk_fma_f32 v[254:255], v[166:167], v[166:167], v[254:255]
	v_pk_fma_f32 v[252:253], v[168:169], v[168:169], v[252:253]
	v_pk_fma_f32 v[254:255], v[170:171], v[170:171], v[254:255]
	v_pk_fma_f32 v[252:253], v[172:173], v[172:173], v[252:253]
	v_pk_fma_f32 v[254:255], v[174:175], v[174:175], v[254:255]
	v_pk_add_f32 v[252:253], v[252:253], v[254:255]
	s_nop 0
	v_add_f32_e32 v183, v252, v253
	s_nop 1
	v_add_f32_dpp v183, v183, v183 quad_perm:[1,0,3,2] row_mask:0xf bank_mask:0xf bound_ctrl:1
	s_nop 1
	v_add_f32_dpp v183, v183, v183 quad_perm:[2,3,0,1] row_mask:0xf bank_mask:0xf bound_ctrl:1
	s_nop 1
	v_add_f32_dpp v183, v183, v183 row_half_mirror row_mask:0xf bank_mask:0xf bound_ctrl:1
	s_nop 1
	v_add_f32_dpp v183, v183, v183 row_mirror row_mask:0xf bank_mask:0xf bound_ctrl:1
	s_nop 1
	v_readlane_b32 s98, v183, 0
	v_readlane_b32 s99, v183, 16
	v_readlane_b32 s100, v183, 32
	v_readlane_b32 s101, v183, 48
	s_nop 1
	v_mov_b32_e32 v183, s98
	v_add_f32_e32 v183, s99, v183
	v_add_f32_e32 v183, s100, v183
	v_add_f32_e32 v183, s101, v183
	v_fmamk_f32 v183, v183, 0x3a800000, v182
	v_cmp_gt_f32_e32 vcc, 0x800000, v183
	v_mul_f32_e32 v181, 0x4b800000, v183
	s_nop 1
	v_cndmask_b32_e32 v183, v183, v181, vcc
	v_rsq_f32_e32 v183, v183
	s_nop 0
	v_mul_f32_e32 v181, 0x45800000, v183
	v_cndmask_b32_e32 v184, v183, v181, vcc
	v_mov_b32_e32 v185, v184
	v_pk_mul_f32 v[160:161], v[160:161], v[184:185]
	v_pk_mul_f32 v[162:163], v[162:163], v[184:185]
	v_pk_mul_f32 v[164:165], v[164:165], v[184:185]
	v_pk_mul_f32 v[166:167], v[166:167], v[184:185]
	v_pk_mul_f32 v[168:169], v[168:169], v[184:185]
	v_pk_mul_f32 v[170:171], v[170:171], v[184:185]
	v_pk_mul_f32 v[172:173], v[172:173], v[184:185]
	v_pk_mul_f32 v[174:175], v[174:175], v[184:185]
	v_pk_fma_f32 v[144:145], v[160:161], v[128:129], v[144:145]
	v_pk_fma_f32 v[146:147], v[162:163], v[130:131], v[146:147]
	v_pk_fma_f32 v[148:149], v[164:165], v[132:133], v[148:149]
	v_pk_fma_f32 v[150:151], v[166:167], v[134:135], v[150:151]
	v_pk_fma_f32 v[152:153], v[168:169], v[136:137], v[152:153]
	v_pk_fma_f32 v[154:155], v[170:171], v[138:139], v[154:155]
	v_pk_fma_f32 v[156:157], v[172:173], v[140:141], v[156:157]
	v_pk_fma_f32 v[158:159], v[174:175], v[142:143], v[158:159]
	v_pk_mul_f32 v[252:253], v[144:145], v[144:145]
	v_pk_mul_f32 v[254:255], v[146:147], v[146:147]
	v_pk_fma_f32 v[252:253], v[148:149], v[148:149], v[252:253]
	v_pk_fma_f32 v[254:255], v[150:151], v[150:151], v[254:255]
	v_pk_fma_f32 v[252:253], v[152:153], v[152:153], v[252:253]
	v_pk_fma_f32 v[254:255], v[154:155], v[154:155], v[254:255]
	v_pk_fma_f32 v[252:253], v[156:157], v[156:157], v[252:253]
	v_pk_fma_f32 v[254:255], v[158:159], v[158:159], v[254:255]
	v_pk_add_f32 v[252:253], v[252:253], v[254:255]
	s_nop 0
	v_add_f32_e32 v183, v252, v253
	s_nop 1
	v_add_f32_dpp v183, v183, v183 quad_perm:[1,0,3,2] row_mask:0xf bank_mask:0xf bound_ctrl:1
	s_nop 1
	v_add_f32_dpp v183, v183, v183 quad_perm:[2,3,0,1] row_mask:0xf bank_mask:0xf bound_ctrl:1
	s_nop 1
	v_add_f32_dpp v183, v183, v183 row_half_mirror row_mask:0xf bank_mask:0xf bound_ctrl:1
	s_nop 1
	v_add_f32_dpp v183, v183, v183 row_mirror row_mask:0xf bank_mask:0xf bound_ctrl:1
	s_nop 1
	v_readlane_b32 s98, v183, 0
	v_readlane_b32 s99, v183, 16
	v_readlane_b32 s100, v183, 32
	v_readlane_b32 s101, v183, 48
	s_nop 1
	v_mov_b32_e32 v183, s98
	v_add_f32_e32 v183, s99, v183
	v_add_f32_e32 v183, s100, v183
	v_add_f32_e32 v183, s101, v183
	v_fmamk_f32 v183, v183, 0x3a800000, v182
	v_cmp_gt_f32_e32 vcc, 0x800000, v183
	v_mul_f32_e32 v181, 0x4b800000, v183
	s_nop 1
	v_cndmask_b32_e32 v183, v183, v181, vcc
	v_rsq_f32_e32 v183, v183
	s_nop 0
	v_mul_f32_e32 v181, 0x45800000, v183
	v_cndmask_b32_e32 v184, v183, v181, vcc
	v_mov_b32_e32 v185, v184
	v_cvt_pk_bf16_f32 v0, v144, v145
	v_cvt_pk_bf16_f32 v1, v146, v147
	v_cvt_pk_bf16_f32 v2, v148, v149
	v_cvt_pk_bf16_f32 v3, v150, v151
	v_cvt_pk_bf16_f32 v4, v152, v153
	v_cvt_pk_bf16_f32 v5, v154, v155
	v_cvt_pk_bf16_f32 v6, v156, v157
	v_cvt_pk_bf16_f32 v7, v158, v159
	v_add_u32_e32 v181, 0x1800000, v177
	global_store_dwordx4 v181, v[0:3], s[78:79]
	global_store_dwordx4 v181, v[4:7], s[78:79] offset:1024
	v_add_u32_e32 v236, 0x0, v237
	s_mov_b64 exec, 1
	global_store_dword v236, v184, s[78:79]
	s_mov_b64 exec, -1
	s_waitcnt vmcnt(24)
	v_lshlrev_b32_e32 v144, 16, v16
	v_and_b32_e32 v145, 0xffff0000, v16
	v_lshlrev_b32_e32 v146, 16, v17
	v_and_b32_e32 v147, 0xffff0000, v17
	v_lshlrev_b32_e32 v148, 16, v18
	v_and_b32_e32 v149, 0xffff0000, v18
	v_lshlrev_b32_e32 v150, 16, v19
	v_and_b32_e32 v151, 0xffff0000, v19
	v_lshlrev_b32_e32 v152, 16, v20
	v_and_b32_e32 v153, 0xffff0000, v20
	v_lshlrev_b32_e32 v154, 16, v21
	v_and_b32_e32 v155, 0xffff0000, v21
	v_lshlrev_b32_e32 v156, 16, v22
	v_and_b32_e32 v157, 0xffff0000, v22
	v_lshlrev_b32_e32 v158, 16, v23
	v_and_b32_e32 v159, 0xffff0000, v23
	v_lshlrev_b32_e32 v160, 16, v24
	v_and_b32_e32 v161, 0xffff0000, v24
	v_lshlrev_b32_e32 v162, 16, v25
	v_and_b32_e32 v163, 0xffff0000, v25
	v_lshlrev_b32_e32 v164, 16, v26
	v_and_b32_e32 v165, 0xffff0000, v26
	v_lshlrev_b32_e32 v166, 16, v27
	v_and_b32_e32 v167, 0xffff0000, v27
	v_lshlrev_b32_e32 v168, 16, v28
	v_and_b32_e32 v169, 0xffff0000, v28
	v_lshlrev_b32_e32 v170, 16, v29
	v_and_b32_e32 v171, 0xffff0000, v29
	v_lshlrev_b32_e32 v172, 16, v30
	v_and_b32_e32 v173, 0xffff0000, v30
	v_lshlrev_b32_e32 v174, 16, v31
	v_and_b32_e32 v175, 0xffff0000, v31
	v_pk_mul_f32 v[252:253], v[160:161], v[160:161]
	v_pk_mul_f32 v[254:255], v[162:163], v[162:163]
	v_pk_fma_f32 v[252:253], v[164:165], v[164:165], v[252:253]
	v_pk_fma_f32 v[254:255], v[166:167], v[166:167], v[254:255]
	v_pk_fma_f32 v[252:253], v[168:169], v[168:169], v[252:253]
	v_pk_fma_f32 v[254:255], v[170:171], v[170:171], v[254:255]
	v_pk_fma_f32 v[252:253], v[172:173], v[172:173], v[252:253]
	v_pk_fma_f32 v[254:255], v[174:175], v[174:175], v[254:255]
	v_pk_add_f32 v[252:253], v[252:253], v[254:255]
	s_nop 0
	v_add_f32_e32 v183, v252, v253
	s_nop 1
	v_add_f32_dpp v183, v183, v183 quad_perm:[1,0,3,2] row_mask:0xf bank_mask:0xf bound_ctrl:1
	s_nop 1
	v_add_f32_dpp v183, v183, v183 quad_perm:[2,3,0,1] row_mask:0xf bank_mask:0xf bound_ctrl:1
	s_nop 1
	v_add_f32_dpp v183, v183, v183 row_half_mirror row_mask:0xf bank_mask:0xf bound_ctrl:1
	s_nop 1
	v_add_f32_dpp v183, v183, v183 row_mirror row_mask:0xf bank_mask:0xf bound_ctrl:1
	s_nop 1
	v_readlane_b32 s98, v183, 0
	v_readlane_b32 s99, v183, 16
	v_readlane_b32 s100, v183, 32
	v_readlane_b32 s101, v183, 48
	s_nop 1
	v_mov_b32_e32 v183, s98
	v_add_f32_e32 v183, s99, v183
	v_add_f32_e32 v183, s100, v183
	v_add_f32_e32 v183, s101, v183
	v_fmamk_f32 v183, v183, 0x3a800000, v182
	v_cmp_gt_f32_e32 vcc, 0x800000, v183
	v_mul_f32_e32 v181, 0x4b800000, v183
	s_nop 1
	v_cndmask_b32_e32 v183, v183, v181, vcc
	v_rsq_f32_e32 v183, v183
	s_nop 0
	v_mul_f32_e32 v181, 0x45800000, v183
	v_cndmask_b32_e32 v184, v183, v181, vcc
	v_mov_b32_e32 v185, v184
	v_pk_mul_f32 v[160:161], v[160:161], v[184:185]
	v_pk_mul_f32 v[162:163], v[162:163], v[184:185]
	v_pk_mul_f32 v[164:165], v[164:165], v[184:185]
	v_pk_mul_f32 v[166:167], v[166:167], v[184:185]
	v_pk_mul_f32 v[168:169], v[168:169], v[184:185]
	v_pk_mul_f32 v[170:171], v[170:171], v[184:185]
	v_pk_mul_f32 v[172:173], v[172:173], v[184:185]
	v_pk_mul_f32 v[174:175], v[174:175], v[184:185]
	v_pk_fma_f32 v[144:145], v[160:161], v[128:129], v[144:145]
	v_pk_fma_f32 v[146:147], v[162:163], v[130:131], v[146:147]
	v_pk_fma_f32 v[148:149], v[164:165], v[132:133], v[148:149]
	v_pk_fma_f32 v[150:151], v[166:167], v[134:135], v[150:151]
	v_pk_fma_f32 v[152:153], v[168:169], v[136:137], v[152:153]
	v_pk_fma_f32 v[154:155], v[170:171], v[138:139], v[154:155]
	v_pk_fma_f32 v[156:157], v[172:173], v[140:141], v[156:157]
	v_pk_fma_f32 v[158:159], v[174:175], v[142:143], v[158:159]
	v_pk_mul_f32 v[252:253], v[144:145], v[144:145]
	v_pk_mul_f32 v[254:255], v[146:147], v[146:147]
	v_pk_fma_f32 v[252:253], v[148:149], v[148:149], v[252:253]
	v_pk_fma_f32 v[254:255], v[150:151], v[150:151], v[254:255]
	v_pk_fma_f32 v[252:253], v[152:153], v[152:153], v[252:253]
	v_pk_fma_f32 v[254:255], v[154:155], v[154:155], v[254:255]
	v_pk_fma_f32 v[252:253], v[156:157], v[156:157], v[252:253]
	v_pk_fma_f32 v[254:255], v[158:159], v[158:159], v[254:255]
	v_pk_add_f32 v[252:253], v[252:253], v[254:255]
	s_nop 0
	v_add_f32_e32 v183, v252, v253
	s_nop 1
	v_add_f32_dpp v183, v183, v183 quad_perm:[1,0,3,2] row_mask:0xf bank_mask:0xf bound_ctrl:1
	s_nop 1
	v_add_f32_dpp v183, v183, v183 quad_perm:[2,3,0,1] row_mask:0xf bank_mask:0xf bound_ctrl:1
	s_nop 1
	v_add_f32_dpp v183, v183, v183 row_half_mirror row_mask:0xf bank_mask:0xf bound_ctrl:1
	s_nop 1
	v_add_f32_dpp v183, v183, v183 row_mirror row_mask:0xf bank_mask:0xf bound_ctrl:1
	s_nop 1
	v_readlane_b32 s98, v183, 0
	v_readlane_b32 s99, v183, 16
	v_readlane_b32 s100, v183, 32
	v_readlane_b32 s101, v183, 48
	s_nop 1
	v_mov_b32_e32 v183, s98
	v_add_f32_e32 v183, s99, v183
	v_add_f32_e32 v183, s100, v183
	v_add_f32_e32 v183, s101, v183
	v_fmamk_f32 v183, v183, 0x3a800000, v182
	v_cmp_gt_f32_e32 vcc, 0x800000, v183
	v_mul_f32_e32 v181, 0x4b800000, v183
	s_nop 1
	v_cndmask_b32_e32 v183, v183, v181, vcc
	v_rsq_f32_e32 v183, v183
	s_nop 0
	v_mul_f32_e32 v181, 0x45800000, v183
	v_cndmask_b32_e32 v184, v183, v181, vcc
	v_mov_b32_e32 v185, v184
	v_cvt_pk_bf16_f32 v16, v144, v145
	v_cvt_pk_bf16_f32 v17, v146, v147
	v_cvt_pk_bf16_f32 v18, v148, v149
	v_cvt_pk_bf16_f32 v19, v150, v151
	v_cvt_pk_bf16_f32 v20, v152, v153
	v_cvt_pk_bf16_f32 v21, v154, v155
	v_cvt_pk_bf16_f32 v22, v156, v157
	v_cvt_pk_bf16_f32 v23, v158, v159
	v_add_u32_e32 v181, 0x1c00000, v177
	global_store_dwordx4 v181, v[16:19], s[78:79]
	global_store_dwordx4 v181, v[20:23], s[78:79] offset:1024
	v_add_u32_e32 v236, 0x2000, v237
	s_mov_b64 exec, 1
	global_store_dword v236, v184, s[78:79]
	s_mov_b64 exec, -1
	s_waitcnt vmcnt(20)
	v_lshlrev_b32_e32 v144, 16, v32
	v_and_b32_e32 v145, 0xffff0000, v32
	v_lshlrev_b32_e32 v146, 16, v33
	v_and_b32_e32 v147, 0xffff0000, v33
	v_lshlrev_b32_e32 v148, 16, v34
	v_and_b32_e32 v149, 0xffff0000, v34
	v_lshlrev_b32_e32 v150, 16, v35
	v_and_b32_e32 v151, 0xffff0000, v35
	v_lshlrev_b32_e32 v152, 16, v36
	v_and_b32_e32 v153, 0xffff0000, v36
	v_lshlrev_b32_e32 v154, 16, v37
	v_and_b32_e32 v155, 0xffff0000, v37
	v_lshlrev_b32_e32 v156, 16, v38
	v_and_b32_e32 v157, 0xffff0000, v38
	v_lshlrev_b32_e32 v158, 16, v39
	v_and_b32_e32 v159, 0xffff0000, v39
	v_lshlrev_b32_e32 v160, 16, v40
	v_and_b32_e32 v161, 0xffff0000, v40
	v_lshlrev_b32_e32 v162, 16, v41
	v_and_b32_e32 v163, 0xffff0000, v41
	v_lshlrev_b32_e32 v164, 16, v42
	v_and_b32_e32 v165, 0xffff0000, v42
	v_lshlrev_b32_e32 v166, 16, v43
	v_and_b32_e32 v167, 0xffff0000, v43
	v_lshlrev_b32_e32 v168, 16, v44
	v_and_b32_e32 v169, 0xffff0000, v44
	v_lshlrev_b32_e32 v170, 16, v45
	v_and_b32_e32 v171, 0xffff0000, v45
	v_lshlrev_b32_e32 v172, 16, v46
	v_and_b32_e32 v173, 0xffff0000, v46
	v_lshlrev_b32_e32 v174, 16, v47
	v_and_b32_e32 v175, 0xffff0000, v47
	v_pk_mul_f32 v[252:253], v[160:161], v[160:161]
	v_pk_mul_f32 v[254:255], v[162:163], v[162:163]
	v_pk_fma_f32 v[252:253], v[164:165], v[164:165], v[252:253]
	v_pk_fma_f32 v[254:255], v[166:167], v[166:167], v[254:255]
	v_pk_fma_f32 v[252:253], v[168:169], v[168:169], v[252:253]
	v_pk_fma_f32 v[254:255], v[170:171], v[170:171], v[254:255]
	v_pk_fma_f32 v[252:253], v[172:173], v[172:173], v[252:253]
	v_pk_fma_f32 v[254:255], v[174:175], v[174:175], v[254:255]
	v_pk_add_f32 v[252:253], v[252:253], v[254:255]
	s_nop 0
	v_add_f32_e32 v183, v252, v253
	s_nop 1
	v_add_f32_dpp v183, v183, v183 quad_perm:[1,0,3,2] row_mask:0xf bank_mask:0xf bound_ctrl:1
	s_nop 1
	v_add_f32_dpp v183, v183, v183 quad_perm:[2,3,0,1] row_mask:0xf bank_mask:0xf bound_ctrl:1
	s_nop 1
	v_add_f32_dpp v183, v183, v183 row_half_mirror row_mask:0xf bank_mask:0xf bound_ctrl:1
	s_nop 1
	v_add_f32_dpp v183, v183, v183 row_mirror row_mask:0xf bank_mask:0xf bound_ctrl:1
	s_nop 1
	v_readlane_b32 s98, v183, 0
	v_readlane_b32 s99, v183, 16
	v_readlane_b32 s100, v183, 32
	v_readlane_b32 s101, v183, 48
	s_nop 1
	v_mov_b32_e32 v183, s98
	v_add_f32_e32 v183, s99, v183
	v_add_f32_e32 v183, s100, v183
	v_add_f32_e32 v183, s101, v183
	v_fmamk_f32 v183, v183, 0x3a800000, v182
	v_cmp_gt_f32_e32 vcc, 0x800000, v183
	v_mul_f32_e32 v181, 0x4b800000, v183
	s_nop 1
	v_cndmask_b32_e32 v183, v183, v181, vcc
	v_rsq_f32_e32 v183, v183
	s_nop 0
	v_mul_f32_e32 v181, 0x45800000, v183
	v_cndmask_b32_e32 v184, v183, v181, vcc
	v_mov_b32_e32 v185, v184
	v_pk_mul_f32 v[160:161], v[160:161], v[184:185]
	v_pk_mul_f32 v[162:163], v[162:163], v[184:185]
	v_pk_mul_f32 v[164:165], v[164:165], v[184:185]
	v_pk_mul_f32 v[166:167], v[166:167], v[184:185]
	v_pk_mul_f32 v[168:169], v[168:169], v[184:185]
	v_pk_mul_f32 v[170:171], v[170:171], v[184:185]
	v_pk_mul_f32 v[172:173], v[172:173], v[184:185]
	v_pk_mul_f32 v[174:175], v[174:175], v[184:185]
	v_pk_fma_f32 v[144:145], v[160:161], v[128:129], v[144:145]
	v_pk_fma_f32 v[146:147], v[162:163], v[130:131], v[146:147]
	v_pk_fma_f32 v[148:149], v[164:165], v[132:133], v[148:149]
	v_pk_fma_f32 v[150:151], v[166:167], v[134:135], v[150:151]
	v_pk_fma_f32 v[152:153], v[168:169], v[136:137], v[152:153]
	v_pk_fma_f32 v[154:155], v[170:171], v[138:139], v[154:155]
	v_pk_fma_f32 v[156:157], v[172:173], v[140:141], v[156:157]
	v_pk_fma_f32 v[158:159], v[174:175], v[142:143], v[158:159]
	v_pk_mul_f32 v[252:253], v[144:145], v[144:145]
	v_pk_mul_f32 v[254:255], v[146:147], v[146:147]
	v_pk_fma_f32 v[252:253], v[148:149], v[148:149], v[252:253]
	v_pk_fma_f32 v[254:255], v[150:151], v[150:151], v[254:255]
	v_pk_fma_f32 v[252:253], v[152:153], v[152:153], v[252:253]
	v_pk_fma_f32 v[254:255], v[154:155], v[154:155], v[254:255]
	v_pk_fma_f32 v[252:253], v[156:157], v[156:157], v[252:253]
	v_pk_fma_f32 v[254:255], v[158:159], v[158:159], v[254:255]
	v_pk_add_f32 v[252:253], v[252:253], v[254:255]
	s_nop 0
	v_add_f32_e32 v183, v252, v253
	s_nop 1
	v_add_f32_dpp v183, v183, v183 quad_perm:[1,0,3,2] row_mask:0xf bank_mask:0xf bound_ctrl:1
	s_nop 1
	v_add_f32_dpp v183, v183, v183 quad_perm:[2,3,0,1] row_mask:0xf bank_mask:0xf bound_ctrl:1
	s_nop 1
	v_add_f32_dpp v183, v183, v183 row_half_mirror row_mask:0xf bank_mask:0xf bound_ctrl:1
	s_nop 1
	v_add_f32_dpp v183, v183, v183 row_mirror row_mask:0xf bank_mask:0xf bound_ctrl:1
	s_nop 1
	v_readlane_b32 s98, v183, 0
	v_readlane_b32 s99, v183, 16
	v_readlane_b32 s100, v183, 32
	v_readlane_b32 s101, v183, 48
	s_nop 1
	v_mov_b32_e32 v183, s98
	v_add_f32_e32 v183, s99, v183
	v_add_f32_e32 v183, s100, v183
	v_add_f32_e32 v183, s101, v183
	v_fmamk_f32 v183, v183, 0x3a800000, v182
	v_cmp_gt_f32_e32 vcc, 0x800000, v183
	v_mul_f32_e32 v181, 0x4b800000, v183
	s_nop 1
	v_cndmask_b32_e32 v183, v183, v181, vcc
	v_rsq_f32_e32 v183, v183
	s_nop 0
	v_mul_f32_e32 v181, 0x45800000, v183
	v_cndmask_b32_e32 v184, v183, v181, vcc
	v_mov_b32_e32 v185, v184
	v_cvt_pk_bf16_f32 v32, v144, v145
	v_cvt_pk_bf16_f32 v33, v146, v147
	v_cvt_pk_bf16_f32 v34, v148, v149
	v_cvt_pk_bf16_f32 v35, v150, v151
	v_cvt_pk_bf16_f32 v36, v152, v153
	v_cvt_pk_bf16_f32 v37, v154, v155
	v_cvt_pk_bf16_f32 v38, v156, v157
	v_cvt_pk_bf16_f32 v39, v158, v159
	v_add_u32_e32 v181, 0x2000000, v177
	global_store_dwordx4 v181, v[32:35], s[78:79]
	global_store_dwordx4 v181, v[36:39], s[78:79] offset:1024
	v_add_u32_e32 v236, 0x4000, v237
	s_mov_b64 exec, 1
	global_store_dword v236, v184, s[78:79]
	s_mov_b64 exec, -1
	s_waitcnt vmcnt(16)
	v_lshlrev_b32_e32 v144, 16, v48
	v_and_b32_e32 v145, 0xffff0000, v48
	v_lshlrev_b32_e32 v146, 16, v49
	v_and_b32_e32 v147, 0xffff0000, v49
	v_lshlrev_b32_e32 v148, 16, v50
	v_and_b32_e32 v149, 0xffff0000, v50
	v_lshlrev_b32_e32 v150, 16, v51
	v_and_b32_e32 v151, 0xffff0000, v51
	v_lshlrev_b32_e32 v152, 16, v52
	v_and_b32_e32 v153, 0xffff0000, v52
	v_lshlrev_b32_e32 v154, 16, v53
	v_and_b32_e32 v155, 0xffff0000, v53
	v_lshlrev_b32_e32 v156, 16, v54
	v_and_b32_e32 v157, 0xffff0000, v54
	v_lshlrev_b32_e32 v158, 16, v55
	v_and_b32_e32 v159, 0xffff0000, v55
	v_lshlrev_b32_e32 v160, 16, v56
	v_and_b32_e32 v161, 0xffff0000, v56
	v_lshlrev_b32_e32 v162, 16, v57
	v_and_b32_e32 v163, 0xffff0000, v57
	v_lshlrev_b32_e32 v164, 16, v58
	v_and_b32_e32 v165, 0xffff0000, v58
	v_lshlrev_b32_e32 v166, 16, v59
	v_and_b32_e32 v167, 0xffff0000, v59
	v_lshlrev_b32_e32 v168, 16, v60
	v_and_b32_e32 v169, 0xffff0000, v60
	v_lshlrev_b32_e32 v170, 16, v61
	v_and_b32_e32 v171, 0xffff0000, v61
	v_lshlrev_b32_e32 v172, 16, v62
	v_and_b32_e32 v173, 0xffff0000, v62
	v_lshlrev_b32_e32 v174, 16, v63
	v_and_b32_e32 v175, 0xffff0000, v63
	v_pk_mul_f32 v[252:253], v[160:161], v[160:161]
	v_pk_mul_f32 v[254:255], v[162:163], v[162:163]
	v_pk_fma_f32 v[252:253], v[164:165], v[164:165], v[252:253]
	v_pk_fma_f32 v[254:255], v[166:167], v[166:167], v[254:255]
	v_pk_fma_f32 v[252:253], v[168:169], v[168:169], v[252:253]
	v_pk_fma_f32 v[254:255], v[170:171], v[170:171], v[254:255]
	v_pk_fma_f32 v[252:253], v[172:173], v[172:173], v[252:253]
	v_pk_fma_f32 v[254:255], v[174:175], v[174:175], v[254:255]
	v_pk_add_f32 v[252:253], v[252:253], v[254:255]
	s_nop 0
	v_add_f32_e32 v183, v252, v253
	s_nop 1
	v_add_f32_dpp v183, v183, v183 quad_perm:[1,0,3,2] row_mask:0xf bank_mask:0xf bound_ctrl:1
	s_nop 1
	v_add_f32_dpp v183, v183, v183 quad_perm:[2,3,0,1] row_mask:0xf bank_mask:0xf bound_ctrl:1
	s_nop 1
	v_add_f32_dpp v183, v183, v183 row_half_mirror row_mask:0xf bank_mask:0xf bound_ctrl:1
	s_nop 1
	v_add_f32_dpp v183, v183, v183 row_mirror row_mask:0xf bank_mask:0xf bound_ctrl:1
	s_nop 1
	v_readlane_b32 s98, v183, 0
	v_readlane_b32 s99, v183, 16
	v_readlane_b32 s100, v183, 32
	v_readlane_b32 s101, v183, 48
	s_nop 1
	v_mov_b32_e32 v183, s98
	v_add_f32_e32 v183, s99, v183
	v_add_f32_e32 v183, s100, v183
	v_add_f32_e32 v183, s101, v183
	v_fmamk_f32 v183, v183, 0x3a800000, v182
	v_cmp_gt_f32_e32 vcc, 0x800000, v183
	v_mul_f32_e32 v181, 0x4b800000, v183
	s_nop 1
	v_cndmask_b32_e32 v183, v183, v181, vcc
	v_rsq_f32_e32 v183, v183
	s_nop 0
	v_mul_f32_e32 v181, 0x45800000, v183
	v_cndmask_b32_e32 v184, v183, v181, vcc
	v_mov_b32_e32 v185, v184
	v_pk_mul_f32 v[160:161], v[160:161], v[184:185]
	v_pk_mul_f32 v[162:163], v[162:163], v[184:185]
	v_pk_mul_f32 v[164:165], v[164:165], v[184:185]
	v_pk_mul_f32 v[166:167], v[166:167], v[184:185]
	v_pk_mul_f32 v[168:169], v[168:169], v[184:185]
	v_pk_mul_f32 v[170:171], v[170:171], v[184:185]
	v_pk_mul_f32 v[172:173], v[172:173], v[184:185]
	v_pk_mul_f32 v[174:175], v[174:175], v[184:185]
	v_pk_fma_f32 v[144:145], v[160:161], v[128:129], v[144:145]
	v_pk_fma_f32 v[146:147], v[162:163], v[130:131], v[146:147]
	v_pk_fma_f32 v[148:149], v[164:165], v[132:133], v[148:149]
	v_pk_fma_f32 v[150:151], v[166:167], v[134:135], v[150:151]
	v_pk_fma_f32 v[152:153], v[168:169], v[136:137], v[152:153]
	v_pk_fma_f32 v[154:155], v[170:171], v[138:139], v[154:155]
	v_pk_fma_f32 v[156:157], v[172:173], v[140:141], v[156:157]
	v_pk_fma_f32 v[158:159], v[174:175], v[142:143], v[158:159]
	v_pk_mul_f32 v[252:253], v[144:145], v[144:145]
	v_pk_mul_f32 v[254:255], v[146:147], v[146:147]
	v_pk_fma_f32 v[252:253], v[148:149], v[148:149], v[252:253]
	v_pk_fma_f32 v[254:255], v[150:151], v[150:151], v[254:255]
	v_pk_fma_f32 v[252:253], v[152:153], v[152:153], v[252:253]
	v_pk_fma_f32 v[254:255], v[154:155], v[154:155], v[254:255]
	v_pk_fma_f32 v[252:253], v[156:157], v[156:157], v[252:253]
	v_pk_fma_f32 v[254:255], v[158:159], v[158:159], v[254:255]
	v_pk_add_f32 v[252:253], v[252:253], v[254:255]
	s_nop 0
	v_add_f32_e32 v183, v252, v253
	s_nop 1
	v_add_f32_dpp v183, v183, v183 quad_perm:[1,0,3,2] row_mask:0xf bank_mask:0xf bound_ctrl:1
	s_nop 1
	v_add_f32_dpp v183, v183, v183 quad_perm:[2,3,0,1] row_mask:0xf bank_mask:0xf bound_ctrl:1
	s_nop 1
	v_add_f32_dpp v183, v183, v183 row_half_mirror row_mask:0xf bank_mask:0xf bound_ctrl:1
	s_nop 1
	v_add_f32_dpp v183, v183, v183 row_mirror row_mask:0xf bank_mask:0xf bound_ctrl:1
	s_nop 1
	v_readlane_b32 s98, v183, 0
	v_readlane_b32 s99, v183, 16
	v_readlane_b32 s100, v183, 32
	v_readlane_b32 s101, v183, 48
	s_nop 1
	v_mov_b32_e32 v183, s98
	v_add_f32_e32 v183, s99, v183
	v_add_f32_e32 v183, s100, v183
	v_add_f32_e32 v183, s101, v183
	v_fmamk_f32 v183, v183, 0x3a800000, v182
	v_cmp_gt_f32_e32 vcc, 0x800000, v183
	v_mul_f32_e32 v181, 0x4b800000, v183
	s_nop 1
	v_cndmask_b32_e32 v183, v183, v181, vcc
	v_rsq_f32_e32 v183, v183
	s_nop 0
	v_mul_f32_e32 v181, 0x45800000, v183
	v_cndmask_b32_e32 v184, v183, v181, vcc
	v_mov_b32_e32 v185, v184
	v_cvt_pk_bf16_f32 v48, v144, v145
	v_cvt_pk_bf16_f32 v49, v146, v147
	v_cvt_pk_bf16_f32 v50, v148, v149
	v_cvt_pk_bf16_f32 v51, v150, v151
	v_cvt_pk_bf16_f32 v52, v152, v153
	v_cvt_pk_bf16_f32 v53, v154, v155
	v_cvt_pk_bf16_f32 v54, v156, v157
	v_cvt_pk_bf16_f32 v55, v158, v159
	v_add_u32_e32 v181, 0x2400000, v177
	global_store_dwordx4 v181, v[48:51], s[78:79]
	global_store_dwordx4 v181, v[52:55], s[78:79] offset:1024
	v_add_u32_e32 v236, 0x6000, v237
	s_mov_b64 exec, 1
	global_store_dword v236, v184, s[78:79]
	s_mov_b64 exec, -1
	s_waitcnt vmcnt(12)
	v_lshlrev_b32_e32 v144, 16, v64
	v_and_b32_e32 v145, 0xffff0000, v64
	v_lshlrev_b32_e32 v146, 16, v65
	v_and_b32_e32 v147, 0xffff0000, v65
	v_lshlrev_b32_e32 v148, 16, v66
	v_and_b32_e32 v149, 0xffff0000, v66
	v_lshlrev_b32_e32 v150, 16, v67
	v_and_b32_e32 v151, 0xffff0000, v67
	v_lshlrev_b32_e32 v152, 16, v68
	v_and_b32_e32 v153, 0xffff0000, v68
	v_lshlrev_b32_e32 v154, 16, v69
	v_and_b32_e32 v155, 0xffff0000, v69
	v_lshlrev_b32_e32 v156, 16, v70
	v_and_b32_e32 v157, 0xffff0000, v70
	v_lshlrev_b32_e32 v158, 16, v71
	v_and_b32_e32 v159, 0xffff0000, v71
	v_lshlrev_b32_e32 v160, 16, v72
	v_and_b32_e32 v161, 0xffff0000, v72
	v_lshlrev_b32_e32 v162, 16, v73
	v_and_b32_e32 v163, 0xffff0000, v73
	v_lshlrev_b32_e32 v164, 16, v74
	v_and_b32_e32 v165, 0xffff0000, v74
	v_lshlrev_b32_e32 v166, 16, v75
	v_and_b32_e32 v167, 0xffff0000, v75
	v_lshlrev_b32_e32 v168, 16, v76
	v_and_b32_e32 v169, 0xffff0000, v76
	v_lshlrev_b32_e32 v170, 16, v77
	v_and_b32_e32 v171, 0xffff0000, v77
	v_lshlrev_b32_e32 v172, 16, v78
	v_and_b32_e32 v173, 0xffff0000, v78
	v_lshlrev_b32_e32 v174, 16, v79
	v_and_b32_e32 v175, 0xffff0000, v79
	v_pk_mul_f32 v[252:253], v[160:161], v[160:161]
	v_pk_mul_f32 v[254:255], v[162:163], v[162:163]
	v_pk_fma_f32 v[252:253], v[164:165], v[164:165], v[252:253]
	v_pk_fma_f32 v[254:255], v[166:167], v[166:167], v[254:255]
	v_pk_fma_f32 v[252:253], v[168:169], v[168:169], v[252:253]
	v_pk_fma_f32 v[254:255], v[170:171], v[170:171], v[254:255]
	v_pk_fma_f32 v[252:253], v[172:173], v[172:173], v[252:253]
	v_pk_fma_f32 v[254:255], v[174:175], v[174:175], v[254:255]
	v_pk_add_f32 v[252:253], v[252:253], v[254:255]
	s_nop 0
	v_add_f32_e32 v183, v252, v253
	s_nop 1
	v_add_f32_dpp v183, v183, v183 quad_perm:[1,0,3,2] row_mask:0xf bank_mask:0xf bound_ctrl:1
	s_nop 1
	v_add_f32_dpp v183, v183, v183 quad_perm:[2,3,0,1] row_mask:0xf bank_mask:0xf bound_ctrl:1
	s_nop 1
	v_add_f32_dpp v183, v183, v183 row_half_mirror row_mask:0xf bank_mask:0xf bound_ctrl:1
	s_nop 1
	v_add_f32_dpp v183, v183, v183 row_mirror row_mask:0xf bank_mask:0xf bound_ctrl:1
	s_nop 1
	v_readlane_b32 s98, v183, 0
	v_readlane_b32 s99, v183, 16
	v_readlane_b32 s100, v183, 32
	v_readlane_b32 s101, v183, 48
	s_nop 1
	v_mov_b32_e32 v183, s98
	v_add_f32_e32 v183, s99, v183
	v_add_f32_e32 v183, s100, v183
	v_add_f32_e32 v183, s101, v183
	v_fmamk_f32 v183, v183, 0x3a800000, v182
	v_cmp_gt_f32_e32 vcc, 0x800000, v183
	v_mul_f32_e32 v181, 0x4b800000, v183
	s_nop 1
	v_cndmask_b32_e32 v183, v183, v181, vcc
	v_rsq_f32_e32 v183, v183
	s_nop 0
	v_mul_f32_e32 v181, 0x45800000, v183
	v_cndmask_b32_e32 v184, v183, v181, vcc
	v_mov_b32_e32 v185, v184
	v_pk_mul_f32 v[160:161], v[160:161], v[184:185]
	v_pk_mul_f32 v[162:163], v[162:163], v[184:185]
	v_pk_mul_f32 v[164:165], v[164:165], v[184:185]
	v_pk_mul_f32 v[166:167], v[166:167], v[184:185]
	v_pk_mul_f32 v[168:169], v[168:169], v[184:185]
	v_pk_mul_f32 v[170:171], v[170:171], v[184:185]
	v_pk_mul_f32 v[172:173], v[172:173], v[184:185]
	v_pk_mul_f32 v[174:175], v[174:175], v[184:185]
	v_pk_fma_f32 v[144:145], v[160:161], v[128:129], v[144:145]
	v_pk_fma_f32 v[146:147], v[162:163], v[130:131], v[146:147]
	v_pk_fma_f32 v[148:149], v[164:165], v[132:133], v[148:149]
	v_pk_fma_f32 v[150:151], v[166:167], v[134:135], v[150:151]
	v_pk_fma_f32 v[152:153], v[168:169], v[136:137], v[152:153]
	v_pk_fma_f32 v[154:155], v[170:171], v[138:139], v[154:155]
	v_pk_fma_f32 v[156:157], v[172:173], v[140:141], v[156:157]
	v_pk_fma_f32 v[158:159], v[174:175], v[142:143], v[158:159]
	v_pk_mul_f32 v[252:253], v[144:145], v[144:145]
	v_pk_mul_f32 v[254:255], v[146:147], v[146:147]
	v_pk_fma_f32 v[252:253], v[148:149], v[148:149], v[252:253]
	v_pk_fma_f32 v[254:255], v[150:151], v[150:151], v[254:255]
	v_pk_fma_f32 v[252:253], v[152:153], v[152:153], v[252:253]
	v_pk_fma_f32 v[254:255], v[154:155], v[154:155], v[254:255]
	v_pk_fma_f32 v[252:253], v[156:157], v[156:157], v[252:253]
	v_pk_fma_f32 v[254:255], v[158:159], v[158:159], v[254:255]
	v_pk_add_f32 v[252:253], v[252:253], v[254:255]
	s_nop 0
	v_add_f32_e32 v183, v252, v253
	s_nop 1
	v_add_f32_dpp v183, v183, v183 quad_perm:[1,0,3,2] row_mask:0xf bank_mask:0xf bound_ctrl:1
	s_nop 1
	v_add_f32_dpp v183, v183, v183 quad_perm:[2,3,0,1] row_mask:0xf bank_mask:0xf bound_ctrl:1
	s_nop 1
	v_add_f32_dpp v183, v183, v183 row_half_mirror row_mask:0xf bank_mask:0xf bound_ctrl:1
	s_nop 1
	v_add_f32_dpp v183, v183, v183 row_mirror row_mask:0xf bank_mask:0xf bound_ctrl:1
	s_nop 1
	v_readlane_b32 s98, v183, 0
	v_readlane_b32 s99, v183, 16
	v_readlane_b32 s100, v183, 32
	v_readlane_b32 s101, v183, 48
	s_nop 1
	v_mov_b32_e32 v183, s98
	v_add_f32_e32 v183, s99, v183
	v_add_f32_e32 v183, s100, v183
	v_add_f32_e32 v183, s101, v183
	v_fmamk_f32 v183, v183, 0x3a800000, v182
	v_cmp_gt_f32_e32 vcc, 0x800000, v183
	v_mul_f32_e32 v181, 0x4b800000, v183
	s_nop 1
	v_cndmask_b32_e32 v183, v183, v181, vcc
	v_rsq_f32_e32 v183, v183
	s_nop 0
	v_mul_f32_e32 v181, 0x45800000, v183
	v_cndmask_b32_e32 v184, v183, v181, vcc
	v_mov_b32_e32 v185, v184
	v_cvt_pk_bf16_f32 v64, v144, v145
	v_cvt_pk_bf16_f32 v65, v146, v147
	v_cvt_pk_bf16_f32 v66, v148, v149
	v_cvt_pk_bf16_f32 v67, v150, v151
	v_cvt_pk_bf16_f32 v68, v152, v153
	v_cvt_pk_bf16_f32 v69, v154, v155
	v_cvt_pk_bf16_f32 v70, v156, v157
	v_cvt_pk_bf16_f32 v71, v158, v159
	v_add_u32_e32 v181, 0x2800000, v177
	global_store_dwordx4 v181, v[64:67], s[78:79]
	global_store_dwordx4 v181, v[68:71], s[78:79] offset:1024
	v_add_u32_e32 v236, 0x8000, v237
	s_mov_b64 exec, 1
	global_store_dword v236, v184, s[78:79]
	s_mov_b64 exec, -1
	s_waitcnt vmcnt(8)
	v_lshlrev_b32_e32 v144, 16, v80
	v_and_b32_e32 v145, 0xffff0000, v80
	v_lshlrev_b32_e32 v146, 16, v81
	v_and_b32_e32 v147, 0xffff0000, v81
	v_lshlrev_b32_e32 v148, 16, v82
	v_and_b32_e32 v149, 0xffff0000, v82
	v_lshlrev_b32_e32 v150, 16, v83
	v_and_b32_e32 v151, 0xffff0000, v83
	v_lshlrev_b32_e32 v152, 16, v84
	v_and_b32_e32 v153, 0xffff0000, v84
	v_lshlrev_b32_e32 v154, 16, v85
	v_and_b32_e32 v155, 0xffff0000, v85
	v_lshlrev_b32_e32 v156, 16, v86
	v_and_b32_e32 v157, 0xffff0000, v86
	v_lshlrev_b32_e32 v158, 16, v87
	v_and_b32_e32 v159, 0xffff0000, v87
	v_lshlrev_b32_e32 v160, 16, v88
	v_and_b32_e32 v161, 0xffff0000, v88
	v_lshlrev_b32_e32 v162, 16, v89
	v_and_b32_e32 v163, 0xffff0000, v89
	v_lshlrev_b32_e32 v164, 16, v90
	v_and_b32_e32 v165, 0xffff0000, v90
	v_lshlrev_b32_e32 v166, 16, v91
	v_and_b32_e32 v167, 0xffff0000, v91
	v_lshlrev_b32_e32 v168, 16, v92
	v_and_b32_e32 v169, 0xffff0000, v92
	v_lshlrev_b32_e32 v170, 16, v93
	v_and_b32_e32 v171, 0xffff0000, v93
	v_lshlrev_b32_e32 v172, 16, v94
	v_and_b32_e32 v173, 0xffff0000, v94
	v_lshlrev_b32_e32 v174, 16, v95
	v_and_b32_e32 v175, 0xffff0000, v95
	v_pk_mul_f32 v[252:253], v[160:161], v[160:161]
	v_pk_mul_f32 v[254:255], v[162:163], v[162:163]
	v_pk_fma_f32 v[252:253], v[164:165], v[164:165], v[252:253]
	v_pk_fma_f32 v[254:255], v[166:167], v[166:167], v[254:255]
	v_pk_fma_f32 v[252:253], v[168:169], v[168:169], v[252:253]
	v_pk_fma_f32 v[254:255], v[170:171], v[170:171], v[254:255]
	v_pk_fma_f32 v[252:253], v[172:173], v[172:173], v[252:253]
	v_pk_fma_f32 v[254:255], v[174:175], v[174:175], v[254:255]
	v_pk_add_f32 v[252:253], v[252:253], v[254:255]
	s_nop 0
	v_add_f32_e32 v183, v252, v253
	s_nop 1
	v_add_f32_dpp v183, v183, v183 quad_perm:[1,0,3,2] row_mask:0xf bank_mask:0xf bound_ctrl:1
	s_nop 1
	v_add_f32_dpp v183, v183, v183 quad_perm:[2,3,0,1] row_mask:0xf bank_mask:0xf bound_ctrl:1
	s_nop 1
	v_add_f32_dpp v183, v183, v183 row_half_mirror row_mask:0xf bank_mask:0xf bound_ctrl:1
	s_nop 1
	v_add_f32_dpp v183, v183, v183 row_mirror row_mask:0xf bank_mask:0xf bound_ctrl:1
	s_nop 1
	v_readlane_b32 s98, v183, 0
	v_readlane_b32 s99, v183, 16
	v_readlane_b32 s100, v183, 32
	v_readlane_b32 s101, v183, 48
	s_nop 1
	v_mov_b32_e32 v183, s98
	v_add_f32_e32 v183, s99, v183
	v_add_f32_e32 v183, s100, v183
	v_add_f32_e32 v183, s101, v183
	v_fmamk_f32 v183, v183, 0x3a800000, v182
	v_cmp_gt_f32_e32 vcc, 0x800000, v183
	v_mul_f32_e32 v181, 0x4b800000, v183
	s_nop 1
	v_cndmask_b32_e32 v183, v183, v181, vcc
	v_rsq_f32_e32 v183, v183
	s_nop 0
	v_mul_f32_e32 v181, 0x45800000, v183
	v_cndmask_b32_e32 v184, v183, v181, vcc
	v_mov_b32_e32 v185, v184
	v_pk_mul_f32 v[160:161], v[160:161], v[184:185]
	v_pk_mul_f32 v[162:163], v[162:163], v[184:185]
	v_pk_mul_f32 v[164:165], v[164:165], v[184:185]
	v_pk_mul_f32 v[166:167], v[166:167], v[184:185]
	v_pk_mul_f32 v[168:169], v[168:169], v[184:185]
	v_pk_mul_f32 v[170:171], v[170:171], v[184:185]
	v_pk_mul_f32 v[172:173], v[172:173], v[184:185]
	v_pk_mul_f32 v[174:175], v[174:175], v[184:185]
	v_pk_fma_f32 v[144:145], v[160:161], v[128:129], v[144:145]
	v_pk_fma_f32 v[146:147], v[162:163], v[130:131], v[146:147]
	v_pk_fma_f32 v[148:149], v[164:165], v[132:133], v[148:149]
	v_pk_fma_f32 v[150:151], v[166:167], v[134:135], v[150:151]
	v_pk_fma_f32 v[152:153], v[168:169], v[136:137], v[152:153]
	v_pk_fma_f32 v[154:155], v[170:171], v[138:139], v[154:155]
	v_pk_fma_f32 v[156:157], v[172:173], v[140:141], v[156:157]
	v_pk_fma_f32 v[158:159], v[174:175], v[142:143], v[158:159]
	v_pk_mul_f32 v[252:253], v[144:145], v[144:145]
	v_pk_mul_f32 v[254:255], v[146:147], v[146:147]
	v_pk_fma_f32 v[252:253], v[148:149], v[148:149], v[252:253]
	v_pk_fma_f32 v[254:255], v[150:151], v[150:151], v[254:255]
	v_pk_fma_f32 v[252:253], v[152:153], v[152:153], v[252:253]
	v_pk_fma_f32 v[254:255], v[154:155], v[154:155], v[254:255]
	v_pk_fma_f32 v[252:253], v[156:157], v[156:157], v[252:253]
	v_pk_fma_f32 v[254:255], v[158:159], v[158:159], v[254:255]
	v_pk_add_f32 v[252:253], v[252:253], v[254:255]
	s_nop 0
	v_add_f32_e32 v183, v252, v253
	s_nop 1
	v_add_f32_dpp v183, v183, v183 quad_perm:[1,0,3,2] row_mask:0xf bank_mask:0xf bound_ctrl:1
	s_nop 1
	v_add_f32_dpp v183, v183, v183 quad_perm:[2,3,0,1] row_mask:0xf bank_mask:0xf bound_ctrl:1
	s_nop 1
	v_add_f32_dpp v183, v183, v183 row_half_mirror row_mask:0xf bank_mask:0xf bound_ctrl:1
	s_nop 1
	v_add_f32_dpp v183, v183, v183 row_mirror row_mask:0xf bank_mask:0xf bound_ctrl:1
	s_nop 1
	v_readlane_b32 s98, v183, 0
	v_readlane_b32 s99, v183, 16
	v_readlane_b32 s100, v183, 32
	v_readlane_b32 s101, v183, 48
	s_nop 1
	v_mov_b32_e32 v183, s98
	v_add_f32_e32 v183, s99, v183
	v_add_f32_e32 v183, s100, v183
	v_add_f32_e32 v183, s101, v183
	v_fmamk_f32 v183, v183, 0x3a800000, v182
	v_cmp_gt_f32_e32 vcc, 0x800000, v183
	v_mul_f32_e32 v181, 0x4b800000, v183
	s_nop 1
	v_cndmask_b32_e32 v183, v183, v181, vcc
	v_rsq_f32_e32 v183, v183
	s_nop 0
	v_mul_f32_e32 v181, 0x45800000, v183
	v_cndmask_b32_e32 v184, v183, v181, vcc
	v_mov_b32_e32 v185, v184
	v_cvt_pk_bf16_f32 v80, v144, v145
	v_cvt_pk_bf16_f32 v81, v146, v147
	v_cvt_pk_bf16_f32 v82, v148, v149
	v_cvt_pk_bf16_f32 v83, v150, v151
	v_cvt_pk_bf16_f32 v84, v152, v153
	v_cvt_pk_bf16_f32 v85, v154, v155
	v_cvt_pk_bf16_f32 v86, v156, v157
	v_cvt_pk_bf16_f32 v87, v158, v159
	v_add_u32_e32 v181, 0x2c00000, v177
	global_store_dwordx4 v181, v[80:83], s[78:79]
	global_store_dwordx4 v181, v[84:87], s[78:79] offset:1024
	v_add_u32_e32 v236, 0xa000, v237
	s_mov_b64 exec, 1
	global_store_dword v236, v184, s[78:79]
	s_mov_b64 exec, -1
	s_waitcnt vmcnt(4)
	v_lshlrev_b32_e32 v144, 16, v96
	v_and_b32_e32 v145, 0xffff0000, v96
	v_lshlrev_b32_e32 v146, 16, v97
	v_and_b32_e32 v147, 0xffff0000, v97
	v_lshlrev_b32_e32 v148, 16, v98
	v_and_b32_e32 v149, 0xffff0000, v98
	v_lshlrev_b32_e32 v150, 16, v99
	v_and_b32_e32 v151, 0xffff0000, v99
	v_lshlrev_b32_e32 v152, 16, v100
	v_and_b32_e32 v153, 0xffff0000, v100
	v_lshlrev_b32_e32 v154, 16, v101
	v_and_b32_e32 v155, 0xffff0000, v101
	v_lshlrev_b32_e32 v156, 16, v102
	v_and_b32_e32 v157, 0xffff0000, v102
	v_lshlrev_b32_e32 v158, 16, v103
	v_and_b32_e32 v159, 0xffff0000, v103
	v_lshlrev_b32_e32 v160, 16, v104
	v_and_b32_e32 v161, 0xffff0000, v104
	v_lshlrev_b32_e32 v162, 16, v105
	v_and_b32_e32 v163, 0xffff0000, v105
	v_lshlrev_b32_e32 v164, 16, v106
	v_and_b32_e32 v165, 0xffff0000, v106
	v_lshlrev_b32_e32 v166, 16, v107
	v_and_b32_e32 v167, 0xffff0000, v107
	v_lshlrev_b32_e32 v168, 16, v108
	v_and_b32_e32 v169, 0xffff0000, v108
	v_lshlrev_b32_e32 v170, 16, v109
	v_and_b32_e32 v171, 0xffff0000, v109
	v_lshlrev_b32_e32 v172, 16, v110
	v_and_b32_e32 v173, 0xffff0000, v110
	v_lshlrev_b32_e32 v174, 16, v111
	v_and_b32_e32 v175, 0xffff0000, v111
	v_pk_mul_f32 v[252:253], v[160:161], v[160:161]
	v_pk_mul_f32 v[254:255], v[162:163], v[162:163]
	v_pk_fma_f32 v[252:253], v[164:165], v[164:165], v[252:253]
	v_pk_fma_f32 v[254:255], v[166:167], v[166:167], v[254:255]
	v_pk_fma_f32 v[252:253], v[168:169], v[168:169], v[252:253]
	v_pk_fma_f32 v[254:255], v[170:171], v[170:171], v[254:255]
	v_pk_fma_f32 v[252:253], v[172:173], v[172:173], v[252:253]
	v_pk_fma_f32 v[254:255], v[174:175], v[174:175], v[254:255]
	v_pk_add_f32 v[252:253], v[252:253], v[254:255]
	s_nop 0
	v_add_f32_e32 v183, v252, v253
	s_nop 1
	v_add_f32_dpp v183, v183, v183 quad_perm:[1,0,3,2] row_mask:0xf bank_mask:0xf bound_ctrl:1
	s_nop 1
	v_add_f32_dpp v183, v183, v183 quad_perm:[2,3,0,1] row_mask:0xf bank_mask:0xf bound_ctrl:1
	s_nop 1
	v_add_f32_dpp v183, v183, v183 row_half_mirror row_mask:0xf bank_mask:0xf bound_ctrl:1
	s_nop 1
	v_add_f32_dpp v183, v183, v183 row_mirror row_mask:0xf bank_mask:0xf bound_ctrl:1
	s_nop 1
	v_readlane_b32 s98, v183, 0
	v_readlane_b32 s99, v183, 16
	v_readlane_b32 s100, v183, 32
	v_readlane_b32 s101, v183, 48
	s_nop 1
	v_mov_b32_e32 v183, s98
	v_add_f32_e32 v183, s99, v183
	v_add_f32_e32 v183, s100, v183
	v_add_f32_e32 v183, s101, v183
	v_fmamk_f32 v183, v183, 0x3a800000, v182
	v_cmp_gt_f32_e32 vcc, 0x800000, v183
	v_mul_f32_e32 v181, 0x4b800000, v183
	s_nop 1
	v_cndmask_b32_e32 v183, v183, v181, vcc
	v_rsq_f32_e32 v183, v183
	s_nop 0
	v_mul_f32_e32 v181, 0x45800000, v183
	v_cndmask_b32_e32 v184, v183, v181, vcc
	v_mov_b32_e32 v185, v184
	v_pk_mul_f32 v[160:161], v[160:161], v[184:185]
	v_pk_mul_f32 v[162:163], v[162:163], v[184:185]
	v_pk_mul_f32 v[164:165], v[164:165], v[184:185]
	v_pk_mul_f32 v[166:167], v[166:167], v[184:185]
	v_pk_mul_f32 v[168:169], v[168:169], v[184:185]
	v_pk_mul_f32 v[170:171], v[170:171], v[184:185]
	v_pk_mul_f32 v[172:173], v[172:173], v[184:185]
	v_pk_mul_f32 v[174:175], v[174:175], v[184:185]
	v_pk_fma_f32 v[144:145], v[160:161], v[128:129], v[144:145]
	v_pk_fma_f32 v[146:147], v[162:163], v[130:131], v[146:147]
	v_pk_fma_f32 v[148:149], v[164:165], v[132:133], v[148:149]
	v_pk_fma_f32 v[150:151], v[166:167], v[134:135], v[150:151]
	v_pk_fma_f32 v[152:153], v[168:169], v[136:137], v[152:153]
	v_pk_fma_f32 v[154:155], v[170:171], v[138:139], v[154:155]
	v_pk_fma_f32 v[156:157], v[172:173], v[140:141], v[156:157]
	v_pk_fma_f32 v[158:159], v[174:175], v[142:143], v[158:159]
	v_pk_mul_f32 v[252:253], v[144:145], v[144:145]
	v_pk_mul_f32 v[254:255], v[146:147], v[146:147]
	v_pk_fma_f32 v[252:253], v[148:149], v[148:149], v[252:253]
	v_pk_fma_f32 v[254:255], v[150:151], v[150:151], v[254:255]
	v_pk_fma_f32 v[252:253], v[152:153], v[152:153], v[252:253]
	v_pk_fma_f32 v[254:255], v[154:155], v[154:155], v[254:255]
	v_pk_fma_f32 v[252:253], v[156:157], v[156:157], v[252:253]
	v_pk_fma_f32 v[254:255], v[158:159], v[158:159], v[254:255]
	v_pk_add_f32 v[252:253], v[252:253], v[254:255]
	s_nop 0
	v_add_f32_e32 v183, v252, v253
	s_nop 1
	v_add_f32_dpp v183, v183, v183 quad_perm:[1,0,3,2] row_mask:0xf bank_mask:0xf bound_ctrl:1
	s_nop 1
	v_add_f32_dpp v183, v183, v183 quad_perm:[2,3,0,1] row_mask:0xf bank_mask:0xf bound_ctrl:1
	s_nop 1
	v_add_f32_dpp v183, v183, v183 row_half_mirror row_mask:0xf bank_mask:0xf bound_ctrl:1
	s_nop 1
	v_add_f32_dpp v183, v183, v183 row_mirror row_mask:0xf bank_mask:0xf bound_ctrl:1
	s_nop 1
	v_readlane_b32 s98, v183, 0
	v_readlane_b32 s99, v183, 16
	v_readlane_b32 s100, v183, 32
	v_readlane_b32 s101, v183, 48
	s_nop 1
	v_mov_b32_e32 v183, s98
	v_add_f32_e32 v183, s99, v183
	v_add_f32_e32 v183, s100, v183
	v_add_f32_e32 v183, s101, v183
	v_fmamk_f32 v183, v183, 0x3a800000, v182
	v_cmp_gt_f32_e32 vcc, 0x800000, v183
	v_mul_f32_e32 v181, 0x4b800000, v183
	s_nop 1
	v_cndmask_b32_e32 v183, v183, v181, vcc
	v_rsq_f32_e32 v183, v183
	s_nop 0
	v_mul_f32_e32 v181, 0x45800000, v183
	v_cndmask_b32_e32 v184, v183, v181, vcc
	v_mov_b32_e32 v185, v184
	v_cvt_pk_bf16_f32 v96, v144, v145
	v_cvt_pk_bf16_f32 v97, v146, v147
	v_cvt_pk_bf16_f32 v98, v148, v149
	v_cvt_pk_bf16_f32 v99, v150, v151
	v_cvt_pk_bf16_f32 v100, v152, v153
	v_cvt_pk_bf16_f32 v101, v154, v155
	v_cvt_pk_bf16_f32 v102, v156, v157
	v_cvt_pk_bf16_f32 v103, v158, v159
	v_add_u32_e32 v181, 0x3000000, v177
	global_store_dwordx4 v181, v[96:99], s[78:79]
	global_store_dwordx4 v181, v[100:103], s[78:79] offset:1024
	v_add_u32_e32 v236, 0xc000, v237
	s_mov_b64 exec, 1
	global_store_dword v236, v184, s[78:79]
	s_mov_b64 exec, -1
	s_waitcnt vmcnt(0)
	v_lshlrev_b32_e32 v144, 16, v112
	v_and_b32_e32 v145, 0xffff0000, v112
	v_lshlrev_b32_e32 v146, 16, v113
	v_and_b32_e32 v147, 0xffff0000, v113
	v_lshlrev_b32_e32 v148, 16, v114
	v_and_b32_e32 v149, 0xffff0000, v114
	v_lshlrev_b32_e32 v150, 16, v115
	v_and_b32_e32 v151, 0xffff0000, v115
	v_lshlrev_b32_e32 v152, 16, v116
	v_and_b32_e32 v153, 0xffff0000, v116
	v_lshlrev_b32_e32 v154, 16, v117
	v_and_b32_e32 v155, 0xffff0000, v117
	v_lshlrev_b32_e32 v156, 16, v118
	v_and_b32_e32 v157, 0xffff0000, v118
	v_lshlrev_b32_e32 v158, 16, v119
	v_and_b32_e32 v159, 0xffff0000, v119
	v_lshlrev_b32_e32 v160, 16, v120
	v_and_b32_e32 v161, 0xffff0000, v120
	v_lshlrev_b32_e32 v162, 16, v121
	v_and_b32_e32 v163, 0xffff0000, v121
	v_lshlrev_b32_e32 v164, 16, v122
	v_and_b32_e32 v165, 0xffff0000, v122
	v_lshlrev_b32_e32 v166, 16, v123
	v_and_b32_e32 v167, 0xffff0000, v123
	v_lshlrev_b32_e32 v168, 16, v124
	v_and_b32_e32 v169, 0xffff0000, v124
	v_lshlrev_b32_e32 v170, 16, v125
	v_and_b32_e32 v171, 0xffff0000, v125
	v_lshlrev_b32_e32 v172, 16, v126
	v_and_b32_e32 v173, 0xffff0000, v126
	v_lshlrev_b32_e32 v174, 16, v127
	v_and_b32_e32 v175, 0xffff0000, v127
	v_pk_mul_f32 v[252:253], v[160:161], v[160:161]
	v_pk_mul_f32 v[254:255], v[162:163], v[162:163]
	v_pk_fma_f32 v[252:253], v[164:165], v[164:165], v[252:253]
	v_pk_fma_f32 v[254:255], v[166:167], v[166:167], v[254:255]
	v_pk_fma_f32 v[252:253], v[168:169], v[168:169], v[252:253]
	v_pk_fma_f32 v[254:255], v[170:171], v[170:171], v[254:255]
	v_pk_fma_f32 v[252:253], v[172:173], v[172:173], v[252:253]
	v_pk_fma_f32 v[254:255], v[174:175], v[174:175], v[254:255]
	v_pk_add_f32 v[252:253], v[252:253], v[254:255]
	s_nop 0
	v_add_f32_e32 v183, v252, v253
	s_nop 1
	v_add_f32_dpp v183, v183, v183 quad_perm:[1,0,3,2] row_mask:0xf bank_mask:0xf bound_ctrl:1
	s_nop 1
	v_add_f32_dpp v183, v183, v183 quad_perm:[2,3,0,1] row_mask:0xf bank_mask:0xf bound_ctrl:1
	s_nop 1
	v_add_f32_dpp v183, v183, v183 row_half_mirror row_mask:0xf bank_mask:0xf bound_ctrl:1
	s_nop 1
	v_add_f32_dpp v183, v183, v183 row_mirror row_mask:0xf bank_mask:0xf bound_ctrl:1
	s_nop 1
	v_readlane_b32 s98, v183, 0
	v_readlane_b32 s99, v183, 16
	v_readlane_b32 s100, v183, 32
	v_readlane_b32 s101, v183, 48
	s_nop 1
	v_mov_b32_e32 v183, s98
	v_add_f32_e32 v183, s99, v183
	v_add_f32_e32 v183, s100, v183
	v_add_f32_e32 v183, s101, v183
	v_fmamk_f32 v183, v183, 0x3a800000, v182
	v_cmp_gt_f32_e32 vcc, 0x800000, v183
	v_mul_f32_e32 v181, 0x4b800000, v183
	s_nop 1
	v_cndmask_b32_e32 v183, v183, v181, vcc
	v_rsq_f32_e32 v183, v183
	s_nop 0
	v_mul_f32_e32 v181, 0x45800000, v183
	v_cndmask_b32_e32 v184, v183, v181, vcc
	v_mov_b32_e32 v185, v184
	v_pk_mul_f32 v[160:161], v[160:161], v[184:185]
	v_pk_mul_f32 v[162:163], v[162:163], v[184:185]
	v_pk_mul_f32 v[164:165], v[164:165], v[184:185]
	v_pk_mul_f32 v[166:167], v[166:167], v[184:185]
	v_pk_mul_f32 v[168:169], v[168:169], v[184:185]
	v_pk_mul_f32 v[170:171], v[170:171], v[184:185]
	v_pk_mul_f32 v[172:173], v[172:173], v[184:185]
	v_pk_mul_f32 v[174:175], v[174:175], v[184:185]
	v_pk_fma_f32 v[144:145], v[160:161], v[128:129], v[144:145]
	v_pk_fma_f32 v[146:147], v[162:163], v[130:131], v[146:147]
	v_pk_fma_f32 v[148:149], v[164:165], v[132:133], v[148:149]
	v_pk_fma_f32 v[150:151], v[166:167], v[134:135], v[150:151]
	v_pk_fma_f32 v[152:153], v[168:169], v[136:137], v[152:153]
	v_pk_fma_f32 v[154:155], v[170:171], v[138:139], v[154:155]
	v_pk_fma_f32 v[156:157], v[172:173], v[140:141], v[156:157]
	v_pk_fma_f32 v[158:159], v[174:175], v[142:143], v[158:159]
	v_pk_mul_f32 v[252:253], v[144:145], v[144:145]
	v_pk_mul_f32 v[254:255], v[146:147], v[146:147]
	v_pk_fma_f32 v[252:253], v[148:149], v[148:149], v[252:253]
	v_pk_fma_f32 v[254:255], v[150:151], v[150:151], v[254:255]
	v_pk_fma_f32 v[252:253], v[152:153], v[152:153], v[252:253]
	v_pk_fma_f32 v[254:255], v[154:155], v[154:155], v[254:255]
	v_pk_fma_f32 v[252:253], v[156:157], v[156:157], v[252:253]
	v_pk_fma_f32 v[254:255], v[158:159], v[158:159], v[254:255]
	v_pk_add_f32 v[252:253], v[252:253], v[254:255]
	s_nop 0
	v_add_f32_e32 v183, v252, v253
	s_nop 1
	v_add_f32_dpp v183, v183, v183 quad_perm:[1,0,3,2] row_mask:0xf bank_mask:0xf bound_ctrl:1
	s_nop 1
	v_add_f32_dpp v183, v183, v183 quad_perm:[2,3,0,1] row_mask:0xf bank_mask:0xf bound_ctrl:1
	s_nop 1
	v_add_f32_dpp v183, v183, v183 row_half_mirror row_mask:0xf bank_mask:0xf bound_ctrl:1
	s_nop 1
	v_add_f32_dpp v183, v183, v183 row_mirror row_mask:0xf bank_mask:0xf bound_ctrl:1
	s_nop 1
	v_readlane_b32 s98, v183, 0
	v_readlane_b32 s99, v183, 16
	v_readlane_b32 s100, v183, 32
	v_readlane_b32 s101, v183, 48
	s_nop 1
	v_mov_b32_e32 v183, s98
	v_add_f32_e32 v183, s99, v183
	v_add_f32_e32 v183, s100, v183
	v_add_f32_e32 v183, s101, v183
	v_fmamk_f32 v183, v183, 0x3a800000, v182
	v_cmp_gt_f32_e32 vcc, 0x800000, v183
	v_mul_f32_e32 v181, 0x4b800000, v183
	s_nop 1
	v_cndmask_b32_e32 v183, v183, v181, vcc
	v_rsq_f32_e32 v183, v183
	s_nop 0
	v_mul_f32_e32 v181, 0x45800000, v183
	v_cndmask_b32_e32 v184, v183, v181, vcc
	v_mov_b32_e32 v185, v184
	v_cvt_pk_bf16_f32 v112, v144, v145
	v_cvt_pk_bf16_f32 v113, v146, v147
	v_cvt_pk_bf16_f32 v114, v148, v149
	v_cvt_pk_bf16_f32 v115, v150, v151
	v_cvt_pk_bf16_f32 v116, v152, v153
	v_cvt_pk_bf16_f32 v117, v154, v155
	v_cvt_pk_bf16_f32 v118, v156, v157
	v_cvt_pk_bf16_f32 v119, v158, v159
	v_add_u32_e32 v181, 0x3400000, v177
	global_store_dwordx4 v181, v[112:115], s[78:79]
	global_store_dwordx4 v181, v[116:119], s[78:79] offset:1024
	v_add_u32_e32 v236, 0xe000, v237
	s_mov_b64 exec, 1
	global_store_dword v236, v184, s[78:79]
	s_mov_b64 exec, -1
	v_readfirstlane_b32 s98, v179
	s_nop 3
	s_cmp_ge_u32 s98, 512
	s_cbranch_scc1 .Lmyxupd_done_3
	v_add_u32_e32 v181, 0x3800000, v177
	global_load_dwordx4 v[0:3], v181, s[78:79]
	global_load_dwordx4 v[4:7], v181, s[78:79] offset:1024
	v_lshl_add_u32 v183, v179, 12, v180
	v_add_u32_e32 v183, 0xbf00000, v183
	v_add_u32_e32 v181, 0x0, v183
	global_load_dwordx4 v[8:11], v181, s[78:79]
	global_load_dwordx4 v[12:15], v181, s[78:79] offset:16
	global_load_dwordx4 v[16:19], v181, s[78:79] offset:2048
	global_load_dwordx4 v[20:23], v181, s[78:79] offset:2064
	v_add_u32_e32 v181, 0x200000, v183
	global_load_dwordx4 v[24:27], v181, s[78:79]
	global_load_dwordx4 v[28:31], v181, s[78:79] offset:16
	global_load_dwordx4 v[32:35], v181, s[78:79] offset:2048
	global_load_dwordx4 v[36:39], v181, s[78:79] offset:2064
	v_add_u32_e32 v181, 0x400000, v183
	global_load_dwordx4 v[40:43], v181, s[78:79]
	global_load_dwordx4 v[44:47], v181, s[78:79] offset:16
	global_load_dwordx4 v[48:51], v181, s[78:79] offset:2048
	global_load_dwordx4 v[52:55], v181, s[78:79] offset:2064
	v_add_u32_e32 v181, 0x600000, v183
	global_load_dwordx4 v[56:59], v181, s[78:79]
	global_load_dwordx4 v[60:63], v181, s[78:79] offset:16
	global_load_dwordx4 v[64:67], v181, s[78:79] offset:2048
	global_load_dwordx4 v[68:71], v181, s[78:79] offset:2064
	v_add_u32_e32 v181, 0x800000, v183
	global_load_dwordx4 v[72:75], v181, s[78:79]
	global_load_dwordx4 v[76:79], v181, s[78:79] offset:16
	global_load_dwordx4 v[80:83], v181, s[78:79] offset:2048
	global_load_dwordx4 v[84:87], v181, s[78:79] offset:2064
	v_add_u32_e32 v181, 0xa00000, v183
	global_load_dwordx4 v[88:91], v181, s[78:79]
	global_load_dwordx4 v[92:95], v181, s[78:79] offset:16
	global_load_dwordx4 v[96:99], v181, s[78:79] offset:2048
	global_load_dwordx4 v[100:103], v181, s[78:79] offset:2064
	s_waitcnt vmcnt(20)
	v_pk_add_f32 v[160:161], v[8:9], 0 op_sel_hi:[1,0]
	v_pk_add_f32 v[162:163], v[10:11], 0 op_sel_hi:[1,0]
	v_pk_add_f32 v[164:165], v[12:13], 0 op_sel_hi:[1,0]
	v_pk_add_f32 v[166:167], v[14:15], 0 op_sel_hi:[1,0]
	v_pk_add_f32 v[168:169], v[16:17], 0 op_sel_hi:[1,0]
	v_pk_add_f32 v[170:171], v[18:19], 0 op_sel_hi:[1,0]
	v_pk_add_f32 v[172:173], v[20:21], 0 op_sel_hi:[1,0]
	v_pk_add_f32 v[174:175], v[22:23], 0 op_sel_hi:[1,0]
	s_waitcnt vmcnt(16)
	v_pk_add_f32 v[160:161], v[160:161], v[24:25]
	v_pk_add_f32 v[162:163], v[162:163], v[26:27]
	v_pk_add_f32 v[164:165], v[164:165], v[28:29]
	v_pk_add_f32 v[166:167], v[166:167], v[30:31]
	v_pk_add_f32 v[168:169], v[168:169], v[32:33]
	v_pk_add_f32 v[170:171], v[170:171], v[34:35]
	v_pk_add_f32 v[172:173], v[172:173], v[36:37]
	v_pk_add_f32 v[174:175], v[174:175], v[38:39]
	s_waitcnt vmcnt(12)
	v_pk_add_f32 v[160:161], v[160:161], v[40:41]
	v_pk_add_f32 v[162:163], v[162:163], v[42:43]
	v_pk_add_f32 v[164:165], v[164:165], v[44:45]
	v_pk_add_f32 v[166:167], v[166:167], v[46:47]
	v_pk_add_f32 v[168:169], v[168:169], v[48:49]
	v_pk_add_f32 v[170:171], v[170:171], v[50:51]
	v_pk_add_f32 v[172:173], v[172:173], v[52:53]
	v_pk_add_f32 v[174:175], v[174:175], v[54:55]
	s_waitcnt vmcnt(8)
	v_pk_add_f32 v[160:161], v[160:161], v[56:57]
	v_pk_add_f32 v[162:163], v[162:163], v[58:59]
	v_pk_add_f32 v[164:165], v[164:165], v[60:61]
	v_pk_add_f32 v[166:167], v[166:167], v[62:63]
	v_pk_add_f32 v[168:169], v[168:169], v[64:65]
	v_pk_add_f32 v[170:171], v[170:171], v[66:67]
	v_pk_add_f32 v[172:173], v[172:173], v[68:69]
	v_pk_add_f32 v[174:175], v[174:175], v[70:71]
	s_waitcnt vmcnt(4)
	v_pk_add_f32 v[160:161], v[160:161], v[72:73]
	v_pk_add_f32 v[162:163], v[162:163], v[74:75]
	v_pk_add_f32 v[164:165], v[164:165], v[76:77]
	v_pk_add_f32 v[166:167], v[166:167], v[78:79]
	v_pk_add_f32 v[168:169], v[168:169], v[80:81]
	v_pk_add_f32 v[170:171], v[170:171], v[82:83]
	v_pk_add_f32 v[172:173], v[172:173], v[84:85]
	v_pk_add_f32 v[174:175], v[174:175], v[86:87]
	s_waitcnt vmcnt(0)
	v_pk_add_f32 v[160:161], v[160:161], v[88:89]
	v_pk_add_f32 v[162:163], v[162:163], v[90:91]
	v_pk_add_f32 v[164:165], v[164:165], v[92:93]
	v_pk_add_f32 v[166:167], v[166:167], v[94:95]
	v_pk_add_f32 v[168:169], v[168:169], v[96:97]
	v_pk_add_f32 v[170:171], v[170:171], v[98:99]
	v_pk_add_f32 v[172:173], v[172:173], v[100:101]
	v_pk_add_f32 v[174:175], v[174:175], v[102:103]
	v_lshlrev_b32_e32 v144, 16, v0
	v_and_b32_e32 v145, 0xffff0000, v0
	v_lshlrev_b32_e32 v146, 16, v1
	v_and_b32_e32 v147, 0xffff0000, v1
	v_lshlrev_b32_e32 v148, 16, v2
	v_and_b32_e32 v149, 0xffff0000, v2
	v_lshlrev_b32_e32 v150, 16, v3
	v_and_b32_e32 v151, 0xffff0000, v3
	v_lshlrev_b32_e32 v152, 16, v4
	v_and_b32_e32 v153, 0xffff0000, v4
	v_lshlrev_b32_e32 v154, 16, v5
	v_and_b32_e32 v155, 0xffff0000, v5
	v_lshlrev_b32_e32 v156, 16, v6
	v_and_b32_e32 v157, 0xffff0000, v6
	v_lshlrev_b32_e32 v158, 16, v7
	v_and_b32_e32 v159, 0xffff0000, v7
	v_add_u32_e32 v181, 0xc00000, v183
	global_load_dwordx4 v[8:11], v181, s[78:79]
	global_load_dwordx4 v[12:15], v181, s[78:79] offset:16
	global_load_dwordx4 v[16:19], v181, s[78:79] offset:2048
	global_load_dwordx4 v[20:23], v181, s[78:79] offset:2064
	v_add_u32_e32 v181, 0xe00000, v183
	global_load_dwordx4 v[24:27], v181, s[78:79]
	global_load_dwordx4 v[28:31], v181, s[78:79] offset:16
	global_load_dwordx4 v[32:35], v181, s[78:79] offset:2048
	global_load_dwordx4 v[36:39], v181, s[78:79] offset:2064
	v_add_u32_e32 v181, 0x1000000, v183
	global_load_dwordx4 v[40:43], v181, s[78:79]
	global_load_dwordx4 v[44:47], v181, s[78:79] offset:16
	global_load_dwordx4 v[48:51], v181, s[78:79] offset:2048
	global_load_dwordx4 v[52:55], v181, s[78:79] offset:2064
	v_add_u32_e32 v181, 0x1200000, v183
	global_load_dwordx4 v[56:59], v181, s[78:79]
	global_load_dwordx4 v[60:63], v181, s[78:79] offset:16
	global_load_dwordx4 v[64:67], v181, s[78:79] offset:2048
	global_load_dwordx4 v[68:71], v181, s[78:79] offset:2064
	v_add_u32_e32 v181, 0x1400000, v183
	global_load_dwordx4 v[72:75], v181, s[78:79]
	global_load_dwordx4 v[76:79], v181, s[78:79] offset:16
	global_load_dwordx4 v[80:83], v181, s[78:79] offset:2048
	global_load_dwordx4 v[84:87], v181, s[78:79] offset:2064
	s_waitcnt vmcnt(16)
	v_pk_add_f32 v[160:161], v[160:161], v[8:9]
	v_pk_add_f32 v[162:163], v[162:163], v[10:11]
	v_pk_add_f32 v[164:165], v[164:165], v[12:13]
	v_pk_add_f32 v[166:167], v[166:167], v[14:15]
	v_pk_add_f32 v[168:169], v[168:169], v[16:17]
	v_pk_add_f32 v[170:171], v[170:171], v[18:19]
	v_pk_add_f32 v[172:173], v[172:173], v[20:21]
	v_pk_add_f32 v[174:175], v[174:175], v[22:23]
	s_waitcnt vmcnt(12)
	v_pk_add_f32 v[160:161], v[160:161], v[24:25]
	v_pk_add_f32 v[162:163], v[162:163], v[26:27]
	v_pk_add_f32 v[164:165], v[164:165], v[28:29]
	v_pk_add_f32 v[166:167], v[166:167], v[30:31]
	v_pk_add_f32 v[168:169], v[168:169], v[32:33]
	v_pk_add_f32 v[170:171], v[170:171], v[34:35]
	v_pk_add_f32 v[172:173], v[172:173], v[36:37]
	v_pk_add_f32 v[174:175], v[174:175], v[38:39]
	s_waitcnt vmcnt(8)
	v_pk_add_f32 v[160:161], v[160:161], v[40:41]
	v_pk_add_f32 v[162:163], v[162:163], v[42:43]
	v_pk_add_f32 v[164:165], v[164:165], v[44:45]
	v_pk_add_f32 v[166:167], v[166:167], v[46:47]
	v_pk_add_f32 v[168:169], v[168:169], v[48:49]
	v_pk_add_f32 v[170:171], v[170:171], v[50:51]
	v_pk_add_f32 v[172:173], v[172:173], v[52:53]
	v_pk_add_f32 v[174:175], v[174:175], v[54:55]
	s_waitcnt vmcnt(4)
	v_pk_add_f32 v[160:161], v[160:161], v[56:57]
	v_pk_add_f32 v[162:163], v[162:163], v[58:59]
	v_pk_add_f32 v[164:165], v[164:165], v[60:61]
	v_pk_add_f32 v[166:167], v[166:167], v[62:63]
	v_pk_add_f32 v[168:169], v[168:169], v[64:65]
	v_pk_add_f32 v[170:171], v[170:171], v[66:67]
	v_pk_add_f32 v[172:173], v[172:173], v[68:69]
	v_pk_add_f32 v[174:175], v[174:175], v[70:71]
	s_waitcnt vmcnt(0)
	v_pk_add_f32 v[160:161], v[160:161], v[72:73]
	v_pk_add_f32 v[162:163], v[162:163], v[74:75]
	v_pk_add_f32 v[164:165], v[164:165], v[76:77]
	v_pk_add_f32 v[166:167], v[166:167], v[78:79]
	v_pk_add_f32 v[168:169], v[168:169], v[80:81]
	v_pk_add_f32 v[170:171], v[170:171], v[82:83]
	v_pk_add_f32 v[172:173], v[172:173], v[84:85]
	v_pk_add_f32 v[174:175], v[174:175], v[86:87]
	v_pk_mul_f32 v[252:253], v[160:161], v[160:161]
	v_pk_mul_f32 v[254:255], v[162:163], v[162:163]
	v_pk_fma_f32 v[252:253], v[164:165], v[164:165], v[252:253]
	v_pk_fma_f32 v[254:255], v[166:167], v[166:167], v[254:255]
	v_pk_fma_f32 v[252:253], v[168:169], v[168:169], v[252:253]
	v_pk_fma_f32 v[254:255], v[170:171], v[170:171], v[254:255]
	v_pk_fma_f32 v[252:253], v[172:173], v[172:173], v[252:253]
	v_pk_fma_f32 v[254:255], v[174:175], v[174:175], v[254:255]
	v_pk_add_f32 v[252:253], v[252:253], v[254:255]
	s_nop 0
	v_add_f32_e32 v183, v252, v253
	s_nop 1
	v_add_f32_dpp v183, v183, v183 quad_perm:[1,0,3,2] row_mask:0xf bank_mask:0xf bound_ctrl:1
	s_nop 1
	v_add_f32_dpp v183, v183, v183 quad_perm:[2,3,0,1] row_mask:0xf bank_mask:0xf bound_ctrl:1
	s_nop 1
	v_add_f32_dpp v183, v183, v183 row_half_mirror row_mask:0xf bank_mask:0xf bound_ctrl:1
	s_nop 1
	v_add_f32_dpp v183, v183, v183 row_mirror row_mask:0xf bank_mask:0xf bound_ctrl:1
	s_nop 1
	v_readlane_b32 s98, v183, 0
	v_readlane_b32 s99, v183, 16
	v_readlane_b32 s100, v183, 32
	v_readlane_b32 s101, v183, 48
	s_nop 1
	v_mov_b32_e32 v183, s98
	v_add_f32_e32 v183, s99, v183
	v_add_f32_e32 v183, s100, v183
	v_add_f32_e32 v183, s101, v183
	v_fmamk_f32 v183, v183, 0x3a800000, v182
	v_cmp_gt_f32_e32 vcc, 0x800000, v183
	v_mul_f32_e32 v181, 0x4b800000, v183
	s_nop 1
	v_cndmask_b32_e32 v183, v183, v181, vcc
	v_rsq_f32_e32 v183, v183
	s_nop 0
	v_mul_f32_e32 v181, 0x45800000, v183
	v_cndmask_b32_e32 v184, v183, v181, vcc
	v_mov_b32_e32 v185, v184
	v_pk_mul_f32 v[160:161], v[160:161], v[184:185]
	v_pk_mul_f32 v[162:163], v[162:163], v[184:185]
	v_pk_mul_f32 v[164:165], v[164:165], v[184:185]
	v_pk_mul_f32 v[166:167], v[166:167], v[184:185]
	v_pk_mul_f32 v[168:169], v[168:169], v[184:185]
	v_pk_mul_f32 v[170:171], v[170:171], v[184:185]
	v_pk_mul_f32 v[172:173], v[172:173], v[184:185]
	v_pk_mul_f32 v[174:175], v[174:175], v[184:185]
	v_pk_fma_f32 v[144:145], v[160:161], v[128:129], v[144:145]
	v_pk_fma_f32 v[146:147], v[162:163], v[130:131], v[146:147]
	v_pk_fma_f32 v[148:149], v[164:165], v[132:133], v[148:149]
	v_pk_fma_f32 v[150:151], v[166:167], v[134:135], v[150:151]
	v_pk_fma_f32 v[152:153], v[168:169], v[136:137], v[152:153]
	v_pk_fma_f32 v[154:155], v[170:171], v[138:139], v[154:155]
	v_pk_fma_f32 v[156:157], v[172:173], v[140:141], v[156:157]
	v_pk_fma_f32 v[158:159], v[174:175], v[142:143], v[158:159]
	v_pk_mul_f32 v[252:253], v[144:145], v[144:145]
	v_pk_mul_f32 v[254:255], v[146:147], v[146:147]
	v_pk_fma_f32 v[252:253], v[148:149], v[148:149], v[252:253]
	v_pk_fma_f32 v[254:255], v[150:151], v[150:151], v[254:255]
	v_pk_fma_f32 v[252:253], v[152:153], v[152:153], v[252:253]
	v_pk_fma_f32 v[254:255], v[154:155], v[154:155], v[254:255]
	v_pk_fma_f32 v[252:253], v[156:157], v[156:157], v[252:253]
	v_pk_fma_f32 v[254:255], v[158:159], v[158:159], v[254:255]
	v_pk_add_f32 v[252:253], v[252:253], v[254:255]
	s_nop 0
	v_add_f32_e32 v183, v252, v253
	s_nop 1
	v_add_f32_dpp v183, v183, v183 quad_perm:[1,0,3,2] row_mask:0xf bank_mask:0xf bound_ctrl:1
	s_nop 1
	v_add_f32_dpp v183, v183, v183 quad_perm:[2,3,0,1] row_mask:0xf bank_mask:0xf bound_ctrl:1
	s_nop 1
	v_add_f32_dpp v183, v183, v183 row_half_mirror row_mask:0xf bank_mask:0xf bound_ctrl:1
	s_nop 1
	v_add_f32_dpp v183, v183, v183 row_mirror row_mask:0xf bank_mask:0xf bound_ctrl:1
	s_nop 1
	v_readlane_b32 s98, v183, 0
	v_readlane_b32 s99, v183, 16
	v_readlane_b32 s100, v183, 32
	v_readlane_b32 s101, v183, 48
	s_nop 1
	v_mov_b32_e32 v183, s98
	v_add_f32_e32 v183, s99, v183
	v_add_f32_e32 v183, s100, v183
	v_add_f32_e32 v183, s101, v183
	v_fmamk_f32 v183, v183, 0x3a800000, v182
	v_cmp_gt_f32_e32 vcc, 0x800000, v183
	v_mul_f32_e32 v181, 0x4b800000, v183
	s_nop 1
	v_cndmask_b32_e32 v183, v183, v181, vcc
	v_rsq_f32_e32 v183, v183
	s_nop 0
	v_mul_f32_e32 v181, 0x45800000, v183
	v_cndmask_b32_e32 v184, v183, v181, vcc
	v_mov_b32_e32 v185, v184
	v_cvt_pk_bf16_f32 v0, v144, v145
	v_cvt_pk_bf16_f32 v1, v146, v147
	v_cvt_pk_bf16_f32 v2, v148, v149
	v_cvt_pk_bf16_f32 v3, v150, v151
	v_cvt_pk_bf16_f32 v4, v152, v153
	v_cvt_pk_bf16_f32 v5, v154, v155
	v_cvt_pk_bf16_f32 v6, v156, v157
	v_cvt_pk_bf16_f32 v7, v158, v159
	v_add_u32_e32 v181, 0x3800000, v177
	global_store_dwordx4 v181, v[0:3], s[78:79]
	global_store_dwordx4 v181, v[4:7], s[78:79] offset:1024
	v_add_u32_e32 v236, 0x10000, v237
	s_mov_b64 exec, 1
	global_store_dword v236, v184, s[78:79]
	s_mov_b64 exec, -1
.Lmyxupd_done_3:
.LBB0_1449:
	v_readlane_b32 s86, v235, 56
	v_readlane_b32 s90, v235, 59
	v_readlane_b32 s87, v235, 57
	v_readlane_b32 s82, v235, 58
	v_readlane_b32 s91, v235, 60
	v_readlane_b32 s80, v235, 45
	v_readlane_b32 s33, v234, 3

.LBB0_1863:
	v_readlane_b32 s0, v235, 52
	v_readlane_b32 s1, v235, 53
	s_and_b64 vcc, exec, s[0:1]
	s_waitcnt lgkmcnt(0)
	s_barrier
	v_mbcnt_lo_u32_b32 v0, -1, 0
	v_mbcnt_hi_u32_b32 v0, -1, v0
	s_cbranch_vccnz .LBB0_1883
	v_lshlrev_b32_e32 v2, 3, v0
	v_ashrrev_i32_e32 v3, 31, v2
	v_readlane_b32 s4, v235, 4
	v_lshlrev_b64 v[4:5], 1, v[2:3]
	v_lshlrev_b64 v[2:3], 2, v[2:3]
	v_readlane_b32 s14, v235, 14
	v_readlane_b32 s15, v235, 15
	v_lshl_add_u64 v[62:63], s[90:91], 0, v[2:3]
	v_readlane_b32 s5, v235, 5
	v_readlane_b32 s6, v235, 6
	v_readlane_b32 s7, v235, 7
	v_readlane_b32 s8, v235, 8
	v_readlane_b32 s9, v235, 9
	v_readlane_b32 s10, v235, 10
	v_readlane_b32 s11, v235, 11
	v_readlane_b32 s12, v235, 12
	v_readlane_b32 s13, v235, 13
	v_readlane_b32 s16, v235, 16
	v_readlane_b32 s17, v235, 17
	v_readlane_b32 s18, v235, 18
	v_readlane_b32 s19, v235, 19
	v_lshl_add_u64 v[2:3], s[14:15], 0, v[2:3]
	s_mov_b64 s[0:1], 0x2000
	v_lshl_add_u64 v[60:61], s[86:87], 0, v[4:5]
	v_lshl_add_u64 v[64:65], s[54:55], 0, v[4:5]
	v_lshl_add_u64 v[66:67], v[2:3], 0, s[0:1]
	s_mov_b32 s1, 0
	v_cmp_eq_u32_e64 s[16:17], 0, v0
	s_mov_b64 s[4:5], 0x200000
	s_mov_b64 s[6:7], 0x200800
	s_mov_b64 s[8:9], 0x400000
	s_mov_b64 s[10:11], 0x400800
	s_mov_b64 s[12:13], 0x600000
	s_mov_b64 s[14:15], 0x600800
	s_mov_b64 s[18:19], 0x800000
	s_mov_b32 s48, 0x800000
	s_mov_b64 s[20:21], 0x800800
	s_mov_b64 s[22:23], 0xa00000
	s_mov_b64 s[24:25], 0xa00800
	s_mov_b64 s[26:27], 0xc00000
	s_mov_b64 s[28:29], 0xc00800
	s_mov_b64 s[36:37], 0xe00000
	s_mov_b64 s[38:39], 0xe00800
	v_mov_b32_e32 v104, 0
	v_mov_b32_e32 v105, 0x358637bd
	v_readlane_b32 s42, v235, 61
	v_readlane_b32 s43, v235, 62
	v_mbcnt_lo_u32_b32 v176, -1, 0
	v_mbcnt_hi_u32_b32 v176, -1, v176
	v_readlane_b32 s98, v235, 49
	v_readlane_b32 s99, v235, 20
	v_readlane_b32 s100, v235, 14
	v_readlane_b32 s101, v235, 15
	s_nop 3
	s_lshr_b32 vcc_lo, s98, 3
	s_and_b32 vcc_hi, vcc_lo, 7
	s_lshl_b32 vcc_hi, vcc_hi, 8
	s_lshr_b32 vcc_lo, vcc_lo, 3
	s_lshl_b32 vcc_lo, vcc_lo, 3
	s_add_i32 s98, vcc_hi, vcc_lo
	s_add_i32 s98, s98, s99
	v_lshlrev_b32_e32 v177, 4, v176
	s_lshl_b32 s99, s98, 11
	v_add_u32_e32 v177, s99, v177
	v_add_u32_e32 v178, 0x1800000, v177
	v_add_u32_e32 v179, 0x9e00000, v177
	v_lshlrev_b32_e32 v180, 5, v176
	v_add_u32_e32 v181, 0x2000, v180
	global_load_dwordx4 v[128:131], v181, s[100:101]
	global_load_dwordx4 v[132:135], v181, s[100:101] offset:16
	global_load_dwordx4 v[136:139], v181, s[100:101] offset:2048
	global_load_dwordx4 v[140:143], v181, s[100:101] offset:2064
	v_mov_b32_e32 v182, 0x358637bd
	global_load_dwordx4 v[0:3], v178, s[78:79]
	global_load_dwordx4 v[4:7], v178, s[78:79] offset:1024
	global_load_dwordx4 v[8:11], v179, s[78:79]
	global_load_dwordx4 v[12:15], v179, s[78:79] offset:1024
	v_add_u32_e32 v178, 0x400000, v178
	v_add_u32_e32 v179, 0x400000, v179
	global_load_dwordx4 v[16:19], v178, s[78:79]
	global_load_dwordx4 v[20:23], v178, s[78:79] offset:1024
	global_load_dwordx4 v[24:27], v179, s[78:79]
	global_load_dwordx4 v[28:31], v179, s[78:79] offset:1024
	v_add_u32_e32 v178, 0x400000, v178
	v_add_u32_e32 v179, 0x400000, v179
	global_load_dwordx4 v[32:35], v178, s[78:79]
	global_load_dwordx4 v[36:39], v178, s[78:79] offset:1024
	global_load_dwordx4 v[40:43], v179, s[78:79]
	global_load_dwordx4 v[44:47], v179, s[78:79] offset:1024
	v_add_u32_e32 v178, 0x400000, v178
	v_add_u32_e32 v179, 0x400000, v179
	global_load_dwordx4 v[48:51], v178, s[78:79]
	global_load_dwordx4 v[52:55], v178, s[78:79] offset:1024
	global_load_dwordx4 v[56:59], v179, s[78:79]
	global_load_dwordx4 v[60:63], v179, s[78:79] offset:1024
	v_add_u32_e32 v178, 0x400000, v178
	v_add_u32_e32 v179, 0x400000, v179
	global_load_dwordx4 v[64:67], v178, s[78:79]
	global_load_dwordx4 v[68:71], v178, s[78:79] offset:1024
	global_load_dwordx4 v[72:75], v179, s[78:79]
	global_load_dwordx4 v[76:79], v179, s[78:79] offset:1024
	v_add_u32_e32 v178, 0x400000, v178
	v_add_u32_e32 v179, 0x400000, v179
	global_load_dwordx4 v[80:83], v178, s[78:79]
	global_load_dwordx4 v[84:87], v178, s[78:79] offset:1024
	global_load_dwordx4 v[88:91], v179, s[78:79]
	global_load_dwordx4 v[92:95], v179, s[78:79] offset:1024
	v_add_u32_e32 v178, 0x400000, v178
	v_add_u32_e32 v179, 0x400000, v179
	global_load_dwordx4 v[96:99], v178, s[78:79]
	global_load_dwordx4 v[100:103], v178, s[78:79] offset:1024
	global_load_dwordx4 v[104:107], v179, s[78:79]
	global_load_dwordx4 v[108:111], v179, s[78:79] offset:1024
	v_add_u32_e32 v178, 0x400000, v178
	v_add_u32_e32 v179, 0x400000, v179
	global_load_dwordx4 v[112:115], v178, s[78:79]
	global_load_dwordx4 v[116:119], v178, s[78:79] offset:1024
	global_load_dwordx4 v[120:123], v179, s[78:79]
	global_load_dwordx4 v[124:127], v179, s[78:79] offset:1024
	v_mov_b32_e32 v183, s98
	v_lshlrev_b32_e32 v237, 2, v183
	v_add_u32_e32 v237, 0x10000, v237
	v_mov_b32_e32 v179, v183
	s_waitcnt vmcnt(28)
	v_lshlrev_b32_e32 v144, 16, v0
	v_and_b32_e32 v145, 0xffff0000, v0
	v_lshlrev_b32_e32 v146, 16, v1
	v_and_b32_e32 v147, 0xffff0000, v1
	v_lshlrev_b32_e32 v148, 16, v2
	v_and_b32_e32 v149, 0xffff0000, v2
	v_lshlrev_b32_e32 v150, 16, v3
	v_and_b32_e32 v151, 0xffff0000, v3
	v_lshlrev_b32_e32 v152, 16, v4
	v_and_b32_e32 v153, 0xffff0000, v4
	v_lshlrev_b32_e32 v154, 16, v5
	v_and_b32_e32 v155, 0xffff0000, v5
	v_lshlrev_b32_e32 v156, 16, v6
	v_and_b32_e32 v157, 0xffff0000, v6
	v_lshlrev_b32_e32 v158, 16, v7
	v_and_b32_e32 v159, 0xffff0000, v7
	v_lshlrev_b32_e32 v160, 16, v8
	v_and_b32_e32 v161, 0xffff0000, v8
	v_lshlrev_b32_e32 v162, 16, v9
	v_and_b32_e32 v163, 0xffff0000, v9
	v_lshlrev_b32_e32 v164, 16, v10
	v_and_b32_e32 v165, 0xffff0000, v10
	v_lshlrev_b32_e32 v166, 16, v11
	v_and_b32_e32 v167, 0xffff0000, v11
	v_lshlrev_b32_e32 v168, 16, v12
	v_and_b32_e32 v169, 0xffff0000, v12
	v_lshlrev_b32_e32 v170, 16, v13
	v_and_b32_e32 v171, 0xffff0000, v13
	v_lshlrev_b32_e32 v172, 16, v14
	v_and_b32_e32 v173, 0xffff0000, v14
	v_lshlrev_b32_e32 v174, 16, v15
	v_and_b32_e32 v175, 0xffff0000, v15
	v_pk_mul_f32 v[252:253], v[160:161], v[160:161]
	v_pk_mul_f32 v[254:255], v[162:163], v[162:163]
	v_pk_fma_f32 v[252:253], v[164:165], v[164:165], v[252:253]
	v_pk_fma_f32 v[254:255], v[166:167], v[166:167], v[254:255]
	v_pk_fma_f32 v[252:253], v[168:169], v[168:169], v[252:253]
	v_pk_fma_f32 v[254:255], v[170:171], v[170:171], v[254:255]
	v_pk_fma_f32 v[252:253], v[172:173], v[172:173], v[252:253]
	v_pk_fma_f32 v[254:255], v[174:175], v[174:175], v[254:255]
	v_pk_add_f32 v[252:253], v[252:253], v[254:255]
	s_nop 0
	v_add_f32_e32 v183, v252, v253
	s_nop 1
	v_add_f32_dpp v183, v183, v183 quad_perm:[1,0,3,2] row_mask:0xf bank_mask:0xf bound_ctrl:1
	s_nop 1
	v_add_f32_dpp v183, v183, v183 quad_perm:[2,3,0,1] row_mask:0xf bank_mask:0xf bound_ctrl:1
	s_nop 1
	v_add_f32_dpp v183, v183, v183 row_half_mirror row_mask:0xf bank_mask:0xf bound_ctrl:1
	s_nop 1
	v_add_f32_dpp v183, v183, v183 row_mirror row_mask:0xf bank_mask:0xf bound_ctrl:1
	s_nop 1
	v_readlane_b32 s98, v183, 0
	v_readlane_b32 s99, v183, 16
	v_readlane_b32 s100, v183, 32
	v_readlane_b32 s101, v183, 48
	s_nop 1
	v_mov_b32_e32 v183, s98
	v_add_f32_e32 v183, s99, v183
	v_add_f32_e32 v183, s100, v183
	v_add_f32_e32 v183, s101, v183
	v_fmamk_f32 v183, v183, 0x3a800000, v182
	v_cmp_gt_f32_e32 vcc, 0x800000, v183
	v_mul_f32_e32 v181, 0x4b800000, v183
	s_nop 1
	v_cndmask_b32_e32 v183, v183, v181, vcc
	v_rsq_f32_e32 v183, v183
	s_nop 0
	v_mul_f32_e32 v181, 0x45800000, v183
	v_cndmask_b32_e32 v184, v183, v181, vcc
	v_mov_b32_e32 v185, v184
	v_pk_mul_f32 v[160:161], v[160:161], v[184:185]
	v_pk_mul_f32 v[162:163], v[162:163], v[184:185]
	v_pk_mul_f32 v[164:165], v[164:165], v[184:185]
	v_pk_mul_f32 v[166:167], v[166:167], v[184:185]
	v_pk_mul_f32 v[168:169], v[168:169], v[184:185]
	v_pk_mul_f32 v[170:171], v[170:171], v[184:185]
	v_pk_mul_f32 v[172:173], v[172:173], v[184:185]
	v_pk_mul_f32 v[174:175], v[174:175], v[184:185]
	v_pk_fma_f32 v[144:145], v[160:161], v[128:129], v[144:145]
	v_pk_fma_f32 v[146:147], v[162:163], v[130:131], v[146:147]
	v_pk_fma_f32 v[148:149], v[164:165], v[132:133], v[148:149]
	v_pk_fma_f32 v[150:151], v[166:167], v[134:135], v[150:151]
	v_pk_fma_f32 v[152:153], v[168:169], v[136:137], v[152:153]
	v_pk_fma_f32 v[154:155], v[170:171], v[138:139], v[154:155]
	v_pk_fma_f32 v[156:157], v[172:173], v[140:141], v[156:157]
	v_pk_fma_f32 v[158:159], v[174:175], v[142:143], v[158:159]
	v_pk_mul_f32 v[252:253], v[144:145], v[144:145]
	v_pk_mul_f32 v[254:255], v[146:147], v[146:147]
	v_pk_fma_f32 v[252:253], v[148:149], v[148:149], v[252:253]
	v_pk_fma_f32 v[254:255], v[150:151], v[150:151], v[254:255]
	v_pk_fma_f32 v[252:253], v[152:153], v[152:153], v[252:253]
	v_pk_fma_f32 v[254:255], v[154:155], v[154:155], v[254:255]
	v_pk_fma_f32 v[252:253], v[156:157], v[156:157], v[252:253]
	v_pk_fma_f32 v[254:255], v[158:159], v[158:159], v[254:255]
	v_pk_add_f32 v[252:253], v[252:253], v[254:255]
	s_nop 0
	v_add_f32_e32 v183, v252, v253
	s_nop 1
	v_add_f32_dpp v183, v183, v183 quad_perm:[1,0,3,2] row_mask:0xf bank_mask:0xf bound_ctrl:1
	s_nop 1
	v_add_f32_dpp v183, v183, v183 quad_perm:[2,3,0,1] row_mask:0xf bank_mask:0xf bound_ctrl:1
	s_nop 1
	v_add_f32_dpp v183, v183, v183 row_half_mirror row_mask:0xf bank_mask:0xf bound_ctrl:1
	s_nop 1
	v_add_f32_dpp v183, v183, v183 row_mirror row_mask:0xf bank_mask:0xf bound_ctrl:1
	s_nop 1
	v_readlane_b32 s98, v183, 0
	v_readlane_b32 s99, v183, 16
	v_readlane_b32 s100, v183, 32
	v_readlane_b32 s101, v183, 48
	s_nop 1
	v_mov_b32_e32 v183, s98
	v_add_f32_e32 v183, s99, v183
	v_add_f32_e32 v183, s100, v183
	v_add_f32_e32 v183, s101, v183
	v_fmamk_f32 v183, v183, 0x3a800000, v182
	v_cmp_gt_f32_e32 vcc, 0x800000, v183
	v_mul_f32_e32 v181, 0x4b800000, v183
	s_nop 1
	v_cndmask_b32_e32 v183, v183, v181, vcc
	v_rsq_f32_e32 v183, v183
	s_nop 0
	v_mul_f32_e32 v181, 0x45800000, v183
	v_cndmask_b32_e32 v184, v183, v181, vcc
	v_mov_b32_e32 v185, v184
	v_cvt_pk_bf16_f32 v0, v144, v145
	v_cvt_pk_bf16_f32 v1, v146, v147
	v_cvt_pk_bf16_f32 v2, v148, v149
	v_cvt_pk_bf16_f32 v3, v150, v151
	v_cvt_pk_bf16_f32 v4, v152, v153
	v_cvt_pk_bf16_f32 v5, v154, v155
	v_cvt_pk_bf16_f32 v6, v156, v157
	v_cvt_pk_bf16_f32 v7, v158, v159
	v_add_u32_e32 v181, 0x1800000, v177
	global_store_dwordx4 v181, v[0:3], s[78:79]
	global_store_dwordx4 v181, v[4:7], s[78:79] offset:1024
	v_add_u32_e32 v236, 0x0, v237
	s_mov_b64 exec, 1
	global_store_dword v236, v184, s[78:79]
	s_mov_b64 exec, -1
	s_waitcnt vmcnt(24)
	v_lshlrev_b32_e32 v144, 16, v16
	v_and_b32_e32 v145, 0xffff0000, v16
	v_lshlrev_b32_e32 v146, 16, v17
	v_and_b32_e32 v147, 0xffff0000, v17
	v_lshlrev_b32_e32 v148, 16, v18
	v_and_b32_e32 v149, 0xffff0000, v18
	v_lshlrev_b32_e32 v150, 16, v19
	v_and_b32_e32 v151, 0xffff0000, v19
	v_lshlrev_b32_e32 v152, 16, v20
	v_and_b32_e32 v153, 0xffff0000, v20
	v_lshlrev_b32_e32 v154, 16, v21
	v_and_b32_e32 v155, 0xffff0000, v21
	v_lshlrev_b32_e32 v156, 16, v22
	v_and_b32_e32 v157, 0xffff0000, v22
	v_lshlrev_b32_e32 v158, 16, v23
	v_and_b32_e32 v159, 0xffff0000, v23
	v_lshlrev_b32_e32 v160, 16, v24
	v_and_b32_e32 v161, 0xffff0000, v24
	v_lshlrev_b32_e32 v162, 16, v25
	v_and_b32_e32 v163, 0xffff0000, v25
	v_lshlrev_b32_e32 v164, 16, v26
	v_and_b32_e32 v165, 0xffff0000, v26
	v_lshlrev_b32_e32 v166, 16, v27
	v_and_b32_e32 v167, 0xffff0000, v27
	v_lshlrev_b32_e32 v168, 16, v28
	v_and_b32_e32 v169, 0xffff0000, v28
	v_lshlrev_b32_e32 v170, 16, v29
	v_and_b32_e32 v171, 0xffff0000, v29
	v_lshlrev_b32_e32 v172, 16, v30
	v_and_b32_e32 v173, 0xffff0000, v30
	v_lshlrev_b32_e32 v174, 16, v31
	v_and_b32_e32 v175, 0xffff0000, v31
	v_pk_mul_f32 v[252:253], v[160:161], v[160:161]
	v_pk_mul_f32 v[254:255], v[162:163], v[162:163]
	v_pk_fma_f32 v[252:253], v[164:165], v[164:165], v[252:253]
	v_pk_fma_f32 v[254:255], v[166:167], v[166:167], v[254:255]
	v_pk_fma_f32 v[252:253], v[168:169], v[168:169], v[252:253]
	v_pk_fma_f32 v[254:255], v[170:171], v[170:171], v[254:255]
	v_pk_fma_f32 v[252:253], v[172:173], v[172:173], v[252:253]
	v_pk_fma_f32 v[254:255], v[174:175], v[174:175], v[254:255]
	v_pk_add_f32 v[252:253], v[252:253], v[254:255]
	s_nop 0
	v_add_f32_e32 v183, v252, v253
	s_nop 1
	v_add_f32_dpp v183, v183, v183 quad_perm:[1,0,3,2] row_mask:0xf bank_mask:0xf bound_ctrl:1
	s_nop 1
	v_add_f32_dpp v183, v183, v183 quad_perm:[2,3,0,1] row_mask:0xf bank_mask:0xf bound_ctrl:1
	s_nop 1
	v_add_f32_dpp v183, v183, v183 row_half_mirror row_mask:0xf bank_mask:0xf bound_ctrl:1
	s_nop 1
	v_add_f32_dpp v183, v183, v183 row_mirror row_mask:0xf bank_mask:0xf bound_ctrl:1
	s_nop 1
	v_readlane_b32 s98, v183, 0
	v_readlane_b32 s99, v183, 16
	v_readlane_b32 s100, v183, 32
	v_readlane_b32 s101, v183, 48
	s_nop 1
	v_mov_b32_e32 v183, s98
	v_add_f32_e32 v183, s99, v183
	v_add_f32_e32 v183, s100, v183
	v_add_f32_e32 v183, s101, v183
	v_fmamk_f32 v183, v183, 0x3a800000, v182
	v_cmp_gt_f32_e32 vcc, 0x800000, v183
	v_mul_f32_e32 v181, 0x4b800000, v183
	s_nop 1
	v_cndmask_b32_e32 v183, v183, v181, vcc
	v_rsq_f32_e32 v183, v183
	s_nop 0
	v_mul_f32_e32 v181, 0x45800000, v183
	v_cndmask_b32_e32 v184, v183, v181, vcc
	v_mov_b32_e32 v185, v184
	v_pk_mul_f32 v[160:161], v[160:161], v[184:185]
	v_pk_mul_f32 v[162:163], v[162:163], v[184:185]
	v_pk_mul_f32 v[164:165], v[164:165], v[184:185]
	v_pk_mul_f32 v[166:167], v[166:167], v[184:185]
	v_pk_mul_f32 v[168:169], v[168:169], v[184:185]
	v_pk_mul_f32 v[170:171], v[170:171], v[184:185]
	v_pk_mul_f32 v[172:173], v[172:173], v[184:185]
	v_pk_mul_f32 v[174:175], v[174:175], v[184:185]
	v_pk_fma_f32 v[144:145], v[160:161], v[128:129], v[144:145]
	v_pk_fma_f32 v[146:147], v[162:163], v[130:131], v[146:147]
	v_pk_fma_f32 v[148:149], v[164:165], v[132:133], v[148:149]
	v_pk_fma_f32 v[150:151], v[166:167], v[134:135], v[150:151]
	v_pk_fma_f32 v[152:153], v[168:169], v[136:137], v[152:153]
	v_pk_fma_f32 v[154:155], v[170:171], v[138:139], v[154:155]
	v_pk_fma_f32 v[156:157], v[172:173], v[140:141], v[156:157]
	v_pk_fma_f32 v[158:159], v[174:175], v[142:143], v[158:159]
	v_pk_mul_f32 v[252:253], v[144:145], v[144:145]
	v_pk_mul_f32 v[254:255], v[146:147], v[146:147]
	v_pk_fma_f32 v[252:253], v[148:149], v[148:149], v[252:253]
	v_pk_fma_f32 v[254:255], v[150:151], v[150:151], v[254:255]
	v_pk_fma_f32 v[252:253], v[152:153], v[152:153], v[252:253]
	v_pk_fma_f32 v[254:255], v[154:155], v[154:155], v[254:255]
	v_pk_fma_f32 v[252:253], v[156:157], v[156:157], v[252:253]
	v_pk_fma_f32 v[254:255], v[158:159], v[158:159], v[254:255]
	v_pk_add_f32 v[252:253], v[252:253], v[254:255]
	s_nop 0
	v_add_f32_e32 v183, v252, v253
	s_nop 1
	v_add_f32_dpp v183, v183, v183 quad_perm:[1,0,3,2] row_mask:0xf bank_mask:0xf bound_ctrl:1
	s_nop 1
	v_add_f32_dpp v183, v183, v183 quad_perm:[2,3,0,1] row_mask:0xf bank_mask:0xf bound_ctrl:1
	s_nop 1
	v_add_f32_dpp v183, v183, v183 row_half_mirror row_mask:0xf bank_mask:0xf bound_ctrl:1
	s_nop 1
	v_add_f32_dpp v183, v183, v183 row_mirror row_mask:0xf bank_mask:0xf bound_ctrl:1
	s_nop 1
	v_readlane_b32 s98, v183, 0
	v_readlane_b32 s99, v183, 16
	v_readlane_b32 s100, v183, 32
	v_readlane_b32 s101, v183, 48
	s_nop 1
	v_mov_b32_e32 v183, s98
	v_add_f32_e32 v183, s99, v183
	v_add_f32_e32 v183, s100, v183
	v_add_f32_e32 v183, s101, v183
	v_fmamk_f32 v183, v183, 0x3a800000, v182
	v_cmp_gt_f32_e32 vcc, 0x800000, v183
	v_mul_f32_e32 v181, 0x4b800000, v183
	s_nop 1
	v_cndmask_b32_e32 v183, v183, v181, vcc
	v_rsq_f32_e32 v183, v183
	s_nop 0
	v_mul_f32_e32 v181, 0x45800000, v183
	v_cndmask_b32_e32 v184, v183, v181, vcc
	v_mov_b32_e32 v185, v184
	v_cvt_pk_bf16_f32 v16, v144, v145
	v_cvt_pk_bf16_f32 v17, v146, v147
	v_cvt_pk_bf16_f32 v18, v148, v149
	v_cvt_pk_bf16_f32 v19, v150, v151
	v_cvt_pk_bf16_f32 v20, v152, v153
	v_cvt_pk_bf16_f32 v21, v154, v155
	v_cvt_pk_bf16_f32 v22, v156, v157
	v_cvt_pk_bf16_f32 v23, v158, v159
	v_add_u32_e32 v181, 0x1c00000, v177
	global_store_dwordx4 v181, v[16:19], s[78:79]
	global_store_dwordx4 v181, v[20:23], s[78:79] offset:1024
	v_add_u32_e32 v236, 0x2000, v237
	s_mov_b64 exec, 1
	global_store_dword v236, v184, s[78:79]
	s_mov_b64 exec, -1
	s_waitcnt vmcnt(20)
	v_lshlrev_b32_e32 v144, 16, v32
	v_and_b32_e32 v145, 0xffff0000, v32
	v_lshlrev_b32_e32 v146, 16, v33
	v_and_b32_e32 v147, 0xffff0000, v33
	v_lshlrev_b32_e32 v148, 16, v34
	v_and_b32_e32 v149, 0xffff0000, v34
	v_lshlrev_b32_e32 v150, 16, v35
	v_and_b32_e32 v151, 0xffff0000, v35
	v_lshlrev_b32_e32 v152, 16, v36
	v_and_b32_e32 v153, 0xffff0000, v36
	v_lshlrev_b32_e32 v154, 16, v37
	v_and_b32_e32 v155, 0xffff0000, v37
	v_lshlrev_b32_e32 v156, 16, v38
	v_and_b32_e32 v157, 0xffff0000, v38
	v_lshlrev_b32_e32 v158, 16, v39
	v_and_b32_e32 v159, 0xffff0000, v39
	v_lshlrev_b32_e32 v160, 16, v40
	v_and_b32_e32 v161, 0xffff0000, v40
	v_lshlrev_b32_e32 v162, 16, v41
	v_and_b32_e32 v163, 0xffff0000, v41
	v_lshlrev_b32_e32 v164, 16, v42
	v_and_b32_e32 v165, 0xffff0000, v42
	v_lshlrev_b32_e32 v166, 16, v43
	v_and_b32_e32 v167, 0xffff0000, v43
	v_lshlrev_b32_e32 v168, 16, v44
	v_and_b32_e32 v169, 0xffff0000, v44
	v_lshlrev_b32_e32 v170, 16, v45
	v_and_b32_e32 v171, 0xffff0000, v45
	v_lshlrev_b32_e32 v172, 16, v46
	v_and_b32_e32 v173, 0xffff0000, v46
	v_lshlrev_b32_e32 v174, 16, v47
	v_and_b32_e32 v175, 0xffff0000, v47
	v_pk_mul_f32 v[252:253], v[160:161], v[160:161]
	v_pk_mul_f32 v[254:255], v[162:163], v[162:163]
	v_pk_fma_f32 v[252:253], v[164:165], v[164:165], v[252:253]
	v_pk_fma_f32 v[254:255], v[166:167], v[166:167], v[254:255]
	v_pk_fma_f32 v[252:253], v[168:169], v[168:169], v[252:253]
	v_pk_fma_f32 v[254:255], v[170:171], v[170:171], v[254:255]
	v_pk_fma_f32 v[252:253], v[172:173], v[172:173], v[252:253]
	v_pk_fma_f32 v[254:255], v[174:175], v[174:175], v[254:255]
	v_pk_add_f32 v[252:253], v[252:253], v[254:255]
	s_nop 0
	v_add_f32_e32 v183, v252, v253
	s_nop 1
	v_add_f32_dpp v183, v183, v183 quad_perm:[1,0,3,2] row_mask:0xf bank_mask:0xf bound_ctrl:1
	s_nop 1
	v_add_f32_dpp v183, v183, v183 quad_perm:[2,3,0,1] row_mask:0xf bank_mask:0xf bound_ctrl:1
	s_nop 1
	v_add_f32_dpp v183, v183, v183 row_half_mirror row_mask:0xf bank_mask:0xf bound_ctrl:1
	s_nop 1
	v_add_f32_dpp v183, v183, v183 row_mirror row_mask:0xf bank_mask:0xf bound_ctrl:1
	s_nop 1
	v_readlane_b32 s98, v183, 0
	v_readlane_b32 s99, v183, 16
	v_readlane_b32 s100, v183, 32
	v_readlane_b32 s101, v183, 48
	s_nop 1
	v_mov_b32_e32 v183, s98
	v_add_f32_e32 v183, s99, v183
	v_add_f32_e32 v183, s100, v183
	v_add_f32_e32 v183, s101, v183
	v_fmamk_f32 v183, v183, 0x3a800000, v182
	v_cmp_gt_f32_e32 vcc, 0x800000, v183
	v_mul_f32_e32 v181, 0x4b800000, v183
	s_nop 1
	v_cndmask_b32_e32 v183, v183, v181, vcc
	v_rsq_f32_e32 v183, v183
	s_nop 0
	v_mul_f32_e32 v181, 0x45800000, v183
	v_cndmask_b32_e32 v184, v183, v181, vcc
	v_mov_b32_e32 v185, v184
	v_pk_mul_f32 v[160:161], v[160:161], v[184:185]
	v_pk_mul_f32 v[162:163], v[162:163], v[184:185]
	v_pk_mul_f32 v[164:165], v[164:165], v[184:185]
	v_pk_mul_f32 v[166:167], v[166:167], v[184:185]
	v_pk_mul_f32 v[168:169], v[168:169], v[184:185]
	v_pk_mul_f32 v[170:171], v[170:171], v[184:185]
	v_pk_mul_f32 v[172:173], v[172:173], v[184:185]
	v_pk_mul_f32 v[174:175], v[174:175], v[184:185]
	v_pk_fma_f32 v[144:145], v[160:161], v[128:129], v[144:145]
	v_pk_fma_f32 v[146:147], v[162:163], v[130:131], v[146:147]
	v_pk_fma_f32 v[148:149], v[164:165], v[132:133], v[148:149]
	v_pk_fma_f32 v[150:151], v[166:167], v[134:135], v[150:151]
	v_pk_fma_f32 v[152:153], v[168:169], v[136:137], v[152:153]
	v_pk_fma_f32 v[154:155], v[170:171], v[138:139], v[154:155]
	v_pk_fma_f32 v[156:157], v[172:173], v[140:141], v[156:157]
	v_pk_fma_f32 v[158:159], v[174:175], v[142:143], v[158:159]
	v_pk_mul_f32 v[252:253], v[144:145], v[144:145]
	v_pk_mul_f32 v[254:255], v[146:147], v[146:147]
	v_pk_fma_f32 v[252:253], v[148:149], v[148:149], v[252:253]
	v_pk_fma_f32 v[254:255], v[150:151], v[150:151], v[254:255]
	v_pk_fma_f32 v[252:253], v[152:153], v[152:153], v[252:253]
	v_pk_fma_f32 v[254:255], v[154:155], v[154:155], v[254:255]
	v_pk_fma_f32 v[252:253], v[156:157], v[156:157], v[252:253]
	v_pk_fma_f32 v[254:255], v[158:159], v[158:159], v[254:255]
	v_pk_add_f32 v[252:253], v[252:253], v[254:255]
	s_nop 0
	v_add_f32_e32 v183, v252, v253
	s_nop 1
	v_add_f32_dpp v183, v183, v183 quad_perm:[1,0,3,2] row_mask:0xf bank_mask:0xf bound_ctrl:1
	s_nop 1
	v_add_f32_dpp v183, v183, v183 quad_perm:[2,3,0,1] row_mask:0xf bank_mask:0xf bound_ctrl:1
	s_nop 1
	v_add_f32_dpp v183, v183, v183 row_half_mirror row_mask:0xf bank_mask:0xf bound_ctrl:1
	s_nop 1
	v_add_f32_dpp v183, v183, v183 row_mirror row_mask:0xf bank_mask:0xf bound_ctrl:1
	s_nop 1
	v_readlane_b32 s98, v183, 0
	v_readlane_b32 s99, v183, 16
	v_readlane_b32 s100, v183, 32
	v_readlane_b32 s101, v183, 48
	s_nop 1
	v_mov_b32_e32 v183, s98
	v_add_f32_e32 v183, s99, v183
	v_add_f32_e32 v183, s100, v183
	v_add_f32_e32 v183, s101, v183
	v_fmamk_f32 v183, v183, 0x3a800000, v182
	v_cmp_gt_f32_e32 vcc, 0x800000, v183
	v_mul_f32_e32 v181, 0x4b800000, v183
	s_nop 1
	v_cndmask_b32_e32 v183, v183, v181, vcc
	v_rsq_f32_e32 v183, v183
	s_nop 0
	v_mul_f32_e32 v181, 0x45800000, v183
	v_cndmask_b32_e32 v184, v183, v181, vcc
	v_mov_b32_e32 v185, v184
	v_cvt_pk_bf16_f32 v32, v144, v145
	v_cvt_pk_bf16_f32 v33, v146, v147
	v_cvt_pk_bf16_f32 v34, v148, v149
	v_cvt_pk_bf16_f32 v35, v150, v151
	v_cvt_pk_bf16_f32 v36, v152, v153
	v_cvt_pk_bf16_f32 v37, v154, v155
	v_cvt_pk_bf16_f32 v38, v156, v157
	v_cvt_pk_bf16_f32 v39, v158, v159
	v_add_u32_e32 v181, 0x2000000, v177
	global_store_dwordx4 v181, v[32:35], s[78:79]
	global_store_dwordx4 v181, v[36:39], s[78:79] offset:1024
	v_add_u32_e32 v236, 0x4000, v237
	s_mov_b64 exec, 1
	global_store_dword v236, v184, s[78:79]
	s_mov_b64 exec, -1
	s_waitcnt vmcnt(16)
	v_lshlrev_b32_e32 v144, 16, v48
	v_and_b32_e32 v145, 0xffff0000, v48
	v_lshlrev_b32_e32 v146, 16, v49
	v_and_b32_e32 v147, 0xffff0000, v49
	v_lshlrev_b32_e32 v148, 16, v50
	v_and_b32_e32 v149, 0xffff0000, v50
	v_lshlrev_b32_e32 v150, 16, v51
	v_and_b32_e32 v151, 0xffff0000, v51
	v_lshlrev_b32_e32 v152, 16, v52
	v_and_b32_e32 v153, 0xffff0000, v52
	v_lshlrev_b32_e32 v154, 16, v53
	v_and_b32_e32 v155, 0xffff0000, v53
	v_lshlrev_b32_e32 v156, 16, v54
	v_and_b32_e32 v157, 0xffff0000, v54
	v_lshlrev_b32_e32 v158, 16, v55
	v_and_b32_e32 v159, 0xffff0000, v55
	v_lshlrev_b32_e32 v160, 16, v56
	v_and_b32_e32 v161, 0xffff0000, v56
	v_lshlrev_b32_e32 v162, 16, v57
	v_and_b32_e32 v163, 0xffff0000, v57
	v_lshlrev_b32_e32 v164, 16, v58
	v_and_b32_e32 v165, 0xffff0000, v58
	v_lshlrev_b32_e32 v166, 16, v59
	v_and_b32_e32 v167, 0xffff0000, v59
	v_lshlrev_b32_e32 v168, 16, v60
	v_and_b32_e32 v169, 0xffff0000, v60
	v_lshlrev_b32_e32 v170, 16, v61
	v_and_b32_e32 v171, 0xffff0000, v61
	v_lshlrev_b32_e32 v172, 16, v62
	v_and_b32_e32 v173, 0xffff0000, v62
	v_lshlrev_b32_e32 v174, 16, v63
	v_and_b32_e32 v175, 0xffff0000, v63
	v_pk_mul_f32 v[252:253], v[160:161], v[160:161]
	v_pk_mul_f32 v[254:255], v[162:163], v[162:163]
	v_pk_fma_f32 v[252:253], v[164:165], v[164:165], v[252:253]
	v_pk_fma_f32 v[254:255], v[166:167], v[166:167], v[254:255]
	v_pk_fma_f32 v[252:253], v[168:169], v[168:169], v[252:253]
	v_pk_fma_f32 v[254:255], v[170:171], v[170:171], v[254:255]
	v_pk_fma_f32 v[252:253], v[172:173], v[172:173], v[252:253]
	v_pk_fma_f32 v[254:255], v[174:175], v[174:175], v[254:255]
	v_pk_add_f32 v[252:253], v[252:253], v[254:255]
	s_nop 0
	v_add_f32_e32 v183, v252, v253
	s_nop 1
	v_add_f32_dpp v183, v183, v183 quad_perm:[1,0,3,2] row_mask:0xf bank_mask:0xf bound_ctrl:1
	s_nop 1
	v_add_f32_dpp v183, v183, v183 quad_perm:[2,3,0,1] row_mask:0xf bank_mask:0xf bound_ctrl:1
	s_nop 1
	v_add_f32_dpp v183, v183, v183 row_half_mirror row_mask:0xf bank_mask:0xf bound_ctrl:1
	s_nop 1
	v_add_f32_dpp v183, v183, v183 row_mirror row_mask:0xf bank_mask:0xf bound_ctrl:1
	s_nop 1
	v_readlane_b32 s98, v183, 0
	v_readlane_b32 s99, v183, 16
	v_readlane_b32 s100, v183, 32
	v_readlane_b32 s101, v183, 48
	s_nop 1
	v_mov_b32_e32 v183, s98
	v_add_f32_e32 v183, s99, v183
	v_add_f32_e32 v183, s100, v183
	v_add_f32_e32 v183, s101, v183
	v_fmamk_f32 v183, v183, 0x3a800000, v182
	v_cmp_gt_f32_e32 vcc, 0x800000, v183
	v_mul_f32_e32 v181, 0x4b800000, v183
	s_nop 1
	v_cndmask_b32_e32 v183, v183, v181, vcc
	v_rsq_f32_e32 v183, v183
	s_nop 0
	v_mul_f32_e32 v181, 0x45800000, v183
	v_cndmask_b32_e32 v184, v183, v181, vcc
	v_mov_b32_e32 v185, v184
	v_pk_mul_f32 v[160:161], v[160:161], v[184:185]
	v_pk_mul_f32 v[162:163], v[162:163], v[184:185]
	v_pk_mul_f32 v[164:165], v[164:165], v[184:185]
	v_pk_mul_f32 v[166:167], v[166:167], v[184:185]
	v_pk_mul_f32 v[168:169], v[168:169], v[184:185]
	v_pk_mul_f32 v[170:171], v[170:171], v[184:185]
	v_pk_mul_f32 v[172:173], v[172:173], v[184:185]
	v_pk_mul_f32 v[174:175], v[174:175], v[184:185]
	v_pk_fma_f32 v[144:145], v[160:161], v[128:129], v[144:145]
	v_pk_fma_f32 v[146:147], v[162:163], v[130:131], v[146:147]
	v_pk_fma_f32 v[148:149], v[164:165], v[132:133], v[148:149]
	v_pk_fma_f32 v[150:151], v[166:167], v[134:135], v[150:151]
	v_pk_fma_f32 v[152:153], v[168:169], v[136:137], v[152:153]
	v_pk_fma_f32 v[154:155], v[170:171], v[138:139], v[154:155]
	v_pk_fma_f32 v[156:157], v[172:173], v[140:141], v[156:157]
	v_pk_fma_f32 v[158:159], v[174:175], v[142:143], v[158:159]
	v_pk_mul_f32 v[252:253], v[144:145], v[144:145]
	v_pk_mul_f32 v[254:255], v[146:147], v[146:147]
	v_pk_fma_f32 v[252:253], v[148:149], v[148:149], v[252:253]
	v_pk_fma_f32 v[254:255], v[150:151], v[150:151], v[254:255]
	v_pk_fma_f32 v[252:253], v[152:153], v[152:153], v[252:253]
	v_pk_fma_f32 v[254:255], v[154:155], v[154:155], v[254:255]
	v_pk_fma_f32 v[252:253], v[156:157], v[156:157], v[252:253]
	v_pk_fma_f32 v[254:255], v[158:159], v[158:159], v[254:255]
	v_pk_add_f32 v[252:253], v[252:253], v[254:255]
	s_nop 0
	v_add_f32_e32 v183, v252, v253
	s_nop 1
	v_add_f32_dpp v183, v183, v183 quad_perm:[1,0,3,2] row_mask:0xf bank_mask:0xf bound_ctrl:1
	s_nop 1
	v_add_f32_dpp v183, v183, v183 quad_perm:[2,3,0,1] row_mask:0xf bank_mask:0xf bound_ctrl:1
	s_nop 1
	v_add_f32_dpp v183, v183, v183 row_half_mirror row_mask:0xf bank_mask:0xf bound_ctrl:1
	s_nop 1
	v_add_f32_dpp v183, v183, v183 row_mirror row_mask:0xf bank_mask:0xf bound_ctrl:1
	s_nop 1
	v_readlane_b32 s98, v183, 0
	v_readlane_b32 s99, v183, 16
	v_readlane_b32 s100, v183, 32
	v_readlane_b32 s101, v183, 48
	s_nop 1
	v_mov_b32_e32 v183, s98
	v_add_f32_e32 v183, s99, v183
	v_add_f32_e32 v183, s100, v183
	v_add_f32_e32 v183, s101, v183
	v_fmamk_f32 v183, v183, 0x3a800000, v182
	v_cmp_gt_f32_e32 vcc, 0x800000, v183
	v_mul_f32_e32 v181, 0x4b800000, v183
	s_nop 1
	v_cndmask_b32_e32 v183, v183, v181, vcc
	v_rsq_f32_e32 v183, v183
	s_nop 0
	v_mul_f32_e32 v181, 0x45800000, v183
	v_cndmask_b32_e32 v184, v183, v181, vcc
	v_mov_b32_e32 v185, v184
	v_cvt_pk_bf16_f32 v48, v144, v145
	v_cvt_pk_bf16_f32 v49, v146, v147
	v_cvt_pk_bf16_f32 v50, v148, v149
	v_cvt_pk_bf16_f32 v51, v150, v151
	v_cvt_pk_bf16_f32 v52, v152, v153
	v_cvt_pk_bf16_f32 v53, v154, v155
	v_cvt_pk_bf16_f32 v54, v156, v157
	v_cvt_pk_bf16_f32 v55, v158, v159
	v_add_u32_e32 v181, 0x2400000, v177
	global_store_dwordx4 v181, v[48:51], s[78:79]
	global_store_dwordx4 v181, v[52:55], s[78:79] offset:1024
	v_add_u32_e32 v236, 0x6000, v237
	s_mov_b64 exec, 1
	global_store_dword v236, v184, s[78:79]
	s_mov_b64 exec, -1
	s_waitcnt vmcnt(12)
	v_lshlrev_b32_e32 v144, 16, v64
	v_and_b32_e32 v145, 0xffff0000, v64
	v_lshlrev_b32_e32 v146, 16, v65
	v_and_b32_e32 v147, 0xffff0000, v65
	v_lshlrev_b32_e32 v148, 16, v66
	v_and_b32_e32 v149, 0xffff0000, v66
	v_lshlrev_b32_e32 v150, 16, v67
	v_and_b32_e32 v151, 0xffff0000, v67
	v_lshlrev_b32_e32 v152, 16, v68
	v_and_b32_e32 v153, 0xffff0000, v68
	v_lshlrev_b32_e32 v154, 16, v69
	v_and_b32_e32 v155, 0xffff0000, v69
	v_lshlrev_b32_e32 v156, 16, v70
	v_and_b32_e32 v157, 0xffff0000, v70
	v_lshlrev_b32_e32 v158, 16, v71
	v_and_b32_e32 v159, 0xffff0000, v71
	v_lshlrev_b32_e32 v160, 16, v72
	v_and_b32_e32 v161, 0xffff0000, v72
	v_lshlrev_b32_e32 v162, 16, v73
	v_and_b32_e32 v163, 0xffff0000, v73
	v_lshlrev_b32_e32 v164, 16, v74
	v_and_b32_e32 v165, 0xffff0000, v74
	v_lshlrev_b32_e32 v166, 16, v75
	v_and_b32_e32 v167, 0xffff0000, v75
	v_lshlrev_b32_e32 v168, 16, v76
	v_and_b32_e32 v169, 0xffff0000, v76
	v_lshlrev_b32_e32 v170, 16, v77
	v_and_b32_e32 v171, 0xffff0000, v77
	v_lshlrev_b32_e32 v172, 16, v78
	v_and_b32_e32 v173, 0xffff0000, v78
	v_lshlrev_b32_e32 v174, 16, v79
	v_and_b32_e32 v175, 0xffff0000, v79
	v_pk_mul_f32 v[252:253], v[160:161], v[160:161]
	v_pk_mul_f32 v[254:255], v[162:163], v[162:163]
	v_pk_fma_f32 v[252:253], v[164:165], v[164:165], v[252:253]
	v_pk_fma_f32 v[254:255], v[166:167], v[166:167], v[254:255]
	v_pk_fma_f32 v[252:253], v[168:169], v[168:169], v[252:253]
	v_pk_fma_f32 v[254:255], v[170:171], v[170:171], v[254:255]
	v_pk_fma_f32 v[252:253], v[172:173], v[172:173], v[252:253]
	v_pk_fma_f32 v[254:255], v[174:175], v[174:175], v[254:255]
	v_pk_add_f32 v[252:253], v[252:253], v[254:255]
	s_nop 0
	v_add_f32_e32 v183, v252, v253
	s_nop 1
	v_add_f32_dpp v183, v183, v183 quad_perm:[1,0,3,2] row_mask:0xf bank_mask:0xf bound_ctrl:1
	s_nop 1
	v_add_f32_dpp v183, v183, v183 quad_perm:[2,3,0,1] row_mask:0xf bank_mask:0xf bound_ctrl:1
	s_nop 1
	v_add_f32_dpp v183, v183, v183 row_half_mirror row_mask:0xf bank_mask:0xf bound_ctrl:1
	s_nop 1
	v_add_f32_dpp v183, v183, v183 row_mirror row_mask:0xf bank_mask:0xf bound_ctrl:1
	s_nop 1
	v_readlane_b32 s98, v183, 0
	v_readlane_b32 s99, v183, 16
	v_readlane_b32 s100, v183, 32
	v_readlane_b32 s101, v183, 48
	s_nop 1
	v_mov_b32_e32 v183, s98
	v_add_f32_e32 v183, s99, v183
	v_add_f32_e32 v183, s100, v183
	v_add_f32_e32 v183, s101, v183
	v_fmamk_f32 v183, v183, 0x3a800000, v182
	v_cmp_gt_f32_e32 vcc, 0x800000, v183
	v_mul_f32_e32 v181, 0x4b800000, v183
	s_nop 1
	v_cndmask_b32_e32 v183, v183, v181, vcc
	v_rsq_f32_e32 v183, v183
	s_nop 0
	v_mul_f32_e32 v181, 0x45800000, v183
	v_cndmask_b32_e32 v184, v183, v181, vcc
	v_mov_b32_e32 v185, v184
	v_pk_mul_f32 v[160:161], v[160:161], v[184:185]
	v_pk_mul_f32 v[162:163], v[162:163], v[184:185]
	v_pk_mul_f32 v[164:165], v[164:165], v[184:185]
	v_pk_mul_f32 v[166:167], v[166:167], v[184:185]
	v_pk_mul_f32 v[168:169], v[168:169], v[184:185]
	v_pk_mul_f32 v[170:171], v[170:171], v[184:185]
	v_pk_mul_f32 v[172:173], v[172:173], v[184:185]
	v_pk_mul_f32 v[174:175], v[174:175], v[184:185]
	v_pk_fma_f32 v[144:145], v[160:161], v[128:129], v[144:145]
	v_pk_fma_f32 v[146:147], v[162:163], v[130:131], v[146:147]
	v_pk_fma_f32 v[148:149], v[164:165], v[132:133], v[148:149]
	v_pk_fma_f32 v[150:151], v[166:167], v[134:135], v[150:151]
	v_pk_fma_f32 v[152:153], v[168:169], v[136:137], v[152:153]
	v_pk_fma_f32 v[154:155], v[170:171], v[138:139], v[154:155]
	v_pk_fma_f32 v[156:157], v[172:173], v[140:141], v[156:157]
	v_pk_fma_f32 v[158:159], v[174:175], v[142:143], v[158:159]
	v_pk_mul_f32 v[252:253], v[144:145], v[144:145]
	v_pk_mul_f32 v[254:255], v[146:147], v[146:147]
	v_pk_fma_f32 v[252:253], v[148:149], v[148:149], v[252:253]
	v_pk_fma_f32 v[254:255], v[150:151], v[150:151], v[254:255]
	v_pk_fma_f32 v[252:253], v[152:153], v[152:153], v[252:253]
	v_pk_fma_f32 v[254:255], v[154:155], v[154:155], v[254:255]
	v_pk_fma_f32 v[252:253], v[156:157], v[156:157], v[252:253]
	v_pk_fma_f32 v[254:255], v[158:159], v[158:159], v[254:255]
	v_pk_add_f32 v[252:253], v[252:253], v[254:255]
	s_nop 0
	v_add_f32_e32 v183, v252, v253
	s_nop 1
	v_add_f32_dpp v183, v183, v183 quad_perm:[1,0,3,2] row_mask:0xf bank_mask:0xf bound_ctrl:1
	s_nop 1
	v_add_f32_dpp v183, v183, v183 quad_perm:[2,3,0,1] row_mask:0xf bank_mask:0xf bound_ctrl:1
	s_nop 1
	v_add_f32_dpp v183, v183, v183 row_half_mirror row_mask:0xf bank_mask:0xf bound_ctrl:1
	s_nop 1
	v_add_f32_dpp v183, v183, v183 row_mirror row_mask:0xf bank_mask:0xf bound_ctrl:1
	s_nop 1
	v_readlane_b32 s98, v183, 0
	v_readlane_b32 s99, v183, 16
	v_readlane_b32 s100, v183, 32
	v_readlane_b32 s101, v183, 48
	s_nop 1
	v_mov_b32_e32 v183, s98
	v_add_f32_e32 v183, s99, v183
	v_add_f32_e32 v183, s100, v183
	v_add_f32_e32 v183, s101, v183
	v_fmamk_f32 v183, v183, 0x3a800000, v182
	v_cmp_gt_f32_e32 vcc, 0x800000, v183
	v_mul_f32_e32 v181, 0x4b800000, v183
	s_nop 1
	v_cndmask_b32_e32 v183, v183, v181, vcc
	v_rsq_f32_e32 v183, v183
	s_nop 0
	v_mul_f32_e32 v181, 0x45800000, v183
	v_cndmask_b32_e32 v184, v183, v181, vcc
	v_mov_b32_e32 v185, v184
	v_cvt_pk_bf16_f32 v64, v144, v145
	v_cvt_pk_bf16_f32 v65, v146, v147
	v_cvt_pk_bf16_f32 v66, v148, v149
	v_cvt_pk_bf16_f32 v67, v150, v151
	v_cvt_pk_bf16_f32 v68, v152, v153
	v_cvt_pk_bf16_f32 v69, v154, v155
	v_cvt_pk_bf16_f32 v70, v156, v157
	v_cvt_pk_bf16_f32 v71, v158, v159
	v_add_u32_e32 v181, 0x2800000, v177
	global_store_dwordx4 v181, v[64:67], s[78:79]
	global_store_dwordx4 v181, v[68:71], s[78:79] offset:1024
	v_add_u32_e32 v236, 0x8000, v237
	s_mov_b64 exec, 1
	global_store_dword v236, v184, s[78:79]
	s_mov_b64 exec, -1
	s_waitcnt vmcnt(8)
	v_lshlrev_b32_e32 v144, 16, v80
	v_and_b32_e32 v145, 0xffff0000, v80
	v_lshlrev_b32_e32 v146, 16, v81
	v_and_b32_e32 v147, 0xffff0000, v81
	v_lshlrev_b32_e32 v148, 16, v82
	v_and_b32_e32 v149, 0xffff0000, v82
	v_lshlrev_b32_e32 v150, 16, v83
	v_and_b32_e32 v151, 0xffff0000, v83
	v_lshlrev_b32_e32 v152, 16, v84
	v_and_b32_e32 v153, 0xffff0000, v84
	v_lshlrev_b32_e32 v154, 16, v85
	v_and_b32_e32 v155, 0xffff0000, v85
	v_lshlrev_b32_e32 v156, 16, v86
	v_and_b32_e32 v157, 0xffff0000, v86
	v_lshlrev_b32_e32 v158, 16, v87
	v_and_b32_e32 v159, 0xffff0000, v87
	v_lshlrev_b32_e32 v160, 16, v88
	v_and_b32_e32 v161, 0xffff0000, v88
	v_lshlrev_b32_e32 v162, 16, v89
	v_and_b32_e32 v163, 0xffff0000, v89
	v_lshlrev_b32_e32 v164, 16, v90
	v_and_b32_e32 v165, 0xffff0000, v90
	v_lshlrev_b32_e32 v166, 16, v91
	v_and_b32_e32 v167, 0xffff0000, v91
	v_lshlrev_b32_e32 v168, 16, v92
	v_and_b32_e32 v169, 0xffff0000, v92
	v_lshlrev_b32_e32 v170, 16, v93
	v_and_b32_e32 v171, 0xffff0000, v93
	v_lshlrev_b32_e32 v172, 16, v94
	v_and_b32_e32 v173, 0xffff0000, v94
	v_lshlrev_b32_e32 v174, 16, v95
	v_and_b32_e32 v175, 0xffff0000, v95
	v_pk_mul_f32 v[252:253], v[160:161], v[160:161]
	v_pk_mul_f32 v[254:255], v[162:163], v[162:163]
	v_pk_fma_f32 v[252:253], v[164:165], v[164:165], v[252:253]
	v_pk_fma_f32 v[254:255], v[166:167], v[166:167], v[254:255]
	v_pk_fma_f32 v[252:253], v[168:169], v[168:169], v[252:253]
	v_pk_fma_f32 v[254:255], v[170:171], v[170:171], v[254:255]
	v_pk_fma_f32 v[252:253], v[172:173], v[172:173], v[252:253]
	v_pk_fma_f32 v[254:255], v[174:175], v[174:175], v[254:255]
	v_pk_add_f32 v[252:253], v[252:253], v[254:255]
	s_nop 0
	v_add_f32_e32 v183, v252, v253
	s_nop 1
	v_add_f32_dpp v183, v183, v183 quad_perm:[1,0,3,2] row_mask:0xf bank_mask:0xf bound_ctrl:1
	s_nop 1
	v_add_f32_dpp v183, v183, v183 quad_perm:[2,3,0,1] row_mask:0xf bank_mask:0xf bound_ctrl:1
	s_nop 1
	v_add_f32_dpp v183, v183, v183 row_half_mirror row_mask:0xf bank_mask:0xf bound_ctrl:1
	s_nop 1
	v_add_f32_dpp v183, v183, v183 row_mirror row_mask:0xf bank_mask:0xf bound_ctrl:1
	s_nop 1
	v_readlane_b32 s98, v183, 0
	v_readlane_b32 s99, v183, 16
	v_readlane_b32 s100, v183, 32
	v_readlane_b32 s101, v183, 48
	s_nop 1
	v_mov_b32_e32 v183, s98
	v_add_f32_e32 v183, s99, v183
	v_add_f32_e32 v183, s100, v183
	v_add_f32_e32 v183, s101, v183
	v_fmamk_f32 v183, v183, 0x3a800000, v182
	v_cmp_gt_f32_e32 vcc, 0x800000, v183
	v_mul_f32_e32 v181, 0x4b800000, v183
	s_nop 1
	v_cndmask_b32_e32 v183, v183, v181, vcc
	v_rsq_f32_e32 v183, v183
	s_nop 0
	v_mul_f32_e32 v181, 0x45800000, v183
	v_cndmask_b32_e32 v184, v183, v181, vcc
	v_mov_b32_e32 v185, v184
	v_pk_mul_f32 v[160:161], v[160:161], v[184:185]
	v_pk_mul_f32 v[162:163], v[162:163], v[184:185]
	v_pk_mul_f32 v[164:165], v[164:165], v[184:185]
	v_pk_mul_f32 v[166:167], v[166:167], v[184:185]
	v_pk_mul_f32 v[168:169], v[168:169], v[184:185]
	v_pk_mul_f32 v[170:171], v[170:171], v[184:185]
	v_pk_mul_f32 v[172:173], v[172:173], v[184:185]
	v_pk_mul_f32 v[174:175], v[174:175], v[184:185]
	v_pk_fma_f32 v[144:145], v[160:161], v[128:129], v[144:145]
	v_pk_fma_f32 v[146:147], v[162:163], v[130:131], v[146:147]
	v_pk_fma_f32 v[148:149], v[164:165], v[132:133], v[148:149]
	v_pk_fma_f32 v[150:151], v[166:167], v[134:135], v[150:151]
	v_pk_fma_f32 v[152:153], v[168:169], v[136:137], v[152:153]
	v_pk_fma_f32 v[154:155], v[170:171], v[138:139], v[154:155]
	v_pk_fma_f32 v[156:157], v[172:173], v[140:141], v[156:157]
	v_pk_fma_f32 v[158:159], v[174:175], v[142:143], v[158:159]
	v_pk_mul_f32 v[252:253], v[144:145], v[144:145]
	v_pk_mul_f32 v[254:255], v[146:147], v[146:147]
	v_pk_fma_f32 v[252:253], v[148:149], v[148:149], v[252:253]
	v_pk_fma_f32 v[254:255], v[150:151], v[150:151], v[254:255]
	v_pk_fma_f32 v[252:253], v[152:153], v[152:153], v[252:253]
	v_pk_fma_f32 v[254:255], v[154:155], v[154:155], v[254:255]
	v_pk_fma_f32 v[252:253], v[156:157], v[156:157], v[252:253]
	v_pk_fma_f32 v[254:255], v[158:159], v[158:159], v[254:255]
	v_pk_add_f32 v[252:253], v[252:253], v[254:255]
	s_nop 0
	v_add_f32_e32 v183, v252, v253
	s_nop 1
	v_add_f32_dpp v183, v183, v183 quad_perm:[1,0,3,2] row_mask:0xf bank_mask:0xf bound_ctrl:1
	s_nop 1
	v_add_f32_dpp v183, v183, v183 quad_perm:[2,3,0,1] row_mask:0xf bank_mask:0xf bound_ctrl:1
	s_nop 1
	v_add_f32_dpp v183, v183, v183 row_half_mirror row_mask:0xf bank_mask:0xf bound_ctrl:1
	s_nop 1
	v_add_f32_dpp v183, v183, v183 row_mirror row_mask:0xf bank_mask:0xf bound_ctrl:1
	s_nop 1
	v_readlane_b32 s98, v183, 0
	v_readlane_b32 s99, v183, 16
	v_readlane_b32 s100, v183, 32
	v_readlane_b32 s101, v183, 48
	s_nop 1
	v_mov_b32_e32 v183, s98
	v_add_f32_e32 v183, s99, v183
	v_add_f32_e32 v183, s100, v183
	v_add_f32_e32 v183, s101, v183
	v_fmamk_f32 v183, v183, 0x3a800000, v182
	v_cmp_gt_f32_e32 vcc, 0x800000, v183
	v_mul_f32_e32 v181, 0x4b800000, v183
	s_nop 1
	v_cndmask_b32_e32 v183, v183, v181, vcc
	v_rsq_f32_e32 v183, v183
	s_nop 0
	v_mul_f32_e32 v181, 0x45800000, v183
	v_cndmask_b32_e32 v184, v183, v181, vcc
	v_mov_b32_e32 v185, v184
	v_cvt_pk_bf16_f32 v80, v144, v145
	v_cvt_pk_bf16_f32 v81, v146, v147
	v_cvt_pk_bf16_f32 v82, v148, v149
	v_cvt_pk_bf16_f32 v83, v150, v151
	v_cvt_pk_bf16_f32 v84, v152, v153
	v_cvt_pk_bf16_f32 v85, v154, v155
	v_cvt_pk_bf16_f32 v86, v156, v157
	v_cvt_pk_bf16_f32 v87, v158, v159
	v_add_u32_e32 v181, 0x2c00000, v177
	global_store_dwordx4 v181, v[80:83], s[78:79]
	global_store_dwordx4 v181, v[84:87], s[78:79] offset:1024
	v_add_u32_e32 v236, 0xa000, v237
	s_mov_b64 exec, 1
	global_store_dword v236, v184, s[78:79]
	s_mov_b64 exec, -1
	s_waitcnt vmcnt(4)
	v_lshlrev_b32_e32 v144, 16, v96
	v_and_b32_e32 v145, 0xffff0000, v96
	v_lshlrev_b32_e32 v146, 16, v97
	v_and_b32_e32 v147, 0xffff0000, v97
	v_lshlrev_b32_e32 v148, 16, v98
	v_and_b32_e32 v149, 0xffff0000, v98
	v_lshlrev_b32_e32 v150, 16, v99
	v_and_b32_e32 v151, 0xffff0000, v99
	v_lshlrev_b32_e32 v152, 16, v100
	v_and_b32_e32 v153, 0xffff0000, v100
	v_lshlrev_b32_e32 v154, 16, v101
	v_and_b32_e32 v155, 0xffff0000, v101
	v_lshlrev_b32_e32 v156, 16, v102
	v_and_b32_e32 v157, 0xffff0000, v102
	v_lshlrev_b32_e32 v158, 16, v103
	v_and_b32_e32 v159, 0xffff0000, v103
	v_lshlrev_b32_e32 v160, 16, v104
	v_and_b32_e32 v161, 0xffff0000, v104
	v_lshlrev_b32_e32 v162, 16, v105
	v_and_b32_e32 v163, 0xffff0000, v105
	v_lshlrev_b32_e32 v164, 16, v106
	v_and_b32_e32 v165, 0xffff0000, v106
	v_lshlrev_b32_e32 v166, 16, v107
	v_and_b32_e32 v167, 0xffff0000, v107
	v_lshlrev_b32_e32 v168, 16, v108
	v_and_b32_e32 v169, 0xffff0000, v108
	v_lshlrev_b32_e32 v170, 16, v109
	v_and_b32_e32 v171, 0xffff0000, v109
	v_lshlrev_b32_e32 v172, 16, v110
	v_and_b32_e32 v173, 0xffff0000, v110
	v_lshlrev_b32_e32 v174, 16, v111
	v_and_b32_e32 v175, 0xffff0000, v111
	v_pk_mul_f32 v[252:253], v[160:161], v[160:161]
	v_pk_mul_f32 v[254:255], v[162:163], v[162:163]
	v_pk_fma_f32 v[252:253], v[164:165], v[164:165], v[252:253]
	v_pk_fma_f32 v[254:255], v[166:167], v[166:167], v[254:255]
	v_pk_fma_f32 v[252:253], v[168:169], v[168:169], v[252:253]
	v_pk_fma_f32 v[254:255], v[170:171], v[170:171], v[254:255]
	v_pk_fma_f32 v[252:253], v[172:173], v[172:173], v[252:253]
	v_pk_fma_f32 v[254:255], v[174:175], v[174:175], v[254:255]
	v_pk_add_f32 v[252:253], v[252:253], v[254:255]
	s_nop 0
	v_add_f32_e32 v183, v252, v253
	s_nop 1
	v_add_f32_dpp v183, v183, v183 quad_perm:[1,0,3,2] row_mask:0xf bank_mask:0xf bound_ctrl:1
	s_nop 1
	v_add_f32_dpp v183, v183, v183 quad_perm:[2,3,0,1] row_mask:0xf bank_mask:0xf bound_ctrl:1
	s_nop 1
	v_add_f32_dpp v183, v183, v183 row_half_mirror row_mask:0xf bank_mask:0xf bound_ctrl:1
	s_nop 1
	v_add_f32_dpp v183, v183, v183 row_mirror row_mask:0xf bank_mask:0xf bound_ctrl:1
	s_nop 1
	v_readlane_b32 s98, v183, 0
	v_readlane_b32 s99, v183, 16
	v_readlane_b32 s100, v183, 32
	v_readlane_b32 s101, v183, 48
	s_nop 1
	v_mov_b32_e32 v183, s98
	v_add_f32_e32 v183, s99, v183
	v_add_f32_e32 v183, s100, v183
	v_add_f32_e32 v183, s101, v183
	v_fmamk_f32 v183, v183, 0x3a800000, v182
	v_cmp_gt_f32_e32 vcc, 0x800000, v183
	v_mul_f32_e32 v181, 0x4b800000, v183
	s_nop 1
	v_cndmask_b32_e32 v183, v183, v181, vcc
	v_rsq_f32_e32 v183, v183
	s_nop 0
	v_mul_f32_e32 v181, 0x45800000, v183
	v_cndmask_b32_e32 v184, v183, v181, vcc
	v_mov_b32_e32 v185, v184
	v_pk_mul_f32 v[160:161], v[160:161], v[184:185]
	v_pk_mul_f32 v[162:163], v[162:163], v[184:185]
	v_pk_mul_f32 v[164:165], v[164:165], v[184:185]
	v_pk_mul_f32 v[166:167], v[166:167], v[184:185]
	v_pk_mul_f32 v[168:169], v[168:169], v[184:185]
	v_pk_mul_f32 v[170:171], v[170:171], v[184:185]
	v_pk_mul_f32 v[172:173], v[172:173], v[184:185]
	v_pk_mul_f32 v[174:175], v[174:175], v[184:185]
	v_pk_fma_f32 v[144:145], v[160:161], v[128:129], v[144:145]
	v_pk_fma_f32 v[146:147], v[162:163], v[130:131], v[146:147]
	v_pk_fma_f32 v[148:149], v[164:165], v[132:133], v[148:149]
	v_pk_fma_f32 v[150:151], v[166:167], v[134:135], v[150:151]
	v_pk_fma_f32 v[152:153], v[168:169], v[136:137], v[152:153]
	v_pk_fma_f32 v[154:155], v[170:171], v[138:139], v[154:155]
	v_pk_fma_f32 v[156:157], v[172:173], v[140:141], v[156:157]
	v_pk_fma_f32 v[158:159], v[174:175], v[142:143], v[158:159]
	v_pk_mul_f32 v[252:253], v[144:145], v[144:145]
	v_pk_mul_f32 v[254:255], v[146:147], v[146:147]
	v_pk_fma_f32 v[252:253], v[148:149], v[148:149], v[252:253]
	v_pk_fma_f32 v[254:255], v[150:151], v[150:151], v[254:255]
	v_pk_fma_f32 v[252:253], v[152:153], v[152:153], v[252:253]
	v_pk_fma_f32 v[254:255], v[154:155], v[154:155], v[254:255]
	v_pk_fma_f32 v[252:253], v[156:157], v[156:157], v[252:253]
	v_pk_fma_f32 v[254:255], v[158:159], v[158:159], v[254:255]
	v_pk_add_f32 v[252:253], v[252:253], v[254:255]
	s_nop 0
	v_add_f32_e32 v183, v252, v253
	s_nop 1
	v_add_f32_dpp v183, v183, v183 quad_perm:[1,0,3,2] row_mask:0xf bank_mask:0xf bound_ctrl:1
	s_nop 1
	v_add_f32_dpp v183, v183, v183 quad_perm:[2,3,0,1] row_mask:0xf bank_mask:0xf bound_ctrl:1
	s_nop 1
	v_add_f32_dpp v183, v183, v183 row_half_mirror row_mask:0xf bank_mask:0xf bound_ctrl:1
	s_nop 1
	v_add_f32_dpp v183, v183, v183 row_mirror row_mask:0xf bank_mask:0xf bound_ctrl:1
	s_nop 1
	v_readlane_b32 s98, v183, 0
	v_readlane_b32 s99, v183, 16
	v_readlane_b32 s100, v183, 32
	v_readlane_b32 s101, v183, 48
	s_nop 1
	v_mov_b32_e32 v183, s98
	v_add_f32_e32 v183, s99, v183
	v_add_f32_e32 v183, s100, v183
	v_add_f32_e32 v183, s101, v183
	v_fmamk_f32 v183, v183, 0x3a800000, v182
	v_cmp_gt_f32_e32 vcc, 0x800000, v183
	v_mul_f32_e32 v181, 0x4b800000, v183
	s_nop 1
	v_cndmask_b32_e32 v183, v183, v181, vcc
	v_rsq_f32_e32 v183, v183
	s_nop 0
	v_mul_f32_e32 v181, 0x45800000, v183
	v_cndmask_b32_e32 v184, v183, v181, vcc
	v_mov_b32_e32 v185, v184
	v_cvt_pk_bf16_f32 v96, v144, v145
	v_cvt_pk_bf16_f32 v97, v146, v147
	v_cvt_pk_bf16_f32 v98, v148, v149
	v_cvt_pk_bf16_f32 v99, v150, v151
	v_cvt_pk_bf16_f32 v100, v152, v153
	v_cvt_pk_bf16_f32 v101, v154, v155
	v_cvt_pk_bf16_f32 v102, v156, v157
	v_cvt_pk_bf16_f32 v103, v158, v159
	v_add_u32_e32 v181, 0x3000000, v177
	global_store_dwordx4 v181, v[96:99], s[78:79]
	global_store_dwordx4 v181, v[100:103], s[78:79] offset:1024
	v_add_u32_e32 v236, 0xc000, v237
	s_mov_b64 exec, 1
	global_store_dword v236, v184, s[78:79]
	s_mov_b64 exec, -1
	s_waitcnt vmcnt(0)
	v_lshlrev_b32_e32 v144, 16, v112
	v_and_b32_e32 v145, 0xffff0000, v112
	v_lshlrev_b32_e32 v146, 16, v113
	v_and_b32_e32 v147, 0xffff0000, v113
	v_lshlrev_b32_e32 v148, 16, v114
	v_and_b32_e32 v149, 0xffff0000, v114
	v_lshlrev_b32_e32 v150, 16, v115
	v_and_b32_e32 v151, 0xffff0000, v115
	v_lshlrev_b32_e32 v152, 16, v116
	v_and_b32_e32 v153, 0xffff0000, v116
	v_lshlrev_b32_e32 v154, 16, v117
	v_and_b32_e32 v155, 0xffff0000, v117
	v_lshlrev_b32_e32 v156, 16, v118
	v_and_b32_e32 v157, 0xffff0000, v118
	v_lshlrev_b32_e32 v158, 16, v119
	v_and_b32_e32 v159, 0xffff0000, v119
	v_lshlrev_b32_e32 v160, 16, v120
	v_and_b32_e32 v161, 0xffff0000, v120
	v_lshlrev_b32_e32 v162, 16, v121
	v_and_b32_e32 v163, 0xffff0000, v121
	v_lshlrev_b32_e32 v164, 16, v122
	v_and_b32_e32 v165, 0xffff0000, v122
	v_lshlrev_b32_e32 v166, 16, v123
	v_and_b32_e32 v167, 0xffff0000, v123
	v_lshlrev_b32_e32 v168, 16, v124
	v_and_b32_e32 v169, 0xffff0000, v124
	v_lshlrev_b32_e32 v170, 16, v125
	v_and_b32_e32 v171, 0xffff0000, v125
	v_lshlrev_b32_e32 v172, 16, v126
	v_and_b32_e32 v173, 0xffff0000, v126
	v_lshlrev_b32_e32 v174, 16, v127
	v_and_b32_e32 v175, 0xffff0000, v127
	v_pk_mul_f32 v[252:253], v[160:161], v[160:161]
	v_pk_mul_f32 v[254:255], v[162:163], v[162:163]
	v_pk_fma_f32 v[252:253], v[164:165], v[164:165], v[252:253]
	v_pk_fma_f32 v[254:255], v[166:167], v[166:167], v[254:255]
	v_pk_fma_f32 v[252:253], v[168:169], v[168:169], v[252:253]
	v_pk_fma_f32 v[254:255], v[170:171], v[170:171], v[254:255]
	v_pk_fma_f32 v[252:253], v[172:173], v[172:173], v[252:253]
	v_pk_fma_f32 v[254:255], v[174:175], v[174:175], v[254:255]
	v_pk_add_f32 v[252:253], v[252:253], v[254:255]
	s_nop 0
	v_add_f32_e32 v183, v252, v253
	s_nop 1
	v_add_f32_dpp v183, v183, v183 quad_perm:[1,0,3,2] row_mask:0xf bank_mask:0xf bound_ctrl:1
	s_nop 1
	v_add_f32_dpp v183, v183, v183 quad_perm:[2,3,0,1] row_mask:0xf bank_mask:0xf bound_ctrl:1
	s_nop 1
	v_add_f32_dpp v183, v183, v183 row_half_mirror row_mask:0xf bank_mask:0xf bound_ctrl:1
	s_nop 1
	v_add_f32_dpp v183, v183, v183 row_mirror row_mask:0xf bank_mask:0xf bound_ctrl:1
	s_nop 1
	v_readlane_b32 s98, v183, 0
	v_readlane_b32 s99, v183, 16
	v_readlane_b32 s100, v183, 32
	v_readlane_b32 s101, v183, 48
	s_nop 1
	v_mov_b32_e32 v183, s98
	v_add_f32_e32 v183, s99, v183
	v_add_f32_e32 v183, s100, v183
	v_add_f32_e32 v183, s101, v183
	v_fmamk_f32 v183, v183, 0x3a800000, v182
	v_cmp_gt_f32_e32 vcc, 0x800000, v183
	v_mul_f32_e32 v181, 0x4b800000, v183
	s_nop 1
	v_cndmask_b32_e32 v183, v183, v181, vcc
	v_rsq_f32_e32 v183, v183
	s_nop 0
	v_mul_f32_e32 v181, 0x45800000, v183
	v_cndmask_b32_e32 v184, v183, v181, vcc
	v_mov_b32_e32 v185, v184
	v_pk_mul_f32 v[160:161], v[160:161], v[184:185]
	v_pk_mul_f32 v[162:163], v[162:163], v[184:185]
	v_pk_mul_f32 v[164:165], v[164:165], v[184:185]
	v_pk_mul_f32 v[166:167], v[166:167], v[184:185]
	v_pk_mul_f32 v[168:169], v[168:169], v[184:185]
	v_pk_mul_f32 v[170:171], v[170:171], v[184:185]
	v_pk_mul_f32 v[172:173], v[172:173], v[184:185]
	v_pk_mul_f32 v[174:175], v[174:175], v[184:185]
	v_pk_fma_f32 v[144:145], v[160:161], v[128:129], v[144:145]
	v_pk_fma_f32 v[146:147], v[162:163], v[130:131], v[146:147]
	v_pk_fma_f32 v[148:149], v[164:165], v[132:133], v[148:149]
	v_pk_fma_f32 v[150:151], v[166:167], v[134:135], v[150:151]
	v_pk_fma_f32 v[152:153], v[168:169], v[136:137], v[152:153]
	v_pk_fma_f32 v[154:155], v[170:171], v[138:139], v[154:155]
	v_pk_fma_f32 v[156:157], v[172:173], v[140:141], v[156:157]
	v_pk_fma_f32 v[158:159], v[174:175], v[142:143], v[158:159]
	v_pk_mul_f32 v[252:253], v[144:145], v[144:145]
	v_pk_mul_f32 v[254:255], v[146:147], v[146:147]
	v_pk_fma_f32 v[252:253], v[148:149], v[148:149], v[252:253]
	v_pk_fma_f32 v[254:255], v[150:151], v[150:151], v[254:255]
	v_pk_fma_f32 v[252:253], v[152:153], v[152:153], v[252:253]
	v_pk_fma_f32 v[254:255], v[154:155], v[154:155], v[254:255]
	v_pk_fma_f32 v[252:253], v[156:157], v[156:157], v[252:253]
	v_pk_fma_f32 v[254:255], v[158:159], v[158:159], v[254:255]
	v_pk_add_f32 v[252:253], v[252:253], v[254:255]
	s_nop 0
	v_add_f32_e32 v183, v252, v253
	s_nop 1
	v_add_f32_dpp v183, v183, v183 quad_perm:[1,0,3,2] row_mask:0xf bank_mask:0xf bound_ctrl:1
	s_nop 1
	v_add_f32_dpp v183, v183, v183 quad_perm:[2,3,0,1] row_mask:0xf bank_mask:0xf bound_ctrl:1
	s_nop 1
	v_add_f32_dpp v183, v183, v183 row_half_mirror row_mask:0xf bank_mask:0xf bound_ctrl:1
	s_nop 1
	v_add_f32_dpp v183, v183, v183 row_mirror row_mask:0xf bank_mask:0xf bound_ctrl:1
	s_nop 1
	v_readlane_b32 s98, v183, 0
	v_readlane_b32 s99, v183, 16
	v_readlane_b32 s100, v183, 32
	v_readlane_b32 s101, v183, 48
	s_nop 1
	v_mov_b32_e32 v183, s98
	v_add_f32_e32 v183, s99, v183
	v_add_f32_e32 v183, s100, v183
	v_add_f32_e32 v183, s101, v183
	v_fmamk_f32 v183, v183, 0x3a800000, v182
	v_cmp_gt_f32_e32 vcc, 0x800000, v183
	v_mul_f32_e32 v181, 0x4b800000, v183
	s_nop 1
	v_cndmask_b32_e32 v183, v183, v181, vcc
	v_rsq_f32_e32 v183, v183
	s_nop 0
	v_mul_f32_e32 v181, 0x45800000, v183
	v_cndmask_b32_e32 v184, v183, v181, vcc
	v_mov_b32_e32 v185, v184
	v_cvt_pk_bf16_f32 v112, v144, v145
	v_cvt_pk_bf16_f32 v113, v146, v147
	v_cvt_pk_bf16_f32 v114, v148, v149
	v_cvt_pk_bf16_f32 v115, v150, v151
	v_cvt_pk_bf16_f32 v116, v152, v153
	v_cvt_pk_bf16_f32 v117, v154, v155
	v_cvt_pk_bf16_f32 v118, v156, v157
	v_cvt_pk_bf16_f32 v119, v158, v159
	v_add_u32_e32 v181, 0x3400000, v177
	global_store_dwordx4 v181, v[112:115], s[78:79]
	global_store_dwordx4 v181, v[116:119], s[78:79] offset:1024
	v_add_u32_e32 v236, 0xe000, v237
	s_mov_b64 exec, 1
	global_store_dword v236, v184, s[78:79]
	s_mov_b64 exec, -1
	v_readfirstlane_b32 s98, v179
	s_nop 3
	s_cmp_ge_u32 s98, 512
	s_cbranch_scc1 .Lmyxupd_done_4
	v_add_u32_e32 v181, 0x3800000, v177
	global_load_dwordx4 v[0:3], v181, s[78:79]
	global_load_dwordx4 v[4:7], v181, s[78:79] offset:1024
	v_lshl_add_u32 v183, v179, 12, v180
	v_add_u32_e32 v183, 0xbf00000, v183
	v_add_u32_e32 v181, 0x0, v183
	global_load_dwordx4 v[8:11], v181, s[78:79]
	global_load_dwordx4 v[12:15], v181, s[78:79] offset:16
	global_load_dwordx4 v[16:19], v181, s[78:79] offset:2048
	global_load_dwordx4 v[20:23], v181, s[78:79] offset:2064
	v_add_u32_e32 v181, 0x200000, v183
	global_load_dwordx4 v[24:27], v181, s[78:79]
	global_load_dwordx4 v[28:31], v181, s[78:79] offset:16
	global_load_dwordx4 v[32:35], v181, s[78:79] offset:2048
	global_load_dwordx4 v[36:39], v181, s[78:79] offset:2064
	v_add_u32_e32 v181, 0x400000, v183
	global_load_dwordx4 v[40:43], v181, s[78:79]
	global_load_dwordx4 v[44:47], v181, s[78:79] offset:16
	global_load_dwordx4 v[48:51], v181, s[78:79] offset:2048
	global_load_dwordx4 v[52:55], v181, s[78:79] offset:2064
	v_add_u32_e32 v181, 0x600000, v183
	global_load_dwordx4 v[56:59], v181, s[78:79]
	global_load_dwordx4 v[60:63], v181, s[78:79] offset:16
	global_load_dwordx4 v[64:67], v181, s[78:79] offset:2048
	global_load_dwordx4 v[68:71], v181, s[78:79] offset:2064
	v_add_u32_e32 v181, 0x800000, v183
	global_load_dwordx4 v[72:75], v181, s[78:79]
	global_load_dwordx4 v[76:79], v181, s[78:79] offset:16
	global_load_dwordx4 v[80:83], v181, s[78:79] offset:2048
	global_load_dwordx4 v[84:87], v181, s[78:79] offset:2064
	v_add_u32_e32 v181, 0xa00000, v183
	global_load_dwordx4 v[88:91], v181, s[78:79]
	global_load_dwordx4 v[92:95], v181, s[78:79] offset:16
	global_load_dwordx4 v[96:99], v181, s[78:79] offset:2048
	global_load_dwordx4 v[100:103], v181, s[78:79] offset:2064
	s_waitcnt vmcnt(20)
	v_pk_add_f32 v[160:161], v[8:9], 0 op_sel_hi:[1,0]
	v_pk_add_f32 v[162:163], v[10:11], 0 op_sel_hi:[1,0]
	v_pk_add_f32 v[164:165], v[12:13], 0 op_sel_hi:[1,0]
	v_pk_add_f32 v[166:167], v[14:15], 0 op_sel_hi:[1,0]
	v_pk_add_f32 v[168:169], v[16:17], 0 op_sel_hi:[1,0]
	v_pk_add_f32 v[170:171], v[18:19], 0 op_sel_hi:[1,0]
	v_pk_add_f32 v[172:173], v[20:21], 0 op_sel_hi:[1,0]
	v_pk_add_f32 v[174:175], v[22:23], 0 op_sel_hi:[1,0]
	s_waitcnt vmcnt(16)
	v_pk_add_f32 v[160:161], v[160:161], v[24:25]
	v_pk_add_f32 v[162:163], v[162:163], v[26:27]
	v_pk_add_f32 v[164:165], v[164:165], v[28:29]
	v_pk_add_f32 v[166:167], v[166:167], v[30:31]
	v_pk_add_f32 v[168:169], v[168:169], v[32:33]
	v_pk_add_f32 v[170:171], v[170:171], v[34:35]
	v_pk_add_f32 v[172:173], v[172:173], v[36:37]
	v_pk_add_f32 v[174:175], v[174:175], v[38:39]
	s_waitcnt vmcnt(12)
	v_pk_add_f32 v[160:161], v[160:161], v[40:41]
	v_pk_add_f32 v[162:163], v[162:163], v[42:43]
	v_pk_add_f32 v[164:165], v[164:165], v[44:45]
	v_pk_add_f32 v[166:167], v[166:167], v[46:47]
	v_pk_add_f32 v[168:169], v[168:169], v[48:49]
	v_pk_add_f32 v[170:171], v[170:171], v[50:51]
	v_pk_add_f32 v[172:173], v[172:173], v[52:53]
	v_pk_add_f32 v[174:175], v[174:175], v[54:55]
	s_waitcnt vmcnt(8)
	v_pk_add_f32 v[160:161], v[160:161], v[56:57]
	v_pk_add_f32 v[162:163], v[162:163], v[58:59]
	v_pk_add_f32 v[164:165], v[164:165], v[60:61]
	v_pk_add_f32 v[166:167], v[166:167], v[62:63]
	v_pk_add_f32 v[168:169], v[168:169], v[64:65]
	v_pk_add_f32 v[170:171], v[170:171], v[66:67]
	v_pk_add_f32 v[172:173], v[172:173], v[68:69]
	v_pk_add_f32 v[174:175], v[174:175], v[70:71]
	s_waitcnt vmcnt(4)
	v_pk_add_f32 v[160:161], v[160:161], v[72:73]
	v_pk_add_f32 v[162:163], v[162:163], v[74:75]
	v_pk_add_f32 v[164:165], v[164:165], v[76:77]
	v_pk_add_f32 v[166:167], v[166:167], v[78:79]
	v_pk_add_f32 v[168:169], v[168:169], v[80:81]
	v_pk_add_f32 v[170:171], v[170:171], v[82:83]
	v_pk_add_f32 v[172:173], v[172:173], v[84:85]
	v_pk_add_f32 v[174:175], v[174:175], v[86:87]
	s_waitcnt vmcnt(0)
	v_pk_add_f32 v[160:161], v[160:161], v[88:89]
	v_pk_add_f32 v[162:163], v[162:163], v[90:91]
	v_pk_add_f32 v[164:165], v[164:165], v[92:93]
	v_pk_add_f32 v[166:167], v[166:167], v[94:95]
	v_pk_add_f32 v[168:169], v[168:169], v[96:97]
	v_pk_add_f32 v[170:171], v[170:171], v[98:99]
	v_pk_add_f32 v[172:173], v[172:173], v[100:101]
	v_pk_add_f32 v[174:175], v[174:175], v[102:103]
	v_lshlrev_b32_e32 v144, 16, v0
	v_and_b32_e32 v145, 0xffff0000, v0
	v_lshlrev_b32_e32 v146, 16, v1
	v_and_b32_e32 v147, 0xffff0000, v1
	v_lshlrev_b32_e32 v148, 16, v2
	v_and_b32_e32 v149, 0xffff0000, v2
	v_lshlrev_b32_e32 v150, 16, v3
	v_and_b32_e32 v151, 0xffff0000, v3
	v_lshlrev_b32_e32 v152, 16, v4
	v_and_b32_e32 v153, 0xffff0000, v4
	v_lshlrev_b32_e32 v154, 16, v5
	v_and_b32_e32 v155, 0xffff0000, v5
	v_lshlrev_b32_e32 v156, 16, v6
	v_and_b32_e32 v157, 0xffff0000, v6
	v_lshlrev_b32_e32 v158, 16, v7
	v_and_b32_e32 v159, 0xffff0000, v7
	v_add_u32_e32 v181, 0xc00000, v183
	global_load_dwordx4 v[8:11], v181, s[78:79]
	global_load_dwordx4 v[12:15], v181, s[78:79] offset:16
	global_load_dwordx4 v[16:19], v181, s[78:79] offset:2048
	global_load_dwordx4 v[20:23], v181, s[78:79] offset:2064
	v_add_u32_e32 v181, 0xe00000, v183
	global_load_dwordx4 v[24:27], v181, s[78:79]
	global_load_dwordx4 v[28:31], v181, s[78:79] offset:16
	global_load_dwordx4 v[32:35], v181, s[78:79] offset:2048
	global_load_dwordx4 v[36:39], v181, s[78:79] offset:2064
	s_waitcnt vmcnt(4)
	v_pk_add_f32 v[160:161], v[160:161], v[8:9]
	v_pk_add_f32 v[162:163], v[162:163], v[10:11]
	v_pk_add_f32 v[164:165], v[164:165], v[12:13]
	v_pk_add_f32 v[166:167], v[166:167], v[14:15]
	v_pk_add_f32 v[168:169], v[168:169], v[16:17]
	v_pk_add_f32 v[170:171], v[170:171], v[18:19]
	v_pk_add_f32 v[172:173], v[172:173], v[20:21]
	v_pk_add_f32 v[174:175], v[174:175], v[22:23]
	s_waitcnt vmcnt(0)
	v_pk_add_f32 v[160:161], v[160:161], v[24:25]
	v_pk_add_f32 v[162:163], v[162:163], v[26:27]
	v_pk_add_f32 v[164:165], v[164:165], v[28:29]
	v_pk_add_f32 v[166:167], v[166:167], v[30:31]
	v_pk_add_f32 v[168:169], v[168:169], v[32:33]
	v_pk_add_f32 v[170:171], v[170:171], v[34:35]
	v_pk_add_f32 v[172:173], v[172:173], v[36:37]
	v_pk_add_f32 v[174:175], v[174:175], v[38:39]
	v_pk_mul_f32 v[252:253], v[160:161], v[160:161]
	v_pk_mul_f32 v[254:255], v[162:163], v[162:163]
	v_pk_fma_f32 v[252:253], v[164:165], v[164:165], v[252:253]
	v_pk_fma_f32 v[254:255], v[166:167], v[166:167], v[254:255]
	v_pk_fma_f32 v[252:253], v[168:169], v[168:169], v[252:253]
	v_pk_fma_f32 v[254:255], v[170:171], v[170:171], v[254:255]
	v_pk_fma_f32 v[252:253], v[172:173], v[172:173], v[252:253]
	v_pk_fma_f32 v[254:255], v[174:175], v[174:175], v[254:255]
	v_pk_add_f32 v[252:253], v[252:253], v[254:255]
	s_nop 0
	v_add_f32_e32 v183, v252, v253
	s_nop 1
	v_add_f32_dpp v183, v183, v183 quad_perm:[1,0,3,2] row_mask:0xf bank_mask:0xf bound_ctrl:1
	s_nop 1
	v_add_f32_dpp v183, v183, v183 quad_perm:[2,3,0,1] row_mask:0xf bank_mask:0xf bound_ctrl:1
	s_nop 1
	v_add_f32_dpp v183, v183, v183 row_half_mirror row_mask:0xf bank_mask:0xf bound_ctrl:1
	s_nop 1
	v_add_f32_dpp v183, v183, v183 row_mirror row_mask:0xf bank_mask:0xf bound_ctrl:1
	s_nop 1
	v_readlane_b32 s98, v183, 0
	v_readlane_b32 s99, v183, 16
	v_readlane_b32 s100, v183, 32
	v_readlane_b32 s101, v183, 48
	s_nop 1
	v_mov_b32_e32 v183, s98
	v_add_f32_e32 v183, s99, v183
	v_add_f32_e32 v183, s100, v183
	v_add_f32_e32 v183, s101, v183
	v_fmamk_f32 v183, v183, 0x3a800000, v182
	v_cmp_gt_f32_e32 vcc, 0x800000, v183
	v_mul_f32_e32 v181, 0x4b800000, v183
	s_nop 1
	v_cndmask_b32_e32 v183, v183, v181, vcc
	v_rsq_f32_e32 v183, v183
	s_nop 0
	v_mul_f32_e32 v181, 0x45800000, v183
	v_cndmask_b32_e32 v184, v183, v181, vcc
	v_mov_b32_e32 v185, v184
	v_pk_mul_f32 v[160:161], v[160:161], v[184:185]
	v_pk_mul_f32 v[162:163], v[162:163], v[184:185]
	v_pk_mul_f32 v[164:165], v[164:165], v[184:185]
	v_pk_mul_f32 v[166:167], v[166:167], v[184:185]
	v_pk_mul_f32 v[168:169], v[168:169], v[184:185]
	v_pk_mul_f32 v[170:171], v[170:171], v[184:185]
	v_pk_mul_f32 v[172:173], v[172:173], v[184:185]
	v_pk_mul_f32 v[174:175], v[174:175], v[184:185]
	v_pk_fma_f32 v[144:145], v[160:161], v[128:129], v[144:145]
	v_pk_fma_f32 v[146:147], v[162:163], v[130:131], v[146:147]
	v_pk_fma_f32 v[148:149], v[164:165], v[132:133], v[148:149]
	v_pk_fma_f32 v[150:151], v[166:167], v[134:135], v[150:151]
	v_pk_fma_f32 v[152:153], v[168:169], v[136:137], v[152:153]
	v_pk_fma_f32 v[154:155], v[170:171], v[138:139], v[154:155]
	v_pk_fma_f32 v[156:157], v[172:173], v[140:141], v[156:157]
	v_pk_fma_f32 v[158:159], v[174:175], v[142:143], v[158:159]
	v_pk_mul_f32 v[252:253], v[144:145], v[144:145]
	v_pk_mul_f32 v[254:255], v[146:147], v[146:147]
	v_pk_fma_f32 v[252:253], v[148:149], v[148:149], v[252:253]
	v_pk_fma_f32 v[254:255], v[150:151], v[150:151], v[254:255]
	v_pk_fma_f32 v[252:253], v[152:153], v[152:153], v[252:253]
	v_pk_fma_f32 v[254:255], v[154:155], v[154:155], v[254:255]
	v_pk_fma_f32 v[252:253], v[156:157], v[156:157], v[252:253]
	v_pk_fma_f32 v[254:255], v[158:159], v[158:159], v[254:255]
	v_pk_add_f32 v[252:253], v[252:253], v[254:255]
	s_nop 0
	v_add_f32_e32 v183, v252, v253
	s_nop 1
	v_add_f32_dpp v183, v183, v183 quad_perm:[1,0,3,2] row_mask:0xf bank_mask:0xf bound_ctrl:1
	s_nop 1
	v_add_f32_dpp v183, v183, v183 quad_perm:[2,3,0,1] row_mask:0xf bank_mask:0xf bound_ctrl:1
	s_nop 1
	v_add_f32_dpp v183, v183, v183 row_half_mirror row_mask:0xf bank_mask:0xf bound_ctrl:1
	s_nop 1
	v_add_f32_dpp v183, v183, v183 row_mirror row_mask:0xf bank_mask:0xf bound_ctrl:1
	s_nop 1
	v_readlane_b32 s98, v183, 0
	v_readlane_b32 s99, v183, 16
	v_readlane_b32 s100, v183, 32
	v_readlane_b32 s101, v183, 48
	s_nop 1
	v_mov_b32_e32 v183, s98
	v_add_f32_e32 v183, s99, v183
	v_add_f32_e32 v183, s100, v183
	v_add_f32_e32 v183, s101, v183
	v_fmamk_f32 v183, v183, 0x3a800000, v182
	v_cmp_gt_f32_e32 vcc, 0x800000, v183
	v_mul_f32_e32 v181, 0x4b800000, v183
	s_nop 1
	v_cndmask_b32_e32 v183, v183, v181, vcc
	v_rsq_f32_e32 v183, v183
	s_nop 0
	v_mul_f32_e32 v181, 0x45800000, v183
	v_cndmask_b32_e32 v184, v183, v181, vcc
	v_mov_b32_e32 v185, v184
	v_cvt_pk_bf16_f32 v0, v144, v145
	v_cvt_pk_bf16_f32 v1, v146, v147
	v_cvt_pk_bf16_f32 v2, v148, v149
	v_cvt_pk_bf16_f32 v3, v150, v151
	v_cvt_pk_bf16_f32 v4, v152, v153
	v_cvt_pk_bf16_f32 v5, v154, v155
	v_cvt_pk_bf16_f32 v6, v156, v157
	v_cvt_pk_bf16_f32 v7, v158, v159
	v_add_u32_e32 v181, 0x3800000, v177
	global_store_dwordx4 v181, v[0:3], s[78:79]
	global_store_dwordx4 v181, v[4:7], s[78:79] offset:1024
	v_add_u32_e32 v236, 0x10000, v237
	s_mov_b64 exec, 1
	global_store_dword v236, v184, s[78:79]
	s_mov_b64 exec, -1

.LBB0_2139:
	v_readlane_b32 s0, v235, 52
	v_readlane_b32 s1, v235, 53
	s_and_b64 vcc, exec, s[0:1]
	s_waitcnt lgkmcnt(0)
	s_barrier
	v_mbcnt_lo_u32_b32 v0, -1, 0
	v_mbcnt_hi_u32_b32 v0, -1, v0
	s_cbranch_vccnz .LBB0_2159
	v_lshlrev_b32_e32 v2, 3, v0
	v_readlane_b32 s4, v235, 4
	v_ashrrev_i32_e32 v3, 31, v2
	v_readlane_b32 s6, v235, 6
	v_readlane_b32 s7, v235, 7
	v_lshlrev_b64 v[4:5], 1, v[2:3]
	v_lshlrev_b64 v[2:3], 2, v[2:3]
	v_readlane_b32 s5, v235, 5
	v_readlane_b32 s10, v235, 10
	v_readlane_b32 s11, v235, 11
	v_readlane_b32 s18, v235, 18
	v_readlane_b32 s19, v235, 19
	v_readlane_b32 s6, v235, 61
	v_lshl_add_u64 v[154:155], s[90:91], 0, v[2:3]
	v_readlane_b32 s8, v235, 8
	v_lshl_add_u64 v[2:3], s[18:19], 0, v[2:3]
	s_mov_b64 s[0:1], 0x2000
	v_readlane_b32 s4, v235, 0
	v_readlane_b32 s7, v235, 62
	s_mov_b32 s10, s6
	s_ashr_i32 s11, s6, 31
	v_readlane_b32 s9, v235, 9
	v_lshl_add_u64 v[158:159], v[2:3], 0, s[0:1]
	s_lshl_b32 s4, s4, 4
	s_add_i32 s0, s6, 0xffffc000
	s_lshl_b64 s[6:7], s[10:11], 2
	s_mov_b32 s8, s10
	v_readlane_b32 s12, v235, 12
	v_readlane_b32 s13, v235, 13
	v_readlane_b32 s14, v235, 14
	v_readlane_b32 s15, v235, 15
	v_readlane_b32 s16, v235, 16
	v_readlane_b32 s17, v235, 17
	v_readlane_b32 s5, v235, 1
	s_add_u32 s80, s6, 0x10000
	v_writelane_b32 v235, s8, 61
	s_addc_u32 s12, s7, 0
	s_ashr_i32 s5, s4, 31
	v_writelane_b32 v235, s9, 62
	s_lshl_b64 s[8:9], s[10:11], 11
	v_lshl_add_u64 v[152:153], s[86:87], 0, v[4:5]
	v_lshl_add_u64 v[156:157], s[54:55], 0, v[4:5]
	s_mov_b32 s1, 0
	v_cmp_eq_u32_e64 s[16:17], 0, v0
	s_lshl_b64 s[6:7], s[4:5], 2
	v_lshl_add_u64 v[160:161], s[8:9], 0, v[4:5]
	s_lshl_b64 s[8:9], s[4:5], 11
	s_mov_b64 s[20:21], 0x600000
	s_mov_b64 s[22:23], 0x600800
	s_mov_b64 s[24:25], 0x800000
	s_mov_b32 s5, 0x800000
	s_mov_b64 s[26:27], 0x800800
	s_mov_b64 s[28:29], 0xa00000
	s_mov_b64 s[36:37], 0xa00800
	s_mov_b64 s[38:39], 0xc00000
	s_mov_b64 s[40:41], 0xc00800
	s_mov_b64 s[42:43], 0xe00000
	s_mov_b64 s[44:45], 0xe00800
	s_mov_b64 s[46:47], 0x1000000
	s_mov_b32 s13, 0x1000000
	s_mov_b64 s[48:49], 0x1000800
	s_mov_b64 s[50:51], 0x1200000
	s_mov_b32 s14, 0x1200000
	s_mov_b64 s[10:11], 0x1200800
	s_mov_b64 s[82:83], 0x1400000
	s_mov_b32 s15, 0x1400000
	s_mov_b64 s[90:91], 0x1400800
	v_mov_b32_e32 v215, 0
	v_mov_b32_e32 v216, 0x358637bd
	v_mbcnt_lo_u32_b32 v176, -1, 0
	v_mbcnt_hi_u32_b32 v176, -1, v176
	v_readlane_b32 s98, v235, 49
	v_readlane_b32 s99, v235, 20
	v_readlane_b32 s100, v235, 18
	v_readlane_b32 s101, v235, 19
	s_nop 3
	s_lshr_b32 vcc_lo, s98, 3
	s_and_b32 vcc_hi, vcc_lo, 7
	s_lshl_b32 vcc_hi, vcc_hi, 8
	s_lshr_b32 vcc_lo, vcc_lo, 3
	s_lshl_b32 vcc_lo, vcc_lo, 3
	s_add_i32 s98, vcc_hi, vcc_lo
	s_add_i32 s98, s98, s99
	v_lshlrev_b32_e32 v177, 4, v176
	s_lshl_b32 s99, s98, 11
	v_add_u32_e32 v177, s99, v177
	v_add_u32_e32 v178, 0x1800000, v177
	v_add_u32_e32 v179, 0x9e00000, v177
	v_lshlrev_b32_e32 v180, 5, v176
	v_add_u32_e32 v181, 0x2000, v180
	global_load_dwordx4 v[128:131], v181, s[100:101]
	global_load_dwordx4 v[132:135], v181, s[100:101] offset:16
	global_load_dwordx4 v[136:139], v181, s[100:101] offset:2048
	global_load_dwordx4 v[140:143], v181, s[100:101] offset:2064
	v_mov_b32_e32 v182, 0x358637bd
	global_load_dwordx4 v[0:3], v178, s[78:79]
	global_load_dwordx4 v[4:7], v178, s[78:79] offset:1024
	global_load_dwordx4 v[8:11], v179, s[78:79]
	global_load_dwordx4 v[12:15], v179, s[78:79] offset:1024
	v_add_u32_e32 v178, 0x400000, v178
	v_add_u32_e32 v179, 0x400000, v179
	global_load_dwordx4 v[16:19], v178, s[78:79]
	global_load_dwordx4 v[20:23], v178, s[78:79] offset:1024
	global_load_dwordx4 v[24:27], v179, s[78:79]
	global_load_dwordx4 v[28:31], v179, s[78:79] offset:1024
	v_add_u32_e32 v178, 0x400000, v178
	v_add_u32_e32 v179, 0x400000, v179
	global_load_dwordx4 v[32:35], v178, s[78:79]
	global_load_dwordx4 v[36:39], v178, s[78:79] offset:1024
	global_load_dwordx4 v[40:43], v179, s[78:79]
	global_load_dwordx4 v[44:47], v179, s[78:79] offset:1024
	v_add_u32_e32 v178, 0x400000, v178
	v_add_u32_e32 v179, 0x400000, v179
	global_load_dwordx4 v[48:51], v178, s[78:79]
	global_load_dwordx4 v[52:55], v178, s[78:79] offset:1024
	global_load_dwordx4 v[56:59], v179, s[78:79]
	global_load_dwordx4 v[60:63], v179, s[78:79] offset:1024
	v_add_u32_e32 v178, 0x400000, v178
	v_add_u32_e32 v179, 0x400000, v179
	global_load_dwordx4 v[64:67], v178, s[78:79]
	global_load_dwordx4 v[68:71], v178, s[78:79] offset:1024
	global_load_dwordx4 v[72:75], v179, s[78:79]
	global_load_dwordx4 v[76:79], v179, s[78:79] offset:1024
	v_add_u32_e32 v178, 0x400000, v178
	v_add_u32_e32 v179, 0x400000, v179
	global_load_dwordx4 v[80:83], v178, s[78:79]
	global_load_dwordx4 v[84:87], v178, s[78:79] offset:1024
	global_load_dwordx4 v[88:91], v179, s[78:79]
	global_load_dwordx4 v[92:95], v179, s[78:79] offset:1024
	v_add_u32_e32 v178, 0x400000, v178
	v_add_u32_e32 v179, 0x400000, v179
	global_load_dwordx4 v[96:99], v178, s[78:79]
	global_load_dwordx4 v[100:103], v178, s[78:79] offset:1024
	global_load_dwordx4 v[104:107], v179, s[78:79]
	global_load_dwordx4 v[108:111], v179, s[78:79] offset:1024
	v_add_u32_e32 v178, 0x400000, v178
	v_add_u32_e32 v179, 0x400000, v179
	global_load_dwordx4 v[112:115], v178, s[78:79]
	global_load_dwordx4 v[116:119], v178, s[78:79] offset:1024
	global_load_dwordx4 v[120:123], v179, s[78:79]
	global_load_dwordx4 v[124:127], v179, s[78:79] offset:1024
	v_mov_b32_e32 v183, s98
	v_lshlrev_b32_e32 v237, 2, v183
	v_add_u32_e32 v237, 0x10000, v237
	v_mov_b32_e32 v179, v183
	s_waitcnt vmcnt(28)
	v_lshlrev_b32_e32 v144, 16, v0
	v_and_b32_e32 v145, 0xffff0000, v0
	v_lshlrev_b32_e32 v146, 16, v1
	v_and_b32_e32 v147, 0xffff0000, v1
	v_lshlrev_b32_e32 v148, 16, v2
	v_and_b32_e32 v149, 0xffff0000, v2
	v_lshlrev_b32_e32 v150, 16, v3
	v_and_b32_e32 v151, 0xffff0000, v3
	v_lshlrev_b32_e32 v152, 16, v4
	v_and_b32_e32 v153, 0xffff0000, v4
	v_lshlrev_b32_e32 v154, 16, v5
	v_and_b32_e32 v155, 0xffff0000, v5
	v_lshlrev_b32_e32 v156, 16, v6
	v_and_b32_e32 v157, 0xffff0000, v6
	v_lshlrev_b32_e32 v158, 16, v7
	v_and_b32_e32 v159, 0xffff0000, v7
	v_lshlrev_b32_e32 v160, 16, v8
	v_and_b32_e32 v161, 0xffff0000, v8
	v_lshlrev_b32_e32 v162, 16, v9
	v_and_b32_e32 v163, 0xffff0000, v9
	v_lshlrev_b32_e32 v164, 16, v10
	v_and_b32_e32 v165, 0xffff0000, v10
	v_lshlrev_b32_e32 v166, 16, v11
	v_and_b32_e32 v167, 0xffff0000, v11
	v_lshlrev_b32_e32 v168, 16, v12
	v_and_b32_e32 v169, 0xffff0000, v12
	v_lshlrev_b32_e32 v170, 16, v13
	v_and_b32_e32 v171, 0xffff0000, v13
	v_lshlrev_b32_e32 v172, 16, v14
	v_and_b32_e32 v173, 0xffff0000, v14
	v_lshlrev_b32_e32 v174, 16, v15
	v_and_b32_e32 v175, 0xffff0000, v15
	v_pk_mul_f32 v[252:253], v[160:161], v[160:161]
	v_pk_mul_f32 v[254:255], v[162:163], v[162:163]
	v_pk_fma_f32 v[252:253], v[164:165], v[164:165], v[252:253]
	v_pk_fma_f32 v[254:255], v[166:167], v[166:167], v[254:255]
	v_pk_fma_f32 v[252:253], v[168:169], v[168:169], v[252:253]
	v_pk_fma_f32 v[254:255], v[170:171], v[170:171], v[254:255]
	v_pk_fma_f32 v[252:253], v[172:173], v[172:173], v[252:253]
	v_pk_fma_f32 v[254:255], v[174:175], v[174:175], v[254:255]
	v_pk_add_f32 v[252:253], v[252:253], v[254:255]
	s_nop 0
	v_add_f32_e32 v183, v252, v253
	s_nop 1
	v_add_f32_dpp v183, v183, v183 quad_perm:[1,0,3,2] row_mask:0xf bank_mask:0xf bound_ctrl:1
	s_nop 1
	v_add_f32_dpp v183, v183, v183 quad_perm:[2,3,0,1] row_mask:0xf bank_mask:0xf bound_ctrl:1
	s_nop 1
	v_add_f32_dpp v183, v183, v183 row_half_mirror row_mask:0xf bank_mask:0xf bound_ctrl:1
	s_nop 1
	v_add_f32_dpp v183, v183, v183 row_mirror row_mask:0xf bank_mask:0xf bound_ctrl:1
	s_nop 1
	v_readlane_b32 s98, v183, 0
	v_readlane_b32 s99, v183, 16
	v_readlane_b32 s100, v183, 32
	v_readlane_b32 s101, v183, 48
	s_nop 1
	v_mov_b32_e32 v183, s98
	v_add_f32_e32 v183, s99, v183
	v_add_f32_e32 v183, s100, v183
	v_add_f32_e32 v183, s101, v183
	v_fmamk_f32 v183, v183, 0x3a800000, v182
	v_cmp_gt_f32_e32 vcc, 0x800000, v183
	v_mul_f32_e32 v181, 0x4b800000, v183
	s_nop 1
	v_cndmask_b32_e32 v183, v183, v181, vcc
	v_rsq_f32_e32 v183, v183
	s_nop 0
	v_mul_f32_e32 v181, 0x45800000, v183
	v_cndmask_b32_e32 v184, v183, v181, vcc
	v_mov_b32_e32 v185, v184
	v_pk_mul_f32 v[160:161], v[160:161], v[184:185]
	v_pk_mul_f32 v[162:163], v[162:163], v[184:185]
	v_pk_mul_f32 v[164:165], v[164:165], v[184:185]
	v_pk_mul_f32 v[166:167], v[166:167], v[184:185]
	v_pk_mul_f32 v[168:169], v[168:169], v[184:185]
	v_pk_mul_f32 v[170:171], v[170:171], v[184:185]
	v_pk_mul_f32 v[172:173], v[172:173], v[184:185]
	v_pk_mul_f32 v[174:175], v[174:175], v[184:185]
	v_pk_fma_f32 v[144:145], v[160:161], v[128:129], v[144:145]
	v_pk_fma_f32 v[146:147], v[162:163], v[130:131], v[146:147]
	v_pk_fma_f32 v[148:149], v[164:165], v[132:133], v[148:149]
	v_pk_fma_f32 v[150:151], v[166:167], v[134:135], v[150:151]
	v_pk_fma_f32 v[152:153], v[168:169], v[136:137], v[152:153]
	v_pk_fma_f32 v[154:155], v[170:171], v[138:139], v[154:155]
	v_pk_fma_f32 v[156:157], v[172:173], v[140:141], v[156:157]
	v_pk_fma_f32 v[158:159], v[174:175], v[142:143], v[158:159]
	v_pk_mul_f32 v[252:253], v[144:145], v[144:145]
	v_pk_mul_f32 v[254:255], v[146:147], v[146:147]
	v_pk_fma_f32 v[252:253], v[148:149], v[148:149], v[252:253]
	v_pk_fma_f32 v[254:255], v[150:151], v[150:151], v[254:255]
	v_pk_fma_f32 v[252:253], v[152:153], v[152:153], v[252:253]
	v_pk_fma_f32 v[254:255], v[154:155], v[154:155], v[254:255]
	v_pk_fma_f32 v[252:253], v[156:157], v[156:157], v[252:253]
	v_pk_fma_f32 v[254:255], v[158:159], v[158:159], v[254:255]
	v_pk_add_f32 v[252:253], v[252:253], v[254:255]
	s_nop 0
	v_add_f32_e32 v183, v252, v253
	s_nop 1
	v_add_f32_dpp v183, v183, v183 quad_perm:[1,0,3,2] row_mask:0xf bank_mask:0xf bound_ctrl:1
	s_nop 1
	v_add_f32_dpp v183, v183, v183 quad_perm:[2,3,0,1] row_mask:0xf bank_mask:0xf bound_ctrl:1
	s_nop 1
	v_add_f32_dpp v183, v183, v183 row_half_mirror row_mask:0xf bank_mask:0xf bound_ctrl:1
	s_nop 1
	v_add_f32_dpp v183, v183, v183 row_mirror row_mask:0xf bank_mask:0xf bound_ctrl:1
	s_nop 1
	v_readlane_b32 s98, v183, 0
	v_readlane_b32 s99, v183, 16
	v_readlane_b32 s100, v183, 32
	v_readlane_b32 s101, v183, 48
	s_nop 1
	v_mov_b32_e32 v183, s98
	v_add_f32_e32 v183, s99, v183
	v_add_f32_e32 v183, s100, v183
	v_add_f32_e32 v183, s101, v183
	v_fmamk_f32 v183, v183, 0x3a800000, v182
	v_cmp_gt_f32_e32 vcc, 0x800000, v183
	v_mul_f32_e32 v181, 0x4b800000, v183
	s_nop 1
	v_cndmask_b32_e32 v183, v183, v181, vcc
	v_rsq_f32_e32 v183, v183
	s_nop 0
	v_mul_f32_e32 v181, 0x45800000, v183
	v_cndmask_b32_e32 v184, v183, v181, vcc
	v_mov_b32_e32 v185, v184
	v_cvt_pk_bf16_f32 v0, v144, v145
	v_cvt_pk_bf16_f32 v1, v146, v147
	v_cvt_pk_bf16_f32 v2, v148, v149
	v_cvt_pk_bf16_f32 v3, v150, v151
	v_cvt_pk_bf16_f32 v4, v152, v153
	v_cvt_pk_bf16_f32 v5, v154, v155
	v_cvt_pk_bf16_f32 v6, v156, v157
	v_cvt_pk_bf16_f32 v7, v158, v159
	v_add_u32_e32 v181, 0x1800000, v177
	global_store_dwordx4 v181, v[0:3], s[78:79]
	global_store_dwordx4 v181, v[4:7], s[78:79] offset:1024
	v_add_u32_e32 v236, 0x0, v237
	s_mov_b64 exec, 1
	global_store_dword v236, v184, s[78:79]
	s_mov_b64 exec, -1
	s_waitcnt vmcnt(24)
	v_lshlrev_b32_e32 v144, 16, v16
	v_and_b32_e32 v145, 0xffff0000, v16
	v_lshlrev_b32_e32 v146, 16, v17
	v_and_b32_e32 v147, 0xffff0000, v17
	v_lshlrev_b32_e32 v148, 16, v18
	v_and_b32_e32 v149, 0xffff0000, v18
	v_lshlrev_b32_e32 v150, 16, v19
	v_and_b32_e32 v151, 0xffff0000, v19
	v_lshlrev_b32_e32 v152, 16, v20
	v_and_b32_e32 v153, 0xffff0000, v20
	v_lshlrev_b32_e32 v154, 16, v21
	v_and_b32_e32 v155, 0xffff0000, v21
	v_lshlrev_b32_e32 v156, 16, v22
	v_and_b32_e32 v157, 0xffff0000, v22
	v_lshlrev_b32_e32 v158, 16, v23
	v_and_b32_e32 v159, 0xffff0000, v23
	v_lshlrev_b32_e32 v160, 16, v24
	v_and_b32_e32 v161, 0xffff0000, v24
	v_lshlrev_b32_e32 v162, 16, v25
	v_and_b32_e32 v163, 0xffff0000, v25
	v_lshlrev_b32_e32 v164, 16, v26
	v_and_b32_e32 v165, 0xffff0000, v26
	v_lshlrev_b32_e32 v166, 16, v27
	v_and_b32_e32 v167, 0xffff0000, v27
	v_lshlrev_b32_e32 v168, 16, v28
	v_and_b32_e32 v169, 0xffff0000, v28
	v_lshlrev_b32_e32 v170, 16, v29
	v_and_b32_e32 v171, 0xffff0000, v29
	v_lshlrev_b32_e32 v172, 16, v30
	v_and_b32_e32 v173, 0xffff0000, v30
	v_lshlrev_b32_e32 v174, 16, v31
	v_and_b32_e32 v175, 0xffff0000, v31
	v_pk_mul_f32 v[252:253], v[160:161], v[160:161]
	v_pk_mul_f32 v[254:255], v[162:163], v[162:163]
	v_pk_fma_f32 v[252:253], v[164:165], v[164:165], v[252:253]
	v_pk_fma_f32 v[254:255], v[166:167], v[166:167], v[254:255]
	v_pk_fma_f32 v[252:253], v[168:169], v[168:169], v[252:253]
	v_pk_fma_f32 v[254:255], v[170:171], v[170:171], v[254:255]
	v_pk_fma_f32 v[252:253], v[172:173], v[172:173], v[252:253]
	v_pk_fma_f32 v[254:255], v[174:175], v[174:175], v[254:255]
	v_pk_add_f32 v[252:253], v[252:253], v[254:255]
	s_nop 0
	v_add_f32_e32 v183, v252, v253
	s_nop 1
	v_add_f32_dpp v183, v183, v183 quad_perm:[1,0,3,2] row_mask:0xf bank_mask:0xf bound_ctrl:1
	s_nop 1
	v_add_f32_dpp v183, v183, v183 quad_perm:[2,3,0,1] row_mask:0xf bank_mask:0xf bound_ctrl:1
	s_nop 1
	v_add_f32_dpp v183, v183, v183 row_half_mirror row_mask:0xf bank_mask:0xf bound_ctrl:1
	s_nop 1
	v_add_f32_dpp v183, v183, v183 row_mirror row_mask:0xf bank_mask:0xf bound_ctrl:1
	s_nop 1
	v_readlane_b32 s98, v183, 0
	v_readlane_b32 s99, v183, 16
	v_readlane_b32 s100, v183, 32
	v_readlane_b32 s101, v183, 48
	s_nop 1
	v_mov_b32_e32 v183, s98
	v_add_f32_e32 v183, s99, v183
	v_add_f32_e32 v183, s100, v183
	v_add_f32_e32 v183, s101, v183
	v_fmamk_f32 v183, v183, 0x3a800000, v182
	v_cmp_gt_f32_e32 vcc, 0x800000, v183
	v_mul_f32_e32 v181, 0x4b800000, v183
	s_nop 1
	v_cndmask_b32_e32 v183, v183, v181, vcc
	v_rsq_f32_e32 v183, v183
	s_nop 0
	v_mul_f32_e32 v181, 0x45800000, v183
	v_cndmask_b32_e32 v184, v183, v181, vcc
	v_mov_b32_e32 v185, v184
	v_pk_mul_f32 v[160:161], v[160:161], v[184:185]
	v_pk_mul_f32 v[162:163], v[162:163], v[184:185]
	v_pk_mul_f32 v[164:165], v[164:165], v[184:185]
	v_pk_mul_f32 v[166:167], v[166:167], v[184:185]
	v_pk_mul_f32 v[168:169], v[168:169], v[184:185]
	v_pk_mul_f32 v[170:171], v[170:171], v[184:185]
	v_pk_mul_f32 v[172:173], v[172:173], v[184:185]
	v_pk_mul_f32 v[174:175], v[174:175], v[184:185]
	v_pk_fma_f32 v[144:145], v[160:161], v[128:129], v[144:145]
	v_pk_fma_f32 v[146:147], v[162:163], v[130:131], v[146:147]
	v_pk_fma_f32 v[148:149], v[164:165], v[132:133], v[148:149]
	v_pk_fma_f32 v[150:151], v[166:167], v[134:135], v[150:151]
	v_pk_fma_f32 v[152:153], v[168:169], v[136:137], v[152:153]
	v_pk_fma_f32 v[154:155], v[170:171], v[138:139], v[154:155]
	v_pk_fma_f32 v[156:157], v[172:173], v[140:141], v[156:157]
	v_pk_fma_f32 v[158:159], v[174:175], v[142:143], v[158:159]
	v_pk_mul_f32 v[252:253], v[144:145], v[144:145]
	v_pk_mul_f32 v[254:255], v[146:147], v[146:147]
	v_pk_fma_f32 v[252:253], v[148:149], v[148:149], v[252:253]
	v_pk_fma_f32 v[254:255], v[150:151], v[150:151], v[254:255]
	v_pk_fma_f32 v[252:253], v[152:153], v[152:153], v[252:253]
	v_pk_fma_f32 v[254:255], v[154:155], v[154:155], v[254:255]
	v_pk_fma_f32 v[252:253], v[156:157], v[156:157], v[252:253]
	v_pk_fma_f32 v[254:255], v[158:159], v[158:159], v[254:255]
	v_pk_add_f32 v[252:253], v[252:253], v[254:255]
	s_nop 0
	v_add_f32_e32 v183, v252, v253
	s_nop 1
	v_add_f32_dpp v183, v183, v183 quad_perm:[1,0,3,2] row_mask:0xf bank_mask:0xf bound_ctrl:1
	s_nop 1
	v_add_f32_dpp v183, v183, v183 quad_perm:[2,3,0,1] row_mask:0xf bank_mask:0xf bound_ctrl:1
	s_nop 1
	v_add_f32_dpp v183, v183, v183 row_half_mirror row_mask:0xf bank_mask:0xf bound_ctrl:1
	s_nop 1
	v_add_f32_dpp v183, v183, v183 row_mirror row_mask:0xf bank_mask:0xf bound_ctrl:1
	s_nop 1
	v_readlane_b32 s98, v183, 0
	v_readlane_b32 s99, v183, 16
	v_readlane_b32 s100, v183, 32
	v_readlane_b32 s101, v183, 48
	s_nop 1
	v_mov_b32_e32 v183, s98
	v_add_f32_e32 v183, s99, v183
	v_add_f32_e32 v183, s100, v183
	v_add_f32_e32 v183, s101, v183
	v_fmamk_f32 v183, v183, 0x3a800000, v182
	v_cmp_gt_f32_e32 vcc, 0x800000, v183
	v_mul_f32_e32 v181, 0x4b800000, v183
	s_nop 1
	v_cndmask_b32_e32 v183, v183, v181, vcc
	v_rsq_f32_e32 v183, v183
	s_nop 0
	v_mul_f32_e32 v181, 0x45800000, v183
	v_cndmask_b32_e32 v184, v183, v181, vcc
	v_mov_b32_e32 v185, v184
	v_cvt_pk_bf16_f32 v16, v144, v145
	v_cvt_pk_bf16_f32 v17, v146, v147
	v_cvt_pk_bf16_f32 v18, v148, v149
	v_cvt_pk_bf16_f32 v19, v150, v151
	v_cvt_pk_bf16_f32 v20, v152, v153
	v_cvt_pk_bf16_f32 v21, v154, v155
	v_cvt_pk_bf16_f32 v22, v156, v157
	v_cvt_pk_bf16_f32 v23, v158, v159
	v_add_u32_e32 v181, 0x1c00000, v177
	global_store_dwordx4 v181, v[16:19], s[78:79]
	global_store_dwordx4 v181, v[20:23], s[78:79] offset:1024
	v_add_u32_e32 v236, 0x2000, v237
	s_mov_b64 exec, 1
	global_store_dword v236, v184, s[78:79]
	s_mov_b64 exec, -1
	s_waitcnt vmcnt(20)
	v_lshlrev_b32_e32 v144, 16, v32
	v_and_b32_e32 v145, 0xffff0000, v32
	v_lshlrev_b32_e32 v146, 16, v33
	v_and_b32_e32 v147, 0xffff0000, v33
	v_lshlrev_b32_e32 v148, 16, v34
	v_and_b32_e32 v149, 0xffff0000, v34
	v_lshlrev_b32_e32 v150, 16, v35
	v_and_b32_e32 v151, 0xffff0000, v35
	v_lshlrev_b32_e32 v152, 16, v36
	v_and_b32_e32 v153, 0xffff0000, v36
	v_lshlrev_b32_e32 v154, 16, v37
	v_and_b32_e32 v155, 0xffff0000, v37
	v_lshlrev_b32_e32 v156, 16, v38
	v_and_b32_e32 v157, 0xffff0000, v38
	v_lshlrev_b32_e32 v158, 16, v39
	v_and_b32_e32 v159, 0xffff0000, v39
	v_lshlrev_b32_e32 v160, 16, v40
	v_and_b32_e32 v161, 0xffff0000, v40
	v_lshlrev_b32_e32 v162, 16, v41
	v_and_b32_e32 v163, 0xffff0000, v41
	v_lshlrev_b32_e32 v164, 16, v42
	v_and_b32_e32 v165, 0xffff0000, v42
	v_lshlrev_b32_e32 v166, 16, v43
	v_and_b32_e32 v167, 0xffff0000, v43
	v_lshlrev_b32_e32 v168, 16, v44
	v_and_b32_e32 v169, 0xffff0000, v44
	v_lshlrev_b32_e32 v170, 16, v45
	v_and_b32_e32 v171, 0xffff0000, v45
	v_lshlrev_b32_e32 v172, 16, v46
	v_and_b32_e32 v173, 0xffff0000, v46
	v_lshlrev_b32_e32 v174, 16, v47
	v_and_b32_e32 v175, 0xffff0000, v47
	v_pk_mul_f32 v[252:253], v[160:161], v[160:161]
	v_pk_mul_f32 v[254:255], v[162:163], v[162:163]
	v_pk_fma_f32 v[252:253], v[164:165], v[164:165], v[252:253]
	v_pk_fma_f32 v[254:255], v[166:167], v[166:167], v[254:255]
	v_pk_fma_f32 v[252:253], v[168:169], v[168:169], v[252:253]
	v_pk_fma_f32 v[254:255], v[170:171], v[170:171], v[254:255]
	v_pk_fma_f32 v[252:253], v[172:173], v[172:173], v[252:253]
	v_pk_fma_f32 v[254:255], v[174:175], v[174:175], v[254:255]
	v_pk_add_f32 v[252:253], v[252:253], v[254:255]
	s_nop 0
	v_add_f32_e32 v183, v252, v253
	s_nop 1
	v_add_f32_dpp v183, v183, v183 quad_perm:[1,0,3,2] row_mask:0xf bank_mask:0xf bound_ctrl:1
	s_nop 1
	v_add_f32_dpp v183, v183, v183 quad_perm:[2,3,0,1] row_mask:0xf bank_mask:0xf bound_ctrl:1
	s_nop 1
	v_add_f32_dpp v183, v183, v183 row_half_mirror row_mask:0xf bank_mask:0xf bound_ctrl:1
	s_nop 1
	v_add_f32_dpp v183, v183, v183 row_mirror row_mask:0xf bank_mask:0xf bound_ctrl:1
	s_nop 1
	v_readlane_b32 s98, v183, 0
	v_readlane_b32 s99, v183, 16
	v_readlane_b32 s100, v183, 32
	v_readlane_b32 s101, v183, 48
	s_nop 1
	v_mov_b32_e32 v183, s98
	v_add_f32_e32 v183, s99, v183
	v_add_f32_e32 v183, s100, v183
	v_add_f32_e32 v183, s101, v183
	v_fmamk_f32 v183, v183, 0x3a800000, v182
	v_cmp_gt_f32_e32 vcc, 0x800000, v183
	v_mul_f32_e32 v181, 0x4b800000, v183
	s_nop 1
	v_cndmask_b32_e32 v183, v183, v181, vcc
	v_rsq_f32_e32 v183, v183
	s_nop 0
	v_mul_f32_e32 v181, 0x45800000, v183
	v_cndmask_b32_e32 v184, v183, v181, vcc
	v_mov_b32_e32 v185, v184
	v_pk_mul_f32 v[160:161], v[160:161], v[184:185]
	v_pk_mul_f32 v[162:163], v[162:163], v[184:185]
	v_pk_mul_f32 v[164:165], v[164:165], v[184:185]
	v_pk_mul_f32 v[166:167], v[166:167], v[184:185]
	v_pk_mul_f32 v[168:169], v[168:169], v[184:185]
	v_pk_mul_f32 v[170:171], v[170:171], v[184:185]
	v_pk_mul_f32 v[172:173], v[172:173], v[184:185]
	v_pk_mul_f32 v[174:175], v[174:175], v[184:185]
	v_pk_fma_f32 v[144:145], v[160:161], v[128:129], v[144:145]
	v_pk_fma_f32 v[146:147], v[162:163], v[130:131], v[146:147]
	v_pk_fma_f32 v[148:149], v[164:165], v[132:133], v[148:149]
	v_pk_fma_f32 v[150:151], v[166:167], v[134:135], v[150:151]
	v_pk_fma_f32 v[152:153], v[168:169], v[136:137], v[152:153]
	v_pk_fma_f32 v[154:155], v[170:171], v[138:139], v[154:155]
	v_pk_fma_f32 v[156:157], v[172:173], v[140:141], v[156:157]
	v_pk_fma_f32 v[158:159], v[174:175], v[142:143], v[158:159]
	v_pk_mul_f32 v[252:253], v[144:145], v[144:145]
	v_pk_mul_f32 v[254:255], v[146:147], v[146:147]
	v_pk_fma_f32 v[252:253], v[148:149], v[148:149], v[252:253]
	v_pk_fma_f32 v[254:255], v[150:151], v[150:151], v[254:255]
	v_pk_fma_f32 v[252:253], v[152:153], v[152:153], v[252:253]
	v_pk_fma_f32 v[254:255], v[154:155], v[154:155], v[254:255]
	v_pk_fma_f32 v[252:253], v[156:157], v[156:157], v[252:253]
	v_pk_fma_f32 v[254:255], v[158:159], v[158:159], v[254:255]
	v_pk_add_f32 v[252:253], v[252:253], v[254:255]
	s_nop 0
	v_add_f32_e32 v183, v252, v253
	s_nop 1
	v_add_f32_dpp v183, v183, v183 quad_perm:[1,0,3,2] row_mask:0xf bank_mask:0xf bound_ctrl:1
	s_nop 1
	v_add_f32_dpp v183, v183, v183 quad_perm:[2,3,0,1] row_mask:0xf bank_mask:0xf bound_ctrl:1
	s_nop 1
	v_add_f32_dpp v183, v183, v183 row_half_mirror row_mask:0xf bank_mask:0xf bound_ctrl:1
	s_nop 1
	v_add_f32_dpp v183, v183, v183 row_mirror row_mask:0xf bank_mask:0xf bound_ctrl:1
	s_nop 1
	v_readlane_b32 s98, v183, 0
	v_readlane_b32 s99, v183, 16
	v_readlane_b32 s100, v183, 32
	v_readlane_b32 s101, v183, 48
	s_nop 1
	v_mov_b32_e32 v183, s98
	v_add_f32_e32 v183, s99, v183
	v_add_f32_e32 v183, s100, v183
	v_add_f32_e32 v183, s101, v183
	v_fmamk_f32 v183, v183, 0x3a800000, v182
	v_cmp_gt_f32_e32 vcc, 0x800000, v183
	v_mul_f32_e32 v181, 0x4b800000, v183
	s_nop 1
	v_cndmask_b32_e32 v183, v183, v181, vcc
	v_rsq_f32_e32 v183, v183
	s_nop 0
	v_mul_f32_e32 v181, 0x45800000, v183
	v_cndmask_b32_e32 v184, v183, v181, vcc
	v_mov_b32_e32 v185, v184
	v_cvt_pk_bf16_f32 v32, v144, v145
	v_cvt_pk_bf16_f32 v33, v146, v147
	v_cvt_pk_bf16_f32 v34, v148, v149
	v_cvt_pk_bf16_f32 v35, v150, v151
	v_cvt_pk_bf16_f32 v36, v152, v153
	v_cvt_pk_bf16_f32 v37, v154, v155
	v_cvt_pk_bf16_f32 v38, v156, v157
	v_cvt_pk_bf16_f32 v39, v158, v159
	v_add_u32_e32 v181, 0x2000000, v177
	global_store_dwordx4 v181, v[32:35], s[78:79]
	global_store_dwordx4 v181, v[36:39], s[78:79] offset:1024
	v_add_u32_e32 v236, 0x4000, v237
	s_mov_b64 exec, 1
	global_store_dword v236, v184, s[78:79]
	s_mov_b64 exec, -1
	s_waitcnt vmcnt(16)
	v_lshlrev_b32_e32 v144, 16, v48
	v_and_b32_e32 v145, 0xffff0000, v48
	v_lshlrev_b32_e32 v146, 16, v49
	v_and_b32_e32 v147, 0xffff0000, v49
	v_lshlrev_b32_e32 v148, 16, v50
	v_and_b32_e32 v149, 0xffff0000, v50
	v_lshlrev_b32_e32 v150, 16, v51
	v_and_b32_e32 v151, 0xffff0000, v51
	v_lshlrev_b32_e32 v152, 16, v52
	v_and_b32_e32 v153, 0xffff0000, v52
	v_lshlrev_b32_e32 v154, 16, v53
	v_and_b32_e32 v155, 0xffff0000, v53
	v_lshlrev_b32_e32 v156, 16, v54
	v_and_b32_e32 v157, 0xffff0000, v54
	v_lshlrev_b32_e32 v158, 16, v55
	v_and_b32_e32 v159, 0xffff0000, v55
	v_lshlrev_b32_e32 v160, 16, v56
	v_and_b32_e32 v161, 0xffff0000, v56
	v_lshlrev_b32_e32 v162, 16, v57
	v_and_b32_e32 v163, 0xffff0000, v57
	v_lshlrev_b32_e32 v164, 16, v58
	v_and_b32_e32 v165, 0xffff0000, v58
	v_lshlrev_b32_e32 v166, 16, v59
	v_and_b32_e32 v167, 0xffff0000, v59
	v_lshlrev_b32_e32 v168, 16, v60
	v_and_b32_e32 v169, 0xffff0000, v60
	v_lshlrev_b32_e32 v170, 16, v61
	v_and_b32_e32 v171, 0xffff0000, v61
	v_lshlrev_b32_e32 v172, 16, v62
	v_and_b32_e32 v173, 0xffff0000, v62
	v_lshlrev_b32_e32 v174, 16, v63
	v_and_b32_e32 v175, 0xffff0000, v63
	v_pk_mul_f32 v[252:253], v[160:161], v[160:161]
	v_pk_mul_f32 v[254:255], v[162:163], v[162:163]
	v_pk_fma_f32 v[252:253], v[164:165], v[164:165], v[252:253]
	v_pk_fma_f32 v[254:255], v[166:167], v[166:167], v[254:255]
	v_pk_fma_f32 v[252:253], v[168:169], v[168:169], v[252:253]
	v_pk_fma_f32 v[254:255], v[170:171], v[170:171], v[254:255]
	v_pk_fma_f32 v[252:253], v[172:173], v[172:173], v[252:253]
	v_pk_fma_f32 v[254:255], v[174:175], v[174:175], v[254:255]
	v_pk_add_f32 v[252:253], v[252:253], v[254:255]
	s_nop 0
	v_add_f32_e32 v183, v252, v253
	s_nop 1
	v_add_f32_dpp v183, v183, v183 quad_perm:[1,0,3,2] row_mask:0xf bank_mask:0xf bound_ctrl:1
	s_nop 1
	v_add_f32_dpp v183, v183, v183 quad_perm:[2,3,0,1] row_mask:0xf bank_mask:0xf bound_ctrl:1
	s_nop 1
	v_add_f32_dpp v183, v183, v183 row_half_mirror row_mask:0xf bank_mask:0xf bound_ctrl:1
	s_nop 1
	v_add_f32_dpp v183, v183, v183 row_mirror row_mask:0xf bank_mask:0xf bound_ctrl:1
	s_nop 1
	v_readlane_b32 s98, v183, 0
	v_readlane_b32 s99, v183, 16
	v_readlane_b32 s100, v183, 32
	v_readlane_b32 s101, v183, 48
	s_nop 1
	v_mov_b32_e32 v183, s98
	v_add_f32_e32 v183, s99, v183
	v_add_f32_e32 v183, s100, v183
	v_add_f32_e32 v183, s101, v183
	v_fmamk_f32 v183, v183, 0x3a800000, v182
	v_cmp_gt_f32_e32 vcc, 0x800000, v183
	v_mul_f32_e32 v181, 0x4b800000, v183
	s_nop 1
	v_cndmask_b32_e32 v183, v183, v181, vcc
	v_rsq_f32_e32 v183, v183
	s_nop 0
	v_mul_f32_e32 v181, 0x45800000, v183
	v_cndmask_b32_e32 v184, v183, v181, vcc
	v_mov_b32_e32 v185, v184
	v_pk_mul_f32 v[160:161], v[160:161], v[184:185]
	v_pk_mul_f32 v[162:163], v[162:163], v[184:185]
	v_pk_mul_f32 v[164:165], v[164:165], v[184:185]
	v_pk_mul_f32 v[166:167], v[166:167], v[184:185]
	v_pk_mul_f32 v[168:169], v[168:169], v[184:185]
	v_pk_mul_f32 v[170:171], v[170:171], v[184:185]
	v_pk_mul_f32 v[172:173], v[172:173], v[184:185]
	v_pk_mul_f32 v[174:175], v[174:175], v[184:185]
	v_pk_fma_f32 v[144:145], v[160:161], v[128:129], v[144:145]
	v_pk_fma_f32 v[146:147], v[162:163], v[130:131], v[146:147]
	v_pk_fma_f32 v[148:149], v[164:165], v[132:133], v[148:149]
	v_pk_fma_f32 v[150:151], v[166:167], v[134:135], v[150:151]
	v_pk_fma_f32 v[152:153], v[168:169], v[136:137], v[152:153]
	v_pk_fma_f32 v[154:155], v[170:171], v[138:139], v[154:155]
	v_pk_fma_f32 v[156:157], v[172:173], v[140:141], v[156:157]
	v_pk_fma_f32 v[158:159], v[174:175], v[142:143], v[158:159]
	v_pk_mul_f32 v[252:253], v[144:145], v[144:145]
	v_pk_mul_f32 v[254:255], v[146:147], v[146:147]
	v_pk_fma_f32 v[252:253], v[148:149], v[148:149], v[252:253]
	v_pk_fma_f32 v[254:255], v[150:151], v[150:151], v[254:255]
	v_pk_fma_f32 v[252:253], v[152:153], v[152:153], v[252:253]
	v_pk_fma_f32 v[254:255], v[154:155], v[154:155], v[254:255]
	v_pk_fma_f32 v[252:253], v[156:157], v[156:157], v[252:253]
	v_pk_fma_f32 v[254:255], v[158:159], v[158:159], v[254:255]
	v_pk_add_f32 v[252:253], v[252:253], v[254:255]
	s_nop 0
	v_add_f32_e32 v183, v252, v253
	s_nop 1
	v_add_f32_dpp v183, v183, v183 quad_perm:[1,0,3,2] row_mask:0xf bank_mask:0xf bound_ctrl:1
	s_nop 1
	v_add_f32_dpp v183, v183, v183 quad_perm:[2,3,0,1] row_mask:0xf bank_mask:0xf bound_ctrl:1
	s_nop 1
	v_add_f32_dpp v183, v183, v183 row_half_mirror row_mask:0xf bank_mask:0xf bound_ctrl:1
	s_nop 1
	v_add_f32_dpp v183, v183, v183 row_mirror row_mask:0xf bank_mask:0xf bound_ctrl:1
	s_nop 1
	v_readlane_b32 s98, v183, 0
	v_readlane_b32 s99, v183, 16
	v_readlane_b32 s100, v183, 32
	v_readlane_b32 s101, v183, 48
	s_nop 1
	v_mov_b32_e32 v183, s98
	v_add_f32_e32 v183, s99, v183
	v_add_f32_e32 v183, s100, v183
	v_add_f32_e32 v183, s101, v183
	v_fmamk_f32 v183, v183, 0x3a800000, v182
	v_cmp_gt_f32_e32 vcc, 0x800000, v183
	v_mul_f32_e32 v181, 0x4b800000, v183
	s_nop 1
	v_cndmask_b32_e32 v183, v183, v181, vcc
	v_rsq_f32_e32 v183, v183
	s_nop 0
	v_mul_f32_e32 v181, 0x45800000, v183
	v_cndmask_b32_e32 v184, v183, v181, vcc
	v_mov_b32_e32 v185, v184
	v_cvt_pk_bf16_f32 v48, v144, v145
	v_cvt_pk_bf16_f32 v49, v146, v147
	v_cvt_pk_bf16_f32 v50, v148, v149
	v_cvt_pk_bf16_f32 v51, v150, v151
	v_cvt_pk_bf16_f32 v52, v152, v153
	v_cvt_pk_bf16_f32 v53, v154, v155
	v_cvt_pk_bf16_f32 v54, v156, v157
	v_cvt_pk_bf16_f32 v55, v158, v159
	v_add_u32_e32 v181, 0x2400000, v177
	global_store_dwordx4 v181, v[48:51], s[78:79]
	global_store_dwordx4 v181, v[52:55], s[78:79] offset:1024
	v_add_u32_e32 v236, 0x6000, v237
	s_mov_b64 exec, 1
	global_store_dword v236, v184, s[78:79]
	s_mov_b64 exec, -1
	s_waitcnt vmcnt(12)
	v_lshlrev_b32_e32 v144, 16, v64
	v_and_b32_e32 v145, 0xffff0000, v64
	v_lshlrev_b32_e32 v146, 16, v65
	v_and_b32_e32 v147, 0xffff0000, v65
	v_lshlrev_b32_e32 v148, 16, v66
	v_and_b32_e32 v149, 0xffff0000, v66
	v_lshlrev_b32_e32 v150, 16, v67
	v_and_b32_e32 v151, 0xffff0000, v67
	v_lshlrev_b32_e32 v152, 16, v68
	v_and_b32_e32 v153, 0xffff0000, v68
	v_lshlrev_b32_e32 v154, 16, v69
	v_and_b32_e32 v155, 0xffff0000, v69
	v_lshlrev_b32_e32 v156, 16, v70
	v_and_b32_e32 v157, 0xffff0000, v70
	v_lshlrev_b32_e32 v158, 16, v71
	v_and_b32_e32 v159, 0xffff0000, v71
	v_lshlrev_b32_e32 v160, 16, v72
	v_and_b32_e32 v161, 0xffff0000, v72
	v_lshlrev_b32_e32 v162, 16, v73
	v_and_b32_e32 v163, 0xffff0000, v73
	v_lshlrev_b32_e32 v164, 16, v74
	v_and_b32_e32 v165, 0xffff0000, v74
	v_lshlrev_b32_e32 v166, 16, v75
	v_and_b32_e32 v167, 0xffff0000, v75
	v_lshlrev_b32_e32 v168, 16, v76
	v_and_b32_e32 v169, 0xffff0000, v76
	v_lshlrev_b32_e32 v170, 16, v77
	v_and_b32_e32 v171, 0xffff0000, v77
	v_lshlrev_b32_e32 v172, 16, v78
	v_and_b32_e32 v173, 0xffff0000, v78
	v_lshlrev_b32_e32 v174, 16, v79
	v_and_b32_e32 v175, 0xffff0000, v79
	v_pk_mul_f32 v[252:253], v[160:161], v[160:161]
	v_pk_mul_f32 v[254:255], v[162:163], v[162:163]
	v_pk_fma_f32 v[252:253], v[164:165], v[164:165], v[252:253]
	v_pk_fma_f32 v[254:255], v[166:167], v[166:167], v[254:255]
	v_pk_fma_f32 v[252:253], v[168:169], v[168:169], v[252:253]
	v_pk_fma_f32 v[254:255], v[170:171], v[170:171], v[254:255]
	v_pk_fma_f32 v[252:253], v[172:173], v[172:173], v[252:253]
	v_pk_fma_f32 v[254:255], v[174:175], v[174:175], v[254:255]
	v_pk_add_f32 v[252:253], v[252:253], v[254:255]
	s_nop 0
	v_add_f32_e32 v183, v252, v253
	s_nop 1
	v_add_f32_dpp v183, v183, v183 quad_perm:[1,0,3,2] row_mask:0xf bank_mask:0xf bound_ctrl:1
	s_nop 1
	v_add_f32_dpp v183, v183, v183 quad_perm:[2,3,0,1] row_mask:0xf bank_mask:0xf bound_ctrl:1
	s_nop 1
	v_add_f32_dpp v183, v183, v183 row_half_mirror row_mask:0xf bank_mask:0xf bound_ctrl:1
	s_nop 1
	v_add_f32_dpp v183, v183, v183 row_mirror row_mask:0xf bank_mask:0xf bound_ctrl:1
	s_nop 1
	v_readlane_b32 s98, v183, 0
	v_readlane_b32 s99, v183, 16
	v_readlane_b32 s100, v183, 32
	v_readlane_b32 s101, v183, 48
	s_nop 1
	v_mov_b32_e32 v183, s98
	v_add_f32_e32 v183, s99, v183
	v_add_f32_e32 v183, s100, v183
	v_add_f32_e32 v183, s101, v183
	v_fmamk_f32 v183, v183, 0x3a800000, v182
	v_cmp_gt_f32_e32 vcc, 0x800000, v183
	v_mul_f32_e32 v181, 0x4b800000, v183
	s_nop 1
	v_cndmask_b32_e32 v183, v183, v181, vcc
	v_rsq_f32_e32 v183, v183
	s_nop 0
	v_mul_f32_e32 v181, 0x45800000, v183
	v_cndmask_b32_e32 v184, v183, v181, vcc
	v_mov_b32_e32 v185, v184
	v_pk_mul_f32 v[160:161], v[160:161], v[184:185]
	v_pk_mul_f32 v[162:163], v[162:163], v[184:185]
	v_pk_mul_f32 v[164:165], v[164:165], v[184:185]
	v_pk_mul_f32 v[166:167], v[166:167], v[184:185]
	v_pk_mul_f32 v[168:169], v[168:169], v[184:185]
	v_pk_mul_f32 v[170:171], v[170:171], v[184:185]
	v_pk_mul_f32 v[172:173], v[172:173], v[184:185]
	v_pk_mul_f32 v[174:175], v[174:175], v[184:185]
	v_pk_fma_f32 v[144:145], v[160:161], v[128:129], v[144:145]
	v_pk_fma_f32 v[146:147], v[162:163], v[130:131], v[146:147]
	v_pk_fma_f32 v[148:149], v[164:165], v[132:133], v[148:149]
	v_pk_fma_f32 v[150:151], v[166:167], v[134:135], v[150:151]
	v_pk_fma_f32 v[152:153], v[168:169], v[136:137], v[152:153]
	v_pk_fma_f32 v[154:155], v[170:171], v[138:139], v[154:155]
	v_pk_fma_f32 v[156:157], v[172:173], v[140:141], v[156:157]
	v_pk_fma_f32 v[158:159], v[174:175], v[142:143], v[158:159]
	v_pk_mul_f32 v[252:253], v[144:145], v[144:145]
	v_pk_mul_f32 v[254:255], v[146:147], v[146:147]
	v_pk_fma_f32 v[252:253], v[148:149], v[148:149], v[252:253]
	v_pk_fma_f32 v[254:255], v[150:151], v[150:151], v[254:255]
	v_pk_fma_f32 v[252:253], v[152:153], v[152:153], v[252:253]
	v_pk_fma_f32 v[254:255], v[154:155], v[154:155], v[254:255]
	v_pk_fma_f32 v[252:253], v[156:157], v[156:157], v[252:253]
	v_pk_fma_f32 v[254:255], v[158:159], v[158:159], v[254:255]
	v_pk_add_f32 v[252:253], v[252:253], v[254:255]
	s_nop 0
	v_add_f32_e32 v183, v252, v253
	s_nop 1
	v_add_f32_dpp v183, v183, v183 quad_perm:[1,0,3,2] row_mask:0xf bank_mask:0xf bound_ctrl:1
	s_nop 1
	v_add_f32_dpp v183, v183, v183 quad_perm:[2,3,0,1] row_mask:0xf bank_mask:0xf bound_ctrl:1
	s_nop 1
	v_add_f32_dpp v183, v183, v183 row_half_mirror row_mask:0xf bank_mask:0xf bound_ctrl:1
	s_nop 1
	v_add_f32_dpp v183, v183, v183 row_mirror row_mask:0xf bank_mask:0xf bound_ctrl:1
	s_nop 1
	v_readlane_b32 s98, v183, 0
	v_readlane_b32 s99, v183, 16
	v_readlane_b32 s100, v183, 32
	v_readlane_b32 s101, v183, 48
	s_nop 1
	v_mov_b32_e32 v183, s98
	v_add_f32_e32 v183, s99, v183
	v_add_f32_e32 v183, s100, v183
	v_add_f32_e32 v183, s101, v183
	v_fmamk_f32 v183, v183, 0x3a800000, v182
	v_cmp_gt_f32_e32 vcc, 0x800000, v183
	v_mul_f32_e32 v181, 0x4b800000, v183
	s_nop 1
	v_cndmask_b32_e32 v183, v183, v181, vcc
	v_rsq_f32_e32 v183, v183
	s_nop 0
	v_mul_f32_e32 v181, 0x45800000, v183
	v_cndmask_b32_e32 v184, v183, v181, vcc
	v_mov_b32_e32 v185, v184
	v_cvt_pk_bf16_f32 v64, v144, v145
	v_cvt_pk_bf16_f32 v65, v146, v147
	v_cvt_pk_bf16_f32 v66, v148, v149
	v_cvt_pk_bf16_f32 v67, v150, v151
	v_cvt_pk_bf16_f32 v68, v152, v153
	v_cvt_pk_bf16_f32 v69, v154, v155
	v_cvt_pk_bf16_f32 v70, v156, v157
	v_cvt_pk_bf16_f32 v71, v158, v159
	v_add_u32_e32 v181, 0x2800000, v177
	global_store_dwordx4 v181, v[64:67], s[78:79]
	global_store_dwordx4 v181, v[68:71], s[78:79] offset:1024
	v_add_u32_e32 v236, 0x8000, v237
	s_mov_b64 exec, 1
	global_store_dword v236, v184, s[78:79]
	s_mov_b64 exec, -1
	s_waitcnt vmcnt(8)
	v_lshlrev_b32_e32 v144, 16, v80
	v_and_b32_e32 v145, 0xffff0000, v80
	v_lshlrev_b32_e32 v146, 16, v81
	v_and_b32_e32 v147, 0xffff0000, v81
	v_lshlrev_b32_e32 v148, 16, v82
	v_and_b32_e32 v149, 0xffff0000, v82
	v_lshlrev_b32_e32 v150, 16, v83
	v_and_b32_e32 v151, 0xffff0000, v83
	v_lshlrev_b32_e32 v152, 16, v84
	v_and_b32_e32 v153, 0xffff0000, v84
	v_lshlrev_b32_e32 v154, 16, v85
	v_and_b32_e32 v155, 0xffff0000, v85
	v_lshlrev_b32_e32 v156, 16, v86
	v_and_b32_e32 v157, 0xffff0000, v86
	v_lshlrev_b32_e32 v158, 16, v87
	v_and_b32_e32 v159, 0xffff0000, v87
	v_lshlrev_b32_e32 v160, 16, v88
	v_and_b32_e32 v161, 0xffff0000, v88
	v_lshlrev_b32_e32 v162, 16, v89
	v_and_b32_e32 v163, 0xffff0000, v89
	v_lshlrev_b32_e32 v164, 16, v90
	v_and_b32_e32 v165, 0xffff0000, v90
	v_lshlrev_b32_e32 v166, 16, v91
	v_and_b32_e32 v167, 0xffff0000, v91
	v_lshlrev_b32_e32 v168, 16, v92
	v_and_b32_e32 v169, 0xffff0000, v92
	v_lshlrev_b32_e32 v170, 16, v93
	v_and_b32_e32 v171, 0xffff0000, v93
	v_lshlrev_b32_e32 v172, 16, v94
	v_and_b32_e32 v173, 0xffff0000, v94
	v_lshlrev_b32_e32 v174, 16, v95
	v_and_b32_e32 v175, 0xffff0000, v95
	v_pk_mul_f32 v[252:253], v[160:161], v[160:161]
	v_pk_mul_f32 v[254:255], v[162:163], v[162:163]
	v_pk_fma_f32 v[252:253], v[164:165], v[164:165], v[252:253]
	v_pk_fma_f32 v[254:255], v[166:167], v[166:167], v[254:255]
	v_pk_fma_f32 v[252:253], v[168:169], v[168:169], v[252:253]
	v_pk_fma_f32 v[254:255], v[170:171], v[170:171], v[254:255]
	v_pk_fma_f32 v[252:253], v[172:173], v[172:173], v[252:253]
	v_pk_fma_f32 v[254:255], v[174:175], v[174:175], v[254:255]
	v_pk_add_f32 v[252:253], v[252:253], v[254:255]
	s_nop 0
	v_add_f32_e32 v183, v252, v253
	s_nop 1
	v_add_f32_dpp v183, v183, v183 quad_perm:[1,0,3,2] row_mask:0xf bank_mask:0xf bound_ctrl:1
	s_nop 1
	v_add_f32_dpp v183, v183, v183 quad_perm:[2,3,0,1] row_mask:0xf bank_mask:0xf bound_ctrl:1
	s_nop 1
	v_add_f32_dpp v183, v183, v183 row_half_mirror row_mask:0xf bank_mask:0xf bound_ctrl:1
	s_nop 1
	v_add_f32_dpp v183, v183, v183 row_mirror row_mask:0xf bank_mask:0xf bound_ctrl:1
	s_nop 1
	v_readlane_b32 s98, v183, 0
	v_readlane_b32 s99, v183, 16
	v_readlane_b32 s100, v183, 32
	v_readlane_b32 s101, v183, 48
	s_nop 1
	v_mov_b32_e32 v183, s98
	v_add_f32_e32 v183, s99, v183
	v_add_f32_e32 v183, s100, v183
	v_add_f32_e32 v183, s101, v183
	v_fmamk_f32 v183, v183, 0x3a800000, v182
	v_cmp_gt_f32_e32 vcc, 0x800000, v183
	v_mul_f32_e32 v181, 0x4b800000, v183
	s_nop 1
	v_cndmask_b32_e32 v183, v183, v181, vcc
	v_rsq_f32_e32 v183, v183
	s_nop 0
	v_mul_f32_e32 v181, 0x45800000, v183
	v_cndmask_b32_e32 v184, v183, v181, vcc
	v_mov_b32_e32 v185, v184
	v_pk_mul_f32 v[160:161], v[160:161], v[184:185]
	v_pk_mul_f32 v[162:163], v[162:163], v[184:185]
	v_pk_mul_f32 v[164:165], v[164:165], v[184:185]
	v_pk_mul_f32 v[166:167], v[166:167], v[184:185]
	v_pk_mul_f32 v[168:169], v[168:169], v[184:185]
	v_pk_mul_f32 v[170:171], v[170:171], v[184:185]
	v_pk_mul_f32 v[172:173], v[172:173], v[184:185]
	v_pk_mul_f32 v[174:175], v[174:175], v[184:185]
	v_pk_fma_f32 v[144:145], v[160:161], v[128:129], v[144:145]
	v_pk_fma_f32 v[146:147], v[162:163], v[130:131], v[146:147]
	v_pk_fma_f32 v[148:149], v[164:165], v[132:133], v[148:149]
	v_pk_fma_f32 v[150:151], v[166:167], v[134:135], v[150:151]
	v_pk_fma_f32 v[152:153], v[168:169], v[136:137], v[152:153]
	v_pk_fma_f32 v[154:155], v[170:171], v[138:139], v[154:155]
	v_pk_fma_f32 v[156:157], v[172:173], v[140:141], v[156:157]
	v_pk_fma_f32 v[158:159], v[174:175], v[142:143], v[158:159]
	v_pk_mul_f32 v[252:253], v[144:145], v[144:145]
	v_pk_mul_f32 v[254:255], v[146:147], v[146:147]
	v_pk_fma_f32 v[252:253], v[148:149], v[148:149], v[252:253]
	v_pk_fma_f32 v[254:255], v[150:151], v[150:151], v[254:255]
	v_pk_fma_f32 v[252:253], v[152:153], v[152:153], v[252:253]
	v_pk_fma_f32 v[254:255], v[154:155], v[154:155], v[254:255]
	v_pk_fma_f32 v[252:253], v[156:157], v[156:157], v[252:253]
	v_pk_fma_f32 v[254:255], v[158:159], v[158:159], v[254:255]
	v_pk_add_f32 v[252:253], v[252:253], v[254:255]
	s_nop 0
	v_add_f32_e32 v183, v252, v253
	s_nop 1
	v_add_f32_dpp v183, v183, v183 quad_perm:[1,0,3,2] row_mask:0xf bank_mask:0xf bound_ctrl:1
	s_nop 1
	v_add_f32_dpp v183, v183, v183 quad_perm:[2,3,0,1] row_mask:0xf bank_mask:0xf bound_ctrl:1
	s_nop 1
	v_add_f32_dpp v183, v183, v183 row_half_mirror row_mask:0xf bank_mask:0xf bound_ctrl:1
	s_nop 1
	v_add_f32_dpp v183, v183, v183 row_mirror row_mask:0xf bank_mask:0xf bound_ctrl:1
	s_nop 1
	v_readlane_b32 s98, v183, 0
	v_readlane_b32 s99, v183, 16
	v_readlane_b32 s100, v183, 32
	v_readlane_b32 s101, v183, 48
	s_nop 1
	v_mov_b32_e32 v183, s98
	v_add_f32_e32 v183, s99, v183
	v_add_f32_e32 v183, s100, v183
	v_add_f32_e32 v183, s101, v183
	v_fmamk_f32 v183, v183, 0x3a800000, v182
	v_cmp_gt_f32_e32 vcc, 0x800000, v183
	v_mul_f32_e32 v181, 0x4b800000, v183
	s_nop 1
	v_cndmask_b32_e32 v183, v183, v181, vcc
	v_rsq_f32_e32 v183, v183
	s_nop 0
	v_mul_f32_e32 v181, 0x45800000, v183
	v_cndmask_b32_e32 v184, v183, v181, vcc
	v_mov_b32_e32 v185, v184
	v_cvt_pk_bf16_f32 v80, v144, v145
	v_cvt_pk_bf16_f32 v81, v146, v147
	v_cvt_pk_bf16_f32 v82, v148, v149
	v_cvt_pk_bf16_f32 v83, v150, v151
	v_cvt_pk_bf16_f32 v84, v152, v153
	v_cvt_pk_bf16_f32 v85, v154, v155
	v_cvt_pk_bf16_f32 v86, v156, v157
	v_cvt_pk_bf16_f32 v87, v158, v159
	v_add_u32_e32 v181, 0x2c00000, v177
	global_store_dwordx4 v181, v[80:83], s[78:79]
	global_store_dwordx4 v181, v[84:87], s[78:79] offset:1024
	v_add_u32_e32 v236, 0xa000, v237
	s_mov_b64 exec, 1
	global_store_dword v236, v184, s[78:79]
	s_mov_b64 exec, -1
	s_waitcnt vmcnt(4)
	v_lshlrev_b32_e32 v144, 16, v96
	v_and_b32_e32 v145, 0xffff0000, v96
	v_lshlrev_b32_e32 v146, 16, v97
	v_and_b32_e32 v147, 0xffff0000, v97
	v_lshlrev_b32_e32 v148, 16, v98
	v_and_b32_e32 v149, 0xffff0000, v98
	v_lshlrev_b32_e32 v150, 16, v99
	v_and_b32_e32 v151, 0xffff0000, v99
	v_lshlrev_b32_e32 v152, 16, v100
	v_and_b32_e32 v153, 0xffff0000, v100
	v_lshlrev_b32_e32 v154, 16, v101
	v_and_b32_e32 v155, 0xffff0000, v101
	v_lshlrev_b32_e32 v156, 16, v102
	v_and_b32_e32 v157, 0xffff0000, v102
	v_lshlrev_b32_e32 v158, 16, v103
	v_and_b32_e32 v159, 0xffff0000, v103
	v_lshlrev_b32_e32 v160, 16, v104
	v_and_b32_e32 v161, 0xffff0000, v104
	v_lshlrev_b32_e32 v162, 16, v105
	v_and_b32_e32 v163, 0xffff0000, v105
	v_lshlrev_b32_e32 v164, 16, v106
	v_and_b32_e32 v165, 0xffff0000, v106
	v_lshlrev_b32_e32 v166, 16, v107
	v_and_b32_e32 v167, 0xffff0000, v107
	v_lshlrev_b32_e32 v168, 16, v108
	v_and_b32_e32 v169, 0xffff0000, v108
	v_lshlrev_b32_e32 v170, 16, v109
	v_and_b32_e32 v171, 0xffff0000, v109
	v_lshlrev_b32_e32 v172, 16, v110
	v_and_b32_e32 v173, 0xffff0000, v110
	v_lshlrev_b32_e32 v174, 16, v111
	v_and_b32_e32 v175, 0xffff0000, v111
	v_pk_mul_f32 v[252:253], v[160:161], v[160:161]
	v_pk_mul_f32 v[254:255], v[162:163], v[162:163]
	v_pk_fma_f32 v[252:253], v[164:165], v[164:165], v[252:253]
	v_pk_fma_f32 v[254:255], v[166:167], v[166:167], v[254:255]
	v_pk_fma_f32 v[252:253], v[168:169], v[168:169], v[252:253]
	v_pk_fma_f32 v[254:255], v[170:171], v[170:171], v[254:255]
	v_pk_fma_f32 v[252:253], v[172:173], v[172:173], v[252:253]
	v_pk_fma_f32 v[254:255], v[174:175], v[174:175], v[254:255]
	v_pk_add_f32 v[252:253], v[252:253], v[254:255]
	s_nop 0
	v_add_f32_e32 v183, v252, v253
	s_nop 1
	v_add_f32_dpp v183, v183, v183 quad_perm:[1,0,3,2] row_mask:0xf bank_mask:0xf bound_ctrl:1
	s_nop 1
	v_add_f32_dpp v183, v183, v183 quad_perm:[2,3,0,1] row_mask:0xf bank_mask:0xf bound_ctrl:1
	s_nop 1
	v_add_f32_dpp v183, v183, v183 row_half_mirror row_mask:0xf bank_mask:0xf bound_ctrl:1
	s_nop 1
	v_add_f32_dpp v183, v183, v183 row_mirror row_mask:0xf bank_mask:0xf bound_ctrl:1
	s_nop 1
	v_readlane_b32 s98, v183, 0
	v_readlane_b32 s99, v183, 16
	v_readlane_b32 s100, v183, 32
	v_readlane_b32 s101, v183, 48
	s_nop 1
	v_mov_b32_e32 v183, s98
	v_add_f32_e32 v183, s99, v183
	v_add_f32_e32 v183, s100, v183
	v_add_f32_e32 v183, s101, v183
	v_fmamk_f32 v183, v183, 0x3a800000, v182
	v_cmp_gt_f32_e32 vcc, 0x800000, v183
	v_mul_f32_e32 v181, 0x4b800000, v183
	s_nop 1
	v_cndmask_b32_e32 v183, v183, v181, vcc
	v_rsq_f32_e32 v183, v183
	s_nop 0
	v_mul_f32_e32 v181, 0x45800000, v183
	v_cndmask_b32_e32 v184, v183, v181, vcc
	v_mov_b32_e32 v185, v184
	v_pk_mul_f32 v[160:161], v[160:161], v[184:185]
	v_pk_mul_f32 v[162:163], v[162:163], v[184:185]
	v_pk_mul_f32 v[164:165], v[164:165], v[184:185]
	v_pk_mul_f32 v[166:167], v[166:167], v[184:185]
	v_pk_mul_f32 v[168:169], v[168:169], v[184:185]
	v_pk_mul_f32 v[170:171], v[170:171], v[184:185]
	v_pk_mul_f32 v[172:173], v[172:173], v[184:185]
	v_pk_mul_f32 v[174:175], v[174:175], v[184:185]
	v_pk_fma_f32 v[144:145], v[160:161], v[128:129], v[144:145]
	v_pk_fma_f32 v[146:147], v[162:163], v[130:131], v[146:147]
	v_pk_fma_f32 v[148:149], v[164:165], v[132:133], v[148:149]
	v_pk_fma_f32 v[150:151], v[166:167], v[134:135], v[150:151]
	v_pk_fma_f32 v[152:153], v[168:169], v[136:137], v[152:153]
	v_pk_fma_f32 v[154:155], v[170:171], v[138:139], v[154:155]
	v_pk_fma_f32 v[156:157], v[172:173], v[140:141], v[156:157]
	v_pk_fma_f32 v[158:159], v[174:175], v[142:143], v[158:159]
	v_pk_mul_f32 v[252:253], v[144:145], v[144:145]
	v_pk_mul_f32 v[254:255], v[146:147], v[146:147]
	v_pk_fma_f32 v[252:253], v[148:149], v[148:149], v[252:253]
	v_pk_fma_f32 v[254:255], v[150:151], v[150:151], v[254:255]
	v_pk_fma_f32 v[252:253], v[152:153], v[152:153], v[252:253]
	v_pk_fma_f32 v[254:255], v[154:155], v[154:155], v[254:255]
	v_pk_fma_f32 v[252:253], v[156:157], v[156:157], v[252:253]
	v_pk_fma_f32 v[254:255], v[158:159], v[158:159], v[254:255]
	v_pk_add_f32 v[252:253], v[252:253], v[254:255]
	s_nop 0
	v_add_f32_e32 v183, v252, v253
	s_nop 1
	v_add_f32_dpp v183, v183, v183 quad_perm:[1,0,3,2] row_mask:0xf bank_mask:0xf bound_ctrl:1
	s_nop 1
	v_add_f32_dpp v183, v183, v183 quad_perm:[2,3,0,1] row_mask:0xf bank_mask:0xf bound_ctrl:1
	s_nop 1
	v_add_f32_dpp v183, v183, v183 row_half_mirror row_mask:0xf bank_mask:0xf bound_ctrl:1
	s_nop 1
	v_add_f32_dpp v183, v183, v183 row_mirror row_mask:0xf bank_mask:0xf bound_ctrl:1
	s_nop 1
	v_readlane_b32 s98, v183, 0
	v_readlane_b32 s99, v183, 16
	v_readlane_b32 s100, v183, 32
	v_readlane_b32 s101, v183, 48
	s_nop 1
	v_mov_b32_e32 v183, s98
	v_add_f32_e32 v183, s99, v183
	v_add_f32_e32 v183, s100, v183
	v_add_f32_e32 v183, s101, v183
	v_fmamk_f32 v183, v183, 0x3a800000, v182
	v_cmp_gt_f32_e32 vcc, 0x800000, v183
	v_mul_f32_e32 v181, 0x4b800000, v183
	s_nop 1
	v_cndmask_b32_e32 v183, v183, v181, vcc
	v_rsq_f32_e32 v183, v183
	s_nop 0
	v_mul_f32_e32 v181, 0x45800000, v183
	v_cndmask_b32_e32 v184, v183, v181, vcc
	v_mov_b32_e32 v185, v184
	v_cvt_pk_bf16_f32 v96, v144, v145
	v_cvt_pk_bf16_f32 v97, v146, v147
	v_cvt_pk_bf16_f32 v98, v148, v149
	v_cvt_pk_bf16_f32 v99, v150, v151
	v_cvt_pk_bf16_f32 v100, v152, v153
	v_cvt_pk_bf16_f32 v101, v154, v155
	v_cvt_pk_bf16_f32 v102, v156, v157
	v_cvt_pk_bf16_f32 v103, v158, v159
	v_add_u32_e32 v181, 0x3000000, v177
	global_store_dwordx4 v181, v[96:99], s[78:79]
	global_store_dwordx4 v181, v[100:103], s[78:79] offset:1024
	v_add_u32_e32 v236, 0xc000, v237
	s_mov_b64 exec, 1
	global_store_dword v236, v184, s[78:79]
	s_mov_b64 exec, -1
	s_waitcnt vmcnt(0)
	v_lshlrev_b32_e32 v144, 16, v112
	v_and_b32_e32 v145, 0xffff0000, v112
	v_lshlrev_b32_e32 v146, 16, v113
	v_and_b32_e32 v147, 0xffff0000, v113
	v_lshlrev_b32_e32 v148, 16, v114
	v_and_b32_e32 v149, 0xffff0000, v114
	v_lshlrev_b32_e32 v150, 16, v115
	v_and_b32_e32 v151, 0xffff0000, v115
	v_lshlrev_b32_e32 v152, 16, v116
	v_and_b32_e32 v153, 0xffff0000, v116
	v_lshlrev_b32_e32 v154, 16, v117
	v_and_b32_e32 v155, 0xffff0000, v117
	v_lshlrev_b32_e32 v156, 16, v118
	v_and_b32_e32 v157, 0xffff0000, v118
	v_lshlrev_b32_e32 v158, 16, v119
	v_and_b32_e32 v159, 0xffff0000, v119
	v_lshlrev_b32_e32 v160, 16, v120
	v_and_b32_e32 v161, 0xffff0000, v120
	v_lshlrev_b32_e32 v162, 16, v121
	v_and_b32_e32 v163, 0xffff0000, v121
	v_lshlrev_b32_e32 v164, 16, v122
	v_and_b32_e32 v165, 0xffff0000, v122
	v_lshlrev_b32_e32 v166, 16, v123
	v_and_b32_e32 v167, 0xffff0000, v123
	v_lshlrev_b32_e32 v168, 16, v124
	v_and_b32_e32 v169, 0xffff0000, v124
	v_lshlrev_b32_e32 v170, 16, v125
	v_and_b32_e32 v171, 0xffff0000, v125
	v_lshlrev_b32_e32 v172, 16, v126
	v_and_b32_e32 v173, 0xffff0000, v126
	v_lshlrev_b32_e32 v174, 16, v127
	v_and_b32_e32 v175, 0xffff0000, v127
	v_pk_mul_f32 v[252:253], v[160:161], v[160:161]
	v_pk_mul_f32 v[254:255], v[162:163], v[162:163]
	v_pk_fma_f32 v[252:253], v[164:165], v[164:165], v[252:253]
	v_pk_fma_f32 v[254:255], v[166:167], v[166:167], v[254:255]
	v_pk_fma_f32 v[252:253], v[168:169], v[168:169], v[252:253]
	v_pk_fma_f32 v[254:255], v[170:171], v[170:171], v[254:255]
	v_pk_fma_f32 v[252:253], v[172:173], v[172:173], v[252:253]
	v_pk_fma_f32 v[254:255], v[174:175], v[174:175], v[254:255]
	v_pk_add_f32 v[252:253], v[252:253], v[254:255]
	s_nop 0
	v_add_f32_e32 v183, v252, v253
	s_nop 1
	v_add_f32_dpp v183, v183, v183 quad_perm:[1,0,3,2] row_mask:0xf bank_mask:0xf bound_ctrl:1
	s_nop 1
	v_add_f32_dpp v183, v183, v183 quad_perm:[2,3,0,1] row_mask:0xf bank_mask:0xf bound_ctrl:1
	s_nop 1
	v_add_f32_dpp v183, v183, v183 row_half_mirror row_mask:0xf bank_mask:0xf bound_ctrl:1
	s_nop 1
	v_add_f32_dpp v183, v183, v183 row_mirror row_mask:0xf bank_mask:0xf bound_ctrl:1
	s_nop 1
	v_readlane_b32 s98, v183, 0
	v_readlane_b32 s99, v183, 16
	v_readlane_b32 s100, v183, 32
	v_readlane_b32 s101, v183, 48
	s_nop 1
	v_mov_b32_e32 v183, s98
	v_add_f32_e32 v183, s99, v183
	v_add_f32_e32 v183, s100, v183
	v_add_f32_e32 v183, s101, v183
	v_fmamk_f32 v183, v183, 0x3a800000, v182
	v_cmp_gt_f32_e32 vcc, 0x800000, v183
	v_mul_f32_e32 v181, 0x4b800000, v183
	s_nop 1
	v_cndmask_b32_e32 v183, v183, v181, vcc
	v_rsq_f32_e32 v183, v183
	s_nop 0
	v_mul_f32_e32 v181, 0x45800000, v183
	v_cndmask_b32_e32 v184, v183, v181, vcc
	v_mov_b32_e32 v185, v184
	v_pk_mul_f32 v[160:161], v[160:161], v[184:185]
	v_pk_mul_f32 v[162:163], v[162:163], v[184:185]
	v_pk_mul_f32 v[164:165], v[164:165], v[184:185]
	v_pk_mul_f32 v[166:167], v[166:167], v[184:185]
	v_pk_mul_f32 v[168:169], v[168:169], v[184:185]
	v_pk_mul_f32 v[170:171], v[170:171], v[184:185]
	v_pk_mul_f32 v[172:173], v[172:173], v[184:185]
	v_pk_mul_f32 v[174:175], v[174:175], v[184:185]
	v_pk_fma_f32 v[144:145], v[160:161], v[128:129], v[144:145]
	v_pk_fma_f32 v[146:147], v[162:163], v[130:131], v[146:147]
	v_pk_fma_f32 v[148:149], v[164:165], v[132:133], v[148:149]
	v_pk_fma_f32 v[150:151], v[166:167], v[134:135], v[150:151]
	v_pk_fma_f32 v[152:153], v[168:169], v[136:137], v[152:153]
	v_pk_fma_f32 v[154:155], v[170:171], v[138:139], v[154:155]
	v_pk_fma_f32 v[156:157], v[172:173], v[140:141], v[156:157]
	v_pk_fma_f32 v[158:159], v[174:175], v[142:143], v[158:159]
	v_pk_mul_f32 v[252:253], v[144:145], v[144:145]
	v_pk_mul_f32 v[254:255], v[146:147], v[146:147]
	v_pk_fma_f32 v[252:253], v[148:149], v[148:149], v[252:253]
	v_pk_fma_f32 v[254:255], v[150:151], v[150:151], v[254:255]
	v_pk_fma_f32 v[252:253], v[152:153], v[152:153], v[252:253]
	v_pk_fma_f32 v[254:255], v[154:155], v[154:155], v[254:255]
	v_pk_fma_f32 v[252:253], v[156:157], v[156:157], v[252:253]
	v_pk_fma_f32 v[254:255], v[158:159], v[158:159], v[254:255]
	v_pk_add_f32 v[252:253], v[252:253], v[254:255]
	s_nop 0
	v_add_f32_e32 v183, v252, v253
	s_nop 1
	v_add_f32_dpp v183, v183, v183 quad_perm:[1,0,3,2] row_mask:0xf bank_mask:0xf bound_ctrl:1
	s_nop 1
	v_add_f32_dpp v183, v183, v183 quad_perm:[2,3,0,1] row_mask:0xf bank_mask:0xf bound_ctrl:1
	s_nop 1
	v_add_f32_dpp v183, v183, v183 row_half_mirror row_mask:0xf bank_mask:0xf bound_ctrl:1
	s_nop 1
	v_add_f32_dpp v183, v183, v183 row_mirror row_mask:0xf bank_mask:0xf bound_ctrl:1
	s_nop 1
	v_readlane_b32 s98, v183, 0
	v_readlane_b32 s99, v183, 16
	v_readlane_b32 s100, v183, 32
	v_readlane_b32 s101, v183, 48
	s_nop 1
	v_mov_b32_e32 v183, s98
	v_add_f32_e32 v183, s99, v183
	v_add_f32_e32 v183, s100, v183
	v_add_f32_e32 v183, s101, v183
	v_fmamk_f32 v183, v183, 0x3a800000, v182
	v_cmp_gt_f32_e32 vcc, 0x800000, v183
	v_mul_f32_e32 v181, 0x4b800000, v183
	s_nop 1
	v_cndmask_b32_e32 v183, v183, v181, vcc
	v_rsq_f32_e32 v183, v183
	s_nop 0
	v_mul_f32_e32 v181, 0x45800000, v183
	v_cndmask_b32_e32 v184, v183, v181, vcc
	v_mov_b32_e32 v185, v184
	v_cvt_pk_bf16_f32 v112, v144, v145
	v_cvt_pk_bf16_f32 v113, v146, v147
	v_cvt_pk_bf16_f32 v114, v148, v149
	v_cvt_pk_bf16_f32 v115, v150, v151
	v_cvt_pk_bf16_f32 v116, v152, v153
	v_cvt_pk_bf16_f32 v117, v154, v155
	v_cvt_pk_bf16_f32 v118, v156, v157
	v_cvt_pk_bf16_f32 v119, v158, v159
	v_add_u32_e32 v181, 0x3400000, v177
	global_store_dwordx4 v181, v[112:115], s[78:79]
	global_store_dwordx4 v181, v[116:119], s[78:79] offset:1024
	v_add_u32_e32 v236, 0xe000, v237
	s_mov_b64 exec, 1
	global_store_dword v236, v184, s[78:79]
	s_mov_b64 exec, -1
	v_readfirstlane_b32 s98, v179
	s_nop 3
	s_cmp_ge_u32 s98, 512
	s_cbranch_scc1 .Lmyxupd_done_5
	v_add_u32_e32 v181, 0x3800000, v177
	global_load_dwordx4 v[0:3], v181, s[78:79]
	global_load_dwordx4 v[4:7], v181, s[78:79] offset:1024
	v_lshl_add_u32 v183, v179, 12, v180
	v_add_u32_e32 v183, 0xbf00000, v183
	v_add_u32_e32 v181, 0x0, v183
	global_load_dwordx4 v[8:11], v181, s[78:79]
	global_load_dwordx4 v[12:15], v181, s[78:79] offset:16
	global_load_dwordx4 v[16:19], v181, s[78:79] offset:2048
	global_load_dwordx4 v[20:23], v181, s[78:79] offset:2064
	v_add_u32_e32 v181, 0x200000, v183
	global_load_dwordx4 v[24:27], v181, s[78:79]
	global_load_dwordx4 v[28:31], v181, s[78:79] offset:16
	global_load_dwordx4 v[32:35], v181, s[78:79] offset:2048
	global_load_dwordx4 v[36:39], v181, s[78:79] offset:2064
	v_add_u32_e32 v181, 0x400000, v183
	global_load_dwordx4 v[40:43], v181, s[78:79]
	global_load_dwordx4 v[44:47], v181, s[78:79] offset:16
	global_load_dwordx4 v[48:51], v181, s[78:79] offset:2048
	global_load_dwordx4 v[52:55], v181, s[78:79] offset:2064
	v_add_u32_e32 v181, 0x600000, v183
	global_load_dwordx4 v[56:59], v181, s[78:79]
	global_load_dwordx4 v[60:63], v181, s[78:79] offset:16
	global_load_dwordx4 v[64:67], v181, s[78:79] offset:2048
	global_load_dwordx4 v[68:71], v181, s[78:79] offset:2064
	v_add_u32_e32 v181, 0x800000, v183
	global_load_dwordx4 v[72:75], v181, s[78:79]
	global_load_dwordx4 v[76:79], v181, s[78:79] offset:16
	global_load_dwordx4 v[80:83], v181, s[78:79] offset:2048
	global_load_dwordx4 v[84:87], v181, s[78:79] offset:2064
	v_add_u32_e32 v181, 0xa00000, v183
	global_load_dwordx4 v[88:91], v181, s[78:79]
	global_load_dwordx4 v[92:95], v181, s[78:79] offset:16
	global_load_dwordx4 v[96:99], v181, s[78:79] offset:2048
	global_load_dwordx4 v[100:103], v181, s[78:79] offset:2064
	s_waitcnt vmcnt(20)
	v_pk_add_f32 v[160:161], v[8:9], 0 op_sel_hi:[1,0]
	v_pk_add_f32 v[162:163], v[10:11], 0 op_sel_hi:[1,0]
	v_pk_add_f32 v[164:165], v[12:13], 0 op_sel_hi:[1,0]
	v_pk_add_f32 v[166:167], v[14:15], 0 op_sel_hi:[1,0]
	v_pk_add_f32 v[168:169], v[16:17], 0 op_sel_hi:[1,0]
	v_pk_add_f32 v[170:171], v[18:19], 0 op_sel_hi:[1,0]
	v_pk_add_f32 v[172:173], v[20:21], 0 op_sel_hi:[1,0]
	v_pk_add_f32 v[174:175], v[22:23], 0 op_sel_hi:[1,0]
	s_waitcnt vmcnt(16)
	v_pk_add_f32 v[160:161], v[160:161], v[24:25]
	v_pk_add_f32 v[162:163], v[162:163], v[26:27]
	v_pk_add_f32 v[164:165], v[164:165], v[28:29]
	v_pk_add_f32 v[166:167], v[166:167], v[30:31]
	v_pk_add_f32 v[168:169], v[168:169], v[32:33]
	v_pk_add_f32 v[170:171], v[170:171], v[34:35]
	v_pk_add_f32 v[172:173], v[172:173], v[36:37]
	v_pk_add_f32 v[174:175], v[174:175], v[38:39]
	s_waitcnt vmcnt(12)
	v_pk_add_f32 v[160:161], v[160:161], v[40:41]
	v_pk_add_f32 v[162:163], v[162:163], v[42:43]
	v_pk_add_f32 v[164:165], v[164:165], v[44:45]
	v_pk_add_f32 v[166:167], v[166:167], v[46:47]
	v_pk_add_f32 v[168:169], v[168:169], v[48:49]
	v_pk_add_f32 v[170:171], v[170:171], v[50:51]
	v_pk_add_f32 v[172:173], v[172:173], v[52:53]
	v_pk_add_f32 v[174:175], v[174:175], v[54:55]
	s_waitcnt vmcnt(8)
	v_pk_add_f32 v[160:161], v[160:161], v[56:57]
	v_pk_add_f32 v[162:163], v[162:163], v[58:59]
	v_pk_add_f32 v[164:165], v[164:165], v[60:61]
	v_pk_add_f32 v[166:167], v[166:167], v[62:63]
	v_pk_add_f32 v[168:169], v[168:169], v[64:65]
	v_pk_add_f32 v[170:171], v[170:171], v[66:67]
	v_pk_add_f32 v[172:173], v[172:173], v[68:69]
	v_pk_add_f32 v[174:175], v[174:175], v[70:71]
	s_waitcnt vmcnt(4)
	v_pk_add_f32 v[160:161], v[160:161], v[72:73]
	v_pk_add_f32 v[162:163], v[162:163], v[74:75]
	v_pk_add_f32 v[164:165], v[164:165], v[76:77]
	v_pk_add_f32 v[166:167], v[166:167], v[78:79]
	v_pk_add_f32 v[168:169], v[168:169], v[80:81]
	v_pk_add_f32 v[170:171], v[170:171], v[82:83]
	v_pk_add_f32 v[172:173], v[172:173], v[84:85]
	v_pk_add_f32 v[174:175], v[174:175], v[86:87]
	s_waitcnt vmcnt(0)
	v_pk_add_f32 v[160:161], v[160:161], v[88:89]
	v_pk_add_f32 v[162:163], v[162:163], v[90:91]
	v_pk_add_f32 v[164:165], v[164:165], v[92:93]
	v_pk_add_f32 v[166:167], v[166:167], v[94:95]
	v_pk_add_f32 v[168:169], v[168:169], v[96:97]
	v_pk_add_f32 v[170:171], v[170:171], v[98:99]
	v_pk_add_f32 v[172:173], v[172:173], v[100:101]
	v_pk_add_f32 v[174:175], v[174:175], v[102:103]
	v_lshlrev_b32_e32 v144, 16, v0
	v_and_b32_e32 v145, 0xffff0000, v0
	v_lshlrev_b32_e32 v146, 16, v1
	v_and_b32_e32 v147, 0xffff0000, v1
	v_lshlrev_b32_e32 v148, 16, v2
	v_and_b32_e32 v149, 0xffff0000, v2
	v_lshlrev_b32_e32 v150, 16, v3
	v_and_b32_e32 v151, 0xffff0000, v3
	v_lshlrev_b32_e32 v152, 16, v4
	v_and_b32_e32 v153, 0xffff0000, v4
	v_lshlrev_b32_e32 v154, 16, v5
	v_and_b32_e32 v155, 0xffff0000, v5
	v_lshlrev_b32_e32 v156, 16, v6
	v_and_b32_e32 v157, 0xffff0000, v6
	v_lshlrev_b32_e32 v158, 16, v7
	v_and_b32_e32 v159, 0xffff0000, v7
	v_add_u32_e32 v181, 0xc00000, v183
	global_load_dwordx4 v[8:11], v181, s[78:79]
	global_load_dwordx4 v[12:15], v181, s[78:79] offset:16
	global_load_dwordx4 v[16:19], v181, s[78:79] offset:2048
	global_load_dwordx4 v[20:23], v181, s[78:79] offset:2064
	v_add_u32_e32 v181, 0xe00000, v183
	global_load_dwordx4 v[24:27], v181, s[78:79]
	global_load_dwordx4 v[28:31], v181, s[78:79] offset:16
	global_load_dwordx4 v[32:35], v181, s[78:79] offset:2048
	global_load_dwordx4 v[36:39], v181, s[78:79] offset:2064
	v_add_u32_e32 v181, 0x1000000, v183
	global_load_dwordx4 v[40:43], v181, s[78:79]
	global_load_dwordx4 v[44:47], v181, s[78:79] offset:16
	global_load_dwordx4 v[48:51], v181, s[78:79] offset:2048
	global_load_dwordx4 v[52:55], v181, s[78:79] offset:2064
	v_add_u32_e32 v181, 0x1200000, v183
	global_load_dwordx4 v[56:59], v181, s[78:79]
	global_load_dwordx4 v[60:63], v181, s[78:79] offset:16
	global_load_dwordx4 v[64:67], v181, s[78:79] offset:2048
	global_load_dwordx4 v[68:71], v181, s[78:79] offset:2064
	v_add_u32_e32 v181, 0x1400000, v183
	global_load_dwordx4 v[72:75], v181, s[78:79]
	global_load_dwordx4 v[76:79], v181, s[78:79] offset:16
	global_load_dwordx4 v[80:83], v181, s[78:79] offset:2048
	global_load_dwordx4 v[84:87], v181, s[78:79] offset:2064
	s_waitcnt vmcnt(16)
	v_pk_add_f32 v[160:161], v[160:161], v[8:9]
	v_pk_add_f32 v[162:163], v[162:163], v[10:11]
	v_pk_add_f32 v[164:165], v[164:165], v[12:13]
	v_pk_add_f32 v[166:167], v[166:167], v[14:15]
	v_pk_add_f32 v[168:169], v[168:169], v[16:17]
	v_pk_add_f32 v[170:171], v[170:171], v[18:19]
	v_pk_add_f32 v[172:173], v[172:173], v[20:21]
	v_pk_add_f32 v[174:175], v[174:175], v[22:23]
	s_waitcnt vmcnt(12)
	v_pk_add_f32 v[160:161], v[160:161], v[24:25]
	v_pk_add_f32 v[162:163], v[162:163], v[26:27]
	v_pk_add_f32 v[164:165], v[164:165], v[28:29]
	v_pk_add_f32 v[166:167], v[166:167], v[30:31]
	v_pk_add_f32 v[168:169], v[168:169], v[32:33]
	v_pk_add_f32 v[170:171], v[170:171], v[34:35]
	v_pk_add_f32 v[172:173], v[172:173], v[36:37]
	v_pk_add_f32 v[174:175], v[174:175], v[38:39]
	s_waitcnt vmcnt(8)
	v_pk_add_f32 v[160:161], v[160:161], v[40:41]
	v_pk_add_f32 v[162:163], v[162:163], v[42:43]
	v_pk_add_f32 v[164:165], v[164:165], v[44:45]
	v_pk_add_f32 v[166:167], v[166:167], v[46:47]
	v_pk_add_f32 v[168:169], v[168:169], v[48:49]
	v_pk_add_f32 v[170:171], v[170:171], v[50:51]
	v_pk_add_f32 v[172:173], v[172:173], v[52:53]
	v_pk_add_f32 v[174:175], v[174:175], v[54:55]
	s_waitcnt vmcnt(4)
	v_pk_add_f32 v[160:161], v[160:161], v[56:57]
	v_pk_add_f32 v[162:163], v[162:163], v[58:59]
	v_pk_add_f32 v[164:165], v[164:165], v[60:61]
	v_pk_add_f32 v[166:167], v[166:167], v[62:63]
	v_pk_add_f32 v[168:169], v[168:169], v[64:65]
	v_pk_add_f32 v[170:171], v[170:171], v[66:67]
	v_pk_add_f32 v[172:173], v[172:173], v[68:69]
	v_pk_add_f32 v[174:175], v[174:175], v[70:71]
	s_waitcnt vmcnt(0)
	v_pk_add_f32 v[160:161], v[160:161], v[72:73]
	v_pk_add_f32 v[162:163], v[162:163], v[74:75]
	v_pk_add_f32 v[164:165], v[164:165], v[76:77]
	v_pk_add_f32 v[166:167], v[166:167], v[78:79]
	v_pk_add_f32 v[168:169], v[168:169], v[80:81]
	v_pk_add_f32 v[170:171], v[170:171], v[82:83]
	v_pk_add_f32 v[172:173], v[172:173], v[84:85]
	v_pk_add_f32 v[174:175], v[174:175], v[86:87]
	v_pk_mul_f32 v[252:253], v[160:161], v[160:161]
	v_pk_mul_f32 v[254:255], v[162:163], v[162:163]
	v_pk_fma_f32 v[252:253], v[164:165], v[164:165], v[252:253]
	v_pk_fma_f32 v[254:255], v[166:167], v[166:167], v[254:255]
	v_pk_fma_f32 v[252:253], v[168:169], v[168:169], v[252:253]
	v_pk_fma_f32 v[254:255], v[170:171], v[170:171], v[254:255]
	v_pk_fma_f32 v[252:253], v[172:173], v[172:173], v[252:253]
	v_pk_fma_f32 v[254:255], v[174:175], v[174:175], v[254:255]
	v_pk_add_f32 v[252:253], v[252:253], v[254:255]
	s_nop 0
	v_add_f32_e32 v183, v252, v253
	s_nop 1
	v_add_f32_dpp v183, v183, v183 quad_perm:[1,0,3,2] row_mask:0xf bank_mask:0xf bound_ctrl:1
	s_nop 1
	v_add_f32_dpp v183, v183, v183 quad_perm:[2,3,0,1] row_mask:0xf bank_mask:0xf bound_ctrl:1
	s_nop 1
	v_add_f32_dpp v183, v183, v183 row_half_mirror row_mask:0xf bank_mask:0xf bound_ctrl:1
	s_nop 1
	v_add_f32_dpp v183, v183, v183 row_mirror row_mask:0xf bank_mask:0xf bound_ctrl:1
	s_nop 1
	v_readlane_b32 s98, v183, 0
	v_readlane_b32 s99, v183, 16
	v_readlane_b32 s100, v183, 32
	v_readlane_b32 s101, v183, 48
	s_nop 1
	v_mov_b32_e32 v183, s98
	v_add_f32_e32 v183, s99, v183
	v_add_f32_e32 v183, s100, v183
	v_add_f32_e32 v183, s101, v183
	v_fmamk_f32 v183, v183, 0x3a800000, v182
	v_cmp_gt_f32_e32 vcc, 0x800000, v183
	v_mul_f32_e32 v181, 0x4b800000, v183
	s_nop 1
	v_cndmask_b32_e32 v183, v183, v181, vcc
	v_rsq_f32_e32 v183, v183
	s_nop 0
	v_mul_f32_e32 v181, 0x45800000, v183
	v_cndmask_b32_e32 v184, v183, v181, vcc
	v_mov_b32_e32 v185, v184
	v_pk_mul_f32 v[160:161], v[160:161], v[184:185]
	v_pk_mul_f32 v[162:163], v[162:163], v[184:185]
	v_pk_mul_f32 v[164:165], v[164:165], v[184:185]
	v_pk_mul_f32 v[166:167], v[166:167], v[184:185]
	v_pk_mul_f32 v[168:169], v[168:169], v[184:185]
	v_pk_mul_f32 v[170:171], v[170:171], v[184:185]
	v_pk_mul_f32 v[172:173], v[172:173], v[184:185]
	v_pk_mul_f32 v[174:175], v[174:175], v[184:185]
	v_pk_fma_f32 v[144:145], v[160:161], v[128:129], v[144:145]
	v_pk_fma_f32 v[146:147], v[162:163], v[130:131], v[146:147]
	v_pk_fma_f32 v[148:149], v[164:165], v[132:133], v[148:149]
	v_pk_fma_f32 v[150:151], v[166:167], v[134:135], v[150:151]
	v_pk_fma_f32 v[152:153], v[168:169], v[136:137], v[152:153]
	v_pk_fma_f32 v[154:155], v[170:171], v[138:139], v[154:155]
	v_pk_fma_f32 v[156:157], v[172:173], v[140:141], v[156:157]
	v_pk_fma_f32 v[158:159], v[174:175], v[142:143], v[158:159]
	v_pk_mul_f32 v[252:253], v[144:145], v[144:145]
	v_pk_mul_f32 v[254:255], v[146:147], v[146:147]
	v_pk_fma_f32 v[252:253], v[148:149], v[148:149], v[252:253]
	v_pk_fma_f32 v[254:255], v[150:151], v[150:151], v[254:255]
	v_pk_fma_f32 v[252:253], v[152:153], v[152:153], v[252:253]
	v_pk_fma_f32 v[254:255], v[154:155], v[154:155], v[254:255]
	v_pk_fma_f32 v[252:253], v[156:157], v[156:157], v[252:253]
	v_pk_fma_f32 v[254:255], v[158:159], v[158:159], v[254:255]
	v_pk_add_f32 v[252:253], v[252:253], v[254:255]
	s_nop 0
	v_add_f32_e32 v183, v252, v253
	s_nop 1
	v_add_f32_dpp v183, v183, v183 quad_perm:[1,0,3,2] row_mask:0xf bank_mask:0xf bound_ctrl:1
	s_nop 1
	v_add_f32_dpp v183, v183, v183 quad_perm:[2,3,0,1] row_mask:0xf bank_mask:0xf bound_ctrl:1
	s_nop 1
	v_add_f32_dpp v183, v183, v183 row_half_mirror row_mask:0xf bank_mask:0xf bound_ctrl:1
	s_nop 1
	v_add_f32_dpp v183, v183, v183 row_mirror row_mask:0xf bank_mask:0xf bound_ctrl:1
	s_nop 1
	v_readlane_b32 s98, v183, 0
	v_readlane_b32 s99, v183, 16
	v_readlane_b32 s100, v183, 32
	v_readlane_b32 s101, v183, 48
	s_nop 1
	v_mov_b32_e32 v183, s98
	v_add_f32_e32 v183, s99, v183
	v_add_f32_e32 v183, s100, v183
	v_add_f32_e32 v183, s101, v183
	v_fmamk_f32 v183, v183, 0x3a800000, v182
	v_cmp_gt_f32_e32 vcc, 0x800000, v183
	v_mul_f32_e32 v181, 0x4b800000, v183
	s_nop 1
	v_cndmask_b32_e32 v183, v183, v181, vcc
	v_rsq_f32_e32 v183, v183
	s_nop 0
	v_mul_f32_e32 v181, 0x45800000, v183
	v_cndmask_b32_e32 v184, v183, v181, vcc
	v_mov_b32_e32 v185, v184
	v_cvt_pk_bf16_f32 v0, v144, v145
	v_cvt_pk_bf16_f32 v1, v146, v147
	v_cvt_pk_bf16_f32 v2, v148, v149
	v_cvt_pk_bf16_f32 v3, v150, v151
	v_cvt_pk_bf16_f32 v4, v152, v153
	v_cvt_pk_bf16_f32 v5, v154, v155
	v_cvt_pk_bf16_f32 v6, v156, v157
	v_cvt_pk_bf16_f32 v7, v158, v159
	v_add_u32_e32 v181, 0x3800000, v177
	global_store_dwordx4 v181, v[0:3], s[78:79]
	global_store_dwordx4 v181, v[4:7], s[78:79] offset:1024
	v_add_u32_e32 v236, 0x10000, v237
	s_mov_b64 exec, 1
	global_store_dword v236, v184, s[78:79]
	s_mov_b64 exec, -1

.LBB0_2573:
	v_readlane_b32 s0, v235, 52
	v_readlane_b32 s1, v235, 53
	s_and_b64 vcc, exec, s[0:1]
	s_waitcnt lgkmcnt(0)
	s_barrier
	v_mbcnt_lo_u32_b32 v0, -1, 0
	v_mbcnt_hi_u32_b32 v0, -1, v0
	s_cbranch_vccnz .LBB0_2593
	v_lshlrev_b32_e32 v2, 3, v0
	v_ashrrev_i32_e32 v3, 31, v2
	v_readlane_b32 s4, v235, 4
	v_lshlrev_b64 v[4:5], 1, v[2:3]
	v_lshlrev_b64 v[2:3], 2, v[2:3]
	v_readlane_b32 s14, v235, 14
	v_readlane_b32 s15, v235, 15
	v_lshl_add_u64 v[62:63], s[90:91], 0, v[2:3]
	v_readlane_b32 s5, v235, 5
	v_readlane_b32 s6, v235, 6
	v_readlane_b32 s7, v235, 7
	v_readlane_b32 s8, v235, 8
	v_readlane_b32 s9, v235, 9
	v_readlane_b32 s10, v235, 10
	v_readlane_b32 s11, v235, 11
	v_readlane_b32 s12, v235, 12
	v_readlane_b32 s13, v235, 13
	v_readlane_b32 s16, v235, 16
	v_readlane_b32 s17, v235, 17
	v_readlane_b32 s18, v235, 18
	v_readlane_b32 s19, v235, 19
	v_lshl_add_u64 v[2:3], s[14:15], 0, v[2:3]
	s_mov_b64 s[0:1], 0x3000
	v_lshl_add_u64 v[60:61], s[86:87], 0, v[4:5]
	v_lshl_add_u64 v[64:65], s[54:55], 0, v[4:5]
	v_lshl_add_u64 v[66:67], v[2:3], 0, s[0:1]
	s_mov_b32 s1, 0
	v_cmp_eq_u32_e64 s[4:5], 0, v0
	s_mov_b64 s[6:7], 0x200000
	s_mov_b64 s[8:9], 0x200800
	s_mov_b64 s[10:11], 0x400000
	s_mov_b64 s[12:13], 0x400800
	s_mov_b64 s[14:15], 0x600000
	s_mov_b64 s[16:17], 0x600800
	s_mov_b64 s[18:19], 0x800000
	s_mov_b32 s48, 0x800000
	s_mov_b64 s[20:21], 0x800800
	s_mov_b64 s[22:23], 0xa00000
	s_mov_b64 s[24:25], 0xa00800
	s_mov_b64 s[26:27], 0xc00000
	s_mov_b64 s[28:29], 0xc00800
	s_mov_b64 s[30:31], 0xe00000
	s_mov_b64 s[36:37], 0xe00800
	v_mov_b32_e32 v104, 0
	v_mov_b32_e32 v105, 0x358637bd
	v_readlane_b32 s38, v235, 61
	v_readlane_b32 s39, v235, 62
	v_mbcnt_lo_u32_b32 v176, -1, 0
	v_mbcnt_hi_u32_b32 v176, -1, v176
	v_readlane_b32 s98, v235, 49
	v_readlane_b32 s99, v235, 20
	v_readlane_b32 s100, v235, 14
	v_readlane_b32 s101, v235, 15
	s_nop 3
	s_lshr_b32 vcc_lo, s98, 3
	s_and_b32 vcc_hi, vcc_lo, 7
	s_lshl_b32 vcc_hi, vcc_hi, 8
	s_lshr_b32 vcc_lo, vcc_lo, 3
	s_lshl_b32 vcc_lo, vcc_lo, 3
	s_add_i32 s98, vcc_hi, vcc_lo
	s_add_i32 s98, s98, s99
	v_lshlrev_b32_e32 v177, 4, v176
	s_lshl_b32 s99, s98, 11
	v_add_u32_e32 v177, s99, v177
	v_add_u32_e32 v178, 0x1800000, v177
	v_add_u32_e32 v179, 0x9e00000, v177
	v_lshlrev_b32_e32 v180, 5, v176
	v_add_u32_e32 v181, 0x3000, v180
	global_load_dwordx4 v[128:131], v181, s[100:101]
	global_load_dwordx4 v[132:135], v181, s[100:101] offset:16
	global_load_dwordx4 v[136:139], v181, s[100:101] offset:2048
	global_load_dwordx4 v[140:143], v181, s[100:101] offset:2064
	v_mov_b32_e32 v182, 0x358637bd
	global_load_dwordx4 v[0:3], v178, s[78:79]
	global_load_dwordx4 v[4:7], v178, s[78:79] offset:1024
	global_load_dwordx4 v[8:11], v179, s[78:79]
	global_load_dwordx4 v[12:15], v179, s[78:79] offset:1024
	v_add_u32_e32 v178, 0x400000, v178
	v_add_u32_e32 v179, 0x400000, v179
	global_load_dwordx4 v[16:19], v178, s[78:79]
	global_load_dwordx4 v[20:23], v178, s[78:79] offset:1024
	global_load_dwordx4 v[24:27], v179, s[78:79]
	global_load_dwordx4 v[28:31], v179, s[78:79] offset:1024
	v_add_u32_e32 v178, 0x400000, v178
	v_add_u32_e32 v179, 0x400000, v179
	global_load_dwordx4 v[32:35], v178, s[78:79]
	global_load_dwordx4 v[36:39], v178, s[78:79] offset:1024
	global_load_dwordx4 v[40:43], v179, s[78:79]
	global_load_dwordx4 v[44:47], v179, s[78:79] offset:1024
	v_add_u32_e32 v178, 0x400000, v178
	v_add_u32_e32 v179, 0x400000, v179
	global_load_dwordx4 v[48:51], v178, s[78:79]
	global_load_dwordx4 v[52:55], v178, s[78:79] offset:1024
	global_load_dwordx4 v[56:59], v179, s[78:79]
	global_load_dwordx4 v[60:63], v179, s[78:79] offset:1024
	v_add_u32_e32 v178, 0x400000, v178
	v_add_u32_e32 v179, 0x400000, v179
	global_load_dwordx4 v[64:67], v178, s[78:79]
	global_load_dwordx4 v[68:71], v178, s[78:79] offset:1024
	global_load_dwordx4 v[72:75], v179, s[78:79]
	global_load_dwordx4 v[76:79], v179, s[78:79] offset:1024
	v_add_u32_e32 v178, 0x400000, v178
	v_add_u32_e32 v179, 0x400000, v179
	global_load_dwordx4 v[80:83], v178, s[78:79]
	global_load_dwordx4 v[84:87], v178, s[78:79] offset:1024
	global_load_dwordx4 v[88:91], v179, s[78:79]
	global_load_dwordx4 v[92:95], v179, s[78:79] offset:1024
	v_add_u32_e32 v178, 0x400000, v178
	v_add_u32_e32 v179, 0x400000, v179
	global_load_dwordx4 v[96:99], v178, s[78:79]
	global_load_dwordx4 v[100:103], v178, s[78:79] offset:1024
	global_load_dwordx4 v[104:107], v179, s[78:79]
	global_load_dwordx4 v[108:111], v179, s[78:79] offset:1024
	v_add_u32_e32 v178, 0x400000, v178
	v_add_u32_e32 v179, 0x400000, v179
	global_load_dwordx4 v[112:115], v178, s[78:79]
	global_load_dwordx4 v[116:119], v178, s[78:79] offset:1024
	global_load_dwordx4 v[120:123], v179, s[78:79]
	global_load_dwordx4 v[124:127], v179, s[78:79] offset:1024
	v_mov_b32_e32 v183, s98
	v_lshlrev_b32_e32 v237, 2, v183
	v_add_u32_e32 v237, 0x10000, v237
	v_mov_b32_e32 v179, v183
	s_waitcnt vmcnt(28)
	v_lshlrev_b32_e32 v144, 16, v0
	v_and_b32_e32 v145, 0xffff0000, v0
	v_lshlrev_b32_e32 v146, 16, v1
	v_and_b32_e32 v147, 0xffff0000, v1
	v_lshlrev_b32_e32 v148, 16, v2
	v_and_b32_e32 v149, 0xffff0000, v2
	v_lshlrev_b32_e32 v150, 16, v3
	v_and_b32_e32 v151, 0xffff0000, v3
	v_lshlrev_b32_e32 v152, 16, v4
	v_and_b32_e32 v153, 0xffff0000, v4
	v_lshlrev_b32_e32 v154, 16, v5
	v_and_b32_e32 v155, 0xffff0000, v5
	v_lshlrev_b32_e32 v156, 16, v6
	v_and_b32_e32 v157, 0xffff0000, v6
	v_lshlrev_b32_e32 v158, 16, v7
	v_and_b32_e32 v159, 0xffff0000, v7
	v_lshlrev_b32_e32 v160, 16, v8
	v_and_b32_e32 v161, 0xffff0000, v8
	v_lshlrev_b32_e32 v162, 16, v9
	v_and_b32_e32 v163, 0xffff0000, v9
	v_lshlrev_b32_e32 v164, 16, v10
	v_and_b32_e32 v165, 0xffff0000, v10
	v_lshlrev_b32_e32 v166, 16, v11
	v_and_b32_e32 v167, 0xffff0000, v11
	v_lshlrev_b32_e32 v168, 16, v12
	v_and_b32_e32 v169, 0xffff0000, v12
	v_lshlrev_b32_e32 v170, 16, v13
	v_and_b32_e32 v171, 0xffff0000, v13
	v_lshlrev_b32_e32 v172, 16, v14
	v_and_b32_e32 v173, 0xffff0000, v14
	v_lshlrev_b32_e32 v174, 16, v15
	v_and_b32_e32 v175, 0xffff0000, v15
	v_pk_mul_f32 v[252:253], v[160:161], v[160:161]
	v_pk_mul_f32 v[254:255], v[162:163], v[162:163]
	v_pk_fma_f32 v[252:253], v[164:165], v[164:165], v[252:253]
	v_pk_fma_f32 v[254:255], v[166:167], v[166:167], v[254:255]
	v_pk_fma_f32 v[252:253], v[168:169], v[168:169], v[252:253]
	v_pk_fma_f32 v[254:255], v[170:171], v[170:171], v[254:255]
	v_pk_fma_f32 v[252:253], v[172:173], v[172:173], v[252:253]
	v_pk_fma_f32 v[254:255], v[174:175], v[174:175], v[254:255]
	v_pk_add_f32 v[252:253], v[252:253], v[254:255]
	s_nop 0
	v_add_f32_e32 v183, v252, v253
	s_nop 1
	v_add_f32_dpp v183, v183, v183 quad_perm:[1,0,3,2] row_mask:0xf bank_mask:0xf bound_ctrl:1
	s_nop 1
	v_add_f32_dpp v183, v183, v183 quad_perm:[2,3,0,1] row_mask:0xf bank_mask:0xf bound_ctrl:1
	s_nop 1
	v_add_f32_dpp v183, v183, v183 row_half_mirror row_mask:0xf bank_mask:0xf bound_ctrl:1
	s_nop 1
	v_add_f32_dpp v183, v183, v183 row_mirror row_mask:0xf bank_mask:0xf bound_ctrl:1
	s_nop 1
	v_readlane_b32 s98, v183, 0
	v_readlane_b32 s99, v183, 16
	v_readlane_b32 s100, v183, 32
	v_readlane_b32 s101, v183, 48
	s_nop 1
	v_mov_b32_e32 v183, s98
	v_add_f32_e32 v183, s99, v183
	v_add_f32_e32 v183, s100, v183
	v_add_f32_e32 v183, s101, v183
	v_fmamk_f32 v183, v183, 0x3a800000, v182
	v_cmp_gt_f32_e32 vcc, 0x800000, v183
	v_mul_f32_e32 v181, 0x4b800000, v183
	s_nop 1
	v_cndmask_b32_e32 v183, v183, v181, vcc
	v_rsq_f32_e32 v183, v183
	s_nop 0
	v_mul_f32_e32 v181, 0x45800000, v183
	v_cndmask_b32_e32 v184, v183, v181, vcc
	v_mov_b32_e32 v185, v184
	v_pk_mul_f32 v[160:161], v[160:161], v[184:185]
	v_pk_mul_f32 v[162:163], v[162:163], v[184:185]
	v_pk_mul_f32 v[164:165], v[164:165], v[184:185]
	v_pk_mul_f32 v[166:167], v[166:167], v[184:185]
	v_pk_mul_f32 v[168:169], v[168:169], v[184:185]
	v_pk_mul_f32 v[170:171], v[170:171], v[184:185]
	v_pk_mul_f32 v[172:173], v[172:173], v[184:185]
	v_pk_mul_f32 v[174:175], v[174:175], v[184:185]
	v_pk_fma_f32 v[144:145], v[160:161], v[128:129], v[144:145]
	v_pk_fma_f32 v[146:147], v[162:163], v[130:131], v[146:147]
	v_pk_fma_f32 v[148:149], v[164:165], v[132:133], v[148:149]
	v_pk_fma_f32 v[150:151], v[166:167], v[134:135], v[150:151]
	v_pk_fma_f32 v[152:153], v[168:169], v[136:137], v[152:153]
	v_pk_fma_f32 v[154:155], v[170:171], v[138:139], v[154:155]
	v_pk_fma_f32 v[156:157], v[172:173], v[140:141], v[156:157]
	v_pk_fma_f32 v[158:159], v[174:175], v[142:143], v[158:159]
	v_pk_mul_f32 v[252:253], v[144:145], v[144:145]
	v_pk_mul_f32 v[254:255], v[146:147], v[146:147]
	v_pk_fma_f32 v[252:253], v[148:149], v[148:149], v[252:253]
	v_pk_fma_f32 v[254:255], v[150:151], v[150:151], v[254:255]
	v_pk_fma_f32 v[252:253], v[152:153], v[152:153], v[252:253]
	v_pk_fma_f32 v[254:255], v[154:155], v[154:155], v[254:255]
	v_pk_fma_f32 v[252:253], v[156:157], v[156:157], v[252:253]
	v_pk_fma_f32 v[254:255], v[158:159], v[158:159], v[254:255]
	v_pk_add_f32 v[252:253], v[252:253], v[254:255]
	s_nop 0
	v_add_f32_e32 v183, v252, v253
	s_nop 1
	v_add_f32_dpp v183, v183, v183 quad_perm:[1,0,3,2] row_mask:0xf bank_mask:0xf bound_ctrl:1
	s_nop 1
	v_add_f32_dpp v183, v183, v183 quad_perm:[2,3,0,1] row_mask:0xf bank_mask:0xf bound_ctrl:1
	s_nop 1
	v_add_f32_dpp v183, v183, v183 row_half_mirror row_mask:0xf bank_mask:0xf bound_ctrl:1
	s_nop 1
	v_add_f32_dpp v183, v183, v183 row_mirror row_mask:0xf bank_mask:0xf bound_ctrl:1
	s_nop 1
	v_readlane_b32 s98, v183, 0
	v_readlane_b32 s99, v183, 16
	v_readlane_b32 s100, v183, 32
	v_readlane_b32 s101, v183, 48
	s_nop 1
	v_mov_b32_e32 v183, s98
	v_add_f32_e32 v183, s99, v183
	v_add_f32_e32 v183, s100, v183
	v_add_f32_e32 v183, s101, v183
	v_fmamk_f32 v183, v183, 0x3a800000, v182
	v_cmp_gt_f32_e32 vcc, 0x800000, v183
	v_mul_f32_e32 v181, 0x4b800000, v183
	s_nop 1
	v_cndmask_b32_e32 v183, v183, v181, vcc
	v_rsq_f32_e32 v183, v183
	s_nop 0
	v_mul_f32_e32 v181, 0x45800000, v183
	v_cndmask_b32_e32 v184, v183, v181, vcc
	v_mov_b32_e32 v185, v184
	v_cvt_pk_bf16_f32 v0, v144, v145
	v_cvt_pk_bf16_f32 v1, v146, v147
	v_cvt_pk_bf16_f32 v2, v148, v149
	v_cvt_pk_bf16_f32 v3, v150, v151
	v_cvt_pk_bf16_f32 v4, v152, v153
	v_cvt_pk_bf16_f32 v5, v154, v155
	v_cvt_pk_bf16_f32 v6, v156, v157
	v_cvt_pk_bf16_f32 v7, v158, v159
	v_add_u32_e32 v181, 0x1800000, v177
	global_store_dwordx4 v181, v[0:3], s[78:79]
	global_store_dwordx4 v181, v[4:7], s[78:79] offset:1024
	v_add_u32_e32 v236, 0x0, v237
	s_mov_b64 exec, 1
	global_store_dword v236, v184, s[78:79]
	s_mov_b64 exec, -1
	s_waitcnt vmcnt(24)
	v_lshlrev_b32_e32 v144, 16, v16
	v_and_b32_e32 v145, 0xffff0000, v16
	v_lshlrev_b32_e32 v146, 16, v17
	v_and_b32_e32 v147, 0xffff0000, v17
	v_lshlrev_b32_e32 v148, 16, v18
	v_and_b32_e32 v149, 0xffff0000, v18
	v_lshlrev_b32_e32 v150, 16, v19
	v_and_b32_e32 v151, 0xffff0000, v19
	v_lshlrev_b32_e32 v152, 16, v20
	v_and_b32_e32 v153, 0xffff0000, v20
	v_lshlrev_b32_e32 v154, 16, v21
	v_and_b32_e32 v155, 0xffff0000, v21
	v_lshlrev_b32_e32 v156, 16, v22
	v_and_b32_e32 v157, 0xffff0000, v22
	v_lshlrev_b32_e32 v158, 16, v23
	v_and_b32_e32 v159, 0xffff0000, v23
	v_lshlrev_b32_e32 v160, 16, v24
	v_and_b32_e32 v161, 0xffff0000, v24
	v_lshlrev_b32_e32 v162, 16, v25
	v_and_b32_e32 v163, 0xffff0000, v25
	v_lshlrev_b32_e32 v164, 16, v26
	v_and_b32_e32 v165, 0xffff0000, v26
	v_lshlrev_b32_e32 v166, 16, v27
	v_and_b32_e32 v167, 0xffff0000, v27
	v_lshlrev_b32_e32 v168, 16, v28
	v_and_b32_e32 v169, 0xffff0000, v28
	v_lshlrev_b32_e32 v170, 16, v29
	v_and_b32_e32 v171, 0xffff0000, v29
	v_lshlrev_b32_e32 v172, 16, v30
	v_and_b32_e32 v173, 0xffff0000, v30
	v_lshlrev_b32_e32 v174, 16, v31
	v_and_b32_e32 v175, 0xffff0000, v31
	v_pk_mul_f32 v[252:253], v[160:161], v[160:161]
	v_pk_mul_f32 v[254:255], v[162:163], v[162:163]
	v_pk_fma_f32 v[252:253], v[164:165], v[164:165], v[252:253]
	v_pk_fma_f32 v[254:255], v[166:167], v[166:167], v[254:255]
	v_pk_fma_f32 v[252:253], v[168:169], v[168:169], v[252:253]
	v_pk_fma_f32 v[254:255], v[170:171], v[170:171], v[254:255]
	v_pk_fma_f32 v[252:253], v[172:173], v[172:173], v[252:253]
	v_pk_fma_f32 v[254:255], v[174:175], v[174:175], v[254:255]
	v_pk_add_f32 v[252:253], v[252:253], v[254:255]
	s_nop 0
	v_add_f32_e32 v183, v252, v253
	s_nop 1
	v_add_f32_dpp v183, v183, v183 quad_perm:[1,0,3,2] row_mask:0xf bank_mask:0xf bound_ctrl:1
	s_nop 1
	v_add_f32_dpp v183, v183, v183 quad_perm:[2,3,0,1] row_mask:0xf bank_mask:0xf bound_ctrl:1
	s_nop 1
	v_add_f32_dpp v183, v183, v183 row_half_mirror row_mask:0xf bank_mask:0xf bound_ctrl:1
	s_nop 1
	v_add_f32_dpp v183, v183, v183 row_mirror row_mask:0xf bank_mask:0xf bound_ctrl:1
	s_nop 1
	v_readlane_b32 s98, v183, 0
	v_readlane_b32 s99, v183, 16
	v_readlane_b32 s100, v183, 32
	v_readlane_b32 s101, v183, 48
	s_nop 1
	v_mov_b32_e32 v183, s98
	v_add_f32_e32 v183, s99, v183
	v_add_f32_e32 v183, s100, v183
	v_add_f32_e32 v183, s101, v183
	v_fmamk_f32 v183, v183, 0x3a800000, v182
	v_cmp_gt_f32_e32 vcc, 0x800000, v183
	v_mul_f32_e32 v181, 0x4b800000, v183
	s_nop 1
	v_cndmask_b32_e32 v183, v183, v181, vcc
	v_rsq_f32_e32 v183, v183
	s_nop 0
	v_mul_f32_e32 v181, 0x45800000, v183
	v_cndmask_b32_e32 v184, v183, v181, vcc
	v_mov_b32_e32 v185, v184
	v_pk_mul_f32 v[160:161], v[160:161], v[184:185]
	v_pk_mul_f32 v[162:163], v[162:163], v[184:185]
	v_pk_mul_f32 v[164:165], v[164:165], v[184:185]
	v_pk_mul_f32 v[166:167], v[166:167], v[184:185]
	v_pk_mul_f32 v[168:169], v[168:169], v[184:185]
	v_pk_mul_f32 v[170:171], v[170:171], v[184:185]
	v_pk_mul_f32 v[172:173], v[172:173], v[184:185]
	v_pk_mul_f32 v[174:175], v[174:175], v[184:185]
	v_pk_fma_f32 v[144:145], v[160:161], v[128:129], v[144:145]
	v_pk_fma_f32 v[146:147], v[162:163], v[130:131], v[146:147]
	v_pk_fma_f32 v[148:149], v[164:165], v[132:133], v[148:149]
	v_pk_fma_f32 v[150:151], v[166:167], v[134:135], v[150:151]
	v_pk_fma_f32 v[152:153], v[168:169], v[136:137], v[152:153]
	v_pk_fma_f32 v[154:155], v[170:171], v[138:139], v[154:155]
	v_pk_fma_f32 v[156:157], v[172:173], v[140:141], v[156:157]
	v_pk_fma_f32 v[158:159], v[174:175], v[142:143], v[158:159]
	v_pk_mul_f32 v[252:253], v[144:145], v[144:145]
	v_pk_mul_f32 v[254:255], v[146:147], v[146:147]
	v_pk_fma_f32 v[252:253], v[148:149], v[148:149], v[252:253]
	v_pk_fma_f32 v[254:255], v[150:151], v[150:151], v[254:255]
	v_pk_fma_f32 v[252:253], v[152:153], v[152:153], v[252:253]
	v_pk_fma_f32 v[254:255], v[154:155], v[154:155], v[254:255]
	v_pk_fma_f32 v[252:253], v[156:157], v[156:157], v[252:253]
	v_pk_fma_f32 v[254:255], v[158:159], v[158:159], v[254:255]
	v_pk_add_f32 v[252:253], v[252:253], v[254:255]
	s_nop 0
	v_add_f32_e32 v183, v252, v253
	s_nop 1
	v_add_f32_dpp v183, v183, v183 quad_perm:[1,0,3,2] row_mask:0xf bank_mask:0xf bound_ctrl:1
	s_nop 1
	v_add_f32_dpp v183, v183, v183 quad_perm:[2,3,0,1] row_mask:0xf bank_mask:0xf bound_ctrl:1
	s_nop 1
	v_add_f32_dpp v183, v183, v183 row_half_mirror row_mask:0xf bank_mask:0xf bound_ctrl:1
	s_nop 1
	v_add_f32_dpp v183, v183, v183 row_mirror row_mask:0xf bank_mask:0xf bound_ctrl:1
	s_nop 1
	v_readlane_b32 s98, v183, 0
	v_readlane_b32 s99, v183, 16
	v_readlane_b32 s100, v183, 32
	v_readlane_b32 s101, v183, 48
	s_nop 1
	v_mov_b32_e32 v183, s98
	v_add_f32_e32 v183, s99, v183
	v_add_f32_e32 v183, s100, v183
	v_add_f32_e32 v183, s101, v183
	v_fmamk_f32 v183, v183, 0x3a800000, v182
	v_cmp_gt_f32_e32 vcc, 0x800000, v183
	v_mul_f32_e32 v181, 0x4b800000, v183
	s_nop 1
	v_cndmask_b32_e32 v183, v183, v181, vcc
	v_rsq_f32_e32 v183, v183
	s_nop 0
	v_mul_f32_e32 v181, 0x45800000, v183
	v_cndmask_b32_e32 v184, v183, v181, vcc
	v_mov_b32_e32 v185, v184
	v_cvt_pk_bf16_f32 v16, v144, v145
	v_cvt_pk_bf16_f32 v17, v146, v147
	v_cvt_pk_bf16_f32 v18, v148, v149
	v_cvt_pk_bf16_f32 v19, v150, v151
	v_cvt_pk_bf16_f32 v20, v152, v153
	v_cvt_pk_bf16_f32 v21, v154, v155
	v_cvt_pk_bf16_f32 v22, v156, v157
	v_cvt_pk_bf16_f32 v23, v158, v159
	v_add_u32_e32 v181, 0x1c00000, v177
	global_store_dwordx4 v181, v[16:19], s[78:79]
	global_store_dwordx4 v181, v[20:23], s[78:79] offset:1024
	v_add_u32_e32 v236, 0x2000, v237
	s_mov_b64 exec, 1
	global_store_dword v236, v184, s[78:79]
	s_mov_b64 exec, -1
	s_waitcnt vmcnt(20)
	v_lshlrev_b32_e32 v144, 16, v32
	v_and_b32_e32 v145, 0xffff0000, v32
	v_lshlrev_b32_e32 v146, 16, v33
	v_and_b32_e32 v147, 0xffff0000, v33
	v_lshlrev_b32_e32 v148, 16, v34
	v_and_b32_e32 v149, 0xffff0000, v34
	v_lshlrev_b32_e32 v150, 16, v35
	v_and_b32_e32 v151, 0xffff0000, v35
	v_lshlrev_b32_e32 v152, 16, v36
	v_and_b32_e32 v153, 0xffff0000, v36
	v_lshlrev_b32_e32 v154, 16, v37
	v_and_b32_e32 v155, 0xffff0000, v37
	v_lshlrev_b32_e32 v156, 16, v38
	v_and_b32_e32 v157, 0xffff0000, v38
	v_lshlrev_b32_e32 v158, 16, v39
	v_and_b32_e32 v159, 0xffff0000, v39
	v_lshlrev_b32_e32 v160, 16, v40
	v_and_b32_e32 v161, 0xffff0000, v40
	v_lshlrev_b32_e32 v162, 16, v41
	v_and_b32_e32 v163, 0xffff0000, v41
	v_lshlrev_b32_e32 v164, 16, v42
	v_and_b32_e32 v165, 0xffff0000, v42
	v_lshlrev_b32_e32 v166, 16, v43
	v_and_b32_e32 v167, 0xffff0000, v43
	v_lshlrev_b32_e32 v168, 16, v44
	v_and_b32_e32 v169, 0xffff0000, v44
	v_lshlrev_b32_e32 v170, 16, v45
	v_and_b32_e32 v171, 0xffff0000, v45
	v_lshlrev_b32_e32 v172, 16, v46
	v_and_b32_e32 v173, 0xffff0000, v46
	v_lshlrev_b32_e32 v174, 16, v47
	v_and_b32_e32 v175, 0xffff0000, v47
	v_pk_mul_f32 v[252:253], v[160:161], v[160:161]
	v_pk_mul_f32 v[254:255], v[162:163], v[162:163]
	v_pk_fma_f32 v[252:253], v[164:165], v[164:165], v[252:253]
	v_pk_fma_f32 v[254:255], v[166:167], v[166:167], v[254:255]
	v_pk_fma_f32 v[252:253], v[168:169], v[168:169], v[252:253]
	v_pk_fma_f32 v[254:255], v[170:171], v[170:171], v[254:255]
	v_pk_fma_f32 v[252:253], v[172:173], v[172:173], v[252:253]
	v_pk_fma_f32 v[254:255], v[174:175], v[174:175], v[254:255]
	v_pk_add_f32 v[252:253], v[252:253], v[254:255]
	s_nop 0
	v_add_f32_e32 v183, v252, v253
	s_nop 1
	v_add_f32_dpp v183, v183, v183 quad_perm:[1,0,3,2] row_mask:0xf bank_mask:0xf bound_ctrl:1
	s_nop 1
	v_add_f32_dpp v183, v183, v183 quad_perm:[2,3,0,1] row_mask:0xf bank_mask:0xf bound_ctrl:1
	s_nop 1
	v_add_f32_dpp v183, v183, v183 row_half_mirror row_mask:0xf bank_mask:0xf bound_ctrl:1
	s_nop 1
	v_add_f32_dpp v183, v183, v183 row_mirror row_mask:0xf bank_mask:0xf bound_ctrl:1
	s_nop 1
	v_readlane_b32 s98, v183, 0
	v_readlane_b32 s99, v183, 16
	v_readlane_b32 s100, v183, 32
	v_readlane_b32 s101, v183, 48
	s_nop 1
	v_mov_b32_e32 v183, s98
	v_add_f32_e32 v183, s99, v183
	v_add_f32_e32 v183, s100, v183
	v_add_f32_e32 v183, s101, v183
	v_fmamk_f32 v183, v183, 0x3a800000, v182
	v_cmp_gt_f32_e32 vcc, 0x800000, v183
	v_mul_f32_e32 v181, 0x4b800000, v183
	s_nop 1
	v_cndmask_b32_e32 v183, v183, v181, vcc
	v_rsq_f32_e32 v183, v183
	s_nop 0
	v_mul_f32_e32 v181, 0x45800000, v183
	v_cndmask_b32_e32 v184, v183, v181, vcc
	v_mov_b32_e32 v185, v184
	v_pk_mul_f32 v[160:161], v[160:161], v[184:185]
	v_pk_mul_f32 v[162:163], v[162:163], v[184:185]
	v_pk_mul_f32 v[164:165], v[164:165], v[184:185]
	v_pk_mul_f32 v[166:167], v[166:167], v[184:185]
	v_pk_mul_f32 v[168:169], v[168:169], v[184:185]
	v_pk_mul_f32 v[170:171], v[170:171], v[184:185]
	v_pk_mul_f32 v[172:173], v[172:173], v[184:185]
	v_pk_mul_f32 v[174:175], v[174:175], v[184:185]
	v_pk_fma_f32 v[144:145], v[160:161], v[128:129], v[144:145]
	v_pk_fma_f32 v[146:147], v[162:163], v[130:131], v[146:147]
	v_pk_fma_f32 v[148:149], v[164:165], v[132:133], v[148:149]
	v_pk_fma_f32 v[150:151], v[166:167], v[134:135], v[150:151]
	v_pk_fma_f32 v[152:153], v[168:169], v[136:137], v[152:153]
	v_pk_fma_f32 v[154:155], v[170:171], v[138:139], v[154:155]
	v_pk_fma_f32 v[156:157], v[172:173], v[140:141], v[156:157]
	v_pk_fma_f32 v[158:159], v[174:175], v[142:143], v[158:159]
	v_pk_mul_f32 v[252:253], v[144:145], v[144:145]
	v_pk_mul_f32 v[254:255], v[146:147], v[146:147]
	v_pk_fma_f32 v[252:253], v[148:149], v[148:149], v[252:253]
	v_pk_fma_f32 v[254:255], v[150:151], v[150:151], v[254:255]
	v_pk_fma_f32 v[252:253], v[152:153], v[152:153], v[252:253]
	v_pk_fma_f32 v[254:255], v[154:155], v[154:155], v[254:255]
	v_pk_fma_f32 v[252:253], v[156:157], v[156:157], v[252:253]
	v_pk_fma_f32 v[254:255], v[158:159], v[158:159], v[254:255]
	v_pk_add_f32 v[252:253], v[252:253], v[254:255]
	s_nop 0
	v_add_f32_e32 v183, v252, v253
	s_nop 1
	v_add_f32_dpp v183, v183, v183 quad_perm:[1,0,3,2] row_mask:0xf bank_mask:0xf bound_ctrl:1
	s_nop 1
	v_add_f32_dpp v183, v183, v183 quad_perm:[2,3,0,1] row_mask:0xf bank_mask:0xf bound_ctrl:1
	s_nop 1
	v_add_f32_dpp v183, v183, v183 row_half_mirror row_mask:0xf bank_mask:0xf bound_ctrl:1
	s_nop 1
	v_add_f32_dpp v183, v183, v183 row_mirror row_mask:0xf bank_mask:0xf bound_ctrl:1
	s_nop 1
	v_readlane_b32 s98, v183, 0
	v_readlane_b32 s99, v183, 16
	v_readlane_b32 s100, v183, 32
	v_readlane_b32 s101, v183, 48
	s_nop 1
	v_mov_b32_e32 v183, s98
	v_add_f32_e32 v183, s99, v183
	v_add_f32_e32 v183, s100, v183
	v_add_f32_e32 v183, s101, v183
	v_fmamk_f32 v183, v183, 0x3a800000, v182
	v_cmp_gt_f32_e32 vcc, 0x800000, v183
	v_mul_f32_e32 v181, 0x4b800000, v183
	s_nop 1
	v_cndmask_b32_e32 v183, v183, v181, vcc
	v_rsq_f32_e32 v183, v183
	s_nop 0
	v_mul_f32_e32 v181, 0x45800000, v183
	v_cndmask_b32_e32 v184, v183, v181, vcc
	v_mov_b32_e32 v185, v184
	v_cvt_pk_bf16_f32 v32, v144, v145
	v_cvt_pk_bf16_f32 v33, v146, v147
	v_cvt_pk_bf16_f32 v34, v148, v149
	v_cvt_pk_bf16_f32 v35, v150, v151
	v_cvt_pk_bf16_f32 v36, v152, v153
	v_cvt_pk_bf16_f32 v37, v154, v155
	v_cvt_pk_bf16_f32 v38, v156, v157
	v_cvt_pk_bf16_f32 v39, v158, v159
	v_add_u32_e32 v181, 0x2000000, v177
	global_store_dwordx4 v181, v[32:35], s[78:79]
	global_store_dwordx4 v181, v[36:39], s[78:79] offset:1024
	v_add_u32_e32 v236, 0x4000, v237
	s_mov_b64 exec, 1
	global_store_dword v236, v184, s[78:79]
	s_mov_b64 exec, -1
	s_waitcnt vmcnt(16)
	v_lshlrev_b32_e32 v144, 16, v48
	v_and_b32_e32 v145, 0xffff0000, v48
	v_lshlrev_b32_e32 v146, 16, v49
	v_and_b32_e32 v147, 0xffff0000, v49
	v_lshlrev_b32_e32 v148, 16, v50
	v_and_b32_e32 v149, 0xffff0000, v50
	v_lshlrev_b32_e32 v150, 16, v51
	v_and_b32_e32 v151, 0xffff0000, v51
	v_lshlrev_b32_e32 v152, 16, v52
	v_and_b32_e32 v153, 0xffff0000, v52
	v_lshlrev_b32_e32 v154, 16, v53
	v_and_b32_e32 v155, 0xffff0000, v53
	v_lshlrev_b32_e32 v156, 16, v54
	v_and_b32_e32 v157, 0xffff0000, v54
	v_lshlrev_b32_e32 v158, 16, v55
	v_and_b32_e32 v159, 0xffff0000, v55
	v_lshlrev_b32_e32 v160, 16, v56
	v_and_b32_e32 v161, 0xffff0000, v56
	v_lshlrev_b32_e32 v162, 16, v57
	v_and_b32_e32 v163, 0xffff0000, v57
	v_lshlrev_b32_e32 v164, 16, v58
	v_and_b32_e32 v165, 0xffff0000, v58
	v_lshlrev_b32_e32 v166, 16, v59
	v_and_b32_e32 v167, 0xffff0000, v59
	v_lshlrev_b32_e32 v168, 16, v60
	v_and_b32_e32 v169, 0xffff0000, v60
	v_lshlrev_b32_e32 v170, 16, v61
	v_and_b32_e32 v171, 0xffff0000, v61
	v_lshlrev_b32_e32 v172, 16, v62
	v_and_b32_e32 v173, 0xffff0000, v62
	v_lshlrev_b32_e32 v174, 16, v63
	v_and_b32_e32 v175, 0xffff0000, v63
	v_pk_mul_f32 v[252:253], v[160:161], v[160:161]
	v_pk_mul_f32 v[254:255], v[162:163], v[162:163]
	v_pk_fma_f32 v[252:253], v[164:165], v[164:165], v[252:253]
	v_pk_fma_f32 v[254:255], v[166:167], v[166:167], v[254:255]
	v_pk_fma_f32 v[252:253], v[168:169], v[168:169], v[252:253]
	v_pk_fma_f32 v[254:255], v[170:171], v[170:171], v[254:255]
	v_pk_fma_f32 v[252:253], v[172:173], v[172:173], v[252:253]
	v_pk_fma_f32 v[254:255], v[174:175], v[174:175], v[254:255]
	v_pk_add_f32 v[252:253], v[252:253], v[254:255]
	s_nop 0
	v_add_f32_e32 v183, v252, v253
	s_nop 1
	v_add_f32_dpp v183, v183, v183 quad_perm:[1,0,3,2] row_mask:0xf bank_mask:0xf bound_ctrl:1
	s_nop 1
	v_add_f32_dpp v183, v183, v183 quad_perm:[2,3,0,1] row_mask:0xf bank_mask:0xf bound_ctrl:1
	s_nop 1
	v_add_f32_dpp v183, v183, v183 row_half_mirror row_mask:0xf bank_mask:0xf bound_ctrl:1
	s_nop 1
	v_add_f32_dpp v183, v183, v183 row_mirror row_mask:0xf bank_mask:0xf bound_ctrl:1
	s_nop 1
	v_readlane_b32 s98, v183, 0
	v_readlane_b32 s99, v183, 16
	v_readlane_b32 s100, v183, 32
	v_readlane_b32 s101, v183, 48
	s_nop 1
	v_mov_b32_e32 v183, s98
	v_add_f32_e32 v183, s99, v183
	v_add_f32_e32 v183, s100, v183
	v_add_f32_e32 v183, s101, v183
	v_fmamk_f32 v183, v183, 0x3a800000, v182
	v_cmp_gt_f32_e32 vcc, 0x800000, v183
	v_mul_f32_e32 v181, 0x4b800000, v183
	s_nop 1
	v_cndmask_b32_e32 v183, v183, v181, vcc
	v_rsq_f32_e32 v183, v183
	s_nop 0
	v_mul_f32_e32 v181, 0x45800000, v183
	v_cndmask_b32_e32 v184, v183, v181, vcc
	v_mov_b32_e32 v185, v184
	v_pk_mul_f32 v[160:161], v[160:161], v[184:185]
	v_pk_mul_f32 v[162:163], v[162:163], v[184:185]
	v_pk_mul_f32 v[164:165], v[164:165], v[184:185]
	v_pk_mul_f32 v[166:167], v[166:167], v[184:185]
	v_pk_mul_f32 v[168:169], v[168:169], v[184:185]
	v_pk_mul_f32 v[170:171], v[170:171], v[184:185]
	v_pk_mul_f32 v[172:173], v[172:173], v[184:185]
	v_pk_mul_f32 v[174:175], v[174:175], v[184:185]
	v_pk_fma_f32 v[144:145], v[160:161], v[128:129], v[144:145]
	v_pk_fma_f32 v[146:147], v[162:163], v[130:131], v[146:147]
	v_pk_fma_f32 v[148:149], v[164:165], v[132:133], v[148:149]
	v_pk_fma_f32 v[150:151], v[166:167], v[134:135], v[150:151]
	v_pk_fma_f32 v[152:153], v[168:169], v[136:137], v[152:153]
	v_pk_fma_f32 v[154:155], v[170:171], v[138:139], v[154:155]
	v_pk_fma_f32 v[156:157], v[172:173], v[140:141], v[156:157]
	v_pk_fma_f32 v[158:159], v[174:175], v[142:143], v[158:159]
	v_pk_mul_f32 v[252:253], v[144:145], v[144:145]
	v_pk_mul_f32 v[254:255], v[146:147], v[146:147]
	v_pk_fma_f32 v[252:253], v[148:149], v[148:149], v[252:253]
	v_pk_fma_f32 v[254:255], v[150:151], v[150:151], v[254:255]
	v_pk_fma_f32 v[252:253], v[152:153], v[152:153], v[252:253]
	v_pk_fma_f32 v[254:255], v[154:155], v[154:155], v[254:255]
	v_pk_fma_f32 v[252:253], v[156:157], v[156:157], v[252:253]
	v_pk_fma_f32 v[254:255], v[158:159], v[158:159], v[254:255]
	v_pk_add_f32 v[252:253], v[252:253], v[254:255]
	s_nop 0
	v_add_f32_e32 v183, v252, v253
	s_nop 1
	v_add_f32_dpp v183, v183, v183 quad_perm:[1,0,3,2] row_mask:0xf bank_mask:0xf bound_ctrl:1
	s_nop 1
	v_add_f32_dpp v183, v183, v183 quad_perm:[2,3,0,1] row_mask:0xf bank_mask:0xf bound_ctrl:1
	s_nop 1
	v_add_f32_dpp v183, v183, v183 row_half_mirror row_mask:0xf bank_mask:0xf bound_ctrl:1
	s_nop 1
	v_add_f32_dpp v183, v183, v183 row_mirror row_mask:0xf bank_mask:0xf bound_ctrl:1
	s_nop 1
	v_readlane_b32 s98, v183, 0
	v_readlane_b32 s99, v183, 16
	v_readlane_b32 s100, v183, 32
	v_readlane_b32 s101, v183, 48
	s_nop 1
	v_mov_b32_e32 v183, s98
	v_add_f32_e32 v183, s99, v183
	v_add_f32_e32 v183, s100, v183
	v_add_f32_e32 v183, s101, v183
	v_fmamk_f32 v183, v183, 0x3a800000, v182
	v_cmp_gt_f32_e32 vcc, 0x800000, v183
	v_mul_f32_e32 v181, 0x4b800000, v183
	s_nop 1
	v_cndmask_b32_e32 v183, v183, v181, vcc
	v_rsq_f32_e32 v183, v183
	s_nop 0
	v_mul_f32_e32 v181, 0x45800000, v183
	v_cndmask_b32_e32 v184, v183, v181, vcc
	v_mov_b32_e32 v185, v184
	v_cvt_pk_bf16_f32 v48, v144, v145
	v_cvt_pk_bf16_f32 v49, v146, v147
	v_cvt_pk_bf16_f32 v50, v148, v149
	v_cvt_pk_bf16_f32 v51, v150, v151
	v_cvt_pk_bf16_f32 v52, v152, v153
	v_cvt_pk_bf16_f32 v53, v154, v155
	v_cvt_pk_bf16_f32 v54, v156, v157
	v_cvt_pk_bf16_f32 v55, v158, v159
	v_add_u32_e32 v181, 0x2400000, v177
	global_store_dwordx4 v181, v[48:51], s[78:79]
	global_store_dwordx4 v181, v[52:55], s[78:79] offset:1024
	v_add_u32_e32 v236, 0x6000, v237
	s_mov_b64 exec, 1
	global_store_dword v236, v184, s[78:79]
	s_mov_b64 exec, -1
	s_waitcnt vmcnt(12)
	v_lshlrev_b32_e32 v144, 16, v64
	v_and_b32_e32 v145, 0xffff0000, v64
	v_lshlrev_b32_e32 v146, 16, v65
	v_and_b32_e32 v147, 0xffff0000, v65
	v_lshlrev_b32_e32 v148, 16, v66
	v_and_b32_e32 v149, 0xffff0000, v66
	v_lshlrev_b32_e32 v150, 16, v67
	v_and_b32_e32 v151, 0xffff0000, v67
	v_lshlrev_b32_e32 v152, 16, v68
	v_and_b32_e32 v153, 0xffff0000, v68
	v_lshlrev_b32_e32 v154, 16, v69
	v_and_b32_e32 v155, 0xffff0000, v69
	v_lshlrev_b32_e32 v156, 16, v70
	v_and_b32_e32 v157, 0xffff0000, v70
	v_lshlrev_b32_e32 v158, 16, v71
	v_and_b32_e32 v159, 0xffff0000, v71
	v_lshlrev_b32_e32 v160, 16, v72
	v_and_b32_e32 v161, 0xffff0000, v72
	v_lshlrev_b32_e32 v162, 16, v73
	v_and_b32_e32 v163, 0xffff0000, v73
	v_lshlrev_b32_e32 v164, 16, v74
	v_and_b32_e32 v165, 0xffff0000, v74
	v_lshlrev_b32_e32 v166, 16, v75
	v_and_b32_e32 v167, 0xffff0000, v75
	v_lshlrev_b32_e32 v168, 16, v76
	v_and_b32_e32 v169, 0xffff0000, v76
	v_lshlrev_b32_e32 v170, 16, v77
	v_and_b32_e32 v171, 0xffff0000, v77
	v_lshlrev_b32_e32 v172, 16, v78
	v_and_b32_e32 v173, 0xffff0000, v78
	v_lshlrev_b32_e32 v174, 16, v79
	v_and_b32_e32 v175, 0xffff0000, v79
	v_pk_mul_f32 v[252:253], v[160:161], v[160:161]
	v_pk_mul_f32 v[254:255], v[162:163], v[162:163]
	v_pk_fma_f32 v[252:253], v[164:165], v[164:165], v[252:253]
	v_pk_fma_f32 v[254:255], v[166:167], v[166:167], v[254:255]
	v_pk_fma_f32 v[252:253], v[168:169], v[168:169], v[252:253]
	v_pk_fma_f32 v[254:255], v[170:171], v[170:171], v[254:255]
	v_pk_fma_f32 v[252:253], v[172:173], v[172:173], v[252:253]
	v_pk_fma_f32 v[254:255], v[174:175], v[174:175], v[254:255]
	v_pk_add_f32 v[252:253], v[252:253], v[254:255]
	s_nop 0
	v_add_f32_e32 v183, v252, v253
	s_nop 1
	v_add_f32_dpp v183, v183, v183 quad_perm:[1,0,3,2] row_mask:0xf bank_mask:0xf bound_ctrl:1
	s_nop 1
	v_add_f32_dpp v183, v183, v183 quad_perm:[2,3,0,1] row_mask:0xf bank_mask:0xf bound_ctrl:1
	s_nop 1
	v_add_f32_dpp v183, v183, v183 row_half_mirror row_mask:0xf bank_mask:0xf bound_ctrl:1
	s_nop 1
	v_add_f32_dpp v183, v183, v183 row_mirror row_mask:0xf bank_mask:0xf bound_ctrl:1
	s_nop 1
	v_readlane_b32 s98, v183, 0
	v_readlane_b32 s99, v183, 16
	v_readlane_b32 s100, v183, 32
	v_readlane_b32 s101, v183, 48
	s_nop 1
	v_mov_b32_e32 v183, s98
	v_add_f32_e32 v183, s99, v183
	v_add_f32_e32 v183, s100, v183
	v_add_f32_e32 v183, s101, v183
	v_fmamk_f32 v183, v183, 0x3a800000, v182
	v_cmp_gt_f32_e32 vcc, 0x800000, v183
	v_mul_f32_e32 v181, 0x4b800000, v183
	s_nop 1
	v_cndmask_b32_e32 v183, v183, v181, vcc
	v_rsq_f32_e32 v183, v183
	s_nop 0
	v_mul_f32_e32 v181, 0x45800000, v183
	v_cndmask_b32_e32 v184, v183, v181, vcc
	v_mov_b32_e32 v185, v184
	v_pk_mul_f32 v[160:161], v[160:161], v[184:185]
	v_pk_mul_f32 v[162:163], v[162:163], v[184:185]
	v_pk_mul_f32 v[164:165], v[164:165], v[184:185]
	v_pk_mul_f32 v[166:167], v[166:167], v[184:185]
	v_pk_mul_f32 v[168:169], v[168:169], v[184:185]
	v_pk_mul_f32 v[170:171], v[170:171], v[184:185]
	v_pk_mul_f32 v[172:173], v[172:173], v[184:185]
	v_pk_mul_f32 v[174:175], v[174:175], v[184:185]
	v_pk_fma_f32 v[144:145], v[160:161], v[128:129], v[144:145]
	v_pk_fma_f32 v[146:147], v[162:163], v[130:131], v[146:147]
	v_pk_fma_f32 v[148:149], v[164:165], v[132:133], v[148:149]
	v_pk_fma_f32 v[150:151], v[166:167], v[134:135], v[150:151]
	v_pk_fma_f32 v[152:153], v[168:169], v[136:137], v[152:153]
	v_pk_fma_f32 v[154:155], v[170:171], v[138:139], v[154:155]
	v_pk_fma_f32 v[156:157], v[172:173], v[140:141], v[156:157]
	v_pk_fma_f32 v[158:159], v[174:175], v[142:143], v[158:159]
	v_pk_mul_f32 v[252:253], v[144:145], v[144:145]
	v_pk_mul_f32 v[254:255], v[146:147], v[146:147]
	v_pk_fma_f32 v[252:253], v[148:149], v[148:149], v[252:253]
	v_pk_fma_f32 v[254:255], v[150:151], v[150:151], v[254:255]
	v_pk_fma_f32 v[252:253], v[152:153], v[152:153], v[252:253]
	v_pk_fma_f32 v[254:255], v[154:155], v[154:155], v[254:255]
	v_pk_fma_f32 v[252:253], v[156:157], v[156:157], v[252:253]
	v_pk_fma_f32 v[254:255], v[158:159], v[158:159], v[254:255]
	v_pk_add_f32 v[252:253], v[252:253], v[254:255]
	s_nop 0
	v_add_f32_e32 v183, v252, v253
	s_nop 1
	v_add_f32_dpp v183, v183, v183 quad_perm:[1,0,3,2] row_mask:0xf bank_mask:0xf bound_ctrl:1
	s_nop 1
	v_add_f32_dpp v183, v183, v183 quad_perm:[2,3,0,1] row_mask:0xf bank_mask:0xf bound_ctrl:1
	s_nop 1
	v_add_f32_dpp v183, v183, v183 row_half_mirror row_mask:0xf bank_mask:0xf bound_ctrl:1
	s_nop 1
	v_add_f32_dpp v183, v183, v183 row_mirror row_mask:0xf bank_mask:0xf bound_ctrl:1
	s_nop 1
	v_readlane_b32 s98, v183, 0
	v_readlane_b32 s99, v183, 16
	v_readlane_b32 s100, v183, 32
	v_readlane_b32 s101, v183, 48
	s_nop 1
	v_mov_b32_e32 v183, s98
	v_add_f32_e32 v183, s99, v183
	v_add_f32_e32 v183, s100, v183
	v_add_f32_e32 v183, s101, v183
	v_fmamk_f32 v183, v183, 0x3a800000, v182
	v_cmp_gt_f32_e32 vcc, 0x800000, v183
	v_mul_f32_e32 v181, 0x4b800000, v183
	s_nop 1
	v_cndmask_b32_e32 v183, v183, v181, vcc
	v_rsq_f32_e32 v183, v183
	s_nop 0
	v_mul_f32_e32 v181, 0x45800000, v183
	v_cndmask_b32_e32 v184, v183, v181, vcc
	v_mov_b32_e32 v185, v184
	v_cvt_pk_bf16_f32 v64, v144, v145
	v_cvt_pk_bf16_f32 v65, v146, v147
	v_cvt_pk_bf16_f32 v66, v148, v149
	v_cvt_pk_bf16_f32 v67, v150, v151
	v_cvt_pk_bf16_f32 v68, v152, v153
	v_cvt_pk_bf16_f32 v69, v154, v155
	v_cvt_pk_bf16_f32 v70, v156, v157
	v_cvt_pk_bf16_f32 v71, v158, v159
	v_add_u32_e32 v181, 0x2800000, v177
	global_store_dwordx4 v181, v[64:67], s[78:79]
	global_store_dwordx4 v181, v[68:71], s[78:79] offset:1024
	v_add_u32_e32 v236, 0x8000, v237
	s_mov_b64 exec, 1
	global_store_dword v236, v184, s[78:79]
	s_mov_b64 exec, -1
	s_waitcnt vmcnt(8)
	v_lshlrev_b32_e32 v144, 16, v80
	v_and_b32_e32 v145, 0xffff0000, v80
	v_lshlrev_b32_e32 v146, 16, v81
	v_and_b32_e32 v147, 0xffff0000, v81
	v_lshlrev_b32_e32 v148, 16, v82
	v_and_b32_e32 v149, 0xffff0000, v82
	v_lshlrev_b32_e32 v150, 16, v83
	v_and_b32_e32 v151, 0xffff0000, v83
	v_lshlrev_b32_e32 v152, 16, v84
	v_and_b32_e32 v153, 0xffff0000, v84
	v_lshlrev_b32_e32 v154, 16, v85
	v_and_b32_e32 v155, 0xffff0000, v85
	v_lshlrev_b32_e32 v156, 16, v86
	v_and_b32_e32 v157, 0xffff0000, v86
	v_lshlrev_b32_e32 v158, 16, v87
	v_and_b32_e32 v159, 0xffff0000, v87
	v_lshlrev_b32_e32 v160, 16, v88
	v_and_b32_e32 v161, 0xffff0000, v88
	v_lshlrev_b32_e32 v162, 16, v89
	v_and_b32_e32 v163, 0xffff0000, v89
	v_lshlrev_b32_e32 v164, 16, v90
	v_and_b32_e32 v165, 0xffff0000, v90
	v_lshlrev_b32_e32 v166, 16, v91
	v_and_b32_e32 v167, 0xffff0000, v91
	v_lshlrev_b32_e32 v168, 16, v92
	v_and_b32_e32 v169, 0xffff0000, v92
	v_lshlrev_b32_e32 v170, 16, v93
	v_and_b32_e32 v171, 0xffff0000, v93
	v_lshlrev_b32_e32 v172, 16, v94
	v_and_b32_e32 v173, 0xffff0000, v94
	v_lshlrev_b32_e32 v174, 16, v95
	v_and_b32_e32 v175, 0xffff0000, v95
	v_pk_mul_f32 v[252:253], v[160:161], v[160:161]
	v_pk_mul_f32 v[254:255], v[162:163], v[162:163]
	v_pk_fma_f32 v[252:253], v[164:165], v[164:165], v[252:253]
	v_pk_fma_f32 v[254:255], v[166:167], v[166:167], v[254:255]
	v_pk_fma_f32 v[252:253], v[168:169], v[168:169], v[252:253]
	v_pk_fma_f32 v[254:255], v[170:171], v[170:171], v[254:255]
	v_pk_fma_f32 v[252:253], v[172:173], v[172:173], v[252:253]
	v_pk_fma_f32 v[254:255], v[174:175], v[174:175], v[254:255]
	v_pk_add_f32 v[252:253], v[252:253], v[254:255]
	s_nop 0
	v_add_f32_e32 v183, v252, v253
	s_nop 1
	v_add_f32_dpp v183, v183, v183 quad_perm:[1,0,3,2] row_mask:0xf bank_mask:0xf bound_ctrl:1
	s_nop 1
	v_add_f32_dpp v183, v183, v183 quad_perm:[2,3,0,1] row_mask:0xf bank_mask:0xf bound_ctrl:1
	s_nop 1
	v_add_f32_dpp v183, v183, v183 row_half_mirror row_mask:0xf bank_mask:0xf bound_ctrl:1
	s_nop 1
	v_add_f32_dpp v183, v183, v183 row_mirror row_mask:0xf bank_mask:0xf bound_ctrl:1
	s_nop 1
	v_readlane_b32 s98, v183, 0
	v_readlane_b32 s99, v183, 16
	v_readlane_b32 s100, v183, 32
	v_readlane_b32 s101, v183, 48
	s_nop 1
	v_mov_b32_e32 v183, s98
	v_add_f32_e32 v183, s99, v183
	v_add_f32_e32 v183, s100, v183
	v_add_f32_e32 v183, s101, v183
	v_fmamk_f32 v183, v183, 0x3a800000, v182
	v_cmp_gt_f32_e32 vcc, 0x800000, v183
	v_mul_f32_e32 v181, 0x4b800000, v183
	s_nop 1
	v_cndmask_b32_e32 v183, v183, v181, vcc
	v_rsq_f32_e32 v183, v183
	s_nop 0
	v_mul_f32_e32 v181, 0x45800000, v183
	v_cndmask_b32_e32 v184, v183, v181, vcc
	v_mov_b32_e32 v185, v184
	v_pk_mul_f32 v[160:161], v[160:161], v[184:185]
	v_pk_mul_f32 v[162:163], v[162:163], v[184:185]
	v_pk_mul_f32 v[164:165], v[164:165], v[184:185]
	v_pk_mul_f32 v[166:167], v[166:167], v[184:185]
	v_pk_mul_f32 v[168:169], v[168:169], v[184:185]
	v_pk_mul_f32 v[170:171], v[170:171], v[184:185]
	v_pk_mul_f32 v[172:173], v[172:173], v[184:185]
	v_pk_mul_f32 v[174:175], v[174:175], v[184:185]
	v_pk_fma_f32 v[144:145], v[160:161], v[128:129], v[144:145]
	v_pk_fma_f32 v[146:147], v[162:163], v[130:131], v[146:147]
	v_pk_fma_f32 v[148:149], v[164:165], v[132:133], v[148:149]
	v_pk_fma_f32 v[150:151], v[166:167], v[134:135], v[150:151]
	v_pk_fma_f32 v[152:153], v[168:169], v[136:137], v[152:153]
	v_pk_fma_f32 v[154:155], v[170:171], v[138:139], v[154:155]
	v_pk_fma_f32 v[156:157], v[172:173], v[140:141], v[156:157]
	v_pk_fma_f32 v[158:159], v[174:175], v[142:143], v[158:159]
	v_pk_mul_f32 v[252:253], v[144:145], v[144:145]
	v_pk_mul_f32 v[254:255], v[146:147], v[146:147]
	v_pk_fma_f32 v[252:253], v[148:149], v[148:149], v[252:253]
	v_pk_fma_f32 v[254:255], v[150:151], v[150:151], v[254:255]
	v_pk_fma_f32 v[252:253], v[152:153], v[152:153], v[252:253]
	v_pk_fma_f32 v[254:255], v[154:155], v[154:155], v[254:255]
	v_pk_fma_f32 v[252:253], v[156:157], v[156:157], v[252:253]
	v_pk_fma_f32 v[254:255], v[158:159], v[158:159], v[254:255]
	v_pk_add_f32 v[252:253], v[252:253], v[254:255]
	s_nop 0
	v_add_f32_e32 v183, v252, v253
	s_nop 1
	v_add_f32_dpp v183, v183, v183 quad_perm:[1,0,3,2] row_mask:0xf bank_mask:0xf bound_ctrl:1
	s_nop 1
	v_add_f32_dpp v183, v183, v183 quad_perm:[2,3,0,1] row_mask:0xf bank_mask:0xf bound_ctrl:1
	s_nop 1
	v_add_f32_dpp v183, v183, v183 row_half_mirror row_mask:0xf bank_mask:0xf bound_ctrl:1
	s_nop 1
	v_add_f32_dpp v183, v183, v183 row_mirror row_mask:0xf bank_mask:0xf bound_ctrl:1
	s_nop 1
	v_readlane_b32 s98, v183, 0
	v_readlane_b32 s99, v183, 16
	v_readlane_b32 s100, v183, 32
	v_readlane_b32 s101, v183, 48
	s_nop 1
	v_mov_b32_e32 v183, s98
	v_add_f32_e32 v183, s99, v183
	v_add_f32_e32 v183, s100, v183
	v_add_f32_e32 v183, s101, v183
	v_fmamk_f32 v183, v183, 0x3a800000, v182
	v_cmp_gt_f32_e32 vcc, 0x800000, v183
	v_mul_f32_e32 v181, 0x4b800000, v183
	s_nop 1
	v_cndmask_b32_e32 v183, v183, v181, vcc
	v_rsq_f32_e32 v183, v183
	s_nop 0
	v_mul_f32_e32 v181, 0x45800000, v183
	v_cndmask_b32_e32 v184, v183, v181, vcc
	v_mov_b32_e32 v185, v184
	v_cvt_pk_bf16_f32 v80, v144, v145
	v_cvt_pk_bf16_f32 v81, v146, v147
	v_cvt_pk_bf16_f32 v82, v148, v149
	v_cvt_pk_bf16_f32 v83, v150, v151
	v_cvt_pk_bf16_f32 v84, v152, v153
	v_cvt_pk_bf16_f32 v85, v154, v155
	v_cvt_pk_bf16_f32 v86, v156, v157
	v_cvt_pk_bf16_f32 v87, v158, v159
	v_add_u32_e32 v181, 0x2c00000, v177
	global_store_dwordx4 v181, v[80:83], s[78:79]
	global_store_dwordx4 v181, v[84:87], s[78:79] offset:1024
	v_add_u32_e32 v236, 0xa000, v237
	s_mov_b64 exec, 1
	global_store_dword v236, v184, s[78:79]
	s_mov_b64 exec, -1
	s_waitcnt vmcnt(4)
	v_lshlrev_b32_e32 v144, 16, v96
	v_and_b32_e32 v145, 0xffff0000, v96
	v_lshlrev_b32_e32 v146, 16, v97
	v_and_b32_e32 v147, 0xffff0000, v97
	v_lshlrev_b32_e32 v148, 16, v98
	v_and_b32_e32 v149, 0xffff0000, v98
	v_lshlrev_b32_e32 v150, 16, v99
	v_and_b32_e32 v151, 0xffff0000, v99
	v_lshlrev_b32_e32 v152, 16, v100
	v_and_b32_e32 v153, 0xffff0000, v100
	v_lshlrev_b32_e32 v154, 16, v101
	v_and_b32_e32 v155, 0xffff0000, v101
	v_lshlrev_b32_e32 v156, 16, v102
	v_and_b32_e32 v157, 0xffff0000, v102
	v_lshlrev_b32_e32 v158, 16, v103
	v_and_b32_e32 v159, 0xffff0000, v103
	v_lshlrev_b32_e32 v160, 16, v104
	v_and_b32_e32 v161, 0xffff0000, v104
	v_lshlrev_b32_e32 v162, 16, v105
	v_and_b32_e32 v163, 0xffff0000, v105
	v_lshlrev_b32_e32 v164, 16, v106
	v_and_b32_e32 v165, 0xffff0000, v106
	v_lshlrev_b32_e32 v166, 16, v107
	v_and_b32_e32 v167, 0xffff0000, v107
	v_lshlrev_b32_e32 v168, 16, v108
	v_and_b32_e32 v169, 0xffff0000, v108
	v_lshlrev_b32_e32 v170, 16, v109
	v_and_b32_e32 v171, 0xffff0000, v109
	v_lshlrev_b32_e32 v172, 16, v110
	v_and_b32_e32 v173, 0xffff0000, v110
	v_lshlrev_b32_e32 v174, 16, v111
	v_and_b32_e32 v175, 0xffff0000, v111
	v_pk_mul_f32 v[252:253], v[160:161], v[160:161]
	v_pk_mul_f32 v[254:255], v[162:163], v[162:163]
	v_pk_fma_f32 v[252:253], v[164:165], v[164:165], v[252:253]
	v_pk_fma_f32 v[254:255], v[166:167], v[166:167], v[254:255]
	v_pk_fma_f32 v[252:253], v[168:169], v[168:169], v[252:253]
	v_pk_fma_f32 v[254:255], v[170:171], v[170:171], v[254:255]
	v_pk_fma_f32 v[252:253], v[172:173], v[172:173], v[252:253]
	v_pk_fma_f32 v[254:255], v[174:175], v[174:175], v[254:255]
	v_pk_add_f32 v[252:253], v[252:253], v[254:255]
	s_nop 0
	v_add_f32_e32 v183, v252, v253
	s_nop 1
	v_add_f32_dpp v183, v183, v183 quad_perm:[1,0,3,2] row_mask:0xf bank_mask:0xf bound_ctrl:1
	s_nop 1
	v_add_f32_dpp v183, v183, v183 quad_perm:[2,3,0,1] row_mask:0xf bank_mask:0xf bound_ctrl:1
	s_nop 1
	v_add_f32_dpp v183, v183, v183 row_half_mirror row_mask:0xf bank_mask:0xf bound_ctrl:1
	s_nop 1
	v_add_f32_dpp v183, v183, v183 row_mirror row_mask:0xf bank_mask:0xf bound_ctrl:1
	s_nop 1
	v_readlane_b32 s98, v183, 0
	v_readlane_b32 s99, v183, 16
	v_readlane_b32 s100, v183, 32
	v_readlane_b32 s101, v183, 48
	s_nop 1
	v_mov_b32_e32 v183, s98
	v_add_f32_e32 v183, s99, v183
	v_add_f32_e32 v183, s100, v183
	v_add_f32_e32 v183, s101, v183
	v_fmamk_f32 v183, v183, 0x3a800000, v182
	v_cmp_gt_f32_e32 vcc, 0x800000, v183
	v_mul_f32_e32 v181, 0x4b800000, v183
	s_nop 1
	v_cndmask_b32_e32 v183, v183, v181, vcc
	v_rsq_f32_e32 v183, v183
	s_nop 0
	v_mul_f32_e32 v181, 0x45800000, v183
	v_cndmask_b32_e32 v184, v183, v181, vcc
	v_mov_b32_e32 v185, v184
	v_pk_mul_f32 v[160:161], v[160:161], v[184:185]
	v_pk_mul_f32 v[162:163], v[162:163], v[184:185]
	v_pk_mul_f32 v[164:165], v[164:165], v[184:185]
	v_pk_mul_f32 v[166:167], v[166:167], v[184:185]
	v_pk_mul_f32 v[168:169], v[168:169], v[184:185]
	v_pk_mul_f32 v[170:171], v[170:171], v[184:185]
	v_pk_mul_f32 v[172:173], v[172:173], v[184:185]
	v_pk_mul_f32 v[174:175], v[174:175], v[184:185]
	v_pk_fma_f32 v[144:145], v[160:161], v[128:129], v[144:145]
	v_pk_fma_f32 v[146:147], v[162:163], v[130:131], v[146:147]
	v_pk_fma_f32 v[148:149], v[164:165], v[132:133], v[148:149]
	v_pk_fma_f32 v[150:151], v[166:167], v[134:135], v[150:151]
	v_pk_fma_f32 v[152:153], v[168:169], v[136:137], v[152:153]
	v_pk_fma_f32 v[154:155], v[170:171], v[138:139], v[154:155]
	v_pk_fma_f32 v[156:157], v[172:173], v[140:141], v[156:157]
	v_pk_fma_f32 v[158:159], v[174:175], v[142:143], v[158:159]
	v_pk_mul_f32 v[252:253], v[144:145], v[144:145]
	v_pk_mul_f32 v[254:255], v[146:147], v[146:147]
	v_pk_fma_f32 v[252:253], v[148:149], v[148:149], v[252:253]
	v_pk_fma_f32 v[254:255], v[150:151], v[150:151], v[254:255]
	v_pk_fma_f32 v[252:253], v[152:153], v[152:153], v[252:253]
	v_pk_fma_f32 v[254:255], v[154:155], v[154:155], v[254:255]
	v_pk_fma_f32 v[252:253], v[156:157], v[156:157], v[252:253]
	v_pk_fma_f32 v[254:255], v[158:159], v[158:159], v[254:255]
	v_pk_add_f32 v[252:253], v[252:253], v[254:255]
	s_nop 0
	v_add_f32_e32 v183, v252, v253
	s_nop 1
	v_add_f32_dpp v183, v183, v183 quad_perm:[1,0,3,2] row_mask:0xf bank_mask:0xf bound_ctrl:1
	s_nop 1
	v_add_f32_dpp v183, v183, v183 quad_perm:[2,3,0,1] row_mask:0xf bank_mask:0xf bound_ctrl:1
	s_nop 1
	v_add_f32_dpp v183, v183, v183 row_half_mirror row_mask:0xf bank_mask:0xf bound_ctrl:1
	s_nop 1
	v_add_f32_dpp v183, v183, v183 row_mirror row_mask:0xf bank_mask:0xf bound_ctrl:1
	s_nop 1
	v_readlane_b32 s98, v183, 0
	v_readlane_b32 s99, v183, 16
	v_readlane_b32 s100, v183, 32
	v_readlane_b32 s101, v183, 48
	s_nop 1
	v_mov_b32_e32 v183, s98
	v_add_f32_e32 v183, s99, v183
	v_add_f32_e32 v183, s100, v183
	v_add_f32_e32 v183, s101, v183
	v_fmamk_f32 v183, v183, 0x3a800000, v182
	v_cmp_gt_f32_e32 vcc, 0x800000, v183
	v_mul_f32_e32 v181, 0x4b800000, v183
	s_nop 1
	v_cndmask_b32_e32 v183, v183, v181, vcc
	v_rsq_f32_e32 v183, v183
	s_nop 0
	v_mul_f32_e32 v181, 0x45800000, v183
	v_cndmask_b32_e32 v184, v183, v181, vcc
	v_mov_b32_e32 v185, v184
	v_cvt_pk_bf16_f32 v96, v144, v145
	v_cvt_pk_bf16_f32 v97, v146, v147
	v_cvt_pk_bf16_f32 v98, v148, v149
	v_cvt_pk_bf16_f32 v99, v150, v151
	v_cvt_pk_bf16_f32 v100, v152, v153
	v_cvt_pk_bf16_f32 v101, v154, v155
	v_cvt_pk_bf16_f32 v102, v156, v157
	v_cvt_pk_bf16_f32 v103, v158, v159
	v_add_u32_e32 v181, 0x3000000, v177
	global_store_dwordx4 v181, v[96:99], s[78:79]
	global_store_dwordx4 v181, v[100:103], s[78:79] offset:1024
	v_add_u32_e32 v236, 0xc000, v237
	s_mov_b64 exec, 1
	global_store_dword v236, v184, s[78:79]
	s_mov_b64 exec, -1
	s_waitcnt vmcnt(0)
	v_lshlrev_b32_e32 v144, 16, v112
	v_and_b32_e32 v145, 0xffff0000, v112
	v_lshlrev_b32_e32 v146, 16, v113
	v_and_b32_e32 v147, 0xffff0000, v113
	v_lshlrev_b32_e32 v148, 16, v114
	v_and_b32_e32 v149, 0xffff0000, v114
	v_lshlrev_b32_e32 v150, 16, v115
	v_and_b32_e32 v151, 0xffff0000, v115
	v_lshlrev_b32_e32 v152, 16, v116
	v_and_b32_e32 v153, 0xffff0000, v116
	v_lshlrev_b32_e32 v154, 16, v117
	v_and_b32_e32 v155, 0xffff0000, v117
	v_lshlrev_b32_e32 v156, 16, v118
	v_and_b32_e32 v157, 0xffff0000, v118
	v_lshlrev_b32_e32 v158, 16, v119
	v_and_b32_e32 v159, 0xffff0000, v119
	v_lshlrev_b32_e32 v160, 16, v120
	v_and_b32_e32 v161, 0xffff0000, v120
	v_lshlrev_b32_e32 v162, 16, v121
	v_and_b32_e32 v163, 0xffff0000, v121
	v_lshlrev_b32_e32 v164, 16, v122
	v_and_b32_e32 v165, 0xffff0000, v122
	v_lshlrev_b32_e32 v166, 16, v123
	v_and_b32_e32 v167, 0xffff0000, v123
	v_lshlrev_b32_e32 v168, 16, v124
	v_and_b32_e32 v169, 0xffff0000, v124
	v_lshlrev_b32_e32 v170, 16, v125
	v_and_b32_e32 v171, 0xffff0000, v125
	v_lshlrev_b32_e32 v172, 16, v126
	v_and_b32_e32 v173, 0xffff0000, v126
	v_lshlrev_b32_e32 v174, 16, v127
	v_and_b32_e32 v175, 0xffff0000, v127
	v_pk_mul_f32 v[252:253], v[160:161], v[160:161]
	v_pk_mul_f32 v[254:255], v[162:163], v[162:163]
	v_pk_fma_f32 v[252:253], v[164:165], v[164:165], v[252:253]
	v_pk_fma_f32 v[254:255], v[166:167], v[166:167], v[254:255]
	v_pk_fma_f32 v[252:253], v[168:169], v[168:169], v[252:253]
	v_pk_fma_f32 v[254:255], v[170:171], v[170:171], v[254:255]
	v_pk_fma_f32 v[252:253], v[172:173], v[172:173], v[252:253]
	v_pk_fma_f32 v[254:255], v[174:175], v[174:175], v[254:255]
	v_pk_add_f32 v[252:253], v[252:253], v[254:255]
	s_nop 0
	v_add_f32_e32 v183, v252, v253
	s_nop 1
	v_add_f32_dpp v183, v183, v183 quad_perm:[1,0,3,2] row_mask:0xf bank_mask:0xf bound_ctrl:1
	s_nop 1
	v_add_f32_dpp v183, v183, v183 quad_perm:[2,3,0,1] row_mask:0xf bank_mask:0xf bound_ctrl:1
	s_nop 1
	v_add_f32_dpp v183, v183, v183 row_half_mirror row_mask:0xf bank_mask:0xf bound_ctrl:1
	s_nop 1
	v_add_f32_dpp v183, v183, v183 row_mirror row_mask:0xf bank_mask:0xf bound_ctrl:1
	s_nop 1
	v_readlane_b32 s98, v183, 0
	v_readlane_b32 s99, v183, 16
	v_readlane_b32 s100, v183, 32
	v_readlane_b32 s101, v183, 48
	s_nop 1
	v_mov_b32_e32 v183, s98
	v_add_f32_e32 v183, s99, v183
	v_add_f32_e32 v183, s100, v183
	v_add_f32_e32 v183, s101, v183
	v_fmamk_f32 v183, v183, 0x3a800000, v182
	v_cmp_gt_f32_e32 vcc, 0x800000, v183
	v_mul_f32_e32 v181, 0x4b800000, v183
	s_nop 1
	v_cndmask_b32_e32 v183, v183, v181, vcc
	v_rsq_f32_e32 v183, v183
	s_nop 0
	v_mul_f32_e32 v181, 0x45800000, v183
	v_cndmask_b32_e32 v184, v183, v181, vcc
	v_mov_b32_e32 v185, v184
	v_pk_mul_f32 v[160:161], v[160:161], v[184:185]
	v_pk_mul_f32 v[162:163], v[162:163], v[184:185]
	v_pk_mul_f32 v[164:165], v[164:165], v[184:185]
	v_pk_mul_f32 v[166:167], v[166:167], v[184:185]
	v_pk_mul_f32 v[168:169], v[168:169], v[184:185]
	v_pk_mul_f32 v[170:171], v[170:171], v[184:185]
	v_pk_mul_f32 v[172:173], v[172:173], v[184:185]
	v_pk_mul_f32 v[174:175], v[174:175], v[184:185]
	v_pk_fma_f32 v[144:145], v[160:161], v[128:129], v[144:145]
	v_pk_fma_f32 v[146:147], v[162:163], v[130:131], v[146:147]
	v_pk_fma_f32 v[148:149], v[164:165], v[132:133], v[148:149]
	v_pk_fma_f32 v[150:151], v[166:167], v[134:135], v[150:151]
	v_pk_fma_f32 v[152:153], v[168:169], v[136:137], v[152:153]
	v_pk_fma_f32 v[154:155], v[170:171], v[138:139], v[154:155]
	v_pk_fma_f32 v[156:157], v[172:173], v[140:141], v[156:157]
	v_pk_fma_f32 v[158:159], v[174:175], v[142:143], v[158:159]
	v_pk_mul_f32 v[252:253], v[144:145], v[144:145]
	v_pk_mul_f32 v[254:255], v[146:147], v[146:147]
	v_pk_fma_f32 v[252:253], v[148:149], v[148:149], v[252:253]
	v_pk_fma_f32 v[254:255], v[150:151], v[150:151], v[254:255]
	v_pk_fma_f32 v[252:253], v[152:153], v[152:153], v[252:253]
	v_pk_fma_f32 v[254:255], v[154:155], v[154:155], v[254:255]
	v_pk_fma_f32 v[252:253], v[156:157], v[156:157], v[252:253]
	v_pk_fma_f32 v[254:255], v[158:159], v[158:159], v[254:255]
	v_pk_add_f32 v[252:253], v[252:253], v[254:255]
	s_nop 0
	v_add_f32_e32 v183, v252, v253
	s_nop 1
	v_add_f32_dpp v183, v183, v183 quad_perm:[1,0,3,2] row_mask:0xf bank_mask:0xf bound_ctrl:1
	s_nop 1
	v_add_f32_dpp v183, v183, v183 quad_perm:[2,3,0,1] row_mask:0xf bank_mask:0xf bound_ctrl:1
	s_nop 1
	v_add_f32_dpp v183, v183, v183 row_half_mirror row_mask:0xf bank_mask:0xf bound_ctrl:1
	s_nop 1
	v_add_f32_dpp v183, v183, v183 row_mirror row_mask:0xf bank_mask:0xf bound_ctrl:1
	s_nop 1
	v_readlane_b32 s98, v183, 0
	v_readlane_b32 s99, v183, 16
	v_readlane_b32 s100, v183, 32
	v_readlane_b32 s101, v183, 48
	s_nop 1
	v_mov_b32_e32 v183, s98
	v_add_f32_e32 v183, s99, v183
	v_add_f32_e32 v183, s100, v183
	v_add_f32_e32 v183, s101, v183
	v_fmamk_f32 v183, v183, 0x3a800000, v182
	v_cmp_gt_f32_e32 vcc, 0x800000, v183
	v_mul_f32_e32 v181, 0x4b800000, v183
	s_nop 1
	v_cndmask_b32_e32 v183, v183, v181, vcc
	v_rsq_f32_e32 v183, v183
	s_nop 0
	v_mul_f32_e32 v181, 0x45800000, v183
	v_cndmask_b32_e32 v184, v183, v181, vcc
	v_mov_b32_e32 v185, v184
	v_cvt_pk_bf16_f32 v112, v144, v145
	v_cvt_pk_bf16_f32 v113, v146, v147
	v_cvt_pk_bf16_f32 v114, v148, v149
	v_cvt_pk_bf16_f32 v115, v150, v151
	v_cvt_pk_bf16_f32 v116, v152, v153
	v_cvt_pk_bf16_f32 v117, v154, v155
	v_cvt_pk_bf16_f32 v118, v156, v157
	v_cvt_pk_bf16_f32 v119, v158, v159
	v_add_u32_e32 v181, 0x3400000, v177
	global_store_dwordx4 v181, v[112:115], s[78:79]
	global_store_dwordx4 v181, v[116:119], s[78:79] offset:1024
	v_add_u32_e32 v236, 0xe000, v237
	s_mov_b64 exec, 1
	global_store_dword v236, v184, s[78:79]
	s_mov_b64 exec, -1
	v_readfirstlane_b32 s98, v179
	s_nop 3
	s_cmp_ge_u32 s98, 512
	s_cbranch_scc1 .Lmyxupd_done_6
	v_add_u32_e32 v181, 0x3800000, v177
	global_load_dwordx4 v[0:3], v181, s[78:79]
	global_load_dwordx4 v[4:7], v181, s[78:79] offset:1024
	v_lshl_add_u32 v183, v179, 12, v180
	v_add_u32_e32 v183, 0xbf00000, v183
	v_add_u32_e32 v181, 0x0, v183
	global_load_dwordx4 v[8:11], v181, s[78:79]
	global_load_dwordx4 v[12:15], v181, s[78:79] offset:16
	global_load_dwordx4 v[16:19], v181, s[78:79] offset:2048
	global_load_dwordx4 v[20:23], v181, s[78:79] offset:2064
	v_add_u32_e32 v181, 0x200000, v183
	global_load_dwordx4 v[24:27], v181, s[78:79]
	global_load_dwordx4 v[28:31], v181, s[78:79] offset:16
	global_load_dwordx4 v[32:35], v181, s[78:79] offset:2048
	global_load_dwordx4 v[36:39], v181, s[78:79] offset:2064
	v_add_u32_e32 v181, 0x400000, v183
	global_load_dwordx4 v[40:43], v181, s[78:79]
	global_load_dwordx4 v[44:47], v181, s[78:79] offset:16
	global_load_dwordx4 v[48:51], v181, s[78:79] offset:2048
	global_load_dwordx4 v[52:55], v181, s[78:79] offset:2064
	v_add_u32_e32 v181, 0x600000, v183
	global_load_dwordx4 v[56:59], v181, s[78:79]
	global_load_dwordx4 v[60:63], v181, s[78:79] offset:16
	global_load_dwordx4 v[64:67], v181, s[78:79] offset:2048
	global_load_dwordx4 v[68:71], v181, s[78:79] offset:2064
	v_add_u32_e32 v181, 0x800000, v183
	global_load_dwordx4 v[72:75], v181, s[78:79]
	global_load_dwordx4 v[76:79], v181, s[78:79] offset:16
	global_load_dwordx4 v[80:83], v181, s[78:79] offset:2048
	global_load_dwordx4 v[84:87], v181, s[78:79] offset:2064
	v_add_u32_e32 v181, 0xa00000, v183
	global_load_dwordx4 v[88:91], v181, s[78:79]
	global_load_dwordx4 v[92:95], v181, s[78:79] offset:16
	global_load_dwordx4 v[96:99], v181, s[78:79] offset:2048
	global_load_dwordx4 v[100:103], v181, s[78:79] offset:2064
	s_waitcnt vmcnt(20)
	v_pk_add_f32 v[160:161], v[8:9], 0 op_sel_hi:[1,0]
	v_pk_add_f32 v[162:163], v[10:11], 0 op_sel_hi:[1,0]
	v_pk_add_f32 v[164:165], v[12:13], 0 op_sel_hi:[1,0]
	v_pk_add_f32 v[166:167], v[14:15], 0 op_sel_hi:[1,0]
	v_pk_add_f32 v[168:169], v[16:17], 0 op_sel_hi:[1,0]
	v_pk_add_f32 v[170:171], v[18:19], 0 op_sel_hi:[1,0]
	v_pk_add_f32 v[172:173], v[20:21], 0 op_sel_hi:[1,0]
	v_pk_add_f32 v[174:175], v[22:23], 0 op_sel_hi:[1,0]
	s_waitcnt vmcnt(16)
	v_pk_add_f32 v[160:161], v[160:161], v[24:25]
	v_pk_add_f32 v[162:163], v[162:163], v[26:27]
	v_pk_add_f32 v[164:165], v[164:165], v[28:29]
	v_pk_add_f32 v[166:167], v[166:167], v[30:31]
	v_pk_add_f32 v[168:169], v[168:169], v[32:33]
	v_pk_add_f32 v[170:171], v[170:171], v[34:35]
	v_pk_add_f32 v[172:173], v[172:173], v[36:37]
	v_pk_add_f32 v[174:175], v[174:175], v[38:39]
	s_waitcnt vmcnt(12)
	v_pk_add_f32 v[160:161], v[160:161], v[40:41]
	v_pk_add_f32 v[162:163], v[162:163], v[42:43]
	v_pk_add_f32 v[164:165], v[164:165], v[44:45]
	v_pk_add_f32 v[166:167], v[166:167], v[46:47]
	v_pk_add_f32 v[168:169], v[168:169], v[48:49]
	v_pk_add_f32 v[170:171], v[170:171], v[50:51]
	v_pk_add_f32 v[172:173], v[172:173], v[52:53]
	v_pk_add_f32 v[174:175], v[174:175], v[54:55]
	s_waitcnt vmcnt(8)
	v_pk_add_f32 v[160:161], v[160:161], v[56:57]
	v_pk_add_f32 v[162:163], v[162:163], v[58:59]
	v_pk_add_f32 v[164:165], v[164:165], v[60:61]
	v_pk_add_f32 v[166:167], v[166:167], v[62:63]
	v_pk_add_f32 v[168:169], v[168:169], v[64:65]
	v_pk_add_f32 v[170:171], v[170:171], v[66:67]
	v_pk_add_f32 v[172:173], v[172:173], v[68:69]
	v_pk_add_f32 v[174:175], v[174:175], v[70:71]
	s_waitcnt vmcnt(4)
	v_pk_add_f32 v[160:161], v[160:161], v[72:73]
	v_pk_add_f32 v[162:163], v[162:163], v[74:75]
	v_pk_add_f32 v[164:165], v[164:165], v[76:77]
	v_pk_add_f32 v[166:167], v[166:167], v[78:79]
	v_pk_add_f32 v[168:169], v[168:169], v[80:81]
	v_pk_add_f32 v[170:171], v[170:171], v[82:83]
	v_pk_add_f32 v[172:173], v[172:173], v[84:85]
	v_pk_add_f32 v[174:175], v[174:175], v[86:87]
	s_waitcnt vmcnt(0)
	v_pk_add_f32 v[160:161], v[160:161], v[88:89]
	v_pk_add_f32 v[162:163], v[162:163], v[90:91]
	v_pk_add_f32 v[164:165], v[164:165], v[92:93]
	v_pk_add_f32 v[166:167], v[166:167], v[94:95]
	v_pk_add_f32 v[168:169], v[168:169], v[96:97]
	v_pk_add_f32 v[170:171], v[170:171], v[98:99]
	v_pk_add_f32 v[172:173], v[172:173], v[100:101]
	v_pk_add_f32 v[174:175], v[174:175], v[102:103]
	v_lshlrev_b32_e32 v144, 16, v0
	v_and_b32_e32 v145, 0xffff0000, v0
	v_lshlrev_b32_e32 v146, 16, v1
	v_and_b32_e32 v147, 0xffff0000, v1
	v_lshlrev_b32_e32 v148, 16, v2
	v_and_b32_e32 v149, 0xffff0000, v2
	v_lshlrev_b32_e32 v150, 16, v3
	v_and_b32_e32 v151, 0xffff0000, v3
	v_lshlrev_b32_e32 v152, 16, v4
	v_and_b32_e32 v153, 0xffff0000, v4
	v_lshlrev_b32_e32 v154, 16, v5
	v_and_b32_e32 v155, 0xffff0000, v5
	v_lshlrev_b32_e32 v156, 16, v6
	v_and_b32_e32 v157, 0xffff0000, v6
	v_lshlrev_b32_e32 v158, 16, v7
	v_and_b32_e32 v159, 0xffff0000, v7
	v_add_u32_e32 v181, 0xc00000, v183
	global_load_dwordx4 v[8:11], v181, s[78:79]
	global_load_dwordx4 v[12:15], v181, s[78:79] offset:16
	global_load_dwordx4 v[16:19], v181, s[78:79] offset:2048
	global_load_dwordx4 v[20:23], v181, s[78:79] offset:2064
	v_add_u32_e32 v181, 0xe00000, v183
	global_load_dwordx4 v[24:27], v181, s[78:79]
	global_load_dwordx4 v[28:31], v181, s[78:79] offset:16
	global_load_dwordx4 v[32:35], v181, s[78:79] offset:2048
	global_load_dwordx4 v[36:39], v181, s[78:79] offset:2064
	s_waitcnt vmcnt(4)
	v_pk_add_f32 v[160:161], v[160:161], v[8:9]
	v_pk_add_f32 v[162:163], v[162:163], v[10:11]
	v_pk_add_f32 v[164:165], v[164:165], v[12:13]
	v_pk_add_f32 v[166:167], v[166:167], v[14:15]
	v_pk_add_f32 v[168:169], v[168:169], v[16:17]
	v_pk_add_f32 v[170:171], v[170:171], v[18:19]
	v_pk_add_f32 v[172:173], v[172:173], v[20:21]
	v_pk_add_f32 v[174:175], v[174:175], v[22:23]
	s_waitcnt vmcnt(0)
	v_pk_add_f32 v[160:161], v[160:161], v[24:25]
	v_pk_add_f32 v[162:163], v[162:163], v[26:27]
	v_pk_add_f32 v[164:165], v[164:165], v[28:29]
	v_pk_add_f32 v[166:167], v[166:167], v[30:31]
	v_pk_add_f32 v[168:169], v[168:169], v[32:33]
	v_pk_add_f32 v[170:171], v[170:171], v[34:35]
	v_pk_add_f32 v[172:173], v[172:173], v[36:37]
	v_pk_add_f32 v[174:175], v[174:175], v[38:39]
	v_pk_mul_f32 v[252:253], v[160:161], v[160:161]
	v_pk_mul_f32 v[254:255], v[162:163], v[162:163]
	v_pk_fma_f32 v[252:253], v[164:165], v[164:165], v[252:253]
	v_pk_fma_f32 v[254:255], v[166:167], v[166:167], v[254:255]
	v_pk_fma_f32 v[252:253], v[168:169], v[168:169], v[252:253]
	v_pk_fma_f32 v[254:255], v[170:171], v[170:171], v[254:255]
	v_pk_fma_f32 v[252:253], v[172:173], v[172:173], v[252:253]
	v_pk_fma_f32 v[254:255], v[174:175], v[174:175], v[254:255]
	v_pk_add_f32 v[252:253], v[252:253], v[254:255]
	s_nop 0
	v_add_f32_e32 v183, v252, v253
	s_nop 1
	v_add_f32_dpp v183, v183, v183 quad_perm:[1,0,3,2] row_mask:0xf bank_mask:0xf bound_ctrl:1
	s_nop 1
	v_add_f32_dpp v183, v183, v183 quad_perm:[2,3,0,1] row_mask:0xf bank_mask:0xf bound_ctrl:1
	s_nop 1
	v_add_f32_dpp v183, v183, v183 row_half_mirror row_mask:0xf bank_mask:0xf bound_ctrl:1
	s_nop 1
	v_add_f32_dpp v183, v183, v183 row_mirror row_mask:0xf bank_mask:0xf bound_ctrl:1
	s_nop 1
	v_readlane_b32 s98, v183, 0
	v_readlane_b32 s99, v183, 16
	v_readlane_b32 s100, v183, 32
	v_readlane_b32 s101, v183, 48
	s_nop 1
	v_mov_b32_e32 v183, s98
	v_add_f32_e32 v183, s99, v183
	v_add_f32_e32 v183, s100, v183
	v_add_f32_e32 v183, s101, v183
	v_fmamk_f32 v183, v183, 0x3a800000, v182
	v_cmp_gt_f32_e32 vcc, 0x800000, v183
	v_mul_f32_e32 v181, 0x4b800000, v183
	s_nop 1
	v_cndmask_b32_e32 v183, v183, v181, vcc
	v_rsq_f32_e32 v183, v183
	s_nop 0
	v_mul_f32_e32 v181, 0x45800000, v183
	v_cndmask_b32_e32 v184, v183, v181, vcc
	v_mov_b32_e32 v185, v184
	v_pk_mul_f32 v[160:161], v[160:161], v[184:185]
	v_pk_mul_f32 v[162:163], v[162:163], v[184:185]
	v_pk_mul_f32 v[164:165], v[164:165], v[184:185]
	v_pk_mul_f32 v[166:167], v[166:167], v[184:185]
	v_pk_mul_f32 v[168:169], v[168:169], v[184:185]
	v_pk_mul_f32 v[170:171], v[170:171], v[184:185]
	v_pk_mul_f32 v[172:173], v[172:173], v[184:185]
	v_pk_mul_f32 v[174:175], v[174:175], v[184:185]
	v_pk_fma_f32 v[144:145], v[160:161], v[128:129], v[144:145]
	v_pk_fma_f32 v[146:147], v[162:163], v[130:131], v[146:147]
	v_pk_fma_f32 v[148:149], v[164:165], v[132:133], v[148:149]
	v_pk_fma_f32 v[150:151], v[166:167], v[134:135], v[150:151]
	v_pk_fma_f32 v[152:153], v[168:169], v[136:137], v[152:153]
	v_pk_fma_f32 v[154:155], v[170:171], v[138:139], v[154:155]
	v_pk_fma_f32 v[156:157], v[172:173], v[140:141], v[156:157]
	v_pk_fma_f32 v[158:159], v[174:175], v[142:143], v[158:159]
	v_pk_mul_f32 v[252:253], v[144:145], v[144:145]
	v_pk_mul_f32 v[254:255], v[146:147], v[146:147]
	v_pk_fma_f32 v[252:253], v[148:149], v[148:149], v[252:253]
	v_pk_fma_f32 v[254:255], v[150:151], v[150:151], v[254:255]
	v_pk_fma_f32 v[252:253], v[152:153], v[152:153], v[252:253]
	v_pk_fma_f32 v[254:255], v[154:155], v[154:155], v[254:255]
	v_pk_fma_f32 v[252:253], v[156:157], v[156:157], v[252:253]
	v_pk_fma_f32 v[254:255], v[158:159], v[158:159], v[254:255]
	v_pk_add_f32 v[252:253], v[252:253], v[254:255]
	s_nop 0
	v_add_f32_e32 v183, v252, v253
	s_nop 1
	v_add_f32_dpp v183, v183, v183 quad_perm:[1,0,3,2] row_mask:0xf bank_mask:0xf bound_ctrl:1
	s_nop 1
	v_add_f32_dpp v183, v183, v183 quad_perm:[2,3,0,1] row_mask:0xf bank_mask:0xf bound_ctrl:1
	s_nop 1
	v_add_f32_dpp v183, v183, v183 row_half_mirror row_mask:0xf bank_mask:0xf bound_ctrl:1
	s_nop 1
	v_add_f32_dpp v183, v183, v183 row_mirror row_mask:0xf bank_mask:0xf bound_ctrl:1
	s_nop 1
	v_readlane_b32 s98, v183, 0
	v_readlane_b32 s99, v183, 16
	v_readlane_b32 s100, v183, 32
	v_readlane_b32 s101, v183, 48
	s_nop 1
	v_mov_b32_e32 v183, s98
	v_add_f32_e32 v183, s99, v183
	v_add_f32_e32 v183, s100, v183
	v_add_f32_e32 v183, s101, v183
	v_fmamk_f32 v183, v183, 0x3a800000, v182
	v_cmp_gt_f32_e32 vcc, 0x800000, v183
	v_mul_f32_e32 v181, 0x4b800000, v183
	s_nop 1
	v_cndmask_b32_e32 v183, v183, v181, vcc
	v_rsq_f32_e32 v183, v183
	s_nop 0
	v_mul_f32_e32 v181, 0x45800000, v183
	v_cndmask_b32_e32 v184, v183, v181, vcc
	v_mov_b32_e32 v185, v184
	v_cvt_pk_bf16_f32 v0, v144, v145
	v_cvt_pk_bf16_f32 v1, v146, v147
	v_cvt_pk_bf16_f32 v2, v148, v149
	v_cvt_pk_bf16_f32 v3, v150, v151
	v_cvt_pk_bf16_f32 v4, v152, v153
	v_cvt_pk_bf16_f32 v5, v154, v155
	v_cvt_pk_bf16_f32 v6, v156, v157
	v_cvt_pk_bf16_f32 v7, v158, v159
	v_add_u32_e32 v181, 0x3800000, v177
	global_store_dwordx4 v181, v[0:3], s[78:79]
	global_store_dwordx4 v181, v[4:7], s[78:79] offset:1024
	v_add_u32_e32 v236, 0x10000, v237
	s_mov_b64 exec, 1
	global_store_dword v236, v184, s[78:79]
	s_mov_b64 exec, -1

.LBB0_2849:
	v_readlane_b32 s0, v235, 52
	v_readlane_b32 s1, v235, 53
	s_and_b64 vcc, exec, s[0:1]
	s_waitcnt lgkmcnt(0)
	s_barrier
	v_mbcnt_lo_u32_b32 v0, -1, 0
	v_mbcnt_hi_u32_b32 v0, -1, v0
	s_cbranch_vccnz .LBB0_2864
	v_lshlrev_b32_e32 v0, 3, v0
	v_ashrrev_i32_e32 v1, 31, v0
	v_readlane_b32 s0, v235, 4
	v_lshlrev_b64 v[2:3], 1, v[0:1]
	v_lshlrev_b64 v[0:1], 2, v[0:1]
	v_readlane_b32 s1, v235, 5
	v_readlane_b32 s14, v235, 18
	v_readlane_b32 s15, v235, 19
	s_mov_b64 s[0:1], 0x3000
	v_readlane_b32 s2, v235, 6
	v_lshl_add_u64 v[4:5], s[14:15], 0, v[0:1]
	v_readlane_b32 s4, v235, 8
	v_readlane_b32 s5, v235, 9
	v_lshl_add_u64 v[50:51], v[4:5], 0, s[0:1]
	v_readlane_b32 s0, v235, 0
	s_ashr_i32 s25, s24, 31
	s_lshl_b32 s0, s0, 4
	s_add_i32 s2, s24, 0xffffc000
	s_lshl_b64 s[4:5], s[24:25], 11
	s_add_u32 s4, s78, s4
	v_readlane_b32 s1, v235, 1
	s_addc_u32 s5, s79, s5
	v_lshl_add_u64 v[44:45], s[86:87], 0, v[2:3]
	v_lshl_add_u64 v[48:49], s[54:55], 0, v[2:3]
	v_readlane_b32 s6, v235, 10
	v_readlane_b32 s7, v235, 11
	v_lshl_add_u64 v[2:3], s[4:5], 0, v[2:3]
	s_mov_b64 s[4:5], 0x9e00000
	s_ashr_i32 s1, s0, 31
	v_lshl_add_u64 v[56:57], v[2:3], 0, s[4:5]
	s_lshl_b64 s[4:5], s[0:1], 11
	s_lshl_b64 s[6:7], s[24:25], 12
	s_add_u32 s6, s76, s6
	s_addc_u32 s7, s77, s7
	v_lshl_add_u64 v[46:47], s[90:91], 0, v[0:1]
	v_readlane_b32 s3, v235, 7
	v_readlane_b32 s8, v235, 12
	v_readlane_b32 s9, v235, 13
	v_readlane_b32 s10, v235, 14
	v_readlane_b32 s11, v235, 15
	v_readlane_b32 s12, v235, 16
	v_readlane_b32 s13, v235, 17
	v_lshl_add_u64 v[52:53], s[74:75], 0, v[0:1]
	v_lshl_add_u64 v[54:55], s[76:77], 0, v[0:1]
	v_lshl_add_u64 v[0:1], s[6:7], 0, v[0:1]
	s_mov_b64 s[6:7], 0x810
	v_lshl_add_u64 v[58:59], v[0:1], 0, s[6:7]
	s_lshl_b64 s[6:7], s[0:1], 12
	s_mov_b32 s3, 0
	s_mov_b64 s[8:9], 0x200000
	s_mov_b64 s[10:11], 0x200800
	s_mov_b64 s[12:13], 0x400000
	s_mov_b64 s[14:15], 0x400800
	s_mov_b64 s[16:17], 0x600000
	s_mov_b64 s[18:19], 0x600800
	s_mov_b64 s[20:21], 0x800000
	s_mov_b32 s1, 0x800000
	s_mov_b64 s[22:23], 0x800800
	s_mov_b64 s[24:25], 0xa00000
	s_mov_b64 s[26:27], 0xa00800
	s_mov_b64 s[28:29], 0xc00000
	s_mov_b64 s[30:31], 0xc00800
	s_mov_b64 s[34:35], 0xe00000
	s_mov_b64 s[36:37], 0xe00800
	s_mov_b64 s[38:39], 0x1000000
	s_mov_b32 s60, 0x1000000
	s_mov_b64 s[40:41], 0x1000800
	s_mov_b64 s[42:43], 0x1200000
	s_mov_b32 s61, 0x1200000
	s_mov_b64 s[44:45], 0x1200800
	s_mov_b64 s[46:47], 0x1400000
	s_mov_b32 s62, 0x1400000
	s_mov_b64 s[48:49], 0x1400800
	v_mov_b32_e32 v100, 0x358637bd
	v_mbcnt_lo_u32_b32 v176, -1, 0
	v_mbcnt_hi_u32_b32 v176, -1, v176
	v_readlane_b32 s98, v235, 49
	v_readlane_b32 s99, v235, 20
	v_readlane_b32 s100, v235, 18
	v_readlane_b32 s101, v235, 19
	s_nop 3
	s_lshr_b32 vcc_lo, s98, 3
	s_and_b32 vcc_hi, vcc_lo, 7
	s_lshl_b32 vcc_hi, vcc_hi, 8
	s_lshr_b32 vcc_lo, vcc_lo, 3
	s_lshl_b32 vcc_lo, vcc_lo, 3
	s_add_i32 s98, vcc_hi, vcc_lo
	s_add_i32 s98, s98, s99
	v_lshlrev_b32_e32 v177, 4, v176
	s_lshl_b32 s99, s98, 11
	v_add_u32_e32 v177, s99, v177
	v_add_u32_e32 v178, 0x1800000, v177
	v_add_u32_e32 v179, 0x9e00000, v177
	v_lshlrev_b32_e32 v180, 5, v176
	v_add_u32_e32 v181, 0x3000, v180
	global_load_dwordx4 v[128:131], v181, s[100:101]
	global_load_dwordx4 v[132:135], v181, s[100:101] offset:16
	global_load_dwordx4 v[136:139], v181, s[100:101] offset:2048
	global_load_dwordx4 v[140:143], v181, s[100:101] offset:2064
	global_load_dwordx4 v[236:239], v180, s[74:75]
	global_load_dwordx4 v[240:243], v180, s[74:75] offset:16
	global_load_dwordx4 v[244:247], v180, s[74:75] offset:2048
	global_load_dwordx4 v[248:251], v180, s[74:75] offset:2064
	v_mov_b32_e32 v182, 0x358637bd
	global_load_dwordx4 v[0:3], v178, s[78:79]
	global_load_dwordx4 v[4:7], v178, s[78:79] offset:1024
	global_load_dwordx4 v[8:11], v179, s[78:79]
	global_load_dwordx4 v[12:15], v179, s[78:79] offset:1024
	v_add_u32_e32 v178, 0x400000, v178
	v_add_u32_e32 v179, 0x400000, v179
	global_load_dwordx4 v[16:19], v178, s[78:79]
	global_load_dwordx4 v[20:23], v178, s[78:79] offset:1024
	global_load_dwordx4 v[24:27], v179, s[78:79]
	global_load_dwordx4 v[28:31], v179, s[78:79] offset:1024
	v_add_u32_e32 v178, 0x400000, v178
	v_add_u32_e32 v179, 0x400000, v179
	global_load_dwordx4 v[32:35], v178, s[78:79]
	global_load_dwordx4 v[36:39], v178, s[78:79] offset:1024
	global_load_dwordx4 v[40:43], v179, s[78:79]
	global_load_dwordx4 v[44:47], v179, s[78:79] offset:1024
	v_add_u32_e32 v178, 0x400000, v178
	v_add_u32_e32 v179, 0x400000, v179
	global_load_dwordx4 v[48:51], v178, s[78:79]
	global_load_dwordx4 v[52:55], v178, s[78:79] offset:1024
	global_load_dwordx4 v[56:59], v179, s[78:79]
	global_load_dwordx4 v[60:63], v179, s[78:79] offset:1024
	v_add_u32_e32 v178, 0x400000, v178
	v_add_u32_e32 v179, 0x400000, v179
	global_load_dwordx4 v[64:67], v178, s[78:79]
	global_load_dwordx4 v[68:71], v178, s[78:79] offset:1024
	global_load_dwordx4 v[72:75], v179, s[78:79]
	global_load_dwordx4 v[76:79], v179, s[78:79] offset:1024
	v_add_u32_e32 v178, 0x400000, v178
	v_add_u32_e32 v179, 0x400000, v179
	global_load_dwordx4 v[80:83], v178, s[78:79]
	global_load_dwordx4 v[84:87], v178, s[78:79] offset:1024
	global_load_dwordx4 v[88:91], v179, s[78:79]
	global_load_dwordx4 v[92:95], v179, s[78:79] offset:1024
	v_add_u32_e32 v178, 0x400000, v178
	v_add_u32_e32 v179, 0x400000, v179
	global_load_dwordx4 v[96:99], v178, s[78:79]
	global_load_dwordx4 v[100:103], v178, s[78:79] offset:1024
	global_load_dwordx4 v[104:107], v179, s[78:79]
	global_load_dwordx4 v[108:111], v179, s[78:79] offset:1024
	v_add_u32_e32 v178, 0x400000, v178
	v_add_u32_e32 v179, 0x400000, v179
	global_load_dwordx4 v[112:115], v178, s[78:79]
	global_load_dwordx4 v[116:119], v178, s[78:79] offset:1024
	global_load_dwordx4 v[120:123], v179, s[78:79]
	global_load_dwordx4 v[124:127], v179, s[78:79] offset:1024
	v_mov_b32_e32 v183, s98
	v_lshl_add_u32 v178, v183, 12, v180
	v_mov_b32_e32 v179, v183
	s_waitcnt vmcnt(28)
	v_lshlrev_b32_e32 v144, 16, v0
	v_and_b32_e32 v145, 0xffff0000, v0
	v_lshlrev_b32_e32 v146, 16, v1
	v_and_b32_e32 v147, 0xffff0000, v1
	v_lshlrev_b32_e32 v148, 16, v2
	v_and_b32_e32 v149, 0xffff0000, v2
	v_lshlrev_b32_e32 v150, 16, v3
	v_and_b32_e32 v151, 0xffff0000, v3
	v_lshlrev_b32_e32 v152, 16, v4
	v_and_b32_e32 v153, 0xffff0000, v4
	v_lshlrev_b32_e32 v154, 16, v5
	v_and_b32_e32 v155, 0xffff0000, v5
	v_lshlrev_b32_e32 v156, 16, v6
	v_and_b32_e32 v157, 0xffff0000, v6
	v_lshlrev_b32_e32 v158, 16, v7
	v_and_b32_e32 v159, 0xffff0000, v7
	v_lshlrev_b32_e32 v160, 16, v8
	v_and_b32_e32 v161, 0xffff0000, v8
	v_lshlrev_b32_e32 v162, 16, v9
	v_and_b32_e32 v163, 0xffff0000, v9
	v_lshlrev_b32_e32 v164, 16, v10
	v_and_b32_e32 v165, 0xffff0000, v10
	v_lshlrev_b32_e32 v166, 16, v11
	v_and_b32_e32 v167, 0xffff0000, v11
	v_lshlrev_b32_e32 v168, 16, v12
	v_and_b32_e32 v169, 0xffff0000, v12
	v_lshlrev_b32_e32 v170, 16, v13
	v_and_b32_e32 v171, 0xffff0000, v13
	v_lshlrev_b32_e32 v172, 16, v14
	v_and_b32_e32 v173, 0xffff0000, v14
	v_lshlrev_b32_e32 v174, 16, v15
	v_and_b32_e32 v175, 0xffff0000, v15
	v_pk_mul_f32 v[252:253], v[160:161], v[160:161]
	v_pk_mul_f32 v[254:255], v[162:163], v[162:163]
	v_pk_fma_f32 v[252:253], v[164:165], v[164:165], v[252:253]
	v_pk_fma_f32 v[254:255], v[166:167], v[166:167], v[254:255]
	v_pk_fma_f32 v[252:253], v[168:169], v[168:169], v[252:253]
	v_pk_fma_f32 v[254:255], v[170:171], v[170:171], v[254:255]
	v_pk_fma_f32 v[252:253], v[172:173], v[172:173], v[252:253]
	v_pk_fma_f32 v[254:255], v[174:175], v[174:175], v[254:255]
	v_pk_add_f32 v[252:253], v[252:253], v[254:255]
	s_nop 0
	v_add_f32_e32 v183, v252, v253
	s_nop 1
	v_add_f32_dpp v183, v183, v183 quad_perm:[1,0,3,2] row_mask:0xf bank_mask:0xf bound_ctrl:1
	s_nop 1
	v_add_f32_dpp v183, v183, v183 quad_perm:[2,3,0,1] row_mask:0xf bank_mask:0xf bound_ctrl:1
	s_nop 1
	v_add_f32_dpp v183, v183, v183 row_half_mirror row_mask:0xf bank_mask:0xf bound_ctrl:1
	s_nop 1
	v_add_f32_dpp v183, v183, v183 row_mirror row_mask:0xf bank_mask:0xf bound_ctrl:1
	s_nop 1
	v_readlane_b32 s98, v183, 0
	v_readlane_b32 s99, v183, 16
	v_readlane_b32 s100, v183, 32
	v_readlane_b32 s101, v183, 48
	s_nop 1
	v_mov_b32_e32 v183, s98
	v_add_f32_e32 v183, s99, v183
	v_add_f32_e32 v183, s100, v183
	v_add_f32_e32 v183, s101, v183
	v_fmamk_f32 v183, v183, 0x3a800000, v182
	v_cmp_gt_f32_e32 vcc, 0x800000, v183
	v_mul_f32_e32 v181, 0x4b800000, v183
	s_nop 1
	v_cndmask_b32_e32 v183, v183, v181, vcc
	v_rsq_f32_e32 v183, v183
	s_nop 0
	v_mul_f32_e32 v181, 0x45800000, v183
	v_cndmask_b32_e32 v184, v183, v181, vcc
	v_mov_b32_e32 v185, v184
	v_pk_mul_f32 v[160:161], v[160:161], v[184:185]
	v_pk_mul_f32 v[162:163], v[162:163], v[184:185]
	v_pk_mul_f32 v[164:165], v[164:165], v[184:185]
	v_pk_mul_f32 v[166:167], v[166:167], v[184:185]
	v_pk_mul_f32 v[168:169], v[168:169], v[184:185]
	v_pk_mul_f32 v[170:171], v[170:171], v[184:185]
	v_pk_mul_f32 v[172:173], v[172:173], v[184:185]
	v_pk_mul_f32 v[174:175], v[174:175], v[184:185]
	v_pk_fma_f32 v[144:145], v[160:161], v[128:129], v[144:145]
	v_pk_fma_f32 v[146:147], v[162:163], v[130:131], v[146:147]
	v_pk_fma_f32 v[148:149], v[164:165], v[132:133], v[148:149]
	v_pk_fma_f32 v[150:151], v[166:167], v[134:135], v[150:151]
	v_pk_fma_f32 v[152:153], v[168:169], v[136:137], v[152:153]
	v_pk_fma_f32 v[154:155], v[170:171], v[138:139], v[154:155]
	v_pk_fma_f32 v[156:157], v[172:173], v[140:141], v[156:157]
	v_pk_fma_f32 v[158:159], v[174:175], v[142:143], v[158:159]
	v_pk_mul_f32 v[252:253], v[144:145], v[144:145]
	v_pk_mul_f32 v[254:255], v[146:147], v[146:147]
	v_pk_fma_f32 v[252:253], v[148:149], v[148:149], v[252:253]
	v_pk_fma_f32 v[254:255], v[150:151], v[150:151], v[254:255]
	v_pk_fma_f32 v[252:253], v[152:153], v[152:153], v[252:253]
	v_pk_fma_f32 v[254:255], v[154:155], v[154:155], v[254:255]
	v_pk_fma_f32 v[252:253], v[156:157], v[156:157], v[252:253]
	v_pk_fma_f32 v[254:255], v[158:159], v[158:159], v[254:255]
	v_pk_add_f32 v[252:253], v[252:253], v[254:255]
	s_nop 0
	v_add_f32_e32 v183, v252, v253
	s_nop 1
	v_add_f32_dpp v183, v183, v183 quad_perm:[1,0,3,2] row_mask:0xf bank_mask:0xf bound_ctrl:1
	s_nop 1
	v_add_f32_dpp v183, v183, v183 quad_perm:[2,3,0,1] row_mask:0xf bank_mask:0xf bound_ctrl:1
	s_nop 1
	v_add_f32_dpp v183, v183, v183 row_half_mirror row_mask:0xf bank_mask:0xf bound_ctrl:1
	s_nop 1
	v_add_f32_dpp v183, v183, v183 row_mirror row_mask:0xf bank_mask:0xf bound_ctrl:1
	s_nop 1
	v_readlane_b32 s98, v183, 0
	v_readlane_b32 s99, v183, 16
	v_readlane_b32 s100, v183, 32
	v_readlane_b32 s101, v183, 48
	s_nop 1
	v_mov_b32_e32 v183, s98
	v_add_f32_e32 v183, s99, v183
	v_add_f32_e32 v183, s100, v183
	v_add_f32_e32 v183, s101, v183
	v_fmamk_f32 v183, v183, 0x3a800000, v182
	v_cmp_gt_f32_e32 vcc, 0x800000, v183
	v_mul_f32_e32 v181, 0x4b800000, v183
	s_nop 1
	v_cndmask_b32_e32 v183, v183, v181, vcc
	v_rsq_f32_e32 v183, v183
	s_nop 0
	v_mul_f32_e32 v181, 0x45800000, v183
	v_cndmask_b32_e32 v184, v183, v181, vcc
	v_mov_b32_e32 v185, v184
	v_pk_mul_f32 v[144:145], v[144:145], v[184:185]
	v_pk_mul_f32 v[146:147], v[146:147], v[184:185]
	v_pk_mul_f32 v[148:149], v[148:149], v[184:185]
	v_pk_mul_f32 v[150:151], v[150:151], v[184:185]
	v_pk_mul_f32 v[152:153], v[152:153], v[184:185]
	v_pk_mul_f32 v[154:155], v[154:155], v[184:185]
	v_pk_mul_f32 v[156:157], v[156:157], v[184:185]
	v_pk_mul_f32 v[158:159], v[158:159], v[184:185]
	v_pk_mul_f32 v[144:145], v[144:145], v[236:237]
	v_pk_mul_f32 v[146:147], v[146:147], v[238:239]
	v_pk_mul_f32 v[148:149], v[148:149], v[240:241]
	v_pk_mul_f32 v[150:151], v[150:151], v[242:243]
	v_pk_mul_f32 v[152:153], v[152:153], v[244:245]
	v_pk_mul_f32 v[154:155], v[154:155], v[246:247]
	v_pk_mul_f32 v[156:157], v[156:157], v[248:249]
	v_pk_mul_f32 v[158:159], v[158:159], v[250:251]
	v_add_u32_e32 v181, 0x0, v178
	global_store_dwordx4 v181, v[144:147], s[76:77]
	global_store_dwordx4 v181, v[148:151], s[76:77] offset:16
	global_store_dwordx4 v181, v[152:155], s[76:77] offset:2048
	global_store_dwordx4 v181, v[156:159], s[76:77] offset:2064
	s_nop 1
	s_waitcnt vmcnt(24)
	v_lshlrev_b32_e32 v144, 16, v16
	v_and_b32_e32 v145, 0xffff0000, v16
	v_lshlrev_b32_e32 v146, 16, v17
	v_and_b32_e32 v147, 0xffff0000, v17
	v_lshlrev_b32_e32 v148, 16, v18
	v_and_b32_e32 v149, 0xffff0000, v18
	v_lshlrev_b32_e32 v150, 16, v19
	v_and_b32_e32 v151, 0xffff0000, v19
	v_lshlrev_b32_e32 v152, 16, v20
	v_and_b32_e32 v153, 0xffff0000, v20
	v_lshlrev_b32_e32 v154, 16, v21
	v_and_b32_e32 v155, 0xffff0000, v21
	v_lshlrev_b32_e32 v156, 16, v22
	v_and_b32_e32 v157, 0xffff0000, v22
	v_lshlrev_b32_e32 v158, 16, v23
	v_and_b32_e32 v159, 0xffff0000, v23
	v_lshlrev_b32_e32 v160, 16, v24
	v_and_b32_e32 v161, 0xffff0000, v24
	v_lshlrev_b32_e32 v162, 16, v25
	v_and_b32_e32 v163, 0xffff0000, v25
	v_lshlrev_b32_e32 v164, 16, v26
	v_and_b32_e32 v165, 0xffff0000, v26
	v_lshlrev_b32_e32 v166, 16, v27
	v_and_b32_e32 v167, 0xffff0000, v27
	v_lshlrev_b32_e32 v168, 16, v28
	v_and_b32_e32 v169, 0xffff0000, v28
	v_lshlrev_b32_e32 v170, 16, v29
	v_and_b32_e32 v171, 0xffff0000, v29
	v_lshlrev_b32_e32 v172, 16, v30
	v_and_b32_e32 v173, 0xffff0000, v30
	v_lshlrev_b32_e32 v174, 16, v31
	v_and_b32_e32 v175, 0xffff0000, v31
	v_pk_mul_f32 v[252:253], v[160:161], v[160:161]
	v_pk_mul_f32 v[254:255], v[162:163], v[162:163]
	v_pk_fma_f32 v[252:253], v[164:165], v[164:165], v[252:253]
	v_pk_fma_f32 v[254:255], v[166:167], v[166:167], v[254:255]
	v_pk_fma_f32 v[252:253], v[168:169], v[168:169], v[252:253]
	v_pk_fma_f32 v[254:255], v[170:171], v[170:171], v[254:255]
	v_pk_fma_f32 v[252:253], v[172:173], v[172:173], v[252:253]
	v_pk_fma_f32 v[254:255], v[174:175], v[174:175], v[254:255]
	v_pk_add_f32 v[252:253], v[252:253], v[254:255]
	s_nop 0
	v_add_f32_e32 v183, v252, v253
	s_nop 1
	v_add_f32_dpp v183, v183, v183 quad_perm:[1,0,3,2] row_mask:0xf bank_mask:0xf bound_ctrl:1
	s_nop 1
	v_add_f32_dpp v183, v183, v183 quad_perm:[2,3,0,1] row_mask:0xf bank_mask:0xf bound_ctrl:1
	s_nop 1
	v_add_f32_dpp v183, v183, v183 row_half_mirror row_mask:0xf bank_mask:0xf bound_ctrl:1
	s_nop 1
	v_add_f32_dpp v183, v183, v183 row_mirror row_mask:0xf bank_mask:0xf bound_ctrl:1
	s_nop 1
	v_readlane_b32 s98, v183, 0
	v_readlane_b32 s99, v183, 16
	v_readlane_b32 s100, v183, 32
	v_readlane_b32 s101, v183, 48
	s_nop 1
	v_mov_b32_e32 v183, s98
	v_add_f32_e32 v183, s99, v183
	v_add_f32_e32 v183, s100, v183
	v_add_f32_e32 v183, s101, v183
	v_fmamk_f32 v183, v183, 0x3a800000, v182
	v_cmp_gt_f32_e32 vcc, 0x800000, v183
	v_mul_f32_e32 v181, 0x4b800000, v183
	s_nop 1
	v_cndmask_b32_e32 v183, v183, v181, vcc
	v_rsq_f32_e32 v183, v183
	s_nop 0
	v_mul_f32_e32 v181, 0x45800000, v183
	v_cndmask_b32_e32 v184, v183, v181, vcc
	v_mov_b32_e32 v185, v184
	v_pk_mul_f32 v[160:161], v[160:161], v[184:185]
	v_pk_mul_f32 v[162:163], v[162:163], v[184:185]
	v_pk_mul_f32 v[164:165], v[164:165], v[184:185]
	v_pk_mul_f32 v[166:167], v[166:167], v[184:185]
	v_pk_mul_f32 v[168:169], v[168:169], v[184:185]
	v_pk_mul_f32 v[170:171], v[170:171], v[184:185]
	v_pk_mul_f32 v[172:173], v[172:173], v[184:185]
	v_pk_mul_f32 v[174:175], v[174:175], v[184:185]
	v_pk_fma_f32 v[144:145], v[160:161], v[128:129], v[144:145]
	v_pk_fma_f32 v[146:147], v[162:163], v[130:131], v[146:147]
	v_pk_fma_f32 v[148:149], v[164:165], v[132:133], v[148:149]
	v_pk_fma_f32 v[150:151], v[166:167], v[134:135], v[150:151]
	v_pk_fma_f32 v[152:153], v[168:169], v[136:137], v[152:153]
	v_pk_fma_f32 v[154:155], v[170:171], v[138:139], v[154:155]
	v_pk_fma_f32 v[156:157], v[172:173], v[140:141], v[156:157]
	v_pk_fma_f32 v[158:159], v[174:175], v[142:143], v[158:159]
	v_pk_mul_f32 v[252:253], v[144:145], v[144:145]
	v_pk_mul_f32 v[254:255], v[146:147], v[146:147]
	v_pk_fma_f32 v[252:253], v[148:149], v[148:149], v[252:253]
	v_pk_fma_f32 v[254:255], v[150:151], v[150:151], v[254:255]
	v_pk_fma_f32 v[252:253], v[152:153], v[152:153], v[252:253]
	v_pk_fma_f32 v[254:255], v[154:155], v[154:155], v[254:255]
	v_pk_fma_f32 v[252:253], v[156:157], v[156:157], v[252:253]
	v_pk_fma_f32 v[254:255], v[158:159], v[158:159], v[254:255]
	v_pk_add_f32 v[252:253], v[252:253], v[254:255]
	s_nop 0
	v_add_f32_e32 v183, v252, v253
	s_nop 1
	v_add_f32_dpp v183, v183, v183 quad_perm:[1,0,3,2] row_mask:0xf bank_mask:0xf bound_ctrl:1
	s_nop 1
	v_add_f32_dpp v183, v183, v183 quad_perm:[2,3,0,1] row_mask:0xf bank_mask:0xf bound_ctrl:1
	s_nop 1
	v_add_f32_dpp v183, v183, v183 row_half_mirror row_mask:0xf bank_mask:0xf bound_ctrl:1
	s_nop 1
	v_add_f32_dpp v183, v183, v183 row_mirror row_mask:0xf bank_mask:0xf bound_ctrl:1
	s_nop 1
	v_readlane_b32 s98, v183, 0
	v_readlane_b32 s99, v183, 16
	v_readlane_b32 s100, v183, 32
	v_readlane_b32 s101, v183, 48
	s_nop 1
	v_mov_b32_e32 v183, s98
	v_add_f32_e32 v183, s99, v183
	v_add_f32_e32 v183, s100, v183
	v_add_f32_e32 v183, s101, v183
	v_fmamk_f32 v183, v183, 0x3a800000, v182
	v_cmp_gt_f32_e32 vcc, 0x800000, v183
	v_mul_f32_e32 v181, 0x4b800000, v183
	s_nop 1
	v_cndmask_b32_e32 v183, v183, v181, vcc
	v_rsq_f32_e32 v183, v183
	s_nop 0
	v_mul_f32_e32 v181, 0x45800000, v183
	v_cndmask_b32_e32 v184, v183, v181, vcc
	v_mov_b32_e32 v185, v184
	v_pk_mul_f32 v[144:145], v[144:145], v[184:185]
	v_pk_mul_f32 v[146:147], v[146:147], v[184:185]
	v_pk_mul_f32 v[148:149], v[148:149], v[184:185]
	v_pk_mul_f32 v[150:151], v[150:151], v[184:185]
	v_pk_mul_f32 v[152:153], v[152:153], v[184:185]
	v_pk_mul_f32 v[154:155], v[154:155], v[184:185]
	v_pk_mul_f32 v[156:157], v[156:157], v[184:185]
	v_pk_mul_f32 v[158:159], v[158:159], v[184:185]
	v_pk_mul_f32 v[144:145], v[144:145], v[236:237]
	v_pk_mul_f32 v[146:147], v[146:147], v[238:239]
	v_pk_mul_f32 v[148:149], v[148:149], v[240:241]
	v_pk_mul_f32 v[150:151], v[150:151], v[242:243]
	v_pk_mul_f32 v[152:153], v[152:153], v[244:245]
	v_pk_mul_f32 v[154:155], v[154:155], v[246:247]
	v_pk_mul_f32 v[156:157], v[156:157], v[248:249]
	v_pk_mul_f32 v[158:159], v[158:159], v[250:251]
	v_add_u32_e32 v181, 0x800000, v178
	global_store_dwordx4 v181, v[144:147], s[76:77]
	global_store_dwordx4 v181, v[148:151], s[76:77] offset:16
	global_store_dwordx4 v181, v[152:155], s[76:77] offset:2048
	global_store_dwordx4 v181, v[156:159], s[76:77] offset:2064
	s_nop 1
	s_waitcnt vmcnt(20)
	v_lshlrev_b32_e32 v144, 16, v32
	v_and_b32_e32 v145, 0xffff0000, v32
	v_lshlrev_b32_e32 v146, 16, v33
	v_and_b32_e32 v147, 0xffff0000, v33
	v_lshlrev_b32_e32 v148, 16, v34
	v_and_b32_e32 v149, 0xffff0000, v34
	v_lshlrev_b32_e32 v150, 16, v35
	v_and_b32_e32 v151, 0xffff0000, v35
	v_lshlrev_b32_e32 v152, 16, v36
	v_and_b32_e32 v153, 0xffff0000, v36
	v_lshlrev_b32_e32 v154, 16, v37
	v_and_b32_e32 v155, 0xffff0000, v37
	v_lshlrev_b32_e32 v156, 16, v38
	v_and_b32_e32 v157, 0xffff0000, v38
	v_lshlrev_b32_e32 v158, 16, v39
	v_and_b32_e32 v159, 0xffff0000, v39
	v_lshlrev_b32_e32 v160, 16, v40
	v_and_b32_e32 v161, 0xffff0000, v40
	v_lshlrev_b32_e32 v162, 16, v41
	v_and_b32_e32 v163, 0xffff0000, v41
	v_lshlrev_b32_e32 v164, 16, v42
	v_and_b32_e32 v165, 0xffff0000, v42
	v_lshlrev_b32_e32 v166, 16, v43
	v_and_b32_e32 v167, 0xffff0000, v43
	v_lshlrev_b32_e32 v168, 16, v44
	v_and_b32_e32 v169, 0xffff0000, v44
	v_lshlrev_b32_e32 v170, 16, v45
	v_and_b32_e32 v171, 0xffff0000, v45
	v_lshlrev_b32_e32 v172, 16, v46
	v_and_b32_e32 v173, 0xffff0000, v46
	v_lshlrev_b32_e32 v174, 16, v47
	v_and_b32_e32 v175, 0xffff0000, v47
	v_pk_mul_f32 v[252:253], v[160:161], v[160:161]
	v_pk_mul_f32 v[254:255], v[162:163], v[162:163]
	v_pk_fma_f32 v[252:253], v[164:165], v[164:165], v[252:253]
	v_pk_fma_f32 v[254:255], v[166:167], v[166:167], v[254:255]
	v_pk_fma_f32 v[252:253], v[168:169], v[168:169], v[252:253]
	v_pk_fma_f32 v[254:255], v[170:171], v[170:171], v[254:255]
	v_pk_fma_f32 v[252:253], v[172:173], v[172:173], v[252:253]
	v_pk_fma_f32 v[254:255], v[174:175], v[174:175], v[254:255]
	v_pk_add_f32 v[252:253], v[252:253], v[254:255]
	s_nop 0
	v_add_f32_e32 v183, v252, v253
	s_nop 1
	v_add_f32_dpp v183, v183, v183 quad_perm:[1,0,3,2] row_mask:0xf bank_mask:0xf bound_ctrl:1
	s_nop 1
	v_add_f32_dpp v183, v183, v183 quad_perm:[2,3,0,1] row_mask:0xf bank_mask:0xf bound_ctrl:1
	s_nop 1
	v_add_f32_dpp v183, v183, v183 row_half_mirror row_mask:0xf bank_mask:0xf bound_ctrl:1
	s_nop 1
	v_add_f32_dpp v183, v183, v183 row_mirror row_mask:0xf bank_mask:0xf bound_ctrl:1
	s_nop 1
	v_readlane_b32 s98, v183, 0
	v_readlane_b32 s99, v183, 16
	v_readlane_b32 s100, v183, 32
	v_readlane_b32 s101, v183, 48
	s_nop 1
	v_mov_b32_e32 v183, s98
	v_add_f32_e32 v183, s99, v183
	v_add_f32_e32 v183, s100, v183
	v_add_f32_e32 v183, s101, v183
	v_fmamk_f32 v183, v183, 0x3a800000, v182
	v_cmp_gt_f32_e32 vcc, 0x800000, v183
	v_mul_f32_e32 v181, 0x4b800000, v183
	s_nop 1
	v_cndmask_b32_e32 v183, v183, v181, vcc
	v_rsq_f32_e32 v183, v183
	s_nop 0
	v_mul_f32_e32 v181, 0x45800000, v183
	v_cndmask_b32_e32 v184, v183, v181, vcc
	v_mov_b32_e32 v185, v184
	v_pk_mul_f32 v[160:161], v[160:161], v[184:185]
	v_pk_mul_f32 v[162:163], v[162:163], v[184:185]
	v_pk_mul_f32 v[164:165], v[164:165], v[184:185]
	v_pk_mul_f32 v[166:167], v[166:167], v[184:185]
	v_pk_mul_f32 v[168:169], v[168:169], v[184:185]
	v_pk_mul_f32 v[170:171], v[170:171], v[184:185]
	v_pk_mul_f32 v[172:173], v[172:173], v[184:185]
	v_pk_mul_f32 v[174:175], v[174:175], v[184:185]
	v_pk_fma_f32 v[144:145], v[160:161], v[128:129], v[144:145]
	v_pk_fma_f32 v[146:147], v[162:163], v[130:131], v[146:147]
	v_pk_fma_f32 v[148:149], v[164:165], v[132:133], v[148:149]
	v_pk_fma_f32 v[150:151], v[166:167], v[134:135], v[150:151]
	v_pk_fma_f32 v[152:153], v[168:169], v[136:137], v[152:153]
	v_pk_fma_f32 v[154:155], v[170:171], v[138:139], v[154:155]
	v_pk_fma_f32 v[156:157], v[172:173], v[140:141], v[156:157]
	v_pk_fma_f32 v[158:159], v[174:175], v[142:143], v[158:159]
	v_pk_mul_f32 v[252:253], v[144:145], v[144:145]
	v_pk_mul_f32 v[254:255], v[146:147], v[146:147]
	v_pk_fma_f32 v[252:253], v[148:149], v[148:149], v[252:253]
	v_pk_fma_f32 v[254:255], v[150:151], v[150:151], v[254:255]
	v_pk_fma_f32 v[252:253], v[152:153], v[152:153], v[252:253]
	v_pk_fma_f32 v[254:255], v[154:155], v[154:155], v[254:255]
	v_pk_fma_f32 v[252:253], v[156:157], v[156:157], v[252:253]
	v_pk_fma_f32 v[254:255], v[158:159], v[158:159], v[254:255]
	v_pk_add_f32 v[252:253], v[252:253], v[254:255]
	s_nop 0
	v_add_f32_e32 v183, v252, v253
	s_nop 1
	v_add_f32_dpp v183, v183, v183 quad_perm:[1,0,3,2] row_mask:0xf bank_mask:0xf bound_ctrl:1
	s_nop 1
	v_add_f32_dpp v183, v183, v183 quad_perm:[2,3,0,1] row_mask:0xf bank_mask:0xf bound_ctrl:1
	s_nop 1
	v_add_f32_dpp v183, v183, v183 row_half_mirror row_mask:0xf bank_mask:0xf bound_ctrl:1
	s_nop 1
	v_add_f32_dpp v183, v183, v183 row_mirror row_mask:0xf bank_mask:0xf bound_ctrl:1
	s_nop 1
	v_readlane_b32 s98, v183, 0
	v_readlane_b32 s99, v183, 16
	v_readlane_b32 s100, v183, 32
	v_readlane_b32 s101, v183, 48
	s_nop 1
	v_mov_b32_e32 v183, s98
	v_add_f32_e32 v183, s99, v183
	v_add_f32_e32 v183, s100, v183
	v_add_f32_e32 v183, s101, v183
	v_fmamk_f32 v183, v183, 0x3a800000, v182
	v_cmp_gt_f32_e32 vcc, 0x800000, v183
	v_mul_f32_e32 v181, 0x4b800000, v183
	s_nop 1
	v_cndmask_b32_e32 v183, v183, v181, vcc
	v_rsq_f32_e32 v183, v183
	s_nop 0
	v_mul_f32_e32 v181, 0x45800000, v183
	v_cndmask_b32_e32 v184, v183, v181, vcc
	v_mov_b32_e32 v185, v184
	v_pk_mul_f32 v[144:145], v[144:145], v[184:185]
	v_pk_mul_f32 v[146:147], v[146:147], v[184:185]
	v_pk_mul_f32 v[148:149], v[148:149], v[184:185]
	v_pk_mul_f32 v[150:151], v[150:151], v[184:185]
	v_pk_mul_f32 v[152:153], v[152:153], v[184:185]
	v_pk_mul_f32 v[154:155], v[154:155], v[184:185]
	v_pk_mul_f32 v[156:157], v[156:157], v[184:185]
	v_pk_mul_f32 v[158:159], v[158:159], v[184:185]
	v_pk_mul_f32 v[144:145], v[144:145], v[236:237]
	v_pk_mul_f32 v[146:147], v[146:147], v[238:239]
	v_pk_mul_f32 v[148:149], v[148:149], v[240:241]
	v_pk_mul_f32 v[150:151], v[150:151], v[242:243]
	v_pk_mul_f32 v[152:153], v[152:153], v[244:245]
	v_pk_mul_f32 v[154:155], v[154:155], v[246:247]
	v_pk_mul_f32 v[156:157], v[156:157], v[248:249]
	v_pk_mul_f32 v[158:159], v[158:159], v[250:251]
	v_add_u32_e32 v181, 0x1000000, v178
	global_store_dwordx4 v181, v[144:147], s[76:77]
	global_store_dwordx4 v181, v[148:151], s[76:77] offset:16
	global_store_dwordx4 v181, v[152:155], s[76:77] offset:2048
	global_store_dwordx4 v181, v[156:159], s[76:77] offset:2064
	s_nop 1
	s_waitcnt vmcnt(16)
	v_lshlrev_b32_e32 v144, 16, v48
	v_and_b32_e32 v145, 0xffff0000, v48
	v_lshlrev_b32_e32 v146, 16, v49
	v_and_b32_e32 v147, 0xffff0000, v49
	v_lshlrev_b32_e32 v148, 16, v50
	v_and_b32_e32 v149, 0xffff0000, v50
	v_lshlrev_b32_e32 v150, 16, v51
	v_and_b32_e32 v151, 0xffff0000, v51
	v_lshlrev_b32_e32 v152, 16, v52
	v_and_b32_e32 v153, 0xffff0000, v52
	v_lshlrev_b32_e32 v154, 16, v53
	v_and_b32_e32 v155, 0xffff0000, v53
	v_lshlrev_b32_e32 v156, 16, v54
	v_and_b32_e32 v157, 0xffff0000, v54
	v_lshlrev_b32_e32 v158, 16, v55
	v_and_b32_e32 v159, 0xffff0000, v55
	v_lshlrev_b32_e32 v160, 16, v56
	v_and_b32_e32 v161, 0xffff0000, v56
	v_lshlrev_b32_e32 v162, 16, v57
	v_and_b32_e32 v163, 0xffff0000, v57
	v_lshlrev_b32_e32 v164, 16, v58
	v_and_b32_e32 v165, 0xffff0000, v58
	v_lshlrev_b32_e32 v166, 16, v59
	v_and_b32_e32 v167, 0xffff0000, v59
	v_lshlrev_b32_e32 v168, 16, v60
	v_and_b32_e32 v169, 0xffff0000, v60
	v_lshlrev_b32_e32 v170, 16, v61
	v_and_b32_e32 v171, 0xffff0000, v61
	v_lshlrev_b32_e32 v172, 16, v62
	v_and_b32_e32 v173, 0xffff0000, v62
	v_lshlrev_b32_e32 v174, 16, v63
	v_and_b32_e32 v175, 0xffff0000, v63
	v_pk_mul_f32 v[252:253], v[160:161], v[160:161]
	v_pk_mul_f32 v[254:255], v[162:163], v[162:163]
	v_pk_fma_f32 v[252:253], v[164:165], v[164:165], v[252:253]
	v_pk_fma_f32 v[254:255], v[166:167], v[166:167], v[254:255]
	v_pk_fma_f32 v[252:253], v[168:169], v[168:169], v[252:253]
	v_pk_fma_f32 v[254:255], v[170:171], v[170:171], v[254:255]
	v_pk_fma_f32 v[252:253], v[172:173], v[172:173], v[252:253]
	v_pk_fma_f32 v[254:255], v[174:175], v[174:175], v[254:255]
	v_pk_add_f32 v[252:253], v[252:253], v[254:255]
	s_nop 0
	v_add_f32_e32 v183, v252, v253
	s_nop 1
	v_add_f32_dpp v183, v183, v183 quad_perm:[1,0,3,2] row_mask:0xf bank_mask:0xf bound_ctrl:1
	s_nop 1
	v_add_f32_dpp v183, v183, v183 quad_perm:[2,3,0,1] row_mask:0xf bank_mask:0xf bound_ctrl:1
	s_nop 1
	v_add_f32_dpp v183, v183, v183 row_half_mirror row_mask:0xf bank_mask:0xf bound_ctrl:1
	s_nop 1
	v_add_f32_dpp v183, v183, v183 row_mirror row_mask:0xf bank_mask:0xf bound_ctrl:1
	s_nop 1
	v_readlane_b32 s98, v183, 0
	v_readlane_b32 s99, v183, 16
	v_readlane_b32 s100, v183, 32
	v_readlane_b32 s101, v183, 48
	s_nop 1
	v_mov_b32_e32 v183, s98
	v_add_f32_e32 v183, s99, v183
	v_add_f32_e32 v183, s100, v183
	v_add_f32_e32 v183, s101, v183
	v_fmamk_f32 v183, v183, 0x3a800000, v182
	v_cmp_gt_f32_e32 vcc, 0x800000, v183
	v_mul_f32_e32 v181, 0x4b800000, v183
	s_nop 1
	v_cndmask_b32_e32 v183, v183, v181, vcc
	v_rsq_f32_e32 v183, v183
	s_nop 0
	v_mul_f32_e32 v181, 0x45800000, v183
	v_cndmask_b32_e32 v184, v183, v181, vcc
	v_mov_b32_e32 v185, v184
	v_pk_mul_f32 v[160:161], v[160:161], v[184:185]
	v_pk_mul_f32 v[162:163], v[162:163], v[184:185]
	v_pk_mul_f32 v[164:165], v[164:165], v[184:185]
	v_pk_mul_f32 v[166:167], v[166:167], v[184:185]
	v_pk_mul_f32 v[168:169], v[168:169], v[184:185]
	v_pk_mul_f32 v[170:171], v[170:171], v[184:185]
	v_pk_mul_f32 v[172:173], v[172:173], v[184:185]
	v_pk_mul_f32 v[174:175], v[174:175], v[184:185]
	v_pk_fma_f32 v[144:145], v[160:161], v[128:129], v[144:145]
	v_pk_fma_f32 v[146:147], v[162:163], v[130:131], v[146:147]
	v_pk_fma_f32 v[148:149], v[164:165], v[132:133], v[148:149]
	v_pk_fma_f32 v[150:151], v[166:167], v[134:135], v[150:151]
	v_pk_fma_f32 v[152:153], v[168:169], v[136:137], v[152:153]
	v_pk_fma_f32 v[154:155], v[170:171], v[138:139], v[154:155]
	v_pk_fma_f32 v[156:157], v[172:173], v[140:141], v[156:157]
	v_pk_fma_f32 v[158:159], v[174:175], v[142:143], v[158:159]
	v_pk_mul_f32 v[252:253], v[144:145], v[144:145]
	v_pk_mul_f32 v[254:255], v[146:147], v[146:147]
	v_pk_fma_f32 v[252:253], v[148:149], v[148:149], v[252:253]
	v_pk_fma_f32 v[254:255], v[150:151], v[150:151], v[254:255]
	v_pk_fma_f32 v[252:253], v[152:153], v[152:153], v[252:253]
	v_pk_fma_f32 v[254:255], v[154:155], v[154:155], v[254:255]
	v_pk_fma_f32 v[252:253], v[156:157], v[156:157], v[252:253]
	v_pk_fma_f32 v[254:255], v[158:159], v[158:159], v[254:255]
	v_pk_add_f32 v[252:253], v[252:253], v[254:255]
	s_nop 0
	v_add_f32_e32 v183, v252, v253
	s_nop 1
	v_add_f32_dpp v183, v183, v183 quad_perm:[1,0,3,2] row_mask:0xf bank_mask:0xf bound_ctrl:1
	s_nop 1
	v_add_f32_dpp v183, v183, v183 quad_perm:[2,3,0,1] row_mask:0xf bank_mask:0xf bound_ctrl:1
	s_nop 1
	v_add_f32_dpp v183, v183, v183 row_half_mirror row_mask:0xf bank_mask:0xf bound_ctrl:1
	s_nop 1
	v_add_f32_dpp v183, v183, v183 row_mirror row_mask:0xf bank_mask:0xf bound_ctrl:1
	s_nop 1
	v_readlane_b32 s98, v183, 0
	v_readlane_b32 s99, v183, 16
	v_readlane_b32 s100, v183, 32
	v_readlane_b32 s101, v183, 48
	s_nop 1
	v_mov_b32_e32 v183, s98
	v_add_f32_e32 v183, s99, v183
	v_add_f32_e32 v183, s100, v183
	v_add_f32_e32 v183, s101, v183
	v_fmamk_f32 v183, v183, 0x3a800000, v182
	v_cmp_gt_f32_e32 vcc, 0x800000, v183
	v_mul_f32_e32 v181, 0x4b800000, v183
	s_nop 1
	v_cndmask_b32_e32 v183, v183, v181, vcc
	v_rsq_f32_e32 v183, v183
	s_nop 0
	v_mul_f32_e32 v181, 0x45800000, v183
	v_cndmask_b32_e32 v184, v183, v181, vcc
	v_mov_b32_e32 v185, v184
	v_pk_mul_f32 v[144:145], v[144:145], v[184:185]
	v_pk_mul_f32 v[146:147], v[146:147], v[184:185]
	v_pk_mul_f32 v[148:149], v[148:149], v[184:185]
	v_pk_mul_f32 v[150:151], v[150:151], v[184:185]
	v_pk_mul_f32 v[152:153], v[152:153], v[184:185]
	v_pk_mul_f32 v[154:155], v[154:155], v[184:185]
	v_pk_mul_f32 v[156:157], v[156:157], v[184:185]
	v_pk_mul_f32 v[158:159], v[158:159], v[184:185]
	v_pk_mul_f32 v[144:145], v[144:145], v[236:237]
	v_pk_mul_f32 v[146:147], v[146:147], v[238:239]
	v_pk_mul_f32 v[148:149], v[148:149], v[240:241]
	v_pk_mul_f32 v[150:151], v[150:151], v[242:243]
	v_pk_mul_f32 v[152:153], v[152:153], v[244:245]
	v_pk_mul_f32 v[154:155], v[154:155], v[246:247]
	v_pk_mul_f32 v[156:157], v[156:157], v[248:249]
	v_pk_mul_f32 v[158:159], v[158:159], v[250:251]
	v_add_u32_e32 v181, 0x1800000, v178
	global_store_dwordx4 v181, v[144:147], s[76:77]
	global_store_dwordx4 v181, v[148:151], s[76:77] offset:16
	global_store_dwordx4 v181, v[152:155], s[76:77] offset:2048
	global_store_dwordx4 v181, v[156:159], s[76:77] offset:2064
	s_nop 1
	s_waitcnt vmcnt(12)
	v_lshlrev_b32_e32 v144, 16, v64
	v_and_b32_e32 v145, 0xffff0000, v64
	v_lshlrev_b32_e32 v146, 16, v65
	v_and_b32_e32 v147, 0xffff0000, v65
	v_lshlrev_b32_e32 v148, 16, v66
	v_and_b32_e32 v149, 0xffff0000, v66
	v_lshlrev_b32_e32 v150, 16, v67
	v_and_b32_e32 v151, 0xffff0000, v67
	v_lshlrev_b32_e32 v152, 16, v68
	v_and_b32_e32 v153, 0xffff0000, v68
	v_lshlrev_b32_e32 v154, 16, v69
	v_and_b32_e32 v155, 0xffff0000, v69
	v_lshlrev_b32_e32 v156, 16, v70
	v_and_b32_e32 v157, 0xffff0000, v70
	v_lshlrev_b32_e32 v158, 16, v71
	v_and_b32_e32 v159, 0xffff0000, v71
	v_lshlrev_b32_e32 v160, 16, v72
	v_and_b32_e32 v161, 0xffff0000, v72
	v_lshlrev_b32_e32 v162, 16, v73
	v_and_b32_e32 v163, 0xffff0000, v73
	v_lshlrev_b32_e32 v164, 16, v74
	v_and_b32_e32 v165, 0xffff0000, v74
	v_lshlrev_b32_e32 v166, 16, v75
	v_and_b32_e32 v167, 0xffff0000, v75
	v_lshlrev_b32_e32 v168, 16, v76
	v_and_b32_e32 v169, 0xffff0000, v76
	v_lshlrev_b32_e32 v170, 16, v77
	v_and_b32_e32 v171, 0xffff0000, v77
	v_lshlrev_b32_e32 v172, 16, v78
	v_and_b32_e32 v173, 0xffff0000, v78
	v_lshlrev_b32_e32 v174, 16, v79
	v_and_b32_e32 v175, 0xffff0000, v79
	v_pk_mul_f32 v[252:253], v[160:161], v[160:161]
	v_pk_mul_f32 v[254:255], v[162:163], v[162:163]
	v_pk_fma_f32 v[252:253], v[164:165], v[164:165], v[252:253]
	v_pk_fma_f32 v[254:255], v[166:167], v[166:167], v[254:255]
	v_pk_fma_f32 v[252:253], v[168:169], v[168:169], v[252:253]
	v_pk_fma_f32 v[254:255], v[170:171], v[170:171], v[254:255]
	v_pk_fma_f32 v[252:253], v[172:173], v[172:173], v[252:253]
	v_pk_fma_f32 v[254:255], v[174:175], v[174:175], v[254:255]
	v_pk_add_f32 v[252:253], v[252:253], v[254:255]
	s_nop 0
	v_add_f32_e32 v183, v252, v253
	s_nop 1
	v_add_f32_dpp v183, v183, v183 quad_perm:[1,0,3,2] row_mask:0xf bank_mask:0xf bound_ctrl:1
	s_nop 1
	v_add_f32_dpp v183, v183, v183 quad_perm:[2,3,0,1] row_mask:0xf bank_mask:0xf bound_ctrl:1
	s_nop 1
	v_add_f32_dpp v183, v183, v183 row_half_mirror row_mask:0xf bank_mask:0xf bound_ctrl:1
	s_nop 1
	v_add_f32_dpp v183, v183, v183 row_mirror row_mask:0xf bank_mask:0xf bound_ctrl:1
	s_nop 1
	v_readlane_b32 s98, v183, 0
	v_readlane_b32 s99, v183, 16
	v_readlane_b32 s100, v183, 32
	v_readlane_b32 s101, v183, 48
	s_nop 1
	v_mov_b32_e32 v183, s98
	v_add_f32_e32 v183, s99, v183
	v_add_f32_e32 v183, s100, v183
	v_add_f32_e32 v183, s101, v183
	v_fmamk_f32 v183, v183, 0x3a800000, v182
	v_cmp_gt_f32_e32 vcc, 0x800000, v183
	v_mul_f32_e32 v181, 0x4b800000, v183
	s_nop 1
	v_cndmask_b32_e32 v183, v183, v181, vcc
	v_rsq_f32_e32 v183, v183
	s_nop 0
	v_mul_f32_e32 v181, 0x45800000, v183
	v_cndmask_b32_e32 v184, v183, v181, vcc
	v_mov_b32_e32 v185, v184
	v_pk_mul_f32 v[160:161], v[160:161], v[184:185]
	v_pk_mul_f32 v[162:163], v[162:163], v[184:185]
	v_pk_mul_f32 v[164:165], v[164:165], v[184:185]
	v_pk_mul_f32 v[166:167], v[166:167], v[184:185]
	v_pk_mul_f32 v[168:169], v[168:169], v[184:185]
	v_pk_mul_f32 v[170:171], v[170:171], v[184:185]
	v_pk_mul_f32 v[172:173], v[172:173], v[184:185]
	v_pk_mul_f32 v[174:175], v[174:175], v[184:185]
	v_pk_fma_f32 v[144:145], v[160:161], v[128:129], v[144:145]
	v_pk_fma_f32 v[146:147], v[162:163], v[130:131], v[146:147]
	v_pk_fma_f32 v[148:149], v[164:165], v[132:133], v[148:149]
	v_pk_fma_f32 v[150:151], v[166:167], v[134:135], v[150:151]
	v_pk_fma_f32 v[152:153], v[168:169], v[136:137], v[152:153]
	v_pk_fma_f32 v[154:155], v[170:171], v[138:139], v[154:155]
	v_pk_fma_f32 v[156:157], v[172:173], v[140:141], v[156:157]
	v_pk_fma_f32 v[158:159], v[174:175], v[142:143], v[158:159]
	v_pk_mul_f32 v[252:253], v[144:145], v[144:145]
	v_pk_mul_f32 v[254:255], v[146:147], v[146:147]
	v_pk_fma_f32 v[252:253], v[148:149], v[148:149], v[252:253]
	v_pk_fma_f32 v[254:255], v[150:151], v[150:151], v[254:255]
	v_pk_fma_f32 v[252:253], v[152:153], v[152:153], v[252:253]
	v_pk_fma_f32 v[254:255], v[154:155], v[154:155], v[254:255]
	v_pk_fma_f32 v[252:253], v[156:157], v[156:157], v[252:253]
	v_pk_fma_f32 v[254:255], v[158:159], v[158:159], v[254:255]
	v_pk_add_f32 v[252:253], v[252:253], v[254:255]
	s_nop 0
	v_add_f32_e32 v183, v252, v253
	s_nop 1
	v_add_f32_dpp v183, v183, v183 quad_perm:[1,0,3,2] row_mask:0xf bank_mask:0xf bound_ctrl:1
	s_nop 1
	v_add_f32_dpp v183, v183, v183 quad_perm:[2,3,0,1] row_mask:0xf bank_mask:0xf bound_ctrl:1
	s_nop 1
	v_add_f32_dpp v183, v183, v183 row_half_mirror row_mask:0xf bank_mask:0xf bound_ctrl:1
	s_nop 1
	v_add_f32_dpp v183, v183, v183 row_mirror row_mask:0xf bank_mask:0xf bound_ctrl:1
	s_nop 1
	v_readlane_b32 s98, v183, 0
	v_readlane_b32 s99, v183, 16
	v_readlane_b32 s100, v183, 32
	v_readlane_b32 s101, v183, 48
	s_nop 1
	v_mov_b32_e32 v183, s98
	v_add_f32_e32 v183, s99, v183
	v_add_f32_e32 v183, s100, v183
	v_add_f32_e32 v183, s101, v183
	v_fmamk_f32 v183, v183, 0x3a800000, v182
	v_cmp_gt_f32_e32 vcc, 0x800000, v183
	v_mul_f32_e32 v181, 0x4b800000, v183
	s_nop 1
	v_cndmask_b32_e32 v183, v183, v181, vcc
	v_rsq_f32_e32 v183, v183
	s_nop 0
	v_mul_f32_e32 v181, 0x45800000, v183
	v_cndmask_b32_e32 v184, v183, v181, vcc
	v_mov_b32_e32 v185, v184
	v_pk_mul_f32 v[144:145], v[144:145], v[184:185]
	v_pk_mul_f32 v[146:147], v[146:147], v[184:185]
	v_pk_mul_f32 v[148:149], v[148:149], v[184:185]
	v_pk_mul_f32 v[150:151], v[150:151], v[184:185]
	v_pk_mul_f32 v[152:153], v[152:153], v[184:185]
	v_pk_mul_f32 v[154:155], v[154:155], v[184:185]
	v_pk_mul_f32 v[156:157], v[156:157], v[184:185]
	v_pk_mul_f32 v[158:159], v[158:159], v[184:185]
	v_pk_mul_f32 v[144:145], v[144:145], v[236:237]
	v_pk_mul_f32 v[146:147], v[146:147], v[238:239]
	v_pk_mul_f32 v[148:149], v[148:149], v[240:241]
	v_pk_mul_f32 v[150:151], v[150:151], v[242:243]
	v_pk_mul_f32 v[152:153], v[152:153], v[244:245]
	v_pk_mul_f32 v[154:155], v[154:155], v[246:247]
	v_pk_mul_f32 v[156:157], v[156:157], v[248:249]
	v_pk_mul_f32 v[158:159], v[158:159], v[250:251]
	v_add_u32_e32 v181, 0x2000000, v178
	global_store_dwordx4 v181, v[144:147], s[76:77]
	global_store_dwordx4 v181, v[148:151], s[76:77] offset:16
	global_store_dwordx4 v181, v[152:155], s[76:77] offset:2048
	global_store_dwordx4 v181, v[156:159], s[76:77] offset:2064
	s_nop 1
	s_waitcnt vmcnt(8)
	v_lshlrev_b32_e32 v144, 16, v80
	v_and_b32_e32 v145, 0xffff0000, v80
	v_lshlrev_b32_e32 v146, 16, v81
	v_and_b32_e32 v147, 0xffff0000, v81
	v_lshlrev_b32_e32 v148, 16, v82
	v_and_b32_e32 v149, 0xffff0000, v82
	v_lshlrev_b32_e32 v150, 16, v83
	v_and_b32_e32 v151, 0xffff0000, v83
	v_lshlrev_b32_e32 v152, 16, v84
	v_and_b32_e32 v153, 0xffff0000, v84
	v_lshlrev_b32_e32 v154, 16, v85
	v_and_b32_e32 v155, 0xffff0000, v85
	v_lshlrev_b32_e32 v156, 16, v86
	v_and_b32_e32 v157, 0xffff0000, v86
	v_lshlrev_b32_e32 v158, 16, v87
	v_and_b32_e32 v159, 0xffff0000, v87
	v_lshlrev_b32_e32 v160, 16, v88
	v_and_b32_e32 v161, 0xffff0000, v88
	v_lshlrev_b32_e32 v162, 16, v89
	v_and_b32_e32 v163, 0xffff0000, v89
	v_lshlrev_b32_e32 v164, 16, v90
	v_and_b32_e32 v165, 0xffff0000, v90
	v_lshlrev_b32_e32 v166, 16, v91
	v_and_b32_e32 v167, 0xffff0000, v91
	v_lshlrev_b32_e32 v168, 16, v92
	v_and_b32_e32 v169, 0xffff0000, v92
	v_lshlrev_b32_e32 v170, 16, v93
	v_and_b32_e32 v171, 0xffff0000, v93
	v_lshlrev_b32_e32 v172, 16, v94
	v_and_b32_e32 v173, 0xffff0000, v94
	v_lshlrev_b32_e32 v174, 16, v95
	v_and_b32_e32 v175, 0xffff0000, v95
	v_pk_mul_f32 v[252:253], v[160:161], v[160:161]
	v_pk_mul_f32 v[254:255], v[162:163], v[162:163]
	v_pk_fma_f32 v[252:253], v[164:165], v[164:165], v[252:253]
	v_pk_fma_f32 v[254:255], v[166:167], v[166:167], v[254:255]
	v_pk_fma_f32 v[252:253], v[168:169], v[168:169], v[252:253]
	v_pk_fma_f32 v[254:255], v[170:171], v[170:171], v[254:255]
	v_pk_fma_f32 v[252:253], v[172:173], v[172:173], v[252:253]
	v_pk_fma_f32 v[254:255], v[174:175], v[174:175], v[254:255]
	v_pk_add_f32 v[252:253], v[252:253], v[254:255]
	s_nop 0
	v_add_f32_e32 v183, v252, v253
	s_nop 1
	v_add_f32_dpp v183, v183, v183 quad_perm:[1,0,3,2] row_mask:0xf bank_mask:0xf bound_ctrl:1
	s_nop 1
	v_add_f32_dpp v183, v183, v183 quad_perm:[2,3,0,1] row_mask:0xf bank_mask:0xf bound_ctrl:1
	s_nop 1
	v_add_f32_dpp v183, v183, v183 row_half_mirror row_mask:0xf bank_mask:0xf bound_ctrl:1
	s_nop 1
	v_add_f32_dpp v183, v183, v183 row_mirror row_mask:0xf bank_mask:0xf bound_ctrl:1
	s_nop 1
	v_readlane_b32 s98, v183, 0
	v_readlane_b32 s99, v183, 16
	v_readlane_b32 s100, v183, 32
	v_readlane_b32 s101, v183, 48
	s_nop 1
	v_mov_b32_e32 v183, s98
	v_add_f32_e32 v183, s99, v183
	v_add_f32_e32 v183, s100, v183
	v_add_f32_e32 v183, s101, v183
	v_fmamk_f32 v183, v183, 0x3a800000, v182
	v_cmp_gt_f32_e32 vcc, 0x800000, v183
	v_mul_f32_e32 v181, 0x4b800000, v183
	s_nop 1
	v_cndmask_b32_e32 v183, v183, v181, vcc
	v_rsq_f32_e32 v183, v183
	s_nop 0
	v_mul_f32_e32 v181, 0x45800000, v183
	v_cndmask_b32_e32 v184, v183, v181, vcc
	v_mov_b32_e32 v185, v184
	v_pk_mul_f32 v[160:161], v[160:161], v[184:185]
	v_pk_mul_f32 v[162:163], v[162:163], v[184:185]
	v_pk_mul_f32 v[164:165], v[164:165], v[184:185]
	v_pk_mul_f32 v[166:167], v[166:167], v[184:185]
	v_pk_mul_f32 v[168:169], v[168:169], v[184:185]
	v_pk_mul_f32 v[170:171], v[170:171], v[184:185]
	v_pk_mul_f32 v[172:173], v[172:173], v[184:185]
	v_pk_mul_f32 v[174:175], v[174:175], v[184:185]
	v_pk_fma_f32 v[144:145], v[160:161], v[128:129], v[144:145]
	v_pk_fma_f32 v[146:147], v[162:163], v[130:131], v[146:147]
	v_pk_fma_f32 v[148:149], v[164:165], v[132:133], v[148:149]
	v_pk_fma_f32 v[150:151], v[166:167], v[134:135], v[150:151]
	v_pk_fma_f32 v[152:153], v[168:169], v[136:137], v[152:153]
	v_pk_fma_f32 v[154:155], v[170:171], v[138:139], v[154:155]
	v_pk_fma_f32 v[156:157], v[172:173], v[140:141], v[156:157]
	v_pk_fma_f32 v[158:159], v[174:175], v[142:143], v[158:159]
	v_pk_mul_f32 v[252:253], v[144:145], v[144:145]
	v_pk_mul_f32 v[254:255], v[146:147], v[146:147]
	v_pk_fma_f32 v[252:253], v[148:149], v[148:149], v[252:253]
	v_pk_fma_f32 v[254:255], v[150:151], v[150:151], v[254:255]
	v_pk_fma_f32 v[252:253], v[152:153], v[152:153], v[252:253]
	v_pk_fma_f32 v[254:255], v[154:155], v[154:155], v[254:255]
	v_pk_fma_f32 v[252:253], v[156:157], v[156:157], v[252:253]
	v_pk_fma_f32 v[254:255], v[158:159], v[158:159], v[254:255]
	v_pk_add_f32 v[252:253], v[252:253], v[254:255]
	s_nop 0
	v_add_f32_e32 v183, v252, v253
	s_nop 1
	v_add_f32_dpp v183, v183, v183 quad_perm:[1,0,3,2] row_mask:0xf bank_mask:0xf bound_ctrl:1
	s_nop 1
	v_add_f32_dpp v183, v183, v183 quad_perm:[2,3,0,1] row_mask:0xf bank_mask:0xf bound_ctrl:1
	s_nop 1
	v_add_f32_dpp v183, v183, v183 row_half_mirror row_mask:0xf bank_mask:0xf bound_ctrl:1
	s_nop 1
	v_add_f32_dpp v183, v183, v183 row_mirror row_mask:0xf bank_mask:0xf bound_ctrl:1
	s_nop 1
	v_readlane_b32 s98, v183, 0
	v_readlane_b32 s99, v183, 16
	v_readlane_b32 s100, v183, 32
	v_readlane_b32 s101, v183, 48
	s_nop 1
	v_mov_b32_e32 v183, s98
	v_add_f32_e32 v183, s99, v183
	v_add_f32_e32 v183, s100, v183
	v_add_f32_e32 v183, s101, v183
	v_fmamk_f32 v183, v183, 0x3a800000, v182
	v_cmp_gt_f32_e32 vcc, 0x800000, v183
	v_mul_f32_e32 v181, 0x4b800000, v183
	s_nop 1
	v_cndmask_b32_e32 v183, v183, v181, vcc
	v_rsq_f32_e32 v183, v183
	s_nop 0
	v_mul_f32_e32 v181, 0x45800000, v183
	v_cndmask_b32_e32 v184, v183, v181, vcc
	v_mov_b32_e32 v185, v184
	v_pk_mul_f32 v[144:145], v[144:145], v[184:185]
	v_pk_mul_f32 v[146:147], v[146:147], v[184:185]
	v_pk_mul_f32 v[148:149], v[148:149], v[184:185]
	v_pk_mul_f32 v[150:151], v[150:151], v[184:185]
	v_pk_mul_f32 v[152:153], v[152:153], v[184:185]
	v_pk_mul_f32 v[154:155], v[154:155], v[184:185]
	v_pk_mul_f32 v[156:157], v[156:157], v[184:185]
	v_pk_mul_f32 v[158:159], v[158:159], v[184:185]
	v_pk_mul_f32 v[144:145], v[144:145], v[236:237]
	v_pk_mul_f32 v[146:147], v[146:147], v[238:239]
	v_pk_mul_f32 v[148:149], v[148:149], v[240:241]
	v_pk_mul_f32 v[150:151], v[150:151], v[242:243]
	v_pk_mul_f32 v[152:153], v[152:153], v[244:245]
	v_pk_mul_f32 v[154:155], v[154:155], v[246:247]
	v_pk_mul_f32 v[156:157], v[156:157], v[248:249]
	v_pk_mul_f32 v[158:159], v[158:159], v[250:251]
	v_add_u32_e32 v181, 0x2800000, v178
	global_store_dwordx4 v181, v[144:147], s[76:77]
	global_store_dwordx4 v181, v[148:151], s[76:77] offset:16
	global_store_dwordx4 v181, v[152:155], s[76:77] offset:2048
	global_store_dwordx4 v181, v[156:159], s[76:77] offset:2064
	s_nop 1
	s_waitcnt vmcnt(4)
	v_lshlrev_b32_e32 v144, 16, v96
	v_and_b32_e32 v145, 0xffff0000, v96
	v_lshlrev_b32_e32 v146, 16, v97
	v_and_b32_e32 v147, 0xffff0000, v97
	v_lshlrev_b32_e32 v148, 16, v98
	v_and_b32_e32 v149, 0xffff0000, v98
	v_lshlrev_b32_e32 v150, 16, v99
	v_and_b32_e32 v151, 0xffff0000, v99
	v_lshlrev_b32_e32 v152, 16, v100
	v_and_b32_e32 v153, 0xffff0000, v100
	v_lshlrev_b32_e32 v154, 16, v101
	v_and_b32_e32 v155, 0xffff0000, v101
	v_lshlrev_b32_e32 v156, 16, v102
	v_and_b32_e32 v157, 0xffff0000, v102
	v_lshlrev_b32_e32 v158, 16, v103
	v_and_b32_e32 v159, 0xffff0000, v103
	v_lshlrev_b32_e32 v160, 16, v104
	v_and_b32_e32 v161, 0xffff0000, v104
	v_lshlrev_b32_e32 v162, 16, v105
	v_and_b32_e32 v163, 0xffff0000, v105
	v_lshlrev_b32_e32 v164, 16, v106
	v_and_b32_e32 v165, 0xffff0000, v106
	v_lshlrev_b32_e32 v166, 16, v107
	v_and_b32_e32 v167, 0xffff0000, v107
	v_lshlrev_b32_e32 v168, 16, v108
	v_and_b32_e32 v169, 0xffff0000, v108
	v_lshlrev_b32_e32 v170, 16, v109
	v_and_b32_e32 v171, 0xffff0000, v109
	v_lshlrev_b32_e32 v172, 16, v110
	v_and_b32_e32 v173, 0xffff0000, v110
	v_lshlrev_b32_e32 v174, 16, v111
	v_and_b32_e32 v175, 0xffff0000, v111
	v_pk_mul_f32 v[252:253], v[160:161], v[160:161]
	v_pk_mul_f32 v[254:255], v[162:163], v[162:163]
	v_pk_fma_f32 v[252:253], v[164:165], v[164:165], v[252:253]
	v_pk_fma_f32 v[254:255], v[166:167], v[166:167], v[254:255]
	v_pk_fma_f32 v[252:253], v[168:169], v[168:169], v[252:253]
	v_pk_fma_f32 v[254:255], v[170:171], v[170:171], v[254:255]
	v_pk_fma_f32 v[252:253], v[172:173], v[172:173], v[252:253]
	v_pk_fma_f32 v[254:255], v[174:175], v[174:175], v[254:255]
	v_pk_add_f32 v[252:253], v[252:253], v[254:255]
	s_nop 0
	v_add_f32_e32 v183, v252, v253
	s_nop 1
	v_add_f32_dpp v183, v183, v183 quad_perm:[1,0,3,2] row_mask:0xf bank_mask:0xf bound_ctrl:1
	s_nop 1
	v_add_f32_dpp v183, v183, v183 quad_perm:[2,3,0,1] row_mask:0xf bank_mask:0xf bound_ctrl:1
	s_nop 1
	v_add_f32_dpp v183, v183, v183 row_half_mirror row_mask:0xf bank_mask:0xf bound_ctrl:1
	s_nop 1
	v_add_f32_dpp v183, v183, v183 row_mirror row_mask:0xf bank_mask:0xf bound_ctrl:1
	s_nop 1
	v_readlane_b32 s98, v183, 0
	v_readlane_b32 s99, v183, 16
	v_readlane_b32 s100, v183, 32
	v_readlane_b32 s101, v183, 48
	s_nop 1
	v_mov_b32_e32 v183, s98
	v_add_f32_e32 v183, s99, v183
	v_add_f32_e32 v183, s100, v183
	v_add_f32_e32 v183, s101, v183
	v_fmamk_f32 v183, v183, 0x3a800000, v182
	v_cmp_gt_f32_e32 vcc, 0x800000, v183
	v_mul_f32_e32 v181, 0x4b800000, v183
	s_nop 1
	v_cndmask_b32_e32 v183, v183, v181, vcc
	v_rsq_f32_e32 v183, v183
	s_nop 0
	v_mul_f32_e32 v181, 0x45800000, v183
	v_cndmask_b32_e32 v184, v183, v181, vcc
	v_mov_b32_e32 v185, v184
	v_pk_mul_f32 v[160:161], v[160:161], v[184:185]
	v_pk_mul_f32 v[162:163], v[162:163], v[184:185]
	v_pk_mul_f32 v[164:165], v[164:165], v[184:185]
	v_pk_mul_f32 v[166:167], v[166:167], v[184:185]
	v_pk_mul_f32 v[168:169], v[168:169], v[184:185]
	v_pk_mul_f32 v[170:171], v[170:171], v[184:185]
	v_pk_mul_f32 v[172:173], v[172:173], v[184:185]
	v_pk_mul_f32 v[174:175], v[174:175], v[184:185]
	v_pk_fma_f32 v[144:145], v[160:161], v[128:129], v[144:145]
	v_pk_fma_f32 v[146:147], v[162:163], v[130:131], v[146:147]
	v_pk_fma_f32 v[148:149], v[164:165], v[132:133], v[148:149]
	v_pk_fma_f32 v[150:151], v[166:167], v[134:135], v[150:151]
	v_pk_fma_f32 v[152:153], v[168:169], v[136:137], v[152:153]
	v_pk_fma_f32 v[154:155], v[170:171], v[138:139], v[154:155]
	v_pk_fma_f32 v[156:157], v[172:173], v[140:141], v[156:157]
	v_pk_fma_f32 v[158:159], v[174:175], v[142:143], v[158:159]
	v_pk_mul_f32 v[252:253], v[144:145], v[144:145]
	v_pk_mul_f32 v[254:255], v[146:147], v[146:147]
	v_pk_fma_f32 v[252:253], v[148:149], v[148:149], v[252:253]
	v_pk_fma_f32 v[254:255], v[150:151], v[150:151], v[254:255]
	v_pk_fma_f32 v[252:253], v[152:153], v[152:153], v[252:253]
	v_pk_fma_f32 v[254:255], v[154:155], v[154:155], v[254:255]
	v_pk_fma_f32 v[252:253], v[156:157], v[156:157], v[252:253]
	v_pk_fma_f32 v[254:255], v[158:159], v[158:159], v[254:255]
	v_pk_add_f32 v[252:253], v[252:253], v[254:255]
	s_nop 0
	v_add_f32_e32 v183, v252, v253
	s_nop 1
	v_add_f32_dpp v183, v183, v183 quad_perm:[1,0,3,2] row_mask:0xf bank_mask:0xf bound_ctrl:1
	s_nop 1
	v_add_f32_dpp v183, v183, v183 quad_perm:[2,3,0,1] row_mask:0xf bank_mask:0xf bound_ctrl:1
	s_nop 1
	v_add_f32_dpp v183, v183, v183 row_half_mirror row_mask:0xf bank_mask:0xf bound_ctrl:1
	s_nop 1
	v_add_f32_dpp v183, v183, v183 row_mirror row_mask:0xf bank_mask:0xf bound_ctrl:1
	s_nop 1
	v_readlane_b32 s98, v183, 0
	v_readlane_b32 s99, v183, 16
	v_readlane_b32 s100, v183, 32
	v_readlane_b32 s101, v183, 48
	s_nop 1
	v_mov_b32_e32 v183, s98
	v_add_f32_e32 v183, s99, v183
	v_add_f32_e32 v183, s100, v183
	v_add_f32_e32 v183, s101, v183
	v_fmamk_f32 v183, v183, 0x3a800000, v182
	v_cmp_gt_f32_e32 vcc, 0x800000, v183
	v_mul_f32_e32 v181, 0x4b800000, v183
	s_nop 1
	v_cndmask_b32_e32 v183, v183, v181, vcc
	v_rsq_f32_e32 v183, v183
	s_nop 0
	v_mul_f32_e32 v181, 0x45800000, v183
	v_cndmask_b32_e32 v184, v183, v181, vcc
	v_mov_b32_e32 v185, v184
	v_pk_mul_f32 v[144:145], v[144:145], v[184:185]
	v_pk_mul_f32 v[146:147], v[146:147], v[184:185]
	v_pk_mul_f32 v[148:149], v[148:149], v[184:185]
	v_pk_mul_f32 v[150:151], v[150:151], v[184:185]
	v_pk_mul_f32 v[152:153], v[152:153], v[184:185]
	v_pk_mul_f32 v[154:155], v[154:155], v[184:185]
	v_pk_mul_f32 v[156:157], v[156:157], v[184:185]
	v_pk_mul_f32 v[158:159], v[158:159], v[184:185]
	v_pk_mul_f32 v[144:145], v[144:145], v[236:237]
	v_pk_mul_f32 v[146:147], v[146:147], v[238:239]
	v_pk_mul_f32 v[148:149], v[148:149], v[240:241]
	v_pk_mul_f32 v[150:151], v[150:151], v[242:243]
	v_pk_mul_f32 v[152:153], v[152:153], v[244:245]
	v_pk_mul_f32 v[154:155], v[154:155], v[246:247]
	v_pk_mul_f32 v[156:157], v[156:157], v[248:249]
	v_pk_mul_f32 v[158:159], v[158:159], v[250:251]
	v_add_u32_e32 v181, 0x3000000, v178
	global_store_dwordx4 v181, v[144:147], s[76:77]
	global_store_dwordx4 v181, v[148:151], s[76:77] offset:16
	global_store_dwordx4 v181, v[152:155], s[76:77] offset:2048
	global_store_dwordx4 v181, v[156:159], s[76:77] offset:2064
	s_nop 1
	s_waitcnt vmcnt(0)
	v_lshlrev_b32_e32 v144, 16, v112
	v_and_b32_e32 v145, 0xffff0000, v112
	v_lshlrev_b32_e32 v146, 16, v113
	v_and_b32_e32 v147, 0xffff0000, v113
	v_lshlrev_b32_e32 v148, 16, v114
	v_and_b32_e32 v149, 0xffff0000, v114
	v_lshlrev_b32_e32 v150, 16, v115
	v_and_b32_e32 v151, 0xffff0000, v115
	v_lshlrev_b32_e32 v152, 16, v116
	v_and_b32_e32 v153, 0xffff0000, v116
	v_lshlrev_b32_e32 v154, 16, v117
	v_and_b32_e32 v155, 0xffff0000, v117
	v_lshlrev_b32_e32 v156, 16, v118
	v_and_b32_e32 v157, 0xffff0000, v118
	v_lshlrev_b32_e32 v158, 16, v119
	v_and_b32_e32 v159, 0xffff0000, v119
	v_lshlrev_b32_e32 v160, 16, v120
	v_and_b32_e32 v161, 0xffff0000, v120
	v_lshlrev_b32_e32 v162, 16, v121
	v_and_b32_e32 v163, 0xffff0000, v121
	v_lshlrev_b32_e32 v164, 16, v122
	v_and_b32_e32 v165, 0xffff0000, v122
	v_lshlrev_b32_e32 v166, 16, v123
	v_and_b32_e32 v167, 0xffff0000, v123
	v_lshlrev_b32_e32 v168, 16, v124
	v_and_b32_e32 v169, 0xffff0000, v124
	v_lshlrev_b32_e32 v170, 16, v125
	v_and_b32_e32 v171, 0xffff0000, v125
	v_lshlrev_b32_e32 v172, 16, v126
	v_and_b32_e32 v173, 0xffff0000, v126
	v_lshlrev_b32_e32 v174, 16, v127
	v_and_b32_e32 v175, 0xffff0000, v127
	v_pk_mul_f32 v[252:253], v[160:161], v[160:161]
	v_pk_mul_f32 v[254:255], v[162:163], v[162:163]
	v_pk_fma_f32 v[252:253], v[164:165], v[164:165], v[252:253]
	v_pk_fma_f32 v[254:255], v[166:167], v[166:167], v[254:255]
	v_pk_fma_f32 v[252:253], v[168:169], v[168:169], v[252:253]
	v_pk_fma_f32 v[254:255], v[170:171], v[170:171], v[254:255]
	v_pk_fma_f32 v[252:253], v[172:173], v[172:173], v[252:253]
	v_pk_fma_f32 v[254:255], v[174:175], v[174:175], v[254:255]
	v_pk_add_f32 v[252:253], v[252:253], v[254:255]
	s_nop 0
	v_add_f32_e32 v183, v252, v253
	s_nop 1
	v_add_f32_dpp v183, v183, v183 quad_perm:[1,0,3,2] row_mask:0xf bank_mask:0xf bound_ctrl:1
	s_nop 1
	v_add_f32_dpp v183, v183, v183 quad_perm:[2,3,0,1] row_mask:0xf bank_mask:0xf bound_ctrl:1
	s_nop 1
	v_add_f32_dpp v183, v183, v183 row_half_mirror row_mask:0xf bank_mask:0xf bound_ctrl:1
	s_nop 1
	v_add_f32_dpp v183, v183, v183 row_mirror row_mask:0xf bank_mask:0xf bound_ctrl:1
	s_nop 1
	v_readlane_b32 s98, v183, 0
	v_readlane_b32 s99, v183, 16
	v_readlane_b32 s100, v183, 32
	v_readlane_b32 s101, v183, 48
	s_nop 1
	v_mov_b32_e32 v183, s98
	v_add_f32_e32 v183, s99, v183
	v_add_f32_e32 v183, s100, v183
	v_add_f32_e32 v183, s101, v183
	v_fmamk_f32 v183, v183, 0x3a800000, v182
	v_cmp_gt_f32_e32 vcc, 0x800000, v183
	v_mul_f32_e32 v181, 0x4b800000, v183
	s_nop 1
	v_cndmask_b32_e32 v183, v183, v181, vcc
	v_rsq_f32_e32 v183, v183
	s_nop 0
	v_mul_f32_e32 v181, 0x45800000, v183
	v_cndmask_b32_e32 v184, v183, v181, vcc
	v_mov_b32_e32 v185, v184
	v_pk_mul_f32 v[160:161], v[160:161], v[184:185]
	v_pk_mul_f32 v[162:163], v[162:163], v[184:185]
	v_pk_mul_f32 v[164:165], v[164:165], v[184:185]
	v_pk_mul_f32 v[166:167], v[166:167], v[184:185]
	v_pk_mul_f32 v[168:169], v[168:169], v[184:185]
	v_pk_mul_f32 v[170:171], v[170:171], v[184:185]
	v_pk_mul_f32 v[172:173], v[172:173], v[184:185]
	v_pk_mul_f32 v[174:175], v[174:175], v[184:185]
	v_pk_fma_f32 v[144:145], v[160:161], v[128:129], v[144:145]
	v_pk_fma_f32 v[146:147], v[162:163], v[130:131], v[146:147]
	v_pk_fma_f32 v[148:149], v[164:165], v[132:133], v[148:149]
	v_pk_fma_f32 v[150:151], v[166:167], v[134:135], v[150:151]
	v_pk_fma_f32 v[152:153], v[168:169], v[136:137], v[152:153]
	v_pk_fma_f32 v[154:155], v[170:171], v[138:139], v[154:155]
	v_pk_fma_f32 v[156:157], v[172:173], v[140:141], v[156:157]
	v_pk_fma_f32 v[158:159], v[174:175], v[142:143], v[158:159]
	v_pk_mul_f32 v[252:253], v[144:145], v[144:145]
	v_pk_mul_f32 v[254:255], v[146:147], v[146:147]
	v_pk_fma_f32 v[252:253], v[148:149], v[148:149], v[252:253]
	v_pk_fma_f32 v[254:255], v[150:151], v[150:151], v[254:255]
	v_pk_fma_f32 v[252:253], v[152:153], v[152:153], v[252:253]
	v_pk_fma_f32 v[254:255], v[154:155], v[154:155], v[254:255]
	v_pk_fma_f32 v[252:253], v[156:157], v[156:157], v[252:253]
	v_pk_fma_f32 v[254:255], v[158:159], v[158:159], v[254:255]
	v_pk_add_f32 v[252:253], v[252:253], v[254:255]
	s_nop 0
	v_add_f32_e32 v183, v252, v253
	s_nop 1
	v_add_f32_dpp v183, v183, v183 quad_perm:[1,0,3,2] row_mask:0xf bank_mask:0xf bound_ctrl:1
	s_nop 1
	v_add_f32_dpp v183, v183, v183 quad_perm:[2,3,0,1] row_mask:0xf bank_mask:0xf bound_ctrl:1
	s_nop 1
	v_add_f32_dpp v183, v183, v183 row_half_mirror row_mask:0xf bank_mask:0xf bound_ctrl:1
	s_nop 1
	v_add_f32_dpp v183, v183, v183 row_mirror row_mask:0xf bank_mask:0xf bound_ctrl:1
	s_nop 1
	v_readlane_b32 s98, v183, 0
	v_readlane_b32 s99, v183, 16
	v_readlane_b32 s100, v183, 32
	v_readlane_b32 s101, v183, 48
	s_nop 1
	v_mov_b32_e32 v183, s98
	v_add_f32_e32 v183, s99, v183
	v_add_f32_e32 v183, s100, v183
	v_add_f32_e32 v183, s101, v183
	v_fmamk_f32 v183, v183, 0x3a800000, v182
	v_cmp_gt_f32_e32 vcc, 0x800000, v183
	v_mul_f32_e32 v181, 0x4b800000, v183
	s_nop 1
	v_cndmask_b32_e32 v183, v183, v181, vcc
	v_rsq_f32_e32 v183, v183
	s_nop 0
	v_mul_f32_e32 v181, 0x45800000, v183
	v_cndmask_b32_e32 v184, v183, v181, vcc
	v_mov_b32_e32 v185, v184
	v_pk_mul_f32 v[144:145], v[144:145], v[184:185]
	v_pk_mul_f32 v[146:147], v[146:147], v[184:185]
	v_pk_mul_f32 v[148:149], v[148:149], v[184:185]
	v_pk_mul_f32 v[150:151], v[150:151], v[184:185]
	v_pk_mul_f32 v[152:153], v[152:153], v[184:185]
	v_pk_mul_f32 v[154:155], v[154:155], v[184:185]
	v_pk_mul_f32 v[156:157], v[156:157], v[184:185]
	v_pk_mul_f32 v[158:159], v[158:159], v[184:185]
	v_pk_mul_f32 v[144:145], v[144:145], v[236:237]
	v_pk_mul_f32 v[146:147], v[146:147], v[238:239]
	v_pk_mul_f32 v[148:149], v[148:149], v[240:241]
	v_pk_mul_f32 v[150:151], v[150:151], v[242:243]
	v_pk_mul_f32 v[152:153], v[152:153], v[244:245]
	v_pk_mul_f32 v[154:155], v[154:155], v[246:247]
	v_pk_mul_f32 v[156:157], v[156:157], v[248:249]
	v_pk_mul_f32 v[158:159], v[158:159], v[250:251]
	v_add_u32_e32 v181, 0x3800000, v178
	global_store_dwordx4 v181, v[144:147], s[76:77]
	global_store_dwordx4 v181, v[148:151], s[76:77] offset:16
	global_store_dwordx4 v181, v[152:155], s[76:77] offset:2048
	global_store_dwordx4 v181, v[156:159], s[76:77] offset:2064
	s_nop 1
	v_readfirstlane_b32 s98, v179
	s_nop 3
	s_cmp_ge_u32 s98, 512
	s_cbranch_scc1 .Lmyxupd_done_7
	v_add_u32_e32 v181, 0x3800000, v177
	global_load_dwordx4 v[0:3], v181, s[78:79]
	global_load_dwordx4 v[4:7], v181, s[78:79] offset:1024
	v_lshl_add_u32 v183, v179, 12, v180
	v_add_u32_e32 v183, 0xbf00000, v183
	v_add_u32_e32 v181, 0x0, v183
	global_load_dwordx4 v[8:11], v181, s[78:79]
	global_load_dwordx4 v[12:15], v181, s[78:79] offset:16
	global_load_dwordx4 v[16:19], v181, s[78:79] offset:2048
	global_load_dwordx4 v[20:23], v181, s[78:79] offset:2064
	v_add_u32_e32 v181, 0x200000, v183
	global_load_dwordx4 v[24:27], v181, s[78:79]
	global_load_dwordx4 v[28:31], v181, s[78:79] offset:16
	global_load_dwordx4 v[32:35], v181, s[78:79] offset:2048
	global_load_dwordx4 v[36:39], v181, s[78:79] offset:2064
	v_add_u32_e32 v181, 0x400000, v183
	global_load_dwordx4 v[40:43], v181, s[78:79]
	global_load_dwordx4 v[44:47], v181, s[78:79] offset:16
	global_load_dwordx4 v[48:51], v181, s[78:79] offset:2048
	global_load_dwordx4 v[52:55], v181, s[78:79] offset:2064
	v_add_u32_e32 v181, 0x600000, v183
	global_load_dwordx4 v[56:59], v181, s[78:79]
	global_load_dwordx4 v[60:63], v181, s[78:79] offset:16
	global_load_dwordx4 v[64:67], v181, s[78:79] offset:2048
	global_load_dwordx4 v[68:71], v181, s[78:79] offset:2064
	v_add_u32_e32 v181, 0x800000, v183
	global_load_dwordx4 v[72:75], v181, s[78:79]
	global_load_dwordx4 v[76:79], v181, s[78:79] offset:16
	global_load_dwordx4 v[80:83], v181, s[78:79] offset:2048
	global_load_dwordx4 v[84:87], v181, s[78:79] offset:2064
	v_add_u32_e32 v181, 0xa00000, v183
	global_load_dwordx4 v[88:91], v181, s[78:79]
	global_load_dwordx4 v[92:95], v181, s[78:79] offset:16
	global_load_dwordx4 v[96:99], v181, s[78:79] offset:2048
	global_load_dwordx4 v[100:103], v181, s[78:79] offset:2064
	s_waitcnt vmcnt(20)
	v_pk_add_f32 v[160:161], v[8:9], 0 op_sel_hi:[1,0]
	v_pk_add_f32 v[162:163], v[10:11], 0 op_sel_hi:[1,0]
	v_pk_add_f32 v[164:165], v[12:13], 0 op_sel_hi:[1,0]
	v_pk_add_f32 v[166:167], v[14:15], 0 op_sel_hi:[1,0]
	v_pk_add_f32 v[168:169], v[16:17], 0 op_sel_hi:[1,0]
	v_pk_add_f32 v[170:171], v[18:19], 0 op_sel_hi:[1,0]
	v_pk_add_f32 v[172:173], v[20:21], 0 op_sel_hi:[1,0]
	v_pk_add_f32 v[174:175], v[22:23], 0 op_sel_hi:[1,0]
	s_waitcnt vmcnt(16)
	v_pk_add_f32 v[160:161], v[160:161], v[24:25]
	v_pk_add_f32 v[162:163], v[162:163], v[26:27]
	v_pk_add_f32 v[164:165], v[164:165], v[28:29]
	v_pk_add_f32 v[166:167], v[166:167], v[30:31]
	v_pk_add_f32 v[168:169], v[168:169], v[32:33]
	v_pk_add_f32 v[170:171], v[170:171], v[34:35]
	v_pk_add_f32 v[172:173], v[172:173], v[36:37]
	v_pk_add_f32 v[174:175], v[174:175], v[38:39]
	s_waitcnt vmcnt(12)
	v_pk_add_f32 v[160:161], v[160:161], v[40:41]
	v_pk_add_f32 v[162:163], v[162:163], v[42:43]
	v_pk_add_f32 v[164:165], v[164:165], v[44:45]
	v_pk_add_f32 v[166:167], v[166:167], v[46:47]
	v_pk_add_f32 v[168:169], v[168:169], v[48:49]
	v_pk_add_f32 v[170:171], v[170:171], v[50:51]
	v_pk_add_f32 v[172:173], v[172:173], v[52:53]
	v_pk_add_f32 v[174:175], v[174:175], v[54:55]
	s_waitcnt vmcnt(8)
	v_pk_add_f32 v[160:161], v[160:161], v[56:57]
	v_pk_add_f32 v[162:163], v[162:163], v[58:59]
	v_pk_add_f32 v[164:165], v[164:165], v[60:61]
	v_pk_add_f32 v[166:167], v[166:167], v[62:63]
	v_pk_add_f32 v[168:169], v[168:169], v[64:65]
	v_pk_add_f32 v[170:171], v[170:171], v[66:67]
	v_pk_add_f32 v[172:173], v[172:173], v[68:69]
	v_pk_add_f32 v[174:175], v[174:175], v[70:71]
	s_waitcnt vmcnt(4)
	v_pk_add_f32 v[160:161], v[160:161], v[72:73]
	v_pk_add_f32 v[162:163], v[162:163], v[74:75]
	v_pk_add_f32 v[164:165], v[164:165], v[76:77]
	v_pk_add_f32 v[166:167], v[166:167], v[78:79]
	v_pk_add_f32 v[168:169], v[168:169], v[80:81]
	v_pk_add_f32 v[170:171], v[170:171], v[82:83]
	v_pk_add_f32 v[172:173], v[172:173], v[84:85]
	v_pk_add_f32 v[174:175], v[174:175], v[86:87]
	s_waitcnt vmcnt(0)
	v_pk_add_f32 v[160:161], v[160:161], v[88:89]
	v_pk_add_f32 v[162:163], v[162:163], v[90:91]
	v_pk_add_f32 v[164:165], v[164:165], v[92:93]
	v_pk_add_f32 v[166:167], v[166:167], v[94:95]
	v_pk_add_f32 v[168:169], v[168:169], v[96:97]
	v_pk_add_f32 v[170:171], v[170:171], v[98:99]
	v_pk_add_f32 v[172:173], v[172:173], v[100:101]
	v_pk_add_f32 v[174:175], v[174:175], v[102:103]
	v_lshlrev_b32_e32 v144, 16, v0
	v_and_b32_e32 v145, 0xffff0000, v0
	v_lshlrev_b32_e32 v146, 16, v1
	v_and_b32_e32 v147, 0xffff0000, v1
	v_lshlrev_b32_e32 v148, 16, v2
	v_and_b32_e32 v149, 0xffff0000, v2
	v_lshlrev_b32_e32 v150, 16, v3
	v_and_b32_e32 v151, 0xffff0000, v3
	v_lshlrev_b32_e32 v152, 16, v4
	v_and_b32_e32 v153, 0xffff0000, v4
	v_lshlrev_b32_e32 v154, 16, v5
	v_and_b32_e32 v155, 0xffff0000, v5
	v_lshlrev_b32_e32 v156, 16, v6
	v_and_b32_e32 v157, 0xffff0000, v6
	v_lshlrev_b32_e32 v158, 16, v7
	v_and_b32_e32 v159, 0xffff0000, v7
	v_add_u32_e32 v181, 0xc00000, v183
	global_load_dwordx4 v[8:11], v181, s[78:79]
	global_load_dwordx4 v[12:15], v181, s[78:79] offset:16
	global_load_dwordx4 v[16:19], v181, s[78:79] offset:2048
	global_load_dwordx4 v[20:23], v181, s[78:79] offset:2064
	v_add_u32_e32 v181, 0xe00000, v183
	global_load_dwordx4 v[24:27], v181, s[78:79]
	global_load_dwordx4 v[28:31], v181, s[78:79] offset:16
	global_load_dwordx4 v[32:35], v181, s[78:79] offset:2048
	global_load_dwordx4 v[36:39], v181, s[78:79] offset:2064
	v_add_u32_e32 v181, 0x1000000, v183
	global_load_dwordx4 v[40:43], v181, s[78:79]
	global_load_dwordx4 v[44:47], v181, s[78:79] offset:16
	global_load_dwordx4 v[48:51], v181, s[78:79] offset:2048
	global_load_dwordx4 v[52:55], v181, s[78:79] offset:2064
	v_add_u32_e32 v181, 0x1200000, v183
	global_load_dwordx4 v[56:59], v181, s[78:79]
	global_load_dwordx4 v[60:63], v181, s[78:79] offset:16
	global_load_dwordx4 v[64:67], v181, s[78:79] offset:2048
	global_load_dwordx4 v[68:71], v181, s[78:79] offset:2064
	v_add_u32_e32 v181, 0x1400000, v183
	global_load_dwordx4 v[72:75], v181, s[78:79]
	global_load_dwordx4 v[76:79], v181, s[78:79] offset:16
	global_load_dwordx4 v[80:83], v181, s[78:79] offset:2048
	global_load_dwordx4 v[84:87], v181, s[78:79] offset:2064
	s_waitcnt vmcnt(16)
	v_pk_add_f32 v[160:161], v[160:161], v[8:9]
	v_pk_add_f32 v[162:163], v[162:163], v[10:11]
	v_pk_add_f32 v[164:165], v[164:165], v[12:13]
	v_pk_add_f32 v[166:167], v[166:167], v[14:15]
	v_pk_add_f32 v[168:169], v[168:169], v[16:17]
	v_pk_add_f32 v[170:171], v[170:171], v[18:19]
	v_pk_add_f32 v[172:173], v[172:173], v[20:21]
	v_pk_add_f32 v[174:175], v[174:175], v[22:23]
	s_waitcnt vmcnt(12)
	v_pk_add_f32 v[160:161], v[160:161], v[24:25]
	v_pk_add_f32 v[162:163], v[162:163], v[26:27]
	v_pk_add_f32 v[164:165], v[164:165], v[28:29]
	v_pk_add_f32 v[166:167], v[166:167], v[30:31]
	v_pk_add_f32 v[168:169], v[168:169], v[32:33]
	v_pk_add_f32 v[170:171], v[170:171], v[34:35]
	v_pk_add_f32 v[172:173], v[172:173], v[36:37]
	v_pk_add_f32 v[174:175], v[174:175], v[38:39]
	s_waitcnt vmcnt(8)
	v_pk_add_f32 v[160:161], v[160:161], v[40:41]
	v_pk_add_f32 v[162:163], v[162:163], v[42:43]
	v_pk_add_f32 v[164:165], v[164:165], v[44:45]
	v_pk_add_f32 v[166:167], v[166:167], v[46:47]
	v_pk_add_f32 v[168:169], v[168:169], v[48:49]
	v_pk_add_f32 v[170:171], v[170:171], v[50:51]
	v_pk_add_f32 v[172:173], v[172:173], v[52:53]
	v_pk_add_f32 v[174:175], v[174:175], v[54:55]
	s_waitcnt vmcnt(4)
	v_pk_add_f32 v[160:161], v[160:161], v[56:57]
	v_pk_add_f32 v[162:163], v[162:163], v[58:59]
	v_pk_add_f32 v[164:165], v[164:165], v[60:61]
	v_pk_add_f32 v[166:167], v[166:167], v[62:63]
	v_pk_add_f32 v[168:169], v[168:169], v[64:65]
	v_pk_add_f32 v[170:171], v[170:171], v[66:67]
	v_pk_add_f32 v[172:173], v[172:173], v[68:69]
	v_pk_add_f32 v[174:175], v[174:175], v[70:71]
	s_waitcnt vmcnt(0)
	v_pk_add_f32 v[160:161], v[160:161], v[72:73]
	v_pk_add_f32 v[162:163], v[162:163], v[74:75]
	v_pk_add_f32 v[164:165], v[164:165], v[76:77]
	v_pk_add_f32 v[166:167], v[166:167], v[78:79]
	v_pk_add_f32 v[168:169], v[168:169], v[80:81]
	v_pk_add_f32 v[170:171], v[170:171], v[82:83]
	v_pk_add_f32 v[172:173], v[172:173], v[84:85]
	v_pk_add_f32 v[174:175], v[174:175], v[86:87]
	v_pk_mul_f32 v[252:253], v[160:161], v[160:161]
	v_pk_mul_f32 v[254:255], v[162:163], v[162:163]
	v_pk_fma_f32 v[252:253], v[164:165], v[164:165], v[252:253]
	v_pk_fma_f32 v[254:255], v[166:167], v[166:167], v[254:255]
	v_pk_fma_f32 v[252:253], v[168:169], v[168:169], v[252:253]
	v_pk_fma_f32 v[254:255], v[170:171], v[170:171], v[254:255]
	v_pk_fma_f32 v[252:253], v[172:173], v[172:173], v[252:253]
	v_pk_fma_f32 v[254:255], v[174:175], v[174:175], v[254:255]
	v_pk_add_f32 v[252:253], v[252:253], v[254:255]
	s_nop 0
	v_add_f32_e32 v183, v252, v253
	s_nop 1
	v_add_f32_dpp v183, v183, v183 quad_perm:[1,0,3,2] row_mask:0xf bank_mask:0xf bound_ctrl:1
	s_nop 1
	v_add_f32_dpp v183, v183, v183 quad_perm:[2,3,0,1] row_mask:0xf bank_mask:0xf bound_ctrl:1
	s_nop 1
	v_add_f32_dpp v183, v183, v183 row_half_mirror row_mask:0xf bank_mask:0xf bound_ctrl:1
	s_nop 1
	v_add_f32_dpp v183, v183, v183 row_mirror row_mask:0xf bank_mask:0xf bound_ctrl:1
	s_nop 1
	v_readlane_b32 s98, v183, 0
	v_readlane_b32 s99, v183, 16
	v_readlane_b32 s100, v183, 32
	v_readlane_b32 s101, v183, 48
	s_nop 1
	v_mov_b32_e32 v183, s98
	v_add_f32_e32 v183, s99, v183
	v_add_f32_e32 v183, s100, v183
	v_add_f32_e32 v183, s101, v183
	v_fmamk_f32 v183, v183, 0x3a800000, v182
	v_cmp_gt_f32_e32 vcc, 0x800000, v183
	v_mul_f32_e32 v181, 0x4b800000, v183
	s_nop 1
	v_cndmask_b32_e32 v183, v183, v181, vcc
	v_rsq_f32_e32 v183, v183
	s_nop 0
	v_mul_f32_e32 v181, 0x45800000, v183
	v_cndmask_b32_e32 v184, v183, v181, vcc
	v_mov_b32_e32 v185, v184
	v_pk_mul_f32 v[160:161], v[160:161], v[184:185]
	v_pk_mul_f32 v[162:163], v[162:163], v[184:185]
	v_pk_mul_f32 v[164:165], v[164:165], v[184:185]
	v_pk_mul_f32 v[166:167], v[166:167], v[184:185]
	v_pk_mul_f32 v[168:169], v[168:169], v[184:185]
	v_pk_mul_f32 v[170:171], v[170:171], v[184:185]
	v_pk_mul_f32 v[172:173], v[172:173], v[184:185]
	v_pk_mul_f32 v[174:175], v[174:175], v[184:185]
	v_pk_fma_f32 v[144:145], v[160:161], v[128:129], v[144:145]
	v_pk_fma_f32 v[146:147], v[162:163], v[130:131], v[146:147]
	v_pk_fma_f32 v[148:149], v[164:165], v[132:133], v[148:149]
	v_pk_fma_f32 v[150:151], v[166:167], v[134:135], v[150:151]
	v_pk_fma_f32 v[152:153], v[168:169], v[136:137], v[152:153]
	v_pk_fma_f32 v[154:155], v[170:171], v[138:139], v[154:155]
	v_pk_fma_f32 v[156:157], v[172:173], v[140:141], v[156:157]
	v_pk_fma_f32 v[158:159], v[174:175], v[142:143], v[158:159]
	v_pk_mul_f32 v[252:253], v[144:145], v[144:145]
	v_pk_mul_f32 v[254:255], v[146:147], v[146:147]
	v_pk_fma_f32 v[252:253], v[148:149], v[148:149], v[252:253]
	v_pk_fma_f32 v[254:255], v[150:151], v[150:151], v[254:255]
	v_pk_fma_f32 v[252:253], v[152:153], v[152:153], v[252:253]
	v_pk_fma_f32 v[254:255], v[154:155], v[154:155], v[254:255]
	v_pk_fma_f32 v[252:253], v[156:157], v[156:157], v[252:253]
	v_pk_fma_f32 v[254:255], v[158:159], v[158:159], v[254:255]
	v_pk_add_f32 v[252:253], v[252:253], v[254:255]
	s_nop 0
	v_add_f32_e32 v183, v252, v253
	s_nop 1
	v_add_f32_dpp v183, v183, v183 quad_perm:[1,0,3,2] row_mask:0xf bank_mask:0xf bound_ctrl:1
	s_nop 1
	v_add_f32_dpp v183, v183, v183 quad_perm:[2,3,0,1] row_mask:0xf bank_mask:0xf bound_ctrl:1
	s_nop 1
	v_add_f32_dpp v183, v183, v183 row_half_mirror row_mask:0xf bank_mask:0xf bound_ctrl:1
	s_nop 1
	v_add_f32_dpp v183, v183, v183 row_mirror row_mask:0xf bank_mask:0xf bound_ctrl:1
	s_nop 1
	v_readlane_b32 s98, v183, 0
	v_readlane_b32 s99, v183, 16
	v_readlane_b32 s100, v183, 32
	v_readlane_b32 s101, v183, 48
	s_nop 1
	v_mov_b32_e32 v183, s98
	v_add_f32_e32 v183, s99, v183
	v_add_f32_e32 v183, s100, v183
	v_add_f32_e32 v183, s101, v183
	v_fmamk_f32 v183, v183, 0x3a800000, v182
	v_cmp_gt_f32_e32 vcc, 0x800000, v183
	v_mul_f32_e32 v181, 0x4b800000, v183
	s_nop 1
	v_cndmask_b32_e32 v183, v183, v181, vcc
	v_rsq_f32_e32 v183, v183
	s_nop 0
	v_mul_f32_e32 v181, 0x45800000, v183
	v_cndmask_b32_e32 v184, v183, v181, vcc
	v_mov_b32_e32 v185, v184
	v_pk_mul_f32 v[144:145], v[144:145], v[184:185]
	v_pk_mul_f32 v[146:147], v[146:147], v[184:185]
	v_pk_mul_f32 v[148:149], v[148:149], v[184:185]
	v_pk_mul_f32 v[150:151], v[150:151], v[184:185]
	v_pk_mul_f32 v[152:153], v[152:153], v[184:185]
	v_pk_mul_f32 v[154:155], v[154:155], v[184:185]
	v_pk_mul_f32 v[156:157], v[156:157], v[184:185]
	v_pk_mul_f32 v[158:159], v[158:159], v[184:185]
	v_pk_mul_f32 v[144:145], v[144:145], v[236:237]
	v_pk_mul_f32 v[146:147], v[146:147], v[238:239]
	v_pk_mul_f32 v[148:149], v[148:149], v[240:241]
	v_pk_mul_f32 v[150:151], v[150:151], v[242:243]
	v_pk_mul_f32 v[152:153], v[152:153], v[244:245]
	v_pk_mul_f32 v[154:155], v[154:155], v[246:247]
	v_pk_mul_f32 v[156:157], v[156:157], v[248:249]
	v_pk_mul_f32 v[158:159], v[158:159], v[250:251]
	v_add_u32_e32 v181, 0x4000000, v178
	global_store_dwordx4 v181, v[144:147], s[76:77]
	global_store_dwordx4 v181, v[148:151], s[76:77] offset:16
	global_store_dwordx4 v181, v[152:155], s[76:77] offset:2048
	global_store_dwordx4 v181, v[156:159], s[76:77] offset:2064
	s_nop 1
.Lmyxupd_done_7:
.LBB0_2864:
	s_endpgm

	.amdhsa_kernel _Z14fwd_megakernel4Args
		.amdhsa_group_segment_fixed_size 0
		.amdhsa_private_segment_fixed_size 0
		.amdhsa_kernarg_size 432
		.amdhsa_user_sgpr_count 2
		.amdhsa_user_sgpr_dispatch_ptr 0
		.amdhsa_user_sgpr_queue_ptr 0
		.amdhsa_user_sgpr_kernarg_segment_ptr 1
		.amdhsa_user_sgpr_dispatch_id 0
		.amdhsa_user_sgpr_kernarg_preload_length 0
		.amdhsa_user_sgpr_kernarg_preload_offset 0
		.amdhsa_user_sgpr_private_segment_size 0
		.amdhsa_uses_dynamic_stack 0
		.amdhsa_enable_private_segment 0
		.amdhsa_system_sgpr_workgroup_id_x 1
		.amdhsa_system_sgpr_workgroup_id_y 0
		.amdhsa_system_sgpr_workgroup_id_z 0
		.amdhsa_system_sgpr_workgroup_info 0
		.amdhsa_system_vgpr_workitem_id 2
		.amdhsa_next_free_vgpr 256
		.amdhsa_next_free_sgpr 102
		.amdhsa_accum_offset 256
		.amdhsa_reserve_vcc 1
		.amdhsa_float_round_mode_32 0
		.amdhsa_float_round_mode_16_64 0
		.amdhsa_float_denorm_mode_32 3
		.amdhsa_float_denorm_mode_16_64 3
		.amdhsa_dx10_clamp 1
		.amdhsa_ieee_mode 1
		.amdhsa_fp16_overflow 0
		.amdhsa_tg_split 0
		.amdhsa_exception_fp_ieee_invalid_op 0
		.amdhsa_exception_fp_denorm_src 0
		.amdhsa_exception_fp_ieee_div_zero 0
		.amdhsa_exception_fp_ieee_overflow 0
		.amdhsa_exception_fp_ieee_underflow 0
		.amdhsa_exception_fp_ieee_inexact 0
		.amdhsa_exception_int_div_zero 0
	.end_amdhsa_kernel

amdhsa.kernels:
  - .agpr_count:     0
    .args:
      - .offset:         0
        .size:           176
        .value_kind:     by_value
      - .offset:         176
        .size:           4
        .value_kind:     hidden_block_count_x
      - .offset:         180
        .size:           4
        .value_kind:     hidden_block_count_y
      - .offset:         184
        .size:           4
        .value_kind:     hidden_block_count_z
      - .offset:         188
        .size:           2
        .value_kind:     hidden_group_size_x
      - .offset:         190
        .size:           2
        .value_kind:     hidden_group_size_y
      - .offset:         192
        .size:           2
        .value_kind:     hidden_group_size_z
      - .offset:         194
        .size:           2
        .value_kind:     hidden_remainder_x
      - .offset:         196
        .size:           2
        .value_kind:     hidden_remainder_y
      - .offset:         198
        .size:           2
        .value_kind:     hidden_remainder_z
      - .offset:         216
        .size:           8
        .value_kind:     hidden_global_offset_x
      - .offset:         224
        .size:           8
        .value_kind:     hidden_global_offset_y
      - .offset:         232
        .size:           8
        .value_kind:     hidden_global_offset_z
      - .offset:         240
        .size:           2
        .value_kind:     hidden_grid_dims
      - .offset:         264
        .size:           8
        .value_kind:     hidden_multigrid_sync_arg
      - .offset:         296
        .size:           4
        .value_kind:     hidden_dynamic_lds_size
    .group_segment_fixed_size: 0
    .kernarg_segment_align: 8
    .kernarg_segment_size: 432
    .language:       OpenCL C
    .language_version:
      - 2
      - 0
    .max_flat_workgroup_size: 512
    .name:           _Z14fwd_megakernel4Args
    .private_segment_fixed_size: 0
    .sgpr_count:     108
    .sgpr_spill_count: 89
    .symbol:         _Z14fwd_megakernel4Args.kd
    .uniform_work_group_size: 1
    .uses_dynamic_stack: false
    .vgpr_count:     256
    .vgpr_spill_count: 0
    .wavefront_size: 64
